# removed s_setprio toggles from the GEMM K-loops on top of the hand-written RMSNorm/SwiGLU/peeled-K-iteration version
# speedup vs baseline: 1.0119x; 1.0050x over previous
; #define PG8_STAGE(bufoff, gbase, voff) do { _Pragma("unroll") for (int _i = 0; _i < 2; ++_i) \
;         __builtin_amdgcn_global_load_lds((const unsigned*)((const char*)(gbase) + (voff)[_i]), (PG8_LAS unsigned*)(lds + (bufoff) + ldsw + _i * 8192), 16, 0, 0); } while (0)
; #define PG8_LDA(dst, b, h) do { _Pragma("unroll") for (int m = 0; m < 4; ++m) _Pragma("unroll") for (int k = 0; k < 2; ++k) dst[m][k] = *(const PG8_LAS bf16x8*)(lds + PG8_SA(b, h) + aoff + m * 2048 + k * 1024); } while (0)
; #define PG8_LDB(dst, b, h) do { _Pragma("unroll") for (int n = 0; n < 2; ++n) _Pragma("unroll") for (int k = 0; k < 2; ++k) dst[n][k] = *(const PG8_LAS bf16x8*)(lds + PG8_SB(b, h) + boff + n * 2048 + k * 1024); } while (0)
; #define PG8_WAIT_V(n) asm volatile("s_waitcnt vmcnt(" #n ")" ::: "memory")
; #define PG8_WAIT_L(n) asm volatile("s_waitcnt lgkmcnt(" #n ")" ::: "memory")
; #define PG8_BAR __builtin_amdgcn_s_barrier()
; #define PG8_SCHED __builtin_amdgcn_sched_barrier(0)
; template <class Epi, class Sched, bool ALIGN_EPI = false, bool SP2 = false>
; __device__ __forceinline__ void gemm_phase(PG8_LAS unsigned char* lds, const Gemm g, const Sched& S, const Epi& E, const int tid_in) {
;     ...
;     for (;;) {
;         const bool has_next = S.next(ui + 1, nxt);
;         const char* nA = has_next ? (const char*)g.A + (size_t)nxt.pm * tstep : cA; const char* nB = has_next ? (const char*)g.Bt + (size_t)nxt.pn * tstep : cB;
;         for (int t = 0; t < nt; t += 2) {
;             const bool last = (t == nt - 2);
;             const char* a1 = cA + (size_t)(t + 1) * kstep;
;             const char* a2 = last ? nA : cA + (size_t)(t + 2) * kstep; const char* b2 = last ? nB : cB + (size_t)(t + 2) * kstep;
;             const char* a3 = a2 + kstep; const char* b3 = b2 + kstep;
;             if (last && has_next) S.a_ready(nxt);
;             if constexpr (SP2) {
;             PG8_LDB(B0, 0, 0); PG8_LDB(B1, 0, 1); PG8_SCHED; PG8_LDA(At, 0, 0); PG8_STAGE(PG8_SA(1, 1), a1 + hstep, voffA);
;             PG8_WAIT_V(8); PG8_WAIT_L(0); PG8_BAR; PG8_MMA(0, 0, At, B0); PG8_MMA(0, 1, At, B1); PG8_BAR; PG8_SCHED;
;             PG8_LDA(At, 0, 1); PG8_STAGE(PG8_SB(0, 0), b2, voffB); PG8_STAGE(PG8_SB(0, 1), b2 + hstep, voffB); PG8_STAGE(PG8_SA(0, 0), a2, voffA);
;             PG8_WAIT_V(8); PG8_WAIT_L(0); PG8_BAR; PG8_MMA(1, 0, At, B0); PG8_MMA(1, 1, At, B1); PG8_BAR; PG8_SCHED;
.LBB0_485:
	s_ashr_i32 s55, s54, 31
	s_lshl_b64 s[76:77], s[54:55], 19
	s_add_u32 s78, s36, s76
	s_addc_u32 s79, s37, s77
	s_and_b64 s[76:77], s[4:5], exec
	s_cselect_b32 s7, s79, s75
	s_cselect_b32 s18, s78, s74
	s_ashr_i32 s53, s52, 31
	s_lshl_b64 s[76:77], s[52:53], 19
	s_add_u32 s80, s34, s76
	s_addc_u32 s81, s35, s77
	s_and_b64 s[76:77], s[4:5], exec
	s_cselect_b32 s53, s81, s1
	s_cselect_b32 s55, s80, s0
	s_add_u32 s82, s74, 0x40080
	s_addc_u32 s83, s75, 0
	s_add_u32 s73, s0, 0x100
	v_mov_b32_e32 v0, 0
	s_addc_u32 s76, s1, 0
	s_mov_b32 s77, -2
	ds_read_b128 v[128:131], v174
	ds_read_b128 v[132:135], v174 offset:1024
	ds_read_b128 v[136:139], v174 offset:2048
	ds_read_b128 v[140:143], v174 offset:3072
	ds_read_b128 v[160:163], v175
	ds_read_b128 v[180:183], v175 offset:1024
	ds_read_b128 v[184:187], v175 offset:2048
	ds_read_b128 v[188:191], v175 offset:3072
	s_add_u32 s0, s82, 0xfffc0080
	s_addc_u32 s1, s83, -1
	s_cmp_eq_u32 s77, 12
	s_cselect_b32 s75, s7, s1
	s_cselect_b32 s74, s18, s0
	s_cselect_b32 s1, s53, s76
	s_cselect_b32 s0, s55, s73
	v_lshl_add_u64 v[164:165], s[82:83], 0, v[152:153]
	s_add_i32 m0, s17, 0xc000
	ds_read_b128 v[192:195], v176
	ds_read_b128 v[196:199], v176 offset:1024
	ds_read_b128 v[200:203], v176 offset:2048
	ds_read_b128 v[204:207], v176 offset:3072
	ds_read_b128 v[208:211], v176 offset:4096
	ds_read_b128 v[212:215], v176 offset:5120
	ds_read_b128 v[216:219], v176 offset:6144
	ds_read_b128 v[220:223], v176 offset:7168
	global_load_lds_dwordx4 v[164:165], off
	v_lshl_add_u64 v[164:165], s[82:83], 0, v[154:155]
	s_add_i32 m0, s17, 0xe000
	s_nop 0
	global_load_lds_dwordx4 v[164:165], off
	s_waitcnt vmcnt(8)
	s_waitcnt lgkmcnt(0)
	s_barrier
	s_waitcnt lgkmcnt(0)
	v_mfma_f32_16x16x32_bf16 v[124:127], v[128:131], v[192:195], 0
	v_mfma_f32_16x16x32_bf16 v[120:123], v[136:139], v[192:195], 0
	v_mfma_f32_16x16x32_bf16 v[108:111], v[128:131], v[200:203], 0
	v_mfma_f32_16x16x32_bf16 v[104:107], v[136:139], v[200:203], 0
	v_mfma_f32_16x16x32_bf16 v[92:95], v[128:131], v[208:211], 0
	v_mfma_f32_16x16x32_bf16 v[88:91], v[136:139], v[208:211], 0
	v_mfma_f32_16x16x32_bf16 v[76:79], v[128:131], v[216:219], 0
	v_mfma_f32_16x16x32_bf16 v[72:75], v[136:139], v[216:219], 0
	v_mfma_f32_16x16x32_bf16 v[124:127], v[132:135], v[196:199], v[124:127]
	v_mfma_f32_16x16x32_bf16 v[120:123], v[140:143], v[196:199], v[120:123]
	v_mfma_f32_16x16x32_bf16 v[108:111], v[132:135], v[204:207], v[108:111]
	v_mfma_f32_16x16x32_bf16 v[104:107], v[140:143], v[204:207], v[104:107]
	v_mfma_f32_16x16x32_bf16 v[92:95], v[132:135], v[212:215], v[92:95]
	v_mfma_f32_16x16x32_bf16 v[88:91], v[140:143], v[212:215], v[88:91]
	v_mfma_f32_16x16x32_bf16 v[76:79], v[132:135], v[220:223], v[76:79]
	v_mfma_f32_16x16x32_bf16 v[72:75], v[140:143], v[220:223], v[72:75]
	v_mfma_f32_16x16x32_bf16 v[116:119], v[160:163], v[192:195], 0
	v_mfma_f32_16x16x32_bf16 v[112:115], v[184:187], v[192:195], 0
	v_mfma_f32_16x16x32_bf16 v[100:103], v[160:163], v[200:203], 0
	v_mfma_f32_16x16x32_bf16 v[96:99], v[184:187], v[200:203], 0
	v_mfma_f32_16x16x32_bf16 v[84:87], v[160:163], v[208:211], 0
	v_mfma_f32_16x16x32_bf16 v[80:83], v[184:187], v[208:211], 0
	v_mfma_f32_16x16x32_bf16 v[68:71], v[160:163], v[216:219], 0
	v_mfma_f32_16x16x32_bf16 v[64:67], v[184:187], v[216:219], 0
	v_mfma_f32_16x16x32_bf16 v[116:119], v[180:183], v[196:199], v[116:119]
	v_mfma_f32_16x16x32_bf16 v[112:115], v[188:191], v[196:199], v[112:115]
	v_mfma_f32_16x16x32_bf16 v[100:103], v[180:183], v[204:207], v[100:103]
	v_mfma_f32_16x16x32_bf16 v[96:99], v[188:191], v[204:207], v[96:99]
	v_mfma_f32_16x16x32_bf16 v[84:87], v[180:183], v[212:215], v[84:87]
	v_mfma_f32_16x16x32_bf16 v[80:83], v[188:191], v[212:215], v[80:83]
	v_mfma_f32_16x16x32_bf16 v[68:71], v[180:183], v[220:223], v[68:71]
	v_mfma_f32_16x16x32_bf16 v[64:67], v[188:191], v[220:223], v[64:67]
	s_barrier
	s_add_i32 s84, s47, s2
	v_lshl_add_u64 v[164:165], s[0:1], 0, v[146:147]
	s_mov_b32 m0, s84
	ds_read_b128 v[192:195], v176 offset:16384
	ds_read_b128 v[196:199], v176 offset:17408
	ds_read_b128 v[200:203], v176 offset:18432
	ds_read_b128 v[204:207], v176 offset:19456
	ds_read_b128 v[208:211], v176 offset:20480
	ds_read_b128 v[212:215], v176 offset:21504
	ds_read_b128 v[216:219], v176 offset:22528
	ds_read_b128 v[220:223], v176 offset:23552
	global_load_lds_dwordx4 v[164:165], off
	s_add_i32 m0, s84, 0x2000
	s_add_u32 s84, s0, 0x40000
	v_lshl_add_u64 v[224:225], s[0:1], 0, v[150:151]
	s_addc_u32 s85, s1, 0
	s_add_i32 s86, s48, s2
	global_load_lds_dwordx4 v[224:225], off
	v_lshl_add_u64 v[226:227], s[84:85], 0, v[146:147]
	s_mov_b32 m0, s86
	v_lshl_add_u64 v[228:229], s[74:75], 0, v[148:149]
	global_load_lds_dwordx4 v[226:227], off
	v_lshl_add_u64 v[226:227], s[84:85], 0, v[150:151]
	s_add_i32 m0, s86, 0x2000
	s_nop 0
	global_load_lds_dwordx4 v[226:227], off
	v_lshl_add_u64 v[226:227], s[74:75], 0, v[144:145]
	s_mov_b32 m0, s17
	s_nop 0
	global_load_lds_dwordx4 v[226:227], off
	s_mov_b32 m0, s38
	s_nop 0
	global_load_lds_dwordx4 v[228:229], off
	s_waitcnt vmcnt(8)
	s_waitcnt lgkmcnt(0)
	s_barrier
; #define PG8_STAGE(bufoff, gbase, voff) do { _Pragma("unroll") for (int _i = 0; _i < 2; ++_i) \
;         __builtin_amdgcn_global_load_lds((const unsigned*)((const char*)(gbase) + (voff)[_i]), (PG8_LAS unsigned*)(lds + (bufoff) + ldsw + _i * 8192), 16, 0, 0); } while (0)
; #define PG8_LDA(dst, b, h) do { _Pragma("unroll") for (int m = 0; m < 4; ++m) _Pragma("unroll") for (int k = 0; k < 2; ++k) dst[m][k] = *(const PG8_LAS bf16x8*)(lds + PG8_SA(b, h) + aoff + m * 2048 + k * 1024); } while (0)
; #define PG8_LDB(dst, b, h) do { _Pragma("unroll") for (int n = 0; n < 2; ++n) _Pragma("unroll") for (int k = 0; k < 2; ++k) dst[n][k] = *(const PG8_LAS bf16x8*)(lds + PG8_SB(b, h) + boff + n * 2048 + k * 1024); } while (0)
; #define PG8_MMA(ai, bj, At, Bt) do { __builtin_amdgcn_s_setprio(1); _Pragma("unroll") for (int m = 0; m < 4; ++m) _Pragma("unroll") for (int n = 0; n < 2; ++n) _Pragma("unroll") for (int k = 0; k < 2; ++k) \
;         acc[ai][bj][m][n] = __builtin_amdgcn_mfma_f32_16x16x32_bf16(Bt[n][k], At[m][k], acc[ai][bj][m][n], 0, 0, 0); __builtin_amdgcn_s_setprio(0); } while (0)
; #define PG8_WAIT_V(n) asm volatile("s_waitcnt vmcnt(" #n ")" ::: "memory")
; #define PG8_WAIT_L(n) asm volatile("s_waitcnt lgkmcnt(" #n ")" ::: "memory")
; #define PG8_BAR __builtin_amdgcn_s_barrier()
; #define PG8_SCHED __builtin_amdgcn_sched_barrier(0)
; template <class Epi, class Sched, bool ALIGN_EPI = false, bool SP2 = false>
; __device__ __forceinline__ void gemm_phase(PG8_LAS unsigned char* lds, const Gemm g, const Sched& S, const Epi& E, const int tid_in) {
;     ...
;             PG8_WAIT_V(8); PG8_WAIT_L(0); PG8_BAR; PG8_MMA(0, 0, At, B0); PG8_MMA(0, 1, At, B1); PG8_BAR; PG8_SCHED;
;             PG8_LDA(At, 0, 1); PG8_STAGE(PG8_SB(0, 0), b2, voffB); PG8_STAGE(PG8_SB(0, 1), b2 + hstep, voffB); PG8_STAGE(PG8_SA(0, 0), a2, voffA);
;             PG8_WAIT_V(8); PG8_WAIT_L(0); PG8_BAR; PG8_MMA(1, 0, At, B0); PG8_MMA(1, 1, At, B1); PG8_BAR; PG8_SCHED;
;             PG8_LDB(B0, 1, 0); PG8_LDB(B1, 1, 1); PG8_SCHED; PG8_LDA(At, 1, 0); PG8_STAGE(PG8_SA(0, 1), a2 + hstep, voffA);
;             PG8_WAIT_V(8); PG8_WAIT_L(0); PG8_BAR; PG8_MMA(0, 0, At, B0); PG8_MMA(0, 1, At, B1); PG8_BAR; PG8_SCHED;
	s_waitcnt lgkmcnt(0)
	v_mfma_f32_16x16x32_bf16 v[60:63], v[128:131], v[192:195], 0
	v_mfma_f32_16x16x32_bf16 v[56:59], v[136:139], v[192:195], 0
	v_mfma_f32_16x16x32_bf16 v[44:47], v[128:131], v[200:203], 0
	v_mfma_f32_16x16x32_bf16 v[40:43], v[136:139], v[200:203], 0
	v_mfma_f32_16x16x32_bf16 v[28:31], v[128:131], v[208:211], 0
	v_mfma_f32_16x16x32_bf16 v[24:27], v[136:139], v[208:211], 0
	v_mfma_f32_16x16x32_bf16 v[12:15], v[128:131], v[216:219], 0
	v_mfma_f32_16x16x32_bf16 v[8:11], v[136:139], v[216:219], 0
	v_mfma_f32_16x16x32_bf16 v[60:63], v[132:135], v[196:199], v[60:63]
	v_mfma_f32_16x16x32_bf16 v[56:59], v[140:143], v[196:199], v[56:59]
	v_mfma_f32_16x16x32_bf16 v[44:47], v[132:135], v[204:207], v[44:47]
	v_mfma_f32_16x16x32_bf16 v[40:43], v[140:143], v[204:207], v[40:43]
	v_mfma_f32_16x16x32_bf16 v[28:31], v[132:135], v[212:215], v[28:31]
	v_mfma_f32_16x16x32_bf16 v[24:27], v[140:143], v[212:215], v[24:27]
	v_mfma_f32_16x16x32_bf16 v[12:15], v[132:135], v[220:223], v[12:15]
	v_mfma_f32_16x16x32_bf16 v[8:11], v[140:143], v[220:223], v[8:11]
	v_mfma_f32_16x16x32_bf16 v[52:55], v[160:163], v[192:195], 0
	v_mfma_f32_16x16x32_bf16 v[48:51], v[184:187], v[192:195], 0
	v_mfma_f32_16x16x32_bf16 v[36:39], v[160:163], v[200:203], 0
	v_mfma_f32_16x16x32_bf16 v[32:35], v[184:187], v[200:203], 0
	v_mfma_f32_16x16x32_bf16 v[20:23], v[160:163], v[208:211], 0
	v_mfma_f32_16x16x32_bf16 v[16:19], v[184:187], v[208:211], 0
	v_mfma_f32_16x16x32_bf16 v[4:7], v[160:163], v[216:219], 0
	v_mfma_f32_16x16x32_bf16 v[0:3], v[184:187], v[216:219], 0
	v_mfma_f32_16x16x32_bf16 v[52:55], v[180:183], v[196:199], v[52:55]
	v_mfma_f32_16x16x32_bf16 v[48:51], v[188:191], v[196:199], v[48:51]
	v_mfma_f32_16x16x32_bf16 v[36:39], v[180:183], v[204:207], v[36:39]
	v_mfma_f32_16x16x32_bf16 v[32:35], v[188:191], v[204:207], v[32:35]
	v_mfma_f32_16x16x32_bf16 v[20:23], v[180:183], v[212:215], v[20:23]
	v_mfma_f32_16x16x32_bf16 v[16:19], v[188:191], v[212:215], v[16:19]
	v_mfma_f32_16x16x32_bf16 v[4:7], v[180:183], v[220:223], v[4:7]
	v_mfma_f32_16x16x32_bf16 v[0:3], v[188:191], v[220:223], v[0:3]
	s_barrier
	s_add_i32 s84, 0, 0x18000
	s_add_i32 s85, 0, 0x1c000
	v_add_u32_e32 v140, s84, v168
	v_add_u32_e32 v179, s85, v168
	ds_read_b128 v[128:131], v140
	ds_read_b128 v[132:135], v140 offset:1024
	ds_read_b128 v[136:139], v140 offset:2048
	ds_read_b128 v[140:143], v140 offset:3072
	ds_read_b128 v[160:163], v179
	ds_read_b128 v[180:183], v179 offset:1024
	ds_read_b128 v[184:187], v179 offset:2048
	ds_read_b128 v[188:191], v179 offset:3072
	s_add_u32 s74, s74, 0x40000
	s_addc_u32 s75, s75, 0
	s_mov_b32 m0, s39
	v_lshl_add_u64 v[230:231], s[74:75], 0, v[144:145]
	ds_read_b128 v[192:195], v176 offset:32768
	ds_read_b128 v[196:199], v176 offset:33792
	ds_read_b128 v[200:203], v176 offset:34816
	ds_read_b128 v[204:207], v176 offset:35840
	ds_read_b128 v[208:211], v176 offset:36864
	ds_read_b128 v[212:215], v176 offset:37888
	ds_read_b128 v[216:219], v176 offset:38912
	ds_read_b128 v[220:223], v176 offset:39936
	global_load_lds_dwordx4 v[230:231], off
	v_lshl_add_u64 v[230:231], s[74:75], 0, v[148:149]
	s_mov_b32 m0, s40
	s_nop 0
	global_load_lds_dwordx4 v[230:231], off
	s_waitcnt vmcnt(8)
	s_waitcnt lgkmcnt(0)
	s_barrier
	s_waitcnt lgkmcnt(0)
	v_mfma_f32_16x16x32_bf16 v[124:127], v[128:131], v[192:195], v[124:127]
	v_mfma_f32_16x16x32_bf16 v[120:123], v[136:139], v[192:195], v[120:123]
	v_mfma_f32_16x16x32_bf16 v[108:111], v[128:131], v[200:203], v[108:111]
	v_mfma_f32_16x16x32_bf16 v[104:107], v[136:139], v[200:203], v[104:107]
	v_mfma_f32_16x16x32_bf16 v[92:95], v[128:131], v[208:211], v[92:95]
	v_mfma_f32_16x16x32_bf16 v[88:91], v[136:139], v[208:211], v[88:91]
	v_mfma_f32_16x16x32_bf16 v[76:79], v[128:131], v[216:219], v[76:79]
	v_mfma_f32_16x16x32_bf16 v[72:75], v[136:139], v[216:219], v[72:75]
	v_mfma_f32_16x16x32_bf16 v[124:127], v[132:135], v[196:199], v[124:127]
	v_mfma_f32_16x16x32_bf16 v[120:123], v[140:143], v[196:199], v[120:123]
	v_mfma_f32_16x16x32_bf16 v[108:111], v[132:135], v[204:207], v[108:111]
	v_mfma_f32_16x16x32_bf16 v[104:107], v[140:143], v[204:207], v[104:107]
	v_mfma_f32_16x16x32_bf16 v[92:95], v[132:135], v[212:215], v[92:95]
	v_mfma_f32_16x16x32_bf16 v[88:91], v[140:143], v[212:215], v[88:91]
	v_mfma_f32_16x16x32_bf16 v[76:79], v[132:135], v[220:223], v[76:79]
	v_mfma_f32_16x16x32_bf16 v[72:75], v[140:143], v[220:223], v[72:75]
	v_mfma_f32_16x16x32_bf16 v[116:119], v[160:163], v[192:195], v[116:119]
	v_mfma_f32_16x16x32_bf16 v[112:115], v[184:187], v[192:195], v[112:115]
	v_mfma_f32_16x16x32_bf16 v[100:103], v[160:163], v[200:203], v[100:103]
	v_mfma_f32_16x16x32_bf16 v[96:99], v[184:187], v[200:203], v[96:99]
	v_mfma_f32_16x16x32_bf16 v[84:87], v[160:163], v[208:211], v[84:87]
	v_mfma_f32_16x16x32_bf16 v[80:83], v[184:187], v[208:211], v[80:83]
	v_mfma_f32_16x16x32_bf16 v[68:71], v[160:163], v[216:219], v[68:71]
	v_mfma_f32_16x16x32_bf16 v[64:67], v[184:187], v[216:219], v[64:67]
	v_mfma_f32_16x16x32_bf16 v[116:119], v[180:183], v[196:199], v[116:119]
	v_mfma_f32_16x16x32_bf16 v[112:115], v[188:191], v[196:199], v[112:115]
	v_mfma_f32_16x16x32_bf16 v[100:103], v[180:183], v[204:207], v[100:103]
	v_mfma_f32_16x16x32_bf16 v[96:99], v[188:191], v[204:207], v[96:99]
	v_mfma_f32_16x16x32_bf16 v[84:87], v[180:183], v[212:215], v[84:87]
	v_mfma_f32_16x16x32_bf16 v[80:83], v[188:191], v[212:215], v[80:83]
	v_mfma_f32_16x16x32_bf16 v[68:71], v[180:183], v[220:223], v[68:71]
	v_mfma_f32_16x16x32_bf16 v[64:67], v[188:191], v[220:223], v[64:67]
	s_barrier
; #define PG8_STAGE(bufoff, gbase, voff) do { _Pragma("unroll") for (int _i = 0; _i < 2; ++_i) \
;         __builtin_amdgcn_global_load_lds((const unsigned*)((const char*)(gbase) + (voff)[_i]), (PG8_LAS unsigned*)(lds + (bufoff) + ldsw + _i * 8192), 16, 0, 0); } while (0)
; #define PG8_LDA(dst, b, h) do { _Pragma("unroll") for (int m = 0; m < 4; ++m) _Pragma("unroll") for (int k = 0; k < 2; ++k) dst[m][k] = *(const PG8_LAS bf16x8*)(lds + PG8_SA(b, h) + aoff + m * 2048 + k * 1024); } while (0)
; #define PG8_LDB(dst, b, h) do { _Pragma("unroll") for (int n = 0; n < 2; ++n) _Pragma("unroll") for (int k = 0; k < 2; ++k) dst[n][k] = *(const PG8_LAS bf16x8*)(lds + PG8_SB(b, h) + boff + n * 2048 + k * 1024); } while (0)
; #define PG8_MMA(ai, bj, At, Bt) do { __builtin_amdgcn_s_setprio(1); _Pragma("unroll") for (int m = 0; m < 4; ++m) _Pragma("unroll") for (int n = 0; n < 2; ++n) _Pragma("unroll") for (int k = 0; k < 2; ++k) \
;         acc[ai][bj][m][n] = __builtin_amdgcn_mfma_f32_16x16x32_bf16(Bt[n][k], At[m][k], acc[ai][bj][m][n], 0, 0, 0); __builtin_amdgcn_s_setprio(0); } while (0)
; #define PG8_WAIT_V(n) asm volatile("s_waitcnt vmcnt(" #n ")" ::: "memory")
; #define PG8_WAIT_L(n) asm volatile("s_waitcnt lgkmcnt(" #n ")" ::: "memory")
; #define PG8_BAR __builtin_amdgcn_s_barrier()
; template <class Epi, class Sched, bool ALIGN_EPI = false, bool SP2 = false>
; __device__ __forceinline__ void gemm_phase(PG8_LAS unsigned char* lds, const Gemm g, const Sched& S, const Epi& E, const int tid_in) {
;     ...
;         for (int t = 0; t < nt; t += 2) {
;             const bool last = (t == nt - 2);
;             const char* a1 = cA + (size_t)(t + 1) * kstep;
;             const char* a2 = last ? nA : cA + (size_t)(t + 2) * kstep; const char* b2 = last ? nB : cB + (size_t)(t + 2) * kstep;
;             const char* a3 = a2 + kstep; const char* b3 = b2 + kstep;
;     ...
;             PG8_LDB(B0, 1, 0); PG8_LDB(B1, 1, 1); PG8_SCHED; PG8_LDA(At, 1, 0); PG8_STAGE(PG8_SA(0, 1), a2 + hstep, voffA);
;             PG8_WAIT_V(8); PG8_WAIT_L(0); PG8_BAR; PG8_MMA(0, 0, At, B0); PG8_MMA(0, 1, At, B1); PG8_BAR; PG8_SCHED;
;             PG8_LDA(At, 1, 1); PG8_STAGE(PG8_SB(1, 0), b3, voffB); PG8_STAGE(PG8_SB(1, 1), b3 + hstep, voffB); PG8_STAGE(PG8_SA(1, 0), a3, voffA);
;             PG8_WAIT_V(8); PG8_WAIT_L(0); PG8_BAR; PG8_MMA(1, 0, At, B0); PG8_MMA(1, 1, At, B1); PG8_BAR; PG8_SCHED;
	s_add_i32 s74, s84, s2
	v_lshl_add_u64 v[164:165], v[164:165], 0, s[28:29]
	s_mov_b32 m0, s74
	ds_read_b128 v[192:195], v176 offset:49152
	ds_read_b128 v[196:199], v176 offset:50176
	ds_read_b128 v[200:203], v176 offset:51200
	ds_read_b128 v[204:207], v176 offset:52224
	ds_read_b128 v[208:211], v176 offset:53248
	ds_read_b128 v[212:215], v176 offset:54272
	ds_read_b128 v[216:219], v176 offset:55296
	ds_read_b128 v[220:223], v176 offset:56320
	global_load_lds_dwordx4 v[164:165], off
	s_add_i32 m0, s74, 0x2000
	s_add_u32 s0, s0, 0x40080
	v_lshl_add_u64 v[164:165], v[224:225], 0, s[28:29]
	s_addc_u32 s1, s1, 0
	s_add_i32 s74, s85, s2
	global_load_lds_dwordx4 v[164:165], off
	v_lshl_add_u64 v[164:165], s[0:1], 0, v[146:147]
	s_mov_b32 m0, s74
	s_nop 0
	global_load_lds_dwordx4 v[164:165], off
	v_lshl_add_u64 v[164:165], s[0:1], 0, v[150:151]
	s_add_i32 m0, s74, 0x2000
	s_nop 0
	global_load_lds_dwordx4 v[164:165], off
	v_lshl_add_u64 v[164:165], v[226:227], 0, s[28:29]
	s_mov_b32 m0, s43
	s_nop 0
	global_load_lds_dwordx4 v[164:165], off
	v_lshl_add_u64 v[164:165], v[228:229], 0, s[28:29]
	s_mov_b32 m0, s44
	s_nop 0
	global_load_lds_dwordx4 v[164:165], off
	s_waitcnt vmcnt(8)
	s_waitcnt lgkmcnt(0)
	s_barrier
	s_waitcnt lgkmcnt(0)
	v_mfma_f32_16x16x32_bf16 v[60:63], v[128:131], v[192:195], v[60:63]
	v_mfma_f32_16x16x32_bf16 v[56:59], v[136:139], v[192:195], v[56:59]
	v_mfma_f32_16x16x32_bf16 v[44:47], v[128:131], v[200:203], v[44:47]
	v_mfma_f32_16x16x32_bf16 v[40:43], v[136:139], v[200:203], v[40:43]
	v_mfma_f32_16x16x32_bf16 v[28:31], v[128:131], v[208:211], v[28:31]
	v_mfma_f32_16x16x32_bf16 v[24:27], v[136:139], v[208:211], v[24:27]
	v_mfma_f32_16x16x32_bf16 v[12:15], v[128:131], v[216:219], v[12:15]
	v_mfma_f32_16x16x32_bf16 v[8:11], v[136:139], v[216:219], v[8:11]
	v_mfma_f32_16x16x32_bf16 v[60:63], v[132:135], v[196:199], v[60:63]
	v_mfma_f32_16x16x32_bf16 v[56:59], v[140:143], v[196:199], v[56:59]
	v_mfma_f32_16x16x32_bf16 v[44:47], v[132:135], v[204:207], v[44:47]
	v_mfma_f32_16x16x32_bf16 v[40:43], v[140:143], v[204:207], v[40:43]
	v_mfma_f32_16x16x32_bf16 v[28:31], v[132:135], v[212:215], v[28:31]
	v_mfma_f32_16x16x32_bf16 v[24:27], v[140:143], v[212:215], v[24:27]
	v_mfma_f32_16x16x32_bf16 v[12:15], v[132:135], v[220:223], v[12:15]
	v_mfma_f32_16x16x32_bf16 v[8:11], v[140:143], v[220:223], v[8:11]
	v_mfma_f32_16x16x32_bf16 v[52:55], v[160:163], v[192:195], v[52:55]
	v_mfma_f32_16x16x32_bf16 v[48:51], v[184:187], v[192:195], v[48:51]
	v_mfma_f32_16x16x32_bf16 v[36:39], v[160:163], v[200:203], v[36:39]
	v_mfma_f32_16x16x32_bf16 v[32:35], v[184:187], v[200:203], v[32:35]
	v_mfma_f32_16x16x32_bf16 v[20:23], v[160:163], v[208:211], v[20:23]
	v_mfma_f32_16x16x32_bf16 v[16:19], v[184:187], v[208:211], v[16:19]
	v_mfma_f32_16x16x32_bf16 v[4:7], v[160:163], v[216:219], v[4:7]
	v_mfma_f32_16x16x32_bf16 v[0:3], v[184:187], v[216:219], v[0:3]
	v_mfma_f32_16x16x32_bf16 v[52:55], v[180:183], v[196:199], v[52:55]
	v_mfma_f32_16x16x32_bf16 v[48:51], v[188:191], v[196:199], v[48:51]
	v_mfma_f32_16x16x32_bf16 v[36:39], v[180:183], v[204:207], v[36:39]
	v_mfma_f32_16x16x32_bf16 v[32:35], v[188:191], v[204:207], v[32:35]
	v_mfma_f32_16x16x32_bf16 v[20:23], v[180:183], v[212:215], v[20:23]
	v_mfma_f32_16x16x32_bf16 v[16:19], v[188:191], v[212:215], v[16:19]
	v_mfma_f32_16x16x32_bf16 v[4:7], v[180:183], v[220:223], v[4:7]
	v_mfma_f32_16x16x32_bf16 v[0:3], v[188:191], v[220:223], v[0:3]
	s_barrier
	s_add_i32 s77, s77, 2
	s_add_u32 s82, s82, 0x100
	s_addc_u32 s83, s83, 0
	s_add_u32 s73, s73, 0x100
	s_addc_u32 s76, s76, 0
	s_cmp_gt_u32 s77, 13
	s_cbranch_scc0 .LBB0_486
	s_branch .Lmy_kdone_1
.LBB0_486:
	ds_read_b128 v[128:131], v174
	ds_read_b128 v[132:135], v174 offset:1024
	ds_read_b128 v[136:139], v174 offset:2048
	ds_read_b128 v[140:143], v174 offset:3072
	ds_read_b128 v[160:163], v175
	ds_read_b128 v[180:183], v175 offset:1024
	ds_read_b128 v[184:187], v175 offset:2048
	ds_read_b128 v[188:191], v175 offset:3072
	s_add_u32 s0, s82, 0xfffc0080
	s_addc_u32 s1, s83, -1
	s_cmp_eq_u32 s77, 12
	s_cselect_b32 s75, s7, s1
	s_cselect_b32 s74, s18, s0
	s_cselect_b32 s1, s53, s76
	s_cselect_b32 s0, s55, s73
	v_lshl_add_u64 v[164:165], s[82:83], 0, v[152:153]
	s_add_i32 m0, s17, 0xc000
	ds_read_b128 v[192:195], v176
	ds_read_b128 v[196:199], v176 offset:1024
	ds_read_b128 v[200:203], v176 offset:2048
	ds_read_b128 v[204:207], v176 offset:3072
	ds_read_b128 v[208:211], v176 offset:4096
	ds_read_b128 v[212:215], v176 offset:5120
	ds_read_b128 v[216:219], v176 offset:6144
	ds_read_b128 v[220:223], v176 offset:7168
	global_load_lds_dwordx4 v[164:165], off
	v_lshl_add_u64 v[164:165], s[82:83], 0, v[154:155]
	s_add_i32 m0, s17, 0xe000
	s_nop 0
	global_load_lds_dwordx4 v[164:165], off
	s_waitcnt vmcnt(8)
	s_waitcnt lgkmcnt(0)
	s_barrier
; #define PG8_STAGE(bufoff, gbase, voff) do { _Pragma("unroll") for (int _i = 0; _i < 2; ++_i) \
;         __builtin_amdgcn_global_load_lds((const unsigned*)((const char*)(gbase) + (voff)[_i]), (PG8_LAS unsigned*)(lds + (bufoff) + ldsw + _i * 8192), 16, 0, 0); } while (0)
; #define PG8_LDA(dst, b, h) do { _Pragma("unroll") for (int m = 0; m < 4; ++m) _Pragma("unroll") for (int k = 0; k < 2; ++k) dst[m][k] = *(const PG8_LAS bf16x8*)(lds + PG8_SA(b, h) + aoff + m * 2048 + k * 1024); } while (0)
; #define PG8_LDB(dst, b, h) do { _Pragma("unroll") for (int n = 0; n < 2; ++n) _Pragma("unroll") for (int k = 0; k < 2; ++k) dst[n][k] = *(const PG8_LAS bf16x8*)(lds + PG8_SB(b, h) + boff + n * 2048 + k * 1024); } while (0)
; #define PG8_MMA(ai, bj, At, Bt) do { __builtin_amdgcn_s_setprio(1); _Pragma("unroll") for (int m = 0; m < 4; ++m) _Pragma("unroll") for (int n = 0; n < 2; ++n) _Pragma("unroll") for (int k = 0; k < 2; ++k) \
;         acc[ai][bj][m][n] = __builtin_amdgcn_mfma_f32_16x16x32_bf16(Bt[n][k], At[m][k], acc[ai][bj][m][n], 0, 0, 0); __builtin_amdgcn_s_setprio(0); } while (0)
; #define PG8_WAIT_V(n) asm volatile("s_waitcnt vmcnt(" #n ")" ::: "memory")
; #define PG8_WAIT_L(n) asm volatile("s_waitcnt lgkmcnt(" #n ")" ::: "memory")
; #define PG8_BAR __builtin_amdgcn_s_barrier()
; #define PG8_SCHED __builtin_amdgcn_sched_barrier(0)
; template <class Epi, class Sched, bool ALIGN_EPI = false, bool SP2 = false>
; __device__ __forceinline__ void gemm_phase(PG8_LAS unsigned char* lds, const Gemm g, const Sched& S, const Epi& E, const int tid_in) {
;     ...
;             PG8_LDB(B0, 0, 0); PG8_LDB(B1, 0, 1); PG8_SCHED; PG8_LDA(At, 0, 0); PG8_STAGE(PG8_SA(1, 1), a1 + hstep, voffA);
;             PG8_WAIT_V(8); PG8_WAIT_L(0); PG8_BAR; PG8_MMA(0, 0, At, B0); PG8_MMA(0, 1, At, B1); PG8_BAR; PG8_SCHED;
;             PG8_LDA(At, 0, 1); PG8_STAGE(PG8_SB(0, 0), b2, voffB); PG8_STAGE(PG8_SB(0, 1), b2 + hstep, voffB); PG8_STAGE(PG8_SA(0, 0), a2, voffA);
;             PG8_WAIT_V(8); PG8_WAIT_L(0); PG8_BAR; PG8_MMA(1, 0, At, B0); PG8_MMA(1, 1, At, B1); PG8_BAR; PG8_SCHED;
	s_waitcnt lgkmcnt(0)
	v_mfma_f32_16x16x32_bf16 v[124:127], v[128:131], v[192:195], v[124:127]
	v_mfma_f32_16x16x32_bf16 v[120:123], v[136:139], v[192:195], v[120:123]
	v_mfma_f32_16x16x32_bf16 v[108:111], v[128:131], v[200:203], v[108:111]
	v_mfma_f32_16x16x32_bf16 v[104:107], v[136:139], v[200:203], v[104:107]
	v_mfma_f32_16x16x32_bf16 v[92:95], v[128:131], v[208:211], v[92:95]
	v_mfma_f32_16x16x32_bf16 v[88:91], v[136:139], v[208:211], v[88:91]
	v_mfma_f32_16x16x32_bf16 v[76:79], v[128:131], v[216:219], v[76:79]
	v_mfma_f32_16x16x32_bf16 v[72:75], v[136:139], v[216:219], v[72:75]
	v_mfma_f32_16x16x32_bf16 v[124:127], v[132:135], v[196:199], v[124:127]
	v_mfma_f32_16x16x32_bf16 v[120:123], v[140:143], v[196:199], v[120:123]
	v_mfma_f32_16x16x32_bf16 v[108:111], v[132:135], v[204:207], v[108:111]
	v_mfma_f32_16x16x32_bf16 v[104:107], v[140:143], v[204:207], v[104:107]
	v_mfma_f32_16x16x32_bf16 v[92:95], v[132:135], v[212:215], v[92:95]
	v_mfma_f32_16x16x32_bf16 v[88:91], v[140:143], v[212:215], v[88:91]
	v_mfma_f32_16x16x32_bf16 v[76:79], v[132:135], v[220:223], v[76:79]
	v_mfma_f32_16x16x32_bf16 v[72:75], v[140:143], v[220:223], v[72:75]
	v_mfma_f32_16x16x32_bf16 v[116:119], v[160:163], v[192:195], v[116:119]
	v_mfma_f32_16x16x32_bf16 v[112:115], v[184:187], v[192:195], v[112:115]
	v_mfma_f32_16x16x32_bf16 v[100:103], v[160:163], v[200:203], v[100:103]
	v_mfma_f32_16x16x32_bf16 v[96:99], v[184:187], v[200:203], v[96:99]
	v_mfma_f32_16x16x32_bf16 v[84:87], v[160:163], v[208:211], v[84:87]
	v_mfma_f32_16x16x32_bf16 v[80:83], v[184:187], v[208:211], v[80:83]
	v_mfma_f32_16x16x32_bf16 v[68:71], v[160:163], v[216:219], v[68:71]
	v_mfma_f32_16x16x32_bf16 v[64:67], v[184:187], v[216:219], v[64:67]
	v_mfma_f32_16x16x32_bf16 v[116:119], v[180:183], v[196:199], v[116:119]
	v_mfma_f32_16x16x32_bf16 v[112:115], v[188:191], v[196:199], v[112:115]
	v_mfma_f32_16x16x32_bf16 v[100:103], v[180:183], v[204:207], v[100:103]
	v_mfma_f32_16x16x32_bf16 v[96:99], v[188:191], v[204:207], v[96:99]
	v_mfma_f32_16x16x32_bf16 v[84:87], v[180:183], v[212:215], v[84:87]
	v_mfma_f32_16x16x32_bf16 v[80:83], v[188:191], v[212:215], v[80:83]
	v_mfma_f32_16x16x32_bf16 v[68:71], v[180:183], v[220:223], v[68:71]
	v_mfma_f32_16x16x32_bf16 v[64:67], v[188:191], v[220:223], v[64:67]
	s_barrier
	s_add_i32 s84, s47, s2
	v_lshl_add_u64 v[164:165], s[0:1], 0, v[146:147]
	s_mov_b32 m0, s84
	ds_read_b128 v[192:195], v176 offset:16384
	ds_read_b128 v[196:199], v176 offset:17408
	ds_read_b128 v[200:203], v176 offset:18432
	ds_read_b128 v[204:207], v176 offset:19456
	ds_read_b128 v[208:211], v176 offset:20480
	ds_read_b128 v[212:215], v176 offset:21504
	ds_read_b128 v[216:219], v176 offset:22528
	ds_read_b128 v[220:223], v176 offset:23552
	global_load_lds_dwordx4 v[164:165], off
	s_add_i32 m0, s84, 0x2000
	s_add_u32 s84, s0, 0x40000
	v_lshl_add_u64 v[224:225], s[0:1], 0, v[150:151]
	s_addc_u32 s85, s1, 0
	s_add_i32 s86, s48, s2
	global_load_lds_dwordx4 v[224:225], off
	v_lshl_add_u64 v[226:227], s[84:85], 0, v[146:147]
	s_mov_b32 m0, s86
	v_lshl_add_u64 v[228:229], s[74:75], 0, v[148:149]
	global_load_lds_dwordx4 v[226:227], off
	v_lshl_add_u64 v[226:227], s[84:85], 0, v[150:151]
	s_add_i32 m0, s86, 0x2000
	s_nop 0
	global_load_lds_dwordx4 v[226:227], off
	v_lshl_add_u64 v[226:227], s[74:75], 0, v[144:145]
	s_mov_b32 m0, s17
	s_nop 0
	global_load_lds_dwordx4 v[226:227], off
	s_mov_b32 m0, s38
	s_nop 0
	global_load_lds_dwordx4 v[228:229], off
	s_waitcnt vmcnt(8)
	s_waitcnt lgkmcnt(0)
	s_barrier
	s_waitcnt lgkmcnt(0)
	v_mfma_f32_16x16x32_bf16 v[60:63], v[128:131], v[192:195], v[60:63]
	v_mfma_f32_16x16x32_bf16 v[56:59], v[136:139], v[192:195], v[56:59]
	v_mfma_f32_16x16x32_bf16 v[44:47], v[128:131], v[200:203], v[44:47]
	v_mfma_f32_16x16x32_bf16 v[40:43], v[136:139], v[200:203], v[40:43]
	v_mfma_f32_16x16x32_bf16 v[28:31], v[128:131], v[208:211], v[28:31]
	v_mfma_f32_16x16x32_bf16 v[24:27], v[136:139], v[208:211], v[24:27]
	v_mfma_f32_16x16x32_bf16 v[12:15], v[128:131], v[216:219], v[12:15]
	v_mfma_f32_16x16x32_bf16 v[8:11], v[136:139], v[216:219], v[8:11]
	v_mfma_f32_16x16x32_bf16 v[60:63], v[132:135], v[196:199], v[60:63]
	v_mfma_f32_16x16x32_bf16 v[56:59], v[140:143], v[196:199], v[56:59]
	v_mfma_f32_16x16x32_bf16 v[44:47], v[132:135], v[204:207], v[44:47]
	v_mfma_f32_16x16x32_bf16 v[40:43], v[140:143], v[204:207], v[40:43]
	v_mfma_f32_16x16x32_bf16 v[28:31], v[132:135], v[212:215], v[28:31]
	v_mfma_f32_16x16x32_bf16 v[24:27], v[140:143], v[212:215], v[24:27]
	v_mfma_f32_16x16x32_bf16 v[12:15], v[132:135], v[220:223], v[12:15]
	v_mfma_f32_16x16x32_bf16 v[8:11], v[140:143], v[220:223], v[8:11]
	v_mfma_f32_16x16x32_bf16 v[52:55], v[160:163], v[192:195], v[52:55]
	v_mfma_f32_16x16x32_bf16 v[48:51], v[184:187], v[192:195], v[48:51]
	v_mfma_f32_16x16x32_bf16 v[36:39], v[160:163], v[200:203], v[36:39]
	v_mfma_f32_16x16x32_bf16 v[32:35], v[184:187], v[200:203], v[32:35]
	v_mfma_f32_16x16x32_bf16 v[20:23], v[160:163], v[208:211], v[20:23]
	v_mfma_f32_16x16x32_bf16 v[16:19], v[184:187], v[208:211], v[16:19]
	v_mfma_f32_16x16x32_bf16 v[4:7], v[160:163], v[216:219], v[4:7]
	v_mfma_f32_16x16x32_bf16 v[0:3], v[184:187], v[216:219], v[0:3]
	v_mfma_f32_16x16x32_bf16 v[52:55], v[180:183], v[196:199], v[52:55]
	v_mfma_f32_16x16x32_bf16 v[48:51], v[188:191], v[196:199], v[48:51]
	v_mfma_f32_16x16x32_bf16 v[36:39], v[180:183], v[204:207], v[36:39]
	v_mfma_f32_16x16x32_bf16 v[32:35], v[188:191], v[204:207], v[32:35]
	v_mfma_f32_16x16x32_bf16 v[20:23], v[180:183], v[212:215], v[20:23]
	v_mfma_f32_16x16x32_bf16 v[16:19], v[188:191], v[212:215], v[16:19]
	v_mfma_f32_16x16x32_bf16 v[4:7], v[180:183], v[220:223], v[4:7]
	v_mfma_f32_16x16x32_bf16 v[0:3], v[188:191], v[220:223], v[0:3]
	s_barrier
; #define PG8_STAGE(bufoff, gbase, voff) do { _Pragma("unroll") for (int _i = 0; _i < 2; ++_i) \
;         __builtin_amdgcn_global_load_lds((const unsigned*)((const char*)(gbase) + (voff)[_i]), (PG8_LAS unsigned*)(lds + (bufoff) + ldsw + _i * 8192), 16, 0, 0); } while (0)
; #define PG8_LDA(dst, b, h) do { _Pragma("unroll") for (int m = 0; m < 4; ++m) _Pragma("unroll") for (int k = 0; k < 2; ++k) dst[m][k] = *(const PG8_LAS bf16x8*)(lds + PG8_SA(b, h) + aoff + m * 2048 + k * 1024); } while (0)
; #define PG8_LDB(dst, b, h) do { _Pragma("unroll") for (int n = 0; n < 2; ++n) _Pragma("unroll") for (int k = 0; k < 2; ++k) dst[n][k] = *(const PG8_LAS bf16x8*)(lds + PG8_SB(b, h) + boff + n * 2048 + k * 1024); } while (0)
; #define PG8_MMA(ai, bj, At, Bt) do { __builtin_amdgcn_s_setprio(1); _Pragma("unroll") for (int m = 0; m < 4; ++m) _Pragma("unroll") for (int n = 0; n < 2; ++n) _Pragma("unroll") for (int k = 0; k < 2; ++k) \
;         acc[ai][bj][m][n] = __builtin_amdgcn_mfma_f32_16x16x32_bf16(Bt[n][k], At[m][k], acc[ai][bj][m][n], 0, 0, 0); __builtin_amdgcn_s_setprio(0); } while (0)
; #define PG8_WAIT_V(n) asm volatile("s_waitcnt vmcnt(" #n ")" ::: "memory")
; #define PG8_WAIT_L(n) asm volatile("s_waitcnt lgkmcnt(" #n ")" ::: "memory")
; #define PG8_BAR __builtin_amdgcn_s_barrier()
; #define PG8_SCHED __builtin_amdgcn_sched_barrier(0)
; template <class Epi, class Sched, bool ALIGN_EPI = false, bool SP2 = false>
; __device__ __forceinline__ void gemm_phase(PG8_LAS unsigned char* lds, const Gemm g, const Sched& S, const Epi& E, const int tid_in) {
;     ...
;             PG8_LDB(B0, 1, 0); PG8_LDB(B1, 1, 1); PG8_SCHED; PG8_LDA(At, 1, 0); PG8_STAGE(PG8_SA(0, 1), a2 + hstep, voffA);
;             PG8_WAIT_V(8); PG8_WAIT_L(0); PG8_BAR; PG8_MMA(0, 0, At, B0); PG8_MMA(0, 1, At, B1); PG8_BAR; PG8_SCHED;
;             PG8_LDA(At, 1, 1); PG8_STAGE(PG8_SB(1, 0), b3, voffB); PG8_STAGE(PG8_SB(1, 1), b3 + hstep, voffB); PG8_STAGE(PG8_SA(1, 0), a3, voffA);
;             PG8_WAIT_V(8); PG8_WAIT_L(0); PG8_BAR; PG8_MMA(1, 0, At, B0); PG8_MMA(1, 1, At, B1); PG8_BAR; PG8_SCHED;
	s_add_i32 s84, 0, 0x18000
	s_add_i32 s85, 0, 0x1c000
	v_add_u32_e32 v140, s84, v168
	v_add_u32_e32 v179, s85, v168
	ds_read_b128 v[128:131], v140
	ds_read_b128 v[132:135], v140 offset:1024
	ds_read_b128 v[136:139], v140 offset:2048
	ds_read_b128 v[140:143], v140 offset:3072
	ds_read_b128 v[160:163], v179
	ds_read_b128 v[180:183], v179 offset:1024
	ds_read_b128 v[184:187], v179 offset:2048
	ds_read_b128 v[188:191], v179 offset:3072
	s_add_u32 s74, s74, 0x40000
	s_addc_u32 s75, s75, 0
	s_mov_b32 m0, s39
	v_lshl_add_u64 v[230:231], s[74:75], 0, v[144:145]
	ds_read_b128 v[192:195], v176 offset:32768
	ds_read_b128 v[196:199], v176 offset:33792
	ds_read_b128 v[200:203], v176 offset:34816
	ds_read_b128 v[204:207], v176 offset:35840
	ds_read_b128 v[208:211], v176 offset:36864
	ds_read_b128 v[212:215], v176 offset:37888
	ds_read_b128 v[216:219], v176 offset:38912
	ds_read_b128 v[220:223], v176 offset:39936
	global_load_lds_dwordx4 v[230:231], off
	v_lshl_add_u64 v[230:231], s[74:75], 0, v[148:149]
	s_mov_b32 m0, s40
	s_nop 0
	global_load_lds_dwordx4 v[230:231], off
	s_waitcnt vmcnt(8)
	s_waitcnt lgkmcnt(0)
	s_barrier
	s_waitcnt lgkmcnt(0)
	v_mfma_f32_16x16x32_bf16 v[124:127], v[128:131], v[192:195], v[124:127]
	v_mfma_f32_16x16x32_bf16 v[120:123], v[136:139], v[192:195], v[120:123]
	v_mfma_f32_16x16x32_bf16 v[108:111], v[128:131], v[200:203], v[108:111]
	v_mfma_f32_16x16x32_bf16 v[104:107], v[136:139], v[200:203], v[104:107]
	v_mfma_f32_16x16x32_bf16 v[92:95], v[128:131], v[208:211], v[92:95]
	v_mfma_f32_16x16x32_bf16 v[88:91], v[136:139], v[208:211], v[88:91]
	v_mfma_f32_16x16x32_bf16 v[76:79], v[128:131], v[216:219], v[76:79]
	v_mfma_f32_16x16x32_bf16 v[72:75], v[136:139], v[216:219], v[72:75]
	v_mfma_f32_16x16x32_bf16 v[124:127], v[132:135], v[196:199], v[124:127]
	v_mfma_f32_16x16x32_bf16 v[120:123], v[140:143], v[196:199], v[120:123]
	v_mfma_f32_16x16x32_bf16 v[108:111], v[132:135], v[204:207], v[108:111]
	v_mfma_f32_16x16x32_bf16 v[104:107], v[140:143], v[204:207], v[104:107]
	v_mfma_f32_16x16x32_bf16 v[92:95], v[132:135], v[212:215], v[92:95]
	v_mfma_f32_16x16x32_bf16 v[88:91], v[140:143], v[212:215], v[88:91]
	v_mfma_f32_16x16x32_bf16 v[76:79], v[132:135], v[220:223], v[76:79]
	v_mfma_f32_16x16x32_bf16 v[72:75], v[140:143], v[220:223], v[72:75]
	v_mfma_f32_16x16x32_bf16 v[116:119], v[160:163], v[192:195], v[116:119]
	v_mfma_f32_16x16x32_bf16 v[112:115], v[184:187], v[192:195], v[112:115]
	v_mfma_f32_16x16x32_bf16 v[100:103], v[160:163], v[200:203], v[100:103]
	v_mfma_f32_16x16x32_bf16 v[96:99], v[184:187], v[200:203], v[96:99]
	v_mfma_f32_16x16x32_bf16 v[84:87], v[160:163], v[208:211], v[84:87]
	v_mfma_f32_16x16x32_bf16 v[80:83], v[184:187], v[208:211], v[80:83]
	v_mfma_f32_16x16x32_bf16 v[68:71], v[160:163], v[216:219], v[68:71]
	v_mfma_f32_16x16x32_bf16 v[64:67], v[184:187], v[216:219], v[64:67]
	v_mfma_f32_16x16x32_bf16 v[116:119], v[180:183], v[196:199], v[116:119]
	v_mfma_f32_16x16x32_bf16 v[112:115], v[188:191], v[196:199], v[112:115]
	v_mfma_f32_16x16x32_bf16 v[100:103], v[180:183], v[204:207], v[100:103]
	v_mfma_f32_16x16x32_bf16 v[96:99], v[188:191], v[204:207], v[96:99]
	v_mfma_f32_16x16x32_bf16 v[84:87], v[180:183], v[212:215], v[84:87]
	v_mfma_f32_16x16x32_bf16 v[80:83], v[188:191], v[212:215], v[80:83]
	v_mfma_f32_16x16x32_bf16 v[68:71], v[180:183], v[220:223], v[68:71]
	v_mfma_f32_16x16x32_bf16 v[64:67], v[188:191], v[220:223], v[64:67]
	s_barrier
	s_add_i32 s74, s84, s2
	v_lshl_add_u64 v[164:165], v[164:165], 0, s[28:29]
	s_mov_b32 m0, s74
	ds_read_b128 v[192:195], v176 offset:49152
	ds_read_b128 v[196:199], v176 offset:50176
	ds_read_b128 v[200:203], v176 offset:51200
	ds_read_b128 v[204:207], v176 offset:52224
	ds_read_b128 v[208:211], v176 offset:53248
	ds_read_b128 v[212:215], v176 offset:54272
	ds_read_b128 v[216:219], v176 offset:55296
	ds_read_b128 v[220:223], v176 offset:56320
	global_load_lds_dwordx4 v[164:165], off
	s_add_i32 m0, s74, 0x2000
	s_add_u32 s0, s0, 0x40080
	v_lshl_add_u64 v[164:165], v[224:225], 0, s[28:29]
	s_addc_u32 s1, s1, 0
	s_add_i32 s74, s85, s2
	global_load_lds_dwordx4 v[164:165], off
	v_lshl_add_u64 v[164:165], s[0:1], 0, v[146:147]
	s_mov_b32 m0, s74
	s_nop 0
	global_load_lds_dwordx4 v[164:165], off
	v_lshl_add_u64 v[164:165], s[0:1], 0, v[150:151]
	s_add_i32 m0, s74, 0x2000
	s_nop 0
	global_load_lds_dwordx4 v[164:165], off
	v_lshl_add_u64 v[164:165], v[226:227], 0, s[28:29]
	s_mov_b32 m0, s43
	s_nop 0
	global_load_lds_dwordx4 v[164:165], off
	v_lshl_add_u64 v[164:165], v[228:229], 0, s[28:29]
	s_mov_b32 m0, s44
	s_nop 0
	global_load_lds_dwordx4 v[164:165], off
	s_waitcnt vmcnt(8)
	s_waitcnt lgkmcnt(0)
	s_barrier
	s_waitcnt lgkmcnt(0)
	v_mfma_f32_16x16x32_bf16 v[60:63], v[128:131], v[192:195], v[60:63]
	v_mfma_f32_16x16x32_bf16 v[56:59], v[136:139], v[192:195], v[56:59]
	v_mfma_f32_16x16x32_bf16 v[44:47], v[128:131], v[200:203], v[44:47]
	v_mfma_f32_16x16x32_bf16 v[40:43], v[136:139], v[200:203], v[40:43]
	v_mfma_f32_16x16x32_bf16 v[28:31], v[128:131], v[208:211], v[28:31]
	v_mfma_f32_16x16x32_bf16 v[24:27], v[136:139], v[208:211], v[24:27]
	v_mfma_f32_16x16x32_bf16 v[12:15], v[128:131], v[216:219], v[12:15]
	v_mfma_f32_16x16x32_bf16 v[8:11], v[136:139], v[216:219], v[8:11]
	v_mfma_f32_16x16x32_bf16 v[60:63], v[132:135], v[196:199], v[60:63]
	v_mfma_f32_16x16x32_bf16 v[56:59], v[140:143], v[196:199], v[56:59]
	v_mfma_f32_16x16x32_bf16 v[44:47], v[132:135], v[204:207], v[44:47]
	v_mfma_f32_16x16x32_bf16 v[40:43], v[140:143], v[204:207], v[40:43]
	v_mfma_f32_16x16x32_bf16 v[28:31], v[132:135], v[212:215], v[28:31]
	v_mfma_f32_16x16x32_bf16 v[24:27], v[140:143], v[212:215], v[24:27]
	v_mfma_f32_16x16x32_bf16 v[12:15], v[132:135], v[220:223], v[12:15]
	v_mfma_f32_16x16x32_bf16 v[8:11], v[140:143], v[220:223], v[8:11]
	v_mfma_f32_16x16x32_bf16 v[52:55], v[160:163], v[192:195], v[52:55]
	v_mfma_f32_16x16x32_bf16 v[48:51], v[184:187], v[192:195], v[48:51]
	v_mfma_f32_16x16x32_bf16 v[36:39], v[160:163], v[200:203], v[36:39]
	v_mfma_f32_16x16x32_bf16 v[32:35], v[184:187], v[200:203], v[32:35]
	v_mfma_f32_16x16x32_bf16 v[20:23], v[160:163], v[208:211], v[20:23]
	v_mfma_f32_16x16x32_bf16 v[16:19], v[184:187], v[208:211], v[16:19]
	v_mfma_f32_16x16x32_bf16 v[4:7], v[160:163], v[216:219], v[4:7]
	v_mfma_f32_16x16x32_bf16 v[0:3], v[184:187], v[216:219], v[0:3]
	v_mfma_f32_16x16x32_bf16 v[52:55], v[180:183], v[196:199], v[52:55]
	v_mfma_f32_16x16x32_bf16 v[48:51], v[188:191], v[196:199], v[48:51]
	v_mfma_f32_16x16x32_bf16 v[36:39], v[180:183], v[204:207], v[36:39]
	v_mfma_f32_16x16x32_bf16 v[32:35], v[188:191], v[204:207], v[32:35]
	v_mfma_f32_16x16x32_bf16 v[20:23], v[180:183], v[212:215], v[20:23]
	v_mfma_f32_16x16x32_bf16 v[16:19], v[188:191], v[212:215], v[16:19]
	v_mfma_f32_16x16x32_bf16 v[4:7], v[180:183], v[220:223], v[4:7]
	v_mfma_f32_16x16x32_bf16 v[0:3], v[188:191], v[220:223], v[0:3]
	s_barrier
	s_add_i32 s77, s77, 2
	s_add_u32 s82, s82, 0x100
	s_addc_u32 s83, s83, 0
	s_add_u32 s73, s73, 0x100
	s_addc_u32 s76, s76, 0
	s_cmp_gt_u32 s77, 13
	s_cbranch_scc0 .LBB0_486

; #define PG8_STAGE(bufoff, gbase, voff) do { _Pragma("unroll") for (int _i = 0; _i < 2; ++_i) \
;         __builtin_amdgcn_global_load_lds((const unsigned*)((const char*)(gbase) + (voff)[_i]), (PG8_LAS unsigned*)(lds + (bufoff) + ldsw + _i * 8192), 16, 0, 0); } while (0)
; #define PG8_LDA(dst, b, h) do { _Pragma("unroll") for (int m = 0; m < 4; ++m) _Pragma("unroll") for (int k = 0; k < 2; ++k) dst[m][k] = *(const PG8_LAS bf16x8*)(lds + PG8_SA(b, h) + aoff + m * 2048 + k * 1024); } while (0)
; #define PG8_LDB(dst, b, h) do { _Pragma("unroll") for (int n = 0; n < 2; ++n) _Pragma("unroll") for (int k = 0; k < 2; ++k) dst[n][k] = *(const PG8_LAS bf16x8*)(lds + PG8_SB(b, h) + boff + n * 2048 + k * 1024); } while (0)
; #define PG8_WAIT_V(n) asm volatile("s_waitcnt vmcnt(" #n ")" ::: "memory")
; #define PG8_WAIT_L(n) asm volatile("s_waitcnt lgkmcnt(" #n ")" ::: "memory")
; #define PG8_BAR __builtin_amdgcn_s_barrier()
; #define PG8_SCHED __builtin_amdgcn_sched_barrier(0)
; template <class Epi, class Sched, bool ALIGN_EPI = false, bool SP2 = false>
; __device__ __forceinline__ void gemm_phase(PG8_LAS unsigned char* lds, const Gemm g, const Sched& S, const Epi& E, const int tid_in) {
;     ...
;     for (;;) {
;         const bool has_next = S.next(ui + 1, nxt);
;         const char* nA = has_next ? (const char*)g.A + (size_t)nxt.pm * tstep : cA; const char* nB = has_next ? (const char*)g.Bt + (size_t)nxt.pn * tstep : cB;
;         for (int t = 0; t < nt; t += 2) {
;             const bool last = (t == nt - 2);
;             const char* a1 = cA + (size_t)(t + 1) * kstep;
;             const char* a2 = last ? nA : cA + (size_t)(t + 2) * kstep; const char* b2 = last ? nB : cB + (size_t)(t + 2) * kstep;
;             const char* a3 = a2 + kstep; const char* b3 = b2 + kstep;
;             if (last && has_next) S.a_ready(nxt);
;             if constexpr (SP2) {
;             PG8_LDB(B0, 0, 0); PG8_LDB(B1, 0, 1); PG8_SCHED; PG8_LDA(At, 0, 0); PG8_STAGE(PG8_SA(1, 1), a1 + hstep, voffA);
;             PG8_WAIT_V(8); PG8_WAIT_L(0); PG8_BAR; PG8_MMA(0, 0, At, B0); PG8_MMA(0, 1, At, B1); PG8_BAR; PG8_SCHED;
;             PG8_LDA(At, 0, 1); PG8_STAGE(PG8_SB(0, 0), b2, voffB); PG8_STAGE(PG8_SB(0, 1), b2 + hstep, voffB); PG8_STAGE(PG8_SA(0, 0), a2, voffA);
;             PG8_WAIT_V(8); PG8_WAIT_L(0); PG8_BAR; PG8_MMA(1, 0, At, B0); PG8_MMA(1, 1, At, B1); PG8_BAR; PG8_SCHED;
.LBB0_688:
	s_ashr_i32 s43, s42, 31
	s_lshl_b64 s[44:45], s[42:43], 19
	s_add_u32 s44, s22, s44
	s_addc_u32 s45, s23, s45
	s_and_b64 s[46:47], s[6:7], exec
	s_cselect_b32 s43, s45, s1
	s_cselect_b32 s53, s44, s0
	s_ashr_i32 s41, s40, 31
	s_lshl_b64 s[46:47], s[40:41], 19
	s_add_u32 s46, s8, s46
	s_addc_u32 s47, s9, s47
	s_and_b64 s[54:55], s[6:7], exec
	s_cselect_b32 s41, s47, s57
	s_cselect_b32 s73, s46, s56
	s_add_u32 s54, s0, 0x40080
	s_addc_u32 s55, s1, 0
	s_add_u32 s74, s56, 0x100
	v_mov_b32_e32 v0, 0
	s_addc_u32 s75, s57, 0
	s_mov_b32 s76, -2
	ds_read_b128 v[92:95], v207
	ds_read_b128 v[100:103], v207 offset:1024
	ds_read_b128 v[112:115], v207 offset:2048
	ds_read_b128 v[124:127], v207 offset:3072
	ds_read_b128 v[136:139], v208
	ds_read_b128 v[148:151], v208 offset:1024
	ds_read_b128 v[152:155], v208 offset:2048
	ds_read_b128 v[156:159], v208 offset:3072
	s_add_u32 s0, s54, 0xfffc0080
	s_addc_u32 s1, s55, -1
	s_cmp_eq_u32 s76, 12
	s_cselect_b32 s57, s43, s1
	s_cselect_b32 s56, s53, s0
	s_cselect_b32 s1, s41, s75
	s_cselect_b32 s0, s73, s74
	v_lshl_add_u64 v[214:215], s[54:55], 0, v[192:193]
	s_add_i32 m0, s30, 0xc000
	ds_read_b128 v[160:163], v209
	ds_read_b128 v[164:167], v209 offset:1024
	ds_read_b128 v[168:171], v209 offset:2048
	ds_read_b128 v[172:175], v209 offset:3072
	ds_read_b128 v[176:179], v209 offset:4096
	ds_read_b128 v[180:183], v209 offset:5120
	ds_read_b128 v[200:203], v209 offset:6144
	ds_read_b128 v[210:213], v209 offset:7168
	global_load_lds_dwordx4 v[214:215], off
	v_lshl_add_u64 v[214:215], s[54:55], 0, v[194:195]
	s_add_i32 m0, s30, 0xe000
	s_nop 0
	global_load_lds_dwordx4 v[214:215], off
	s_waitcnt vmcnt(8)
	s_waitcnt lgkmcnt(0)
	s_barrier
	s_waitcnt lgkmcnt(0)
	v_mfma_f32_16x16x32_bf16 v[144:147], v[92:95], v[160:163], 0
	v_mfma_f32_16x16x32_bf16 v[140:143], v[112:115], v[160:163], 0
	v_mfma_f32_16x16x32_bf16 v[120:123], v[92:95], v[168:171], 0
	v_mfma_f32_16x16x32_bf16 v[116:119], v[112:115], v[168:171], 0
	v_mfma_f32_16x16x32_bf16 v[96:99], v[92:95], v[176:179], 0
	v_mfma_f32_16x16x32_bf16 v[88:91], v[112:115], v[176:179], 0
	v_mfma_f32_16x16x32_bf16 v[76:79], v[92:95], v[200:203], 0
	v_mfma_f32_16x16x32_bf16 v[72:75], v[112:115], v[200:203], 0
	v_mfma_f32_16x16x32_bf16 v[144:147], v[100:103], v[164:167], v[144:147]
	v_mfma_f32_16x16x32_bf16 v[140:143], v[124:127], v[164:167], v[140:143]
	v_mfma_f32_16x16x32_bf16 v[120:123], v[100:103], v[172:175], v[120:123]
	v_mfma_f32_16x16x32_bf16 v[116:119], v[124:127], v[172:175], v[116:119]
	v_mfma_f32_16x16x32_bf16 v[96:99], v[100:103], v[180:183], v[96:99]
	v_mfma_f32_16x16x32_bf16 v[88:91], v[124:127], v[180:183], v[88:91]
	v_mfma_f32_16x16x32_bf16 v[76:79], v[100:103], v[210:213], v[76:79]
	v_mfma_f32_16x16x32_bf16 v[72:75], v[124:127], v[210:213], v[72:75]
	v_mfma_f32_16x16x32_bf16 v[132:135], v[136:139], v[160:163], 0
	v_mfma_f32_16x16x32_bf16 v[128:131], v[152:155], v[160:163], 0
	v_mfma_f32_16x16x32_bf16 v[108:111], v[136:139], v[168:171], 0
	v_mfma_f32_16x16x32_bf16 v[104:107], v[152:155], v[168:171], 0
	v_mfma_f32_16x16x32_bf16 v[84:87], v[136:139], v[176:179], 0
	v_mfma_f32_16x16x32_bf16 v[80:83], v[152:155], v[176:179], 0
	v_mfma_f32_16x16x32_bf16 v[68:71], v[136:139], v[200:203], 0
	v_mfma_f32_16x16x32_bf16 v[64:67], v[152:155], v[200:203], 0
	v_mfma_f32_16x16x32_bf16 v[132:135], v[148:151], v[164:167], v[132:135]
	v_mfma_f32_16x16x32_bf16 v[128:131], v[156:159], v[164:167], v[128:131]
	v_mfma_f32_16x16x32_bf16 v[108:111], v[148:151], v[172:175], v[108:111]
	v_mfma_f32_16x16x32_bf16 v[104:107], v[156:159], v[172:175], v[104:107]
	v_mfma_f32_16x16x32_bf16 v[84:87], v[148:151], v[180:183], v[84:87]
	v_mfma_f32_16x16x32_bf16 v[80:83], v[156:159], v[180:183], v[80:83]
	v_mfma_f32_16x16x32_bf16 v[68:71], v[148:151], v[210:213], v[68:71]
	v_mfma_f32_16x16x32_bf16 v[64:67], v[156:159], v[210:213], v[64:67]
	s_barrier
	s_add_i32 s77, s49, s2
	v_lshl_add_u64 v[214:215], s[0:1], 0, v[186:187]
	s_mov_b32 m0, s77
	ds_read_b128 v[160:163], v209 offset:16384
	ds_read_b128 v[164:167], v209 offset:17408
	ds_read_b128 v[168:171], v209 offset:18432
	ds_read_b128 v[172:175], v209 offset:19456
	ds_read_b128 v[176:179], v209 offset:20480
	ds_read_b128 v[180:183], v209 offset:21504
	ds_read_b128 v[200:203], v209 offset:22528
	ds_read_b128 v[210:213], v209 offset:23552
	global_load_lds_dwordx4 v[214:215], off
	s_add_i32 m0, s77, 0x2000
	s_add_u32 s78, s0, 0x40000
	v_lshl_add_u64 v[216:217], s[0:1], 0, v[190:191]
	s_addc_u32 s79, s1, 0
	s_add_i32 s77, s50, s2
	global_load_lds_dwordx4 v[216:217], off
	v_lshl_add_u64 v[218:219], s[78:79], 0, v[186:187]
	s_mov_b32 m0, s77
	v_lshl_add_u64 v[220:221], s[56:57], 0, v[188:189]
	global_load_lds_dwordx4 v[218:219], off
	v_lshl_add_u64 v[218:219], s[78:79], 0, v[190:191]
	s_add_i32 m0, s77, 0x2000
	s_nop 0
	global_load_lds_dwordx4 v[218:219], off
	v_lshl_add_u64 v[218:219], s[56:57], 0, v[184:185]
	s_mov_b32 m0, s30
	s_nop 0
	global_load_lds_dwordx4 v[218:219], off
	s_mov_b32 m0, s31
	s_nop 0
	global_load_lds_dwordx4 v[220:221], off
	s_waitcnt vmcnt(8)
	s_waitcnt lgkmcnt(0)
	s_barrier
; #define PG8_STAGE(bufoff, gbase, voff) do { _Pragma("unroll") for (int _i = 0; _i < 2; ++_i) \
;         __builtin_amdgcn_global_load_lds((const unsigned*)((const char*)(gbase) + (voff)[_i]), (PG8_LAS unsigned*)(lds + (bufoff) + ldsw + _i * 8192), 16, 0, 0); } while (0)
; #define PG8_LDA(dst, b, h) do { _Pragma("unroll") for (int m = 0; m < 4; ++m) _Pragma("unroll") for (int k = 0; k < 2; ++k) dst[m][k] = *(const PG8_LAS bf16x8*)(lds + PG8_SA(b, h) + aoff + m * 2048 + k * 1024); } while (0)
; #define PG8_LDB(dst, b, h) do { _Pragma("unroll") for (int n = 0; n < 2; ++n) _Pragma("unroll") for (int k = 0; k < 2; ++k) dst[n][k] = *(const PG8_LAS bf16x8*)(lds + PG8_SB(b, h) + boff + n * 2048 + k * 1024); } while (0)
; #define PG8_MMA(ai, bj, At, Bt) do { __builtin_amdgcn_s_setprio(1); _Pragma("unroll") for (int m = 0; m < 4; ++m) _Pragma("unroll") for (int n = 0; n < 2; ++n) _Pragma("unroll") for (int k = 0; k < 2; ++k) \
;         acc[ai][bj][m][n] = __builtin_amdgcn_mfma_f32_16x16x32_bf16(Bt[n][k], At[m][k], acc[ai][bj][m][n], 0, 0, 0); __builtin_amdgcn_s_setprio(0); } while (0)
; #define PG8_WAIT_V(n) asm volatile("s_waitcnt vmcnt(" #n ")" ::: "memory")
; #define PG8_WAIT_L(n) asm volatile("s_waitcnt lgkmcnt(" #n ")" ::: "memory")
; #define PG8_BAR __builtin_amdgcn_s_barrier()
; #define PG8_SCHED __builtin_amdgcn_sched_barrier(0)
; template <class Epi, class Sched, bool ALIGN_EPI = false, bool SP2 = false>
; __device__ __forceinline__ void gemm_phase(PG8_LAS unsigned char* lds, const Gemm g, const Sched& S, const Epi& E, const int tid_in) {
;     ...
;             PG8_WAIT_V(8); PG8_WAIT_L(0); PG8_BAR; PG8_MMA(0, 0, At, B0); PG8_MMA(0, 1, At, B1); PG8_BAR; PG8_SCHED;
;             PG8_LDA(At, 0, 1); PG8_STAGE(PG8_SB(0, 0), b2, voffB); PG8_STAGE(PG8_SB(0, 1), b2 + hstep, voffB); PG8_STAGE(PG8_SA(0, 0), a2, voffA);
;             PG8_WAIT_V(8); PG8_WAIT_L(0); PG8_BAR; PG8_MMA(1, 0, At, B0); PG8_MMA(1, 1, At, B1); PG8_BAR; PG8_SCHED;
;             PG8_LDB(B0, 1, 0); PG8_LDB(B1, 1, 1); PG8_SCHED; PG8_LDA(At, 1, 0); PG8_STAGE(PG8_SA(0, 1), a2 + hstep, voffA);
;             PG8_WAIT_V(8); PG8_WAIT_L(0); PG8_BAR; PG8_MMA(0, 0, At, B0); PG8_MMA(0, 1, At, B1); PG8_BAR; PG8_SCHED;
	s_waitcnt lgkmcnt(0)
	v_mfma_f32_16x16x32_bf16 v[60:63], v[92:95], v[160:163], 0
	v_mfma_f32_16x16x32_bf16 v[56:59], v[112:115], v[160:163], 0
	v_mfma_f32_16x16x32_bf16 v[44:47], v[92:95], v[168:171], 0
	v_mfma_f32_16x16x32_bf16 v[40:43], v[112:115], v[168:171], 0
	v_mfma_f32_16x16x32_bf16 v[28:31], v[92:95], v[176:179], 0
	v_mfma_f32_16x16x32_bf16 v[24:27], v[112:115], v[176:179], 0
	v_mfma_f32_16x16x32_bf16 v[12:15], v[92:95], v[200:203], 0
	v_mfma_f32_16x16x32_bf16 v[8:11], v[112:115], v[200:203], 0
	v_mfma_f32_16x16x32_bf16 v[60:63], v[100:103], v[164:167], v[60:63]
	v_mfma_f32_16x16x32_bf16 v[56:59], v[124:127], v[164:167], v[56:59]
	v_mfma_f32_16x16x32_bf16 v[44:47], v[100:103], v[172:175], v[44:47]
	v_mfma_f32_16x16x32_bf16 v[40:43], v[124:127], v[172:175], v[40:43]
	v_mfma_f32_16x16x32_bf16 v[28:31], v[100:103], v[180:183], v[28:31]
	v_mfma_f32_16x16x32_bf16 v[24:27], v[124:127], v[180:183], v[24:27]
	v_mfma_f32_16x16x32_bf16 v[12:15], v[100:103], v[210:213], v[12:15]
	v_mfma_f32_16x16x32_bf16 v[8:11], v[124:127], v[210:213], v[8:11]
	v_mfma_f32_16x16x32_bf16 v[52:55], v[136:139], v[160:163], 0
	v_mfma_f32_16x16x32_bf16 v[48:51], v[152:155], v[160:163], 0
	v_mfma_f32_16x16x32_bf16 v[36:39], v[136:139], v[168:171], 0
	v_mfma_f32_16x16x32_bf16 v[32:35], v[152:155], v[168:171], 0
	v_mfma_f32_16x16x32_bf16 v[20:23], v[136:139], v[176:179], 0
	v_mfma_f32_16x16x32_bf16 v[16:19], v[152:155], v[176:179], 0
	v_mfma_f32_16x16x32_bf16 v[4:7], v[136:139], v[200:203], 0
	v_mfma_f32_16x16x32_bf16 v[0:3], v[152:155], v[200:203], 0
	v_mfma_f32_16x16x32_bf16 v[52:55], v[148:151], v[164:167], v[52:55]
	v_mfma_f32_16x16x32_bf16 v[48:51], v[156:159], v[164:167], v[48:51]
	v_mfma_f32_16x16x32_bf16 v[36:39], v[148:151], v[172:175], v[36:39]
	v_mfma_f32_16x16x32_bf16 v[32:35], v[156:159], v[172:175], v[32:35]
	v_mfma_f32_16x16x32_bf16 v[20:23], v[148:151], v[180:183], v[20:23]
	v_mfma_f32_16x16x32_bf16 v[16:19], v[156:159], v[180:183], v[16:19]
	v_mfma_f32_16x16x32_bf16 v[4:7], v[148:151], v[210:213], v[4:7]
	v_mfma_f32_16x16x32_bf16 v[0:3], v[156:159], v[210:213], v[0:3]
	s_barrier
	s_add_i32 s77, 0, 0x18000
	s_add_i32 s78, 0, 0x1c000
	v_add_u32_e32 v124, s77, v205
	v_add_u32_e32 v156, s78, v205
	ds_read_b128 v[92:95], v124
	ds_read_b128 v[100:103], v124 offset:1024
	ds_read_b128 v[112:115], v124 offset:2048
	ds_read_b128 v[124:127], v124 offset:3072
	ds_read_b128 v[136:139], v156
	ds_read_b128 v[148:151], v156 offset:1024
	ds_read_b128 v[152:155], v156 offset:2048
	ds_read_b128 v[156:159], v156 offset:3072
	s_add_u32 s56, s56, 0x40000
	s_addc_u32 s57, s57, 0
	s_mov_b32 m0, s34
	v_lshl_add_u64 v[222:223], s[56:57], 0, v[184:185]
	ds_read_b128 v[160:163], v209 offset:32768
	ds_read_b128 v[164:167], v209 offset:33792
	ds_read_b128 v[168:171], v209 offset:34816
	ds_read_b128 v[172:175], v209 offset:35840
	ds_read_b128 v[176:179], v209 offset:36864
	ds_read_b128 v[180:183], v209 offset:37888
	ds_read_b128 v[200:203], v209 offset:38912
	ds_read_b128 v[210:213], v209 offset:39936
	global_load_lds_dwordx4 v[222:223], off
	v_lshl_add_u64 v[222:223], s[56:57], 0, v[188:189]
	s_mov_b32 m0, s35
	s_nop 0
	global_load_lds_dwordx4 v[222:223], off
	s_waitcnt vmcnt(8)
	s_waitcnt lgkmcnt(0)
	s_barrier
	s_waitcnt lgkmcnt(0)
	v_mfma_f32_16x16x32_bf16 v[144:147], v[92:95], v[160:163], v[144:147]
	v_mfma_f32_16x16x32_bf16 v[140:143], v[112:115], v[160:163], v[140:143]
	v_mfma_f32_16x16x32_bf16 v[120:123], v[92:95], v[168:171], v[120:123]
	v_mfma_f32_16x16x32_bf16 v[116:119], v[112:115], v[168:171], v[116:119]
	v_mfma_f32_16x16x32_bf16 v[96:99], v[92:95], v[176:179], v[96:99]
	v_mfma_f32_16x16x32_bf16 v[88:91], v[112:115], v[176:179], v[88:91]
	v_mfma_f32_16x16x32_bf16 v[76:79], v[92:95], v[200:203], v[76:79]
	v_mfma_f32_16x16x32_bf16 v[72:75], v[112:115], v[200:203], v[72:75]
	v_mfma_f32_16x16x32_bf16 v[144:147], v[100:103], v[164:167], v[144:147]
	v_mfma_f32_16x16x32_bf16 v[140:143], v[124:127], v[164:167], v[140:143]
	v_mfma_f32_16x16x32_bf16 v[120:123], v[100:103], v[172:175], v[120:123]
	v_mfma_f32_16x16x32_bf16 v[116:119], v[124:127], v[172:175], v[116:119]
	v_mfma_f32_16x16x32_bf16 v[96:99], v[100:103], v[180:183], v[96:99]
	v_mfma_f32_16x16x32_bf16 v[88:91], v[124:127], v[180:183], v[88:91]
	v_mfma_f32_16x16x32_bf16 v[76:79], v[100:103], v[210:213], v[76:79]
	v_mfma_f32_16x16x32_bf16 v[72:75], v[124:127], v[210:213], v[72:75]
	v_mfma_f32_16x16x32_bf16 v[132:135], v[136:139], v[160:163], v[132:135]
	v_mfma_f32_16x16x32_bf16 v[128:131], v[152:155], v[160:163], v[128:131]
	v_mfma_f32_16x16x32_bf16 v[108:111], v[136:139], v[168:171], v[108:111]
	v_mfma_f32_16x16x32_bf16 v[104:107], v[152:155], v[168:171], v[104:107]
	v_mfma_f32_16x16x32_bf16 v[84:87], v[136:139], v[176:179], v[84:87]
	v_mfma_f32_16x16x32_bf16 v[80:83], v[152:155], v[176:179], v[80:83]
	v_mfma_f32_16x16x32_bf16 v[68:71], v[136:139], v[200:203], v[68:71]
	v_mfma_f32_16x16x32_bf16 v[64:67], v[152:155], v[200:203], v[64:67]
	v_mfma_f32_16x16x32_bf16 v[132:135], v[148:151], v[164:167], v[132:135]
	v_mfma_f32_16x16x32_bf16 v[128:131], v[156:159], v[164:167], v[128:131]
	v_mfma_f32_16x16x32_bf16 v[108:111], v[148:151], v[172:175], v[108:111]
	v_mfma_f32_16x16x32_bf16 v[104:107], v[156:159], v[172:175], v[104:107]
	v_mfma_f32_16x16x32_bf16 v[84:87], v[148:151], v[180:183], v[84:87]
	v_mfma_f32_16x16x32_bf16 v[80:83], v[156:159], v[180:183], v[80:83]
	v_mfma_f32_16x16x32_bf16 v[68:71], v[148:151], v[210:213], v[68:71]
	v_mfma_f32_16x16x32_bf16 v[64:67], v[156:159], v[210:213], v[64:67]
	s_barrier
; #define PG8_STAGE(bufoff, gbase, voff) do { _Pragma("unroll") for (int _i = 0; _i < 2; ++_i) \
;         __builtin_amdgcn_global_load_lds((const unsigned*)((const char*)(gbase) + (voff)[_i]), (PG8_LAS unsigned*)(lds + (bufoff) + ldsw + _i * 8192), 16, 0, 0); } while (0)
; #define PG8_LDA(dst, b, h) do { _Pragma("unroll") for (int m = 0; m < 4; ++m) _Pragma("unroll") for (int k = 0; k < 2; ++k) dst[m][k] = *(const PG8_LAS bf16x8*)(lds + PG8_SA(b, h) + aoff + m * 2048 + k * 1024); } while (0)
; #define PG8_LDB(dst, b, h) do { _Pragma("unroll") for (int n = 0; n < 2; ++n) _Pragma("unroll") for (int k = 0; k < 2; ++k) dst[n][k] = *(const PG8_LAS bf16x8*)(lds + PG8_SB(b, h) + boff + n * 2048 + k * 1024); } while (0)
; #define PG8_MMA(ai, bj, At, Bt) do { __builtin_amdgcn_s_setprio(1); _Pragma("unroll") for (int m = 0; m < 4; ++m) _Pragma("unroll") for (int n = 0; n < 2; ++n) _Pragma("unroll") for (int k = 0; k < 2; ++k) \
;         acc[ai][bj][m][n] = __builtin_amdgcn_mfma_f32_16x16x32_bf16(Bt[n][k], At[m][k], acc[ai][bj][m][n], 0, 0, 0); __builtin_amdgcn_s_setprio(0); } while (0)
; #define PG8_WAIT_V(n) asm volatile("s_waitcnt vmcnt(" #n ")" ::: "memory")
; #define PG8_WAIT_L(n) asm volatile("s_waitcnt lgkmcnt(" #n ")" ::: "memory")
; #define PG8_BAR __builtin_amdgcn_s_barrier()
; template <class Epi, class Sched, bool ALIGN_EPI = false, bool SP2 = false>
; __device__ __forceinline__ void gemm_phase(PG8_LAS unsigned char* lds, const Gemm g, const Sched& S, const Epi& E, const int tid_in) {
;     ...
;         for (int t = 0; t < nt; t += 2) {
;             const bool last = (t == nt - 2);
;             const char* a1 = cA + (size_t)(t + 1) * kstep;
;             const char* a2 = last ? nA : cA + (size_t)(t + 2) * kstep; const char* b2 = last ? nB : cB + (size_t)(t + 2) * kstep;
;             const char* a3 = a2 + kstep; const char* b3 = b2 + kstep;
;     ...
;             PG8_LDB(B0, 1, 0); PG8_LDB(B1, 1, 1); PG8_SCHED; PG8_LDA(At, 1, 0); PG8_STAGE(PG8_SA(0, 1), a2 + hstep, voffA);
;             PG8_WAIT_V(8); PG8_WAIT_L(0); PG8_BAR; PG8_MMA(0, 0, At, B0); PG8_MMA(0, 1, At, B1); PG8_BAR; PG8_SCHED;
;             PG8_LDA(At, 1, 1); PG8_STAGE(PG8_SB(1, 0), b3, voffB); PG8_STAGE(PG8_SB(1, 1), b3 + hstep, voffB); PG8_STAGE(PG8_SA(1, 0), a3, voffA);
;             PG8_WAIT_V(8); PG8_WAIT_L(0); PG8_BAR; PG8_MMA(1, 0, At, B0); PG8_MMA(1, 1, At, B1); PG8_BAR; PG8_SCHED;
	s_add_i32 s56, s77, s2
	v_lshl_add_u64 v[214:215], v[214:215], 0, s[26:27]
	s_mov_b32 m0, s56
	ds_read_b128 v[160:163], v209 offset:49152
	ds_read_b128 v[164:167], v209 offset:50176
	ds_read_b128 v[168:171], v209 offset:51200
	ds_read_b128 v[172:175], v209 offset:52224
	ds_read_b128 v[176:179], v209 offset:53248
	ds_read_b128 v[180:183], v209 offset:54272
	ds_read_b128 v[200:203], v209 offset:55296
	ds_read_b128 v[210:213], v209 offset:56320
	global_load_lds_dwordx4 v[214:215], off
	s_add_i32 m0, s56, 0x2000
	s_add_u32 s0, s0, 0x40080
	v_lshl_add_u64 v[214:215], v[216:217], 0, s[26:27]
	s_addc_u32 s1, s1, 0
	s_add_i32 s56, s78, s2
	global_load_lds_dwordx4 v[214:215], off
	v_lshl_add_u64 v[214:215], s[0:1], 0, v[186:187]
	s_mov_b32 m0, s56
	s_nop 0
	global_load_lds_dwordx4 v[214:215], off
	v_lshl_add_u64 v[214:215], s[0:1], 0, v[190:191]
	s_add_i32 m0, s56, 0x2000
	s_nop 0
	global_load_lds_dwordx4 v[214:215], off
	v_lshl_add_u64 v[214:215], v[218:219], 0, s[26:27]
	s_mov_b32 m0, s37
	s_nop 0
	global_load_lds_dwordx4 v[214:215], off
	v_lshl_add_u64 v[214:215], v[220:221], 0, s[26:27]
	s_mov_b32 m0, s38
	s_nop 0
	global_load_lds_dwordx4 v[214:215], off
	s_waitcnt vmcnt(8)
	s_waitcnt lgkmcnt(0)
	s_barrier
	s_waitcnt lgkmcnt(0)
	v_mfma_f32_16x16x32_bf16 v[60:63], v[92:95], v[160:163], v[60:63]
	v_mfma_f32_16x16x32_bf16 v[56:59], v[112:115], v[160:163], v[56:59]
	v_mfma_f32_16x16x32_bf16 v[44:47], v[92:95], v[168:171], v[44:47]
	v_mfma_f32_16x16x32_bf16 v[40:43], v[112:115], v[168:171], v[40:43]
	v_mfma_f32_16x16x32_bf16 v[28:31], v[92:95], v[176:179], v[28:31]
	v_mfma_f32_16x16x32_bf16 v[24:27], v[112:115], v[176:179], v[24:27]
	v_mfma_f32_16x16x32_bf16 v[12:15], v[92:95], v[200:203], v[12:15]
	v_mfma_f32_16x16x32_bf16 v[8:11], v[112:115], v[200:203], v[8:11]
	v_mfma_f32_16x16x32_bf16 v[60:63], v[100:103], v[164:167], v[60:63]
	v_mfma_f32_16x16x32_bf16 v[56:59], v[124:127], v[164:167], v[56:59]
	v_mfma_f32_16x16x32_bf16 v[44:47], v[100:103], v[172:175], v[44:47]
	v_mfma_f32_16x16x32_bf16 v[40:43], v[124:127], v[172:175], v[40:43]
	v_mfma_f32_16x16x32_bf16 v[28:31], v[100:103], v[180:183], v[28:31]
	v_mfma_f32_16x16x32_bf16 v[24:27], v[124:127], v[180:183], v[24:27]
	v_mfma_f32_16x16x32_bf16 v[12:15], v[100:103], v[210:213], v[12:15]
	v_mfma_f32_16x16x32_bf16 v[8:11], v[124:127], v[210:213], v[8:11]
	v_mfma_f32_16x16x32_bf16 v[52:55], v[136:139], v[160:163], v[52:55]
	v_mfma_f32_16x16x32_bf16 v[48:51], v[152:155], v[160:163], v[48:51]
	v_mfma_f32_16x16x32_bf16 v[36:39], v[136:139], v[168:171], v[36:39]
	v_mfma_f32_16x16x32_bf16 v[32:35], v[152:155], v[168:171], v[32:35]
	v_mfma_f32_16x16x32_bf16 v[20:23], v[136:139], v[176:179], v[20:23]
	v_mfma_f32_16x16x32_bf16 v[16:19], v[152:155], v[176:179], v[16:19]
	v_mfma_f32_16x16x32_bf16 v[4:7], v[136:139], v[200:203], v[4:7]
	v_mfma_f32_16x16x32_bf16 v[0:3], v[152:155], v[200:203], v[0:3]
	v_mfma_f32_16x16x32_bf16 v[52:55], v[148:151], v[164:167], v[52:55]
	v_mfma_f32_16x16x32_bf16 v[48:51], v[156:159], v[164:167], v[48:51]
	v_mfma_f32_16x16x32_bf16 v[36:39], v[148:151], v[172:175], v[36:39]
	v_mfma_f32_16x16x32_bf16 v[32:35], v[156:159], v[172:175], v[32:35]
	v_mfma_f32_16x16x32_bf16 v[20:23], v[148:151], v[180:183], v[20:23]
	v_mfma_f32_16x16x32_bf16 v[16:19], v[156:159], v[180:183], v[16:19]
	v_mfma_f32_16x16x32_bf16 v[4:7], v[148:151], v[210:213], v[4:7]
	v_mfma_f32_16x16x32_bf16 v[0:3], v[156:159], v[210:213], v[0:3]
	s_barrier
	s_add_i32 s76, s76, 2
	s_add_u32 s54, s54, 0x100
	s_addc_u32 s55, s55, 0
	s_add_u32 s74, s74, 0x100
	s_addc_u32 s75, s75, 0
	s_cmp_gt_u32 s76, 13
	s_cbranch_scc0 .LBB0_689
	s_branch .Lmy_kdone_2
.LBB0_689:
	ds_read_b128 v[92:95], v207
	ds_read_b128 v[100:103], v207 offset:1024
	ds_read_b128 v[112:115], v207 offset:2048
	ds_read_b128 v[124:127], v207 offset:3072
	ds_read_b128 v[136:139], v208
	ds_read_b128 v[148:151], v208 offset:1024
	ds_read_b128 v[152:155], v208 offset:2048
	ds_read_b128 v[156:159], v208 offset:3072
	s_add_u32 s0, s54, 0xfffc0080
	s_addc_u32 s1, s55, -1
	s_cmp_eq_u32 s76, 12
	s_cselect_b32 s57, s43, s1
	s_cselect_b32 s56, s53, s0
	s_cselect_b32 s1, s41, s75
	s_cselect_b32 s0, s73, s74
	v_lshl_add_u64 v[214:215], s[54:55], 0, v[192:193]
	s_add_i32 m0, s30, 0xc000
	ds_read_b128 v[160:163], v209
	ds_read_b128 v[164:167], v209 offset:1024
	ds_read_b128 v[168:171], v209 offset:2048
	ds_read_b128 v[172:175], v209 offset:3072
	ds_read_b128 v[176:179], v209 offset:4096
	ds_read_b128 v[180:183], v209 offset:5120
	ds_read_b128 v[200:203], v209 offset:6144
	ds_read_b128 v[210:213], v209 offset:7168
	global_load_lds_dwordx4 v[214:215], off
	v_lshl_add_u64 v[214:215], s[54:55], 0, v[194:195]
	s_add_i32 m0, s30, 0xe000
	s_nop 0
	global_load_lds_dwordx4 v[214:215], off
	s_waitcnt vmcnt(8)
	s_waitcnt lgkmcnt(0)
	s_barrier
; #define PG8_STAGE(bufoff, gbase, voff) do { _Pragma("unroll") for (int _i = 0; _i < 2; ++_i) \
;         __builtin_amdgcn_global_load_lds((const unsigned*)((const char*)(gbase) + (voff)[_i]), (PG8_LAS unsigned*)(lds + (bufoff) + ldsw + _i * 8192), 16, 0, 0); } while (0)
; #define PG8_LDA(dst, b, h) do { _Pragma("unroll") for (int m = 0; m < 4; ++m) _Pragma("unroll") for (int k = 0; k < 2; ++k) dst[m][k] = *(const PG8_LAS bf16x8*)(lds + PG8_SA(b, h) + aoff + m * 2048 + k * 1024); } while (0)
; #define PG8_LDB(dst, b, h) do { _Pragma("unroll") for (int n = 0; n < 2; ++n) _Pragma("unroll") for (int k = 0; k < 2; ++k) dst[n][k] = *(const PG8_LAS bf16x8*)(lds + PG8_SB(b, h) + boff + n * 2048 + k * 1024); } while (0)
; #define PG8_MMA(ai, bj, At, Bt) do { __builtin_amdgcn_s_setprio(1); _Pragma("unroll") for (int m = 0; m < 4; ++m) _Pragma("unroll") for (int n = 0; n < 2; ++n) _Pragma("unroll") for (int k = 0; k < 2; ++k) \
;         acc[ai][bj][m][n] = __builtin_amdgcn_mfma_f32_16x16x32_bf16(Bt[n][k], At[m][k], acc[ai][bj][m][n], 0, 0, 0); __builtin_amdgcn_s_setprio(0); } while (0)
; #define PG8_WAIT_V(n) asm volatile("s_waitcnt vmcnt(" #n ")" ::: "memory")
; #define PG8_WAIT_L(n) asm volatile("s_waitcnt lgkmcnt(" #n ")" ::: "memory")
; #define PG8_BAR __builtin_amdgcn_s_barrier()
; #define PG8_SCHED __builtin_amdgcn_sched_barrier(0)
; template <class Epi, class Sched, bool ALIGN_EPI = false, bool SP2 = false>
; __device__ __forceinline__ void gemm_phase(PG8_LAS unsigned char* lds, const Gemm g, const Sched& S, const Epi& E, const int tid_in) {
;     ...
;             PG8_LDB(B0, 0, 0); PG8_LDB(B1, 0, 1); PG8_SCHED; PG8_LDA(At, 0, 0); PG8_STAGE(PG8_SA(1, 1), a1 + hstep, voffA);
;             PG8_WAIT_V(8); PG8_WAIT_L(0); PG8_BAR; PG8_MMA(0, 0, At, B0); PG8_MMA(0, 1, At, B1); PG8_BAR; PG8_SCHED;
;             PG8_LDA(At, 0, 1); PG8_STAGE(PG8_SB(0, 0), b2, voffB); PG8_STAGE(PG8_SB(0, 1), b2 + hstep, voffB); PG8_STAGE(PG8_SA(0, 0), a2, voffA);
;             PG8_WAIT_V(8); PG8_WAIT_L(0); PG8_BAR; PG8_MMA(1, 0, At, B0); PG8_MMA(1, 1, At, B1); PG8_BAR; PG8_SCHED;
	s_waitcnt lgkmcnt(0)
	v_mfma_f32_16x16x32_bf16 v[144:147], v[92:95], v[160:163], v[144:147]
	v_mfma_f32_16x16x32_bf16 v[140:143], v[112:115], v[160:163], v[140:143]
	v_mfma_f32_16x16x32_bf16 v[120:123], v[92:95], v[168:171], v[120:123]
	v_mfma_f32_16x16x32_bf16 v[116:119], v[112:115], v[168:171], v[116:119]
	v_mfma_f32_16x16x32_bf16 v[96:99], v[92:95], v[176:179], v[96:99]
	v_mfma_f32_16x16x32_bf16 v[88:91], v[112:115], v[176:179], v[88:91]
	v_mfma_f32_16x16x32_bf16 v[76:79], v[92:95], v[200:203], v[76:79]
	v_mfma_f32_16x16x32_bf16 v[72:75], v[112:115], v[200:203], v[72:75]
	v_mfma_f32_16x16x32_bf16 v[144:147], v[100:103], v[164:167], v[144:147]
	v_mfma_f32_16x16x32_bf16 v[140:143], v[124:127], v[164:167], v[140:143]
	v_mfma_f32_16x16x32_bf16 v[120:123], v[100:103], v[172:175], v[120:123]
	v_mfma_f32_16x16x32_bf16 v[116:119], v[124:127], v[172:175], v[116:119]
	v_mfma_f32_16x16x32_bf16 v[96:99], v[100:103], v[180:183], v[96:99]
	v_mfma_f32_16x16x32_bf16 v[88:91], v[124:127], v[180:183], v[88:91]
	v_mfma_f32_16x16x32_bf16 v[76:79], v[100:103], v[210:213], v[76:79]
	v_mfma_f32_16x16x32_bf16 v[72:75], v[124:127], v[210:213], v[72:75]
	v_mfma_f32_16x16x32_bf16 v[132:135], v[136:139], v[160:163], v[132:135]
	v_mfma_f32_16x16x32_bf16 v[128:131], v[152:155], v[160:163], v[128:131]
	v_mfma_f32_16x16x32_bf16 v[108:111], v[136:139], v[168:171], v[108:111]
	v_mfma_f32_16x16x32_bf16 v[104:107], v[152:155], v[168:171], v[104:107]
	v_mfma_f32_16x16x32_bf16 v[84:87], v[136:139], v[176:179], v[84:87]
	v_mfma_f32_16x16x32_bf16 v[80:83], v[152:155], v[176:179], v[80:83]
	v_mfma_f32_16x16x32_bf16 v[68:71], v[136:139], v[200:203], v[68:71]
	v_mfma_f32_16x16x32_bf16 v[64:67], v[152:155], v[200:203], v[64:67]
	v_mfma_f32_16x16x32_bf16 v[132:135], v[148:151], v[164:167], v[132:135]
	v_mfma_f32_16x16x32_bf16 v[128:131], v[156:159], v[164:167], v[128:131]
	v_mfma_f32_16x16x32_bf16 v[108:111], v[148:151], v[172:175], v[108:111]
	v_mfma_f32_16x16x32_bf16 v[104:107], v[156:159], v[172:175], v[104:107]
	v_mfma_f32_16x16x32_bf16 v[84:87], v[148:151], v[180:183], v[84:87]
	v_mfma_f32_16x16x32_bf16 v[80:83], v[156:159], v[180:183], v[80:83]
	v_mfma_f32_16x16x32_bf16 v[68:71], v[148:151], v[210:213], v[68:71]
	v_mfma_f32_16x16x32_bf16 v[64:67], v[156:159], v[210:213], v[64:67]
	s_barrier
	s_add_i32 s77, s49, s2
	v_lshl_add_u64 v[214:215], s[0:1], 0, v[186:187]
	s_mov_b32 m0, s77
	ds_read_b128 v[160:163], v209 offset:16384
	ds_read_b128 v[164:167], v209 offset:17408
	ds_read_b128 v[168:171], v209 offset:18432
	ds_read_b128 v[172:175], v209 offset:19456
	ds_read_b128 v[176:179], v209 offset:20480
	ds_read_b128 v[180:183], v209 offset:21504
	ds_read_b128 v[200:203], v209 offset:22528
	ds_read_b128 v[210:213], v209 offset:23552
	global_load_lds_dwordx4 v[214:215], off
	s_add_i32 m0, s77, 0x2000
	s_add_u32 s78, s0, 0x40000
	v_lshl_add_u64 v[216:217], s[0:1], 0, v[190:191]
	s_addc_u32 s79, s1, 0
	s_add_i32 s77, s50, s2
	global_load_lds_dwordx4 v[216:217], off
	v_lshl_add_u64 v[218:219], s[78:79], 0, v[186:187]
	s_mov_b32 m0, s77
	v_lshl_add_u64 v[220:221], s[56:57], 0, v[188:189]
	global_load_lds_dwordx4 v[218:219], off
	v_lshl_add_u64 v[218:219], s[78:79], 0, v[190:191]
	s_add_i32 m0, s77, 0x2000
	s_nop 0
	global_load_lds_dwordx4 v[218:219], off
	v_lshl_add_u64 v[218:219], s[56:57], 0, v[184:185]
	s_mov_b32 m0, s30
	s_nop 0
	global_load_lds_dwordx4 v[218:219], off
	s_mov_b32 m0, s31
	s_nop 0
	global_load_lds_dwordx4 v[220:221], off
	s_waitcnt vmcnt(8)
	s_waitcnt lgkmcnt(0)
	s_barrier
	s_waitcnt lgkmcnt(0)
	v_mfma_f32_16x16x32_bf16 v[60:63], v[92:95], v[160:163], v[60:63]
	v_mfma_f32_16x16x32_bf16 v[56:59], v[112:115], v[160:163], v[56:59]
	v_mfma_f32_16x16x32_bf16 v[44:47], v[92:95], v[168:171], v[44:47]
	v_mfma_f32_16x16x32_bf16 v[40:43], v[112:115], v[168:171], v[40:43]
	v_mfma_f32_16x16x32_bf16 v[28:31], v[92:95], v[176:179], v[28:31]
	v_mfma_f32_16x16x32_bf16 v[24:27], v[112:115], v[176:179], v[24:27]
	v_mfma_f32_16x16x32_bf16 v[12:15], v[92:95], v[200:203], v[12:15]
	v_mfma_f32_16x16x32_bf16 v[8:11], v[112:115], v[200:203], v[8:11]
	v_mfma_f32_16x16x32_bf16 v[60:63], v[100:103], v[164:167], v[60:63]
	v_mfma_f32_16x16x32_bf16 v[56:59], v[124:127], v[164:167], v[56:59]
	v_mfma_f32_16x16x32_bf16 v[44:47], v[100:103], v[172:175], v[44:47]
	v_mfma_f32_16x16x32_bf16 v[40:43], v[124:127], v[172:175], v[40:43]
	v_mfma_f32_16x16x32_bf16 v[28:31], v[100:103], v[180:183], v[28:31]
	v_mfma_f32_16x16x32_bf16 v[24:27], v[124:127], v[180:183], v[24:27]
	v_mfma_f32_16x16x32_bf16 v[12:15], v[100:103], v[210:213], v[12:15]
	v_mfma_f32_16x16x32_bf16 v[8:11], v[124:127], v[210:213], v[8:11]
	v_mfma_f32_16x16x32_bf16 v[52:55], v[136:139], v[160:163], v[52:55]
	v_mfma_f32_16x16x32_bf16 v[48:51], v[152:155], v[160:163], v[48:51]
	v_mfma_f32_16x16x32_bf16 v[36:39], v[136:139], v[168:171], v[36:39]
	v_mfma_f32_16x16x32_bf16 v[32:35], v[152:155], v[168:171], v[32:35]
	v_mfma_f32_16x16x32_bf16 v[20:23], v[136:139], v[176:179], v[20:23]
	v_mfma_f32_16x16x32_bf16 v[16:19], v[152:155], v[176:179], v[16:19]
	v_mfma_f32_16x16x32_bf16 v[4:7], v[136:139], v[200:203], v[4:7]
	v_mfma_f32_16x16x32_bf16 v[0:3], v[152:155], v[200:203], v[0:3]
	v_mfma_f32_16x16x32_bf16 v[52:55], v[148:151], v[164:167], v[52:55]
	v_mfma_f32_16x16x32_bf16 v[48:51], v[156:159], v[164:167], v[48:51]
	v_mfma_f32_16x16x32_bf16 v[36:39], v[148:151], v[172:175], v[36:39]
	v_mfma_f32_16x16x32_bf16 v[32:35], v[156:159], v[172:175], v[32:35]
	v_mfma_f32_16x16x32_bf16 v[20:23], v[148:151], v[180:183], v[20:23]
	v_mfma_f32_16x16x32_bf16 v[16:19], v[156:159], v[180:183], v[16:19]
	v_mfma_f32_16x16x32_bf16 v[4:7], v[148:151], v[210:213], v[4:7]
	v_mfma_f32_16x16x32_bf16 v[0:3], v[156:159], v[210:213], v[0:3]
	s_barrier
; #define PG8_STAGE(bufoff, gbase, voff) do { _Pragma("unroll") for (int _i = 0; _i < 2; ++_i) \
;         __builtin_amdgcn_global_load_lds((const unsigned*)((const char*)(gbase) + (voff)[_i]), (PG8_LAS unsigned*)(lds + (bufoff) + ldsw + _i * 8192), 16, 0, 0); } while (0)
; #define PG8_LDA(dst, b, h) do { _Pragma("unroll") for (int m = 0; m < 4; ++m) _Pragma("unroll") for (int k = 0; k < 2; ++k) dst[m][k] = *(const PG8_LAS bf16x8*)(lds + PG8_SA(b, h) + aoff + m * 2048 + k * 1024); } while (0)
; #define PG8_LDB(dst, b, h) do { _Pragma("unroll") for (int n = 0; n < 2; ++n) _Pragma("unroll") for (int k = 0; k < 2; ++k) dst[n][k] = *(const PG8_LAS bf16x8*)(lds + PG8_SB(b, h) + boff + n * 2048 + k * 1024); } while (0)
; #define PG8_MMA(ai, bj, At, Bt) do { __builtin_amdgcn_s_setprio(1); _Pragma("unroll") for (int m = 0; m < 4; ++m) _Pragma("unroll") for (int n = 0; n < 2; ++n) _Pragma("unroll") for (int k = 0; k < 2; ++k) \
;         acc[ai][bj][m][n] = __builtin_amdgcn_mfma_f32_16x16x32_bf16(Bt[n][k], At[m][k], acc[ai][bj][m][n], 0, 0, 0); __builtin_amdgcn_s_setprio(0); } while (0)
; #define PG8_WAIT_V(n) asm volatile("s_waitcnt vmcnt(" #n ")" ::: "memory")
; #define PG8_WAIT_L(n) asm volatile("s_waitcnt lgkmcnt(" #n ")" ::: "memory")
; #define PG8_BAR __builtin_amdgcn_s_barrier()
; #define PG8_SCHED __builtin_amdgcn_sched_barrier(0)
; template <class Epi, class Sched, bool ALIGN_EPI = false, bool SP2 = false>
; __device__ __forceinline__ void gemm_phase(PG8_LAS unsigned char* lds, const Gemm g, const Sched& S, const Epi& E, const int tid_in) {
;     ...
;             PG8_LDB(B0, 1, 0); PG8_LDB(B1, 1, 1); PG8_SCHED; PG8_LDA(At, 1, 0); PG8_STAGE(PG8_SA(0, 1), a2 + hstep, voffA);
;             PG8_WAIT_V(8); PG8_WAIT_L(0); PG8_BAR; PG8_MMA(0, 0, At, B0); PG8_MMA(0, 1, At, B1); PG8_BAR; PG8_SCHED;
;             PG8_LDA(At, 1, 1); PG8_STAGE(PG8_SB(1, 0), b3, voffB); PG8_STAGE(PG8_SB(1, 1), b3 + hstep, voffB); PG8_STAGE(PG8_SA(1, 0), a3, voffA);
;             PG8_WAIT_V(8); PG8_WAIT_L(0); PG8_BAR; PG8_MMA(1, 0, At, B0); PG8_MMA(1, 1, At, B1); PG8_BAR; PG8_SCHED;
	s_add_i32 s77, 0, 0x18000
	s_add_i32 s78, 0, 0x1c000
	v_add_u32_e32 v124, s77, v205
	v_add_u32_e32 v156, s78, v205
	ds_read_b128 v[92:95], v124
	ds_read_b128 v[100:103], v124 offset:1024
	ds_read_b128 v[112:115], v124 offset:2048
	ds_read_b128 v[124:127], v124 offset:3072
	ds_read_b128 v[136:139], v156
	ds_read_b128 v[148:151], v156 offset:1024
	ds_read_b128 v[152:155], v156 offset:2048
	ds_read_b128 v[156:159], v156 offset:3072
	s_add_u32 s56, s56, 0x40000
	s_addc_u32 s57, s57, 0
	s_mov_b32 m0, s34
	v_lshl_add_u64 v[222:223], s[56:57], 0, v[184:185]
	ds_read_b128 v[160:163], v209 offset:32768
	ds_read_b128 v[164:167], v209 offset:33792
	ds_read_b128 v[168:171], v209 offset:34816
	ds_read_b128 v[172:175], v209 offset:35840
	ds_read_b128 v[176:179], v209 offset:36864
	ds_read_b128 v[180:183], v209 offset:37888
	ds_read_b128 v[200:203], v209 offset:38912
	ds_read_b128 v[210:213], v209 offset:39936
	global_load_lds_dwordx4 v[222:223], off
	v_lshl_add_u64 v[222:223], s[56:57], 0, v[188:189]
	s_mov_b32 m0, s35
	s_nop 0
	global_load_lds_dwordx4 v[222:223], off
	s_waitcnt vmcnt(8)
	s_waitcnt lgkmcnt(0)
	s_barrier
	s_waitcnt lgkmcnt(0)
	v_mfma_f32_16x16x32_bf16 v[144:147], v[92:95], v[160:163], v[144:147]
	v_mfma_f32_16x16x32_bf16 v[140:143], v[112:115], v[160:163], v[140:143]
	v_mfma_f32_16x16x32_bf16 v[120:123], v[92:95], v[168:171], v[120:123]
	v_mfma_f32_16x16x32_bf16 v[116:119], v[112:115], v[168:171], v[116:119]
	v_mfma_f32_16x16x32_bf16 v[96:99], v[92:95], v[176:179], v[96:99]
	v_mfma_f32_16x16x32_bf16 v[88:91], v[112:115], v[176:179], v[88:91]
	v_mfma_f32_16x16x32_bf16 v[76:79], v[92:95], v[200:203], v[76:79]
	v_mfma_f32_16x16x32_bf16 v[72:75], v[112:115], v[200:203], v[72:75]
	v_mfma_f32_16x16x32_bf16 v[144:147], v[100:103], v[164:167], v[144:147]
	v_mfma_f32_16x16x32_bf16 v[140:143], v[124:127], v[164:167], v[140:143]
	v_mfma_f32_16x16x32_bf16 v[120:123], v[100:103], v[172:175], v[120:123]
	v_mfma_f32_16x16x32_bf16 v[116:119], v[124:127], v[172:175], v[116:119]
	v_mfma_f32_16x16x32_bf16 v[96:99], v[100:103], v[180:183], v[96:99]
	v_mfma_f32_16x16x32_bf16 v[88:91], v[124:127], v[180:183], v[88:91]
	v_mfma_f32_16x16x32_bf16 v[76:79], v[100:103], v[210:213], v[76:79]
	v_mfma_f32_16x16x32_bf16 v[72:75], v[124:127], v[210:213], v[72:75]
	v_mfma_f32_16x16x32_bf16 v[132:135], v[136:139], v[160:163], v[132:135]
	v_mfma_f32_16x16x32_bf16 v[128:131], v[152:155], v[160:163], v[128:131]
	v_mfma_f32_16x16x32_bf16 v[108:111], v[136:139], v[168:171], v[108:111]
	v_mfma_f32_16x16x32_bf16 v[104:107], v[152:155], v[168:171], v[104:107]
	v_mfma_f32_16x16x32_bf16 v[84:87], v[136:139], v[176:179], v[84:87]
	v_mfma_f32_16x16x32_bf16 v[80:83], v[152:155], v[176:179], v[80:83]
	v_mfma_f32_16x16x32_bf16 v[68:71], v[136:139], v[200:203], v[68:71]
	v_mfma_f32_16x16x32_bf16 v[64:67], v[152:155], v[200:203], v[64:67]
	v_mfma_f32_16x16x32_bf16 v[132:135], v[148:151], v[164:167], v[132:135]
	v_mfma_f32_16x16x32_bf16 v[128:131], v[156:159], v[164:167], v[128:131]
	v_mfma_f32_16x16x32_bf16 v[108:111], v[148:151], v[172:175], v[108:111]
	v_mfma_f32_16x16x32_bf16 v[104:107], v[156:159], v[172:175], v[104:107]
	v_mfma_f32_16x16x32_bf16 v[84:87], v[148:151], v[180:183], v[84:87]
	v_mfma_f32_16x16x32_bf16 v[80:83], v[156:159], v[180:183], v[80:83]
	v_mfma_f32_16x16x32_bf16 v[68:71], v[148:151], v[210:213], v[68:71]
	v_mfma_f32_16x16x32_bf16 v[64:67], v[156:159], v[210:213], v[64:67]
	s_barrier
	s_add_i32 s56, s77, s2
	v_lshl_add_u64 v[214:215], v[214:215], 0, s[26:27]
	s_mov_b32 m0, s56
	ds_read_b128 v[160:163], v209 offset:49152
	ds_read_b128 v[164:167], v209 offset:50176
	ds_read_b128 v[168:171], v209 offset:51200
	ds_read_b128 v[172:175], v209 offset:52224
	ds_read_b128 v[176:179], v209 offset:53248
	ds_read_b128 v[180:183], v209 offset:54272
	ds_read_b128 v[200:203], v209 offset:55296
	ds_read_b128 v[210:213], v209 offset:56320
	global_load_lds_dwordx4 v[214:215], off
	s_add_i32 m0, s56, 0x2000
	s_add_u32 s0, s0, 0x40080
	v_lshl_add_u64 v[214:215], v[216:217], 0, s[26:27]
	s_addc_u32 s1, s1, 0
	s_add_i32 s56, s78, s2
	global_load_lds_dwordx4 v[214:215], off
	v_lshl_add_u64 v[214:215], s[0:1], 0, v[186:187]
	s_mov_b32 m0, s56
	s_nop 0
	global_load_lds_dwordx4 v[214:215], off
	v_lshl_add_u64 v[214:215], s[0:1], 0, v[190:191]
	s_add_i32 m0, s56, 0x2000
	s_nop 0
	global_load_lds_dwordx4 v[214:215], off
	v_lshl_add_u64 v[214:215], v[218:219], 0, s[26:27]
	s_mov_b32 m0, s37
	s_nop 0
	global_load_lds_dwordx4 v[214:215], off
	v_lshl_add_u64 v[214:215], v[220:221], 0, s[26:27]
	s_mov_b32 m0, s38
	s_nop 0
	global_load_lds_dwordx4 v[214:215], off
	s_waitcnt vmcnt(8)
	s_waitcnt lgkmcnt(0)
	s_barrier
	s_waitcnt lgkmcnt(0)
	v_mfma_f32_16x16x32_bf16 v[60:63], v[92:95], v[160:163], v[60:63]
	v_mfma_f32_16x16x32_bf16 v[56:59], v[112:115], v[160:163], v[56:59]
	v_mfma_f32_16x16x32_bf16 v[44:47], v[92:95], v[168:171], v[44:47]
	v_mfma_f32_16x16x32_bf16 v[40:43], v[112:115], v[168:171], v[40:43]
	v_mfma_f32_16x16x32_bf16 v[28:31], v[92:95], v[176:179], v[28:31]
	v_mfma_f32_16x16x32_bf16 v[24:27], v[112:115], v[176:179], v[24:27]
	v_mfma_f32_16x16x32_bf16 v[12:15], v[92:95], v[200:203], v[12:15]
	v_mfma_f32_16x16x32_bf16 v[8:11], v[112:115], v[200:203], v[8:11]
	v_mfma_f32_16x16x32_bf16 v[60:63], v[100:103], v[164:167], v[60:63]
	v_mfma_f32_16x16x32_bf16 v[56:59], v[124:127], v[164:167], v[56:59]
	v_mfma_f32_16x16x32_bf16 v[44:47], v[100:103], v[172:175], v[44:47]
	v_mfma_f32_16x16x32_bf16 v[40:43], v[124:127], v[172:175], v[40:43]
	v_mfma_f32_16x16x32_bf16 v[28:31], v[100:103], v[180:183], v[28:31]
	v_mfma_f32_16x16x32_bf16 v[24:27], v[124:127], v[180:183], v[24:27]
	v_mfma_f32_16x16x32_bf16 v[12:15], v[100:103], v[210:213], v[12:15]
	v_mfma_f32_16x16x32_bf16 v[8:11], v[124:127], v[210:213], v[8:11]
	v_mfma_f32_16x16x32_bf16 v[52:55], v[136:139], v[160:163], v[52:55]
	v_mfma_f32_16x16x32_bf16 v[48:51], v[152:155], v[160:163], v[48:51]
	v_mfma_f32_16x16x32_bf16 v[36:39], v[136:139], v[168:171], v[36:39]
	v_mfma_f32_16x16x32_bf16 v[32:35], v[152:155], v[168:171], v[32:35]
	v_mfma_f32_16x16x32_bf16 v[20:23], v[136:139], v[176:179], v[20:23]
	v_mfma_f32_16x16x32_bf16 v[16:19], v[152:155], v[176:179], v[16:19]
	v_mfma_f32_16x16x32_bf16 v[4:7], v[136:139], v[200:203], v[4:7]
	v_mfma_f32_16x16x32_bf16 v[0:3], v[152:155], v[200:203], v[0:3]
	v_mfma_f32_16x16x32_bf16 v[52:55], v[148:151], v[164:167], v[52:55]
	v_mfma_f32_16x16x32_bf16 v[48:51], v[156:159], v[164:167], v[48:51]
	v_mfma_f32_16x16x32_bf16 v[36:39], v[148:151], v[172:175], v[36:39]
	v_mfma_f32_16x16x32_bf16 v[32:35], v[156:159], v[172:175], v[32:35]
	v_mfma_f32_16x16x32_bf16 v[20:23], v[148:151], v[180:183], v[20:23]
	v_mfma_f32_16x16x32_bf16 v[16:19], v[156:159], v[180:183], v[16:19]
	v_mfma_f32_16x16x32_bf16 v[4:7], v[148:151], v[210:213], v[4:7]
	v_mfma_f32_16x16x32_bf16 v[0:3], v[156:159], v[210:213], v[0:3]
	s_barrier
	s_add_i32 s76, s76, 2
	s_add_u32 s54, s54, 0x100
	s_addc_u32 s55, s55, 0
	s_add_u32 s74, s74, 0x100
	s_addc_u32 s75, s75, 0
	s_cmp_gt_u32 s76, 13
	s_cbranch_scc0 .LBB0_689

; #define PG8_STAGE(bufoff, gbase, voff) do { _Pragma("unroll") for (int _i = 0; _i < 2; ++_i) \
;         __builtin_amdgcn_global_load_lds((const unsigned*)((const char*)(gbase) + (voff)[_i]), (PG8_LAS unsigned*)(lds + (bufoff) + ldsw + _i * 8192), 16, 0, 0); } while (0)
; #define PG8_LDA(dst, b, h) do { _Pragma("unroll") for (int m = 0; m < 4; ++m) _Pragma("unroll") for (int k = 0; k < 2; ++k) dst[m][k] = *(const PG8_LAS bf16x8*)(lds + PG8_SA(b, h) + aoff + m * 2048 + k * 1024); } while (0)
; #define PG8_LDB(dst, b, h) do { _Pragma("unroll") for (int n = 0; n < 2; ++n) _Pragma("unroll") for (int k = 0; k < 2; ++k) dst[n][k] = *(const PG8_LAS bf16x8*)(lds + PG8_SB(b, h) + boff + n * 2048 + k * 1024); } while (0)
; #define PG8_WAIT_V(n) asm volatile("s_waitcnt vmcnt(" #n ")" ::: "memory")
; #define PG8_WAIT_L(n) asm volatile("s_waitcnt lgkmcnt(" #n ")" ::: "memory")
; #define PG8_BAR __builtin_amdgcn_s_barrier()
; #define PG8_SCHED __builtin_amdgcn_sched_barrier(0)
; template <class Epi, class Sched, bool ALIGN_EPI = false, bool SP2 = false>
; __device__ __forceinline__ void gemm_phase(PG8_LAS unsigned char* lds, const Gemm g, const Sched& S, const Epi& E, const int tid_in) {
;     ...
;         const char* nA = has_next ? (const char*)g.A + (size_t)nxt.pm * tstep : cA; const char* nB = has_next ? (const char*)g.Bt + (size_t)nxt.pn * tstep : cB;
;         for (int t = 0; t < nt; t += 2) {
;             const bool last = (t == nt - 2);
;             const char* a1 = cA + (size_t)(t + 1) * kstep;
;             const char* a2 = last ? nA : cA + (size_t)(t + 2) * kstep; const char* b2 = last ? nB : cB + (size_t)(t + 2) * kstep;
;             const char* a3 = a2 + kstep; const char* b3 = b2 + kstep;
;             if (last && has_next) S.a_ready(nxt);
;             if constexpr (SP2) {
;             PG8_LDB(B0, 0, 0); PG8_LDB(B1, 0, 1); PG8_SCHED; PG8_LDA(At, 0, 0); PG8_STAGE(PG8_SA(1, 1), a1 + hstep, voffA);
;             PG8_WAIT_V(8); PG8_WAIT_L(0); PG8_BAR; PG8_MMA(0, 0, At, B0); PG8_MMA(0, 1, At, B1); PG8_BAR; PG8_SCHED;
;             PG8_LDA(At, 0, 1); PG8_STAGE(PG8_SB(0, 0), b2, voffB); PG8_STAGE(PG8_SB(0, 1), b2 + hstep, voffB); PG8_STAGE(PG8_SA(0, 0), a2, voffA);
;             PG8_WAIT_V(8); PG8_WAIT_L(0); PG8_BAR; PG8_MMA(1, 0, At, B0); PG8_MMA(1, 1, At, B1); PG8_BAR; PG8_SCHED;
.LBB0_1199:
	s_ashr_i32 s45, s44, 31
	s_lshl_b64 s[8:9], s[44:45], 19
	s_add_u32 s46, s36, s8
	s_addc_u32 s47, s37, s9
	s_and_b64 s[8:9], s[4:5], exec
	s_cselect_b32 s45, s47, s55
	s_cselect_b32 s76, s46, s54
	s_ashr_i32 s43, s42, 31
	s_lshl_b64 s[8:9], s[42:43], 19
	s_add_u32 s52, s34, s8
	s_addc_u32 s53, s35, s9
	s_and_b64 s[8:9], s[4:5], exec
	s_cselect_b32 s43, s53, s1
	s_cselect_b32 s77, s52, s0
	s_add_u32 s8, s54, 0x40080
	s_addc_u32 s9, s55, 0
	s_add_u32 s78, s0, 0x100
	v_mov_b32_e32 v0, 0
	s_addc_u32 s79, s1, 0
	s_mov_b32 s80, -2
	ds_read_b128 v[160:163], v154
	ds_read_b128 v[164:167], v154 offset:1024
	ds_read_b128 v[168:171], v154 offset:2048
	ds_read_b128 v[172:175], v154 offset:3072
	ds_read_b128 v[176:179], v155
	ds_read_b128 v[180:183], v155 offset:1024
	ds_read_b128 v[184:187], v155 offset:2048
	ds_read_b128 v[188:191], v155 offset:3072
	s_add_u32 s0, s8, 0xfffc0080
	s_addc_u32 s1, s9, -1
	s_cmp_eq_u32 s80, 12
	s_cselect_b32 s55, s45, s1
	s_cselect_b32 s54, s76, s0
	s_cselect_b32 s1, s43, s79
	s_cselect_b32 s0, s77, s78
	v_lshl_add_u64 v[144:145], s[8:9], 0, v[136:137]
	s_add_i32 m0, s38, 0xc000
	ds_read_b128 v[192:195], v156
	ds_read_b128 v[196:199], v156 offset:1024
	ds_read_b128 v[200:203], v156 offset:2048
	ds_read_b128 v[204:207], v156 offset:3072
	ds_read_b128 v[208:211], v156 offset:4096
	ds_read_b128 v[212:215], v156 offset:5120
	ds_read_b128 v[216:219], v156 offset:6144
	ds_read_b128 v[220:223], v156 offset:7168
	global_load_lds_dwordx4 v[144:145], off
	v_lshl_add_u64 v[144:145], s[8:9], 0, v[138:139]
	s_add_i32 m0, s38, 0xe000
	s_nop 0
	global_load_lds_dwordx4 v[144:145], off
	s_waitcnt vmcnt(8)
	s_waitcnt lgkmcnt(0)
	s_barrier
	s_waitcnt lgkmcnt(0)
	v_mfma_f32_16x16x32_bf16 v[124:127], v[160:163], v[192:195], 0
	v_mfma_f32_16x16x32_bf16 v[116:119], v[168:171], v[192:195], 0
	v_mfma_f32_16x16x32_bf16 v[108:111], v[160:163], v[200:203], 0
	v_mfma_f32_16x16x32_bf16 v[100:103], v[168:171], v[200:203], 0
	v_mfma_f32_16x16x32_bf16 v[92:95], v[160:163], v[208:211], 0
	v_mfma_f32_16x16x32_bf16 v[84:87], v[168:171], v[208:211], 0
	v_mfma_f32_16x16x32_bf16 v[76:79], v[160:163], v[216:219], 0
	v_mfma_f32_16x16x32_bf16 v[68:71], v[168:171], v[216:219], 0
	v_mfma_f32_16x16x32_bf16 v[124:127], v[164:167], v[196:199], v[124:127]
	v_mfma_f32_16x16x32_bf16 v[116:119], v[172:175], v[196:199], v[116:119]
	v_mfma_f32_16x16x32_bf16 v[108:111], v[164:167], v[204:207], v[108:111]
	v_mfma_f32_16x16x32_bf16 v[100:103], v[172:175], v[204:207], v[100:103]
	v_mfma_f32_16x16x32_bf16 v[92:95], v[164:167], v[212:215], v[92:95]
	v_mfma_f32_16x16x32_bf16 v[84:87], v[172:175], v[212:215], v[84:87]
	v_mfma_f32_16x16x32_bf16 v[76:79], v[164:167], v[220:223], v[76:79]
	v_mfma_f32_16x16x32_bf16 v[68:71], v[172:175], v[220:223], v[68:71]
	v_mfma_f32_16x16x32_bf16 v[120:123], v[176:179], v[192:195], 0
	v_mfma_f32_16x16x32_bf16 v[112:115], v[184:187], v[192:195], 0
	v_mfma_f32_16x16x32_bf16 v[104:107], v[176:179], v[200:203], 0
	v_mfma_f32_16x16x32_bf16 v[96:99], v[184:187], v[200:203], 0
	v_mfma_f32_16x16x32_bf16 v[88:91], v[176:179], v[208:211], 0
	v_mfma_f32_16x16x32_bf16 v[80:83], v[184:187], v[208:211], 0
	v_mfma_f32_16x16x32_bf16 v[72:75], v[176:179], v[216:219], 0
	v_mfma_f32_16x16x32_bf16 v[64:67], v[184:187], v[216:219], 0
	v_mfma_f32_16x16x32_bf16 v[120:123], v[180:183], v[196:199], v[120:123]
	v_mfma_f32_16x16x32_bf16 v[112:115], v[188:191], v[196:199], v[112:115]
	v_mfma_f32_16x16x32_bf16 v[104:107], v[180:183], v[204:207], v[104:107]
	v_mfma_f32_16x16x32_bf16 v[96:99], v[188:191], v[204:207], v[96:99]
	v_mfma_f32_16x16x32_bf16 v[88:91], v[180:183], v[212:215], v[88:91]
	v_mfma_f32_16x16x32_bf16 v[80:83], v[188:191], v[212:215], v[80:83]
	v_mfma_f32_16x16x32_bf16 v[72:75], v[180:183], v[220:223], v[72:75]
	v_mfma_f32_16x16x32_bf16 v[64:67], v[188:191], v[220:223], v[64:67]
	s_barrier
	s_add_i32 s81, s57, s31
	v_lshl_add_u64 v[144:145], s[0:1], 0, v[130:131]
	s_mov_b32 m0, s81
	ds_read_b128 v[192:195], v156 offset:16384
	ds_read_b128 v[196:199], v156 offset:17408
	ds_read_b128 v[200:203], v156 offset:18432
	ds_read_b128 v[204:207], v156 offset:19456
	ds_read_b128 v[208:211], v156 offset:20480
	ds_read_b128 v[212:215], v156 offset:21504
	ds_read_b128 v[216:219], v156 offset:22528
	ds_read_b128 v[220:223], v156 offset:23552
	global_load_lds_dwordx4 v[144:145], off
	s_add_i32 m0, s81, 0x2000
	s_add_u32 s82, s0, 0x40000
	v_lshl_add_u64 v[224:225], s[0:1], 0, v[134:135]
	s_addc_u32 s83, s1, 0
	s_add_i32 s81, s73, s31
	global_load_lds_dwordx4 v[224:225], off
	v_lshl_add_u64 v[226:227], s[82:83], 0, v[130:131]
	s_mov_b32 m0, s81
	v_lshl_add_u64 v[228:229], s[54:55], 0, v[132:133]
	global_load_lds_dwordx4 v[226:227], off
	v_lshl_add_u64 v[226:227], s[82:83], 0, v[134:135]
	s_add_i32 m0, s81, 0x2000
	s_nop 0
	global_load_lds_dwordx4 v[226:227], off
	v_lshl_add_u64 v[226:227], s[54:55], 0, v[128:129]
	s_mov_b32 m0, s38
	s_nop 0
	global_load_lds_dwordx4 v[226:227], off
	s_mov_b32 m0, s39
	s_nop 0
	global_load_lds_dwordx4 v[228:229], off
	s_waitcnt vmcnt(8)
	s_waitcnt lgkmcnt(0)
	s_barrier
; #define PG8_STAGE(bufoff, gbase, voff) do { _Pragma("unroll") for (int _i = 0; _i < 2; ++_i) \
;         __builtin_amdgcn_global_load_lds((const unsigned*)((const char*)(gbase) + (voff)[_i]), (PG8_LAS unsigned*)(lds + (bufoff) + ldsw + _i * 8192), 16, 0, 0); } while (0)
; #define PG8_LDA(dst, b, h) do { _Pragma("unroll") for (int m = 0; m < 4; ++m) _Pragma("unroll") for (int k = 0; k < 2; ++k) dst[m][k] = *(const PG8_LAS bf16x8*)(lds + PG8_SA(b, h) + aoff + m * 2048 + k * 1024); } while (0)
; #define PG8_LDB(dst, b, h) do { _Pragma("unroll") for (int n = 0; n < 2; ++n) _Pragma("unroll") for (int k = 0; k < 2; ++k) dst[n][k] = *(const PG8_LAS bf16x8*)(lds + PG8_SB(b, h) + boff + n * 2048 + k * 1024); } while (0)
; #define PG8_MMA(ai, bj, At, Bt) do { __builtin_amdgcn_s_setprio(1); _Pragma("unroll") for (int m = 0; m < 4; ++m) _Pragma("unroll") for (int n = 0; n < 2; ++n) _Pragma("unroll") for (int k = 0; k < 2; ++k) \
;         acc[ai][bj][m][n] = __builtin_amdgcn_mfma_f32_16x16x32_bf16(Bt[n][k], At[m][k], acc[ai][bj][m][n], 0, 0, 0); __builtin_amdgcn_s_setprio(0); } while (0)
; #define PG8_WAIT_V(n) asm volatile("s_waitcnt vmcnt(" #n ")" ::: "memory")
; #define PG8_WAIT_L(n) asm volatile("s_waitcnt lgkmcnt(" #n ")" ::: "memory")
; #define PG8_BAR __builtin_amdgcn_s_barrier()
; #define PG8_SCHED __builtin_amdgcn_sched_barrier(0)
; template <class Epi, class Sched, bool ALIGN_EPI = false, bool SP2 = false>
; __device__ __forceinline__ void gemm_phase(PG8_LAS unsigned char* lds, const Gemm g, const Sched& S, const Epi& E, const int tid_in) {
;     ...
;             PG8_WAIT_V(8); PG8_WAIT_L(0); PG8_BAR; PG8_MMA(0, 0, At, B0); PG8_MMA(0, 1, At, B1); PG8_BAR; PG8_SCHED;
;             PG8_LDA(At, 0, 1); PG8_STAGE(PG8_SB(0, 0), b2, voffB); PG8_STAGE(PG8_SB(0, 1), b2 + hstep, voffB); PG8_STAGE(PG8_SA(0, 0), a2, voffA);
;             PG8_WAIT_V(8); PG8_WAIT_L(0); PG8_BAR; PG8_MMA(1, 0, At, B0); PG8_MMA(1, 1, At, B1); PG8_BAR; PG8_SCHED;
;             PG8_LDB(B0, 1, 0); PG8_LDB(B1, 1, 1); PG8_SCHED; PG8_LDA(At, 1, 0); PG8_STAGE(PG8_SA(0, 1), a2 + hstep, voffA);
;             PG8_WAIT_V(8); PG8_WAIT_L(0); PG8_BAR; PG8_MMA(0, 0, At, B0); PG8_MMA(0, 1, At, B1); PG8_BAR; PG8_SCHED;
	s_waitcnt lgkmcnt(0)
	v_mfma_f32_16x16x32_bf16 v[60:63], v[160:163], v[192:195], 0
	v_mfma_f32_16x16x32_bf16 v[52:55], v[168:171], v[192:195], 0
	v_mfma_f32_16x16x32_bf16 v[44:47], v[160:163], v[200:203], 0
	v_mfma_f32_16x16x32_bf16 v[36:39], v[168:171], v[200:203], 0
	v_mfma_f32_16x16x32_bf16 v[28:31], v[160:163], v[208:211], 0
	v_mfma_f32_16x16x32_bf16 v[20:23], v[168:171], v[208:211], 0
	v_mfma_f32_16x16x32_bf16 v[12:15], v[160:163], v[216:219], 0
	v_mfma_f32_16x16x32_bf16 v[4:7], v[168:171], v[216:219], 0
	v_mfma_f32_16x16x32_bf16 v[60:63], v[164:167], v[196:199], v[60:63]
	v_mfma_f32_16x16x32_bf16 v[52:55], v[172:175], v[196:199], v[52:55]
	v_mfma_f32_16x16x32_bf16 v[44:47], v[164:167], v[204:207], v[44:47]
	v_mfma_f32_16x16x32_bf16 v[36:39], v[172:175], v[204:207], v[36:39]
	v_mfma_f32_16x16x32_bf16 v[28:31], v[164:167], v[212:215], v[28:31]
	v_mfma_f32_16x16x32_bf16 v[20:23], v[172:175], v[212:215], v[20:23]
	v_mfma_f32_16x16x32_bf16 v[12:15], v[164:167], v[220:223], v[12:15]
	v_mfma_f32_16x16x32_bf16 v[4:7], v[172:175], v[220:223], v[4:7]
	v_mfma_f32_16x16x32_bf16 v[56:59], v[176:179], v[192:195], 0
	v_mfma_f32_16x16x32_bf16 v[48:51], v[184:187], v[192:195], 0
	v_mfma_f32_16x16x32_bf16 v[40:43], v[176:179], v[200:203], 0
	v_mfma_f32_16x16x32_bf16 v[32:35], v[184:187], v[200:203], 0
	v_mfma_f32_16x16x32_bf16 v[24:27], v[176:179], v[208:211], 0
	v_mfma_f32_16x16x32_bf16 v[16:19], v[184:187], v[208:211], 0
	v_mfma_f32_16x16x32_bf16 v[8:11], v[176:179], v[216:219], 0
	v_mfma_f32_16x16x32_bf16 v[0:3], v[184:187], v[216:219], 0
	v_mfma_f32_16x16x32_bf16 v[56:59], v[180:183], v[196:199], v[56:59]
	v_mfma_f32_16x16x32_bf16 v[48:51], v[188:191], v[196:199], v[48:51]
	v_mfma_f32_16x16x32_bf16 v[40:43], v[180:183], v[204:207], v[40:43]
	v_mfma_f32_16x16x32_bf16 v[32:35], v[188:191], v[204:207], v[32:35]
	v_mfma_f32_16x16x32_bf16 v[24:27], v[180:183], v[212:215], v[24:27]
	v_mfma_f32_16x16x32_bf16 v[16:19], v[188:191], v[212:215], v[16:19]
	v_mfma_f32_16x16x32_bf16 v[8:11], v[180:183], v[220:223], v[8:11]
	v_mfma_f32_16x16x32_bf16 v[0:3], v[188:191], v[220:223], v[0:3]
	s_barrier
	s_add_i32 s81, 0, 0x18000
	v_add_u32_e32 v159, s81, v148
	s_add_i32 s82, 0, 0x1c000
	ds_read_b128 v[160:163], v159
	ds_read_b128 v[164:167], v159 offset:1024
	ds_read_b128 v[168:171], v159 offset:2048
	ds_read_b128 v[172:175], v159 offset:3072
	v_add_u32_e32 v159, s82, v148
	ds_read_b128 v[176:179], v159
	ds_read_b128 v[180:183], v159 offset:1024
	ds_read_b128 v[184:187], v159 offset:2048
	ds_read_b128 v[188:191], v159 offset:3072
	s_add_u32 s54, s54, 0x40000
	s_addc_u32 s55, s55, 0
	s_mov_b32 m0, s40
	v_lshl_add_u64 v[230:231], s[54:55], 0, v[128:129]
	ds_read_b128 v[192:195], v156 offset:32768
	ds_read_b128 v[196:199], v156 offset:33792
	ds_read_b128 v[200:203], v156 offset:34816
	ds_read_b128 v[204:207], v156 offset:35840
	ds_read_b128 v[208:211], v156 offset:36864
	ds_read_b128 v[212:215], v156 offset:37888
	ds_read_b128 v[216:219], v156 offset:38912
	ds_read_b128 v[220:223], v156 offset:39936
	global_load_lds_dwordx4 v[230:231], off
	v_lshl_add_u64 v[230:231], s[54:55], 0, v[132:133]
	s_mov_b32 m0, s41
	s_nop 0
	global_load_lds_dwordx4 v[230:231], off
	s_waitcnt vmcnt(8)
	s_waitcnt lgkmcnt(0)
	s_barrier
	s_waitcnt lgkmcnt(0)
	v_mfma_f32_16x16x32_bf16 v[124:127], v[160:163], v[192:195], v[124:127]
	v_mfma_f32_16x16x32_bf16 v[116:119], v[168:171], v[192:195], v[116:119]
	v_mfma_f32_16x16x32_bf16 v[108:111], v[160:163], v[200:203], v[108:111]
	v_mfma_f32_16x16x32_bf16 v[100:103], v[168:171], v[200:203], v[100:103]
	v_mfma_f32_16x16x32_bf16 v[92:95], v[160:163], v[208:211], v[92:95]
	v_mfma_f32_16x16x32_bf16 v[84:87], v[168:171], v[208:211], v[84:87]
	v_mfma_f32_16x16x32_bf16 v[76:79], v[160:163], v[216:219], v[76:79]
	v_mfma_f32_16x16x32_bf16 v[68:71], v[168:171], v[216:219], v[68:71]
	v_mfma_f32_16x16x32_bf16 v[124:127], v[164:167], v[196:199], v[124:127]
	v_mfma_f32_16x16x32_bf16 v[116:119], v[172:175], v[196:199], v[116:119]
	v_mfma_f32_16x16x32_bf16 v[108:111], v[164:167], v[204:207], v[108:111]
	v_mfma_f32_16x16x32_bf16 v[100:103], v[172:175], v[204:207], v[100:103]
	v_mfma_f32_16x16x32_bf16 v[92:95], v[164:167], v[212:215], v[92:95]
	v_mfma_f32_16x16x32_bf16 v[84:87], v[172:175], v[212:215], v[84:87]
	v_mfma_f32_16x16x32_bf16 v[76:79], v[164:167], v[220:223], v[76:79]
	v_mfma_f32_16x16x32_bf16 v[68:71], v[172:175], v[220:223], v[68:71]
	v_mfma_f32_16x16x32_bf16 v[120:123], v[176:179], v[192:195], v[120:123]
	v_mfma_f32_16x16x32_bf16 v[112:115], v[184:187], v[192:195], v[112:115]
	v_mfma_f32_16x16x32_bf16 v[104:107], v[176:179], v[200:203], v[104:107]
	v_mfma_f32_16x16x32_bf16 v[96:99], v[184:187], v[200:203], v[96:99]
	v_mfma_f32_16x16x32_bf16 v[88:91], v[176:179], v[208:211], v[88:91]
	v_mfma_f32_16x16x32_bf16 v[80:83], v[184:187], v[208:211], v[80:83]
	v_mfma_f32_16x16x32_bf16 v[72:75], v[176:179], v[216:219], v[72:75]
	v_mfma_f32_16x16x32_bf16 v[64:67], v[184:187], v[216:219], v[64:67]
	v_mfma_f32_16x16x32_bf16 v[120:123], v[180:183], v[196:199], v[120:123]
	v_mfma_f32_16x16x32_bf16 v[112:115], v[188:191], v[196:199], v[112:115]
	v_mfma_f32_16x16x32_bf16 v[104:107], v[180:183], v[204:207], v[104:107]
	v_mfma_f32_16x16x32_bf16 v[96:99], v[188:191], v[204:207], v[96:99]
	v_mfma_f32_16x16x32_bf16 v[88:91], v[180:183], v[212:215], v[88:91]
	v_mfma_f32_16x16x32_bf16 v[80:83], v[188:191], v[212:215], v[80:83]
	v_mfma_f32_16x16x32_bf16 v[72:75], v[180:183], v[220:223], v[72:75]
	v_mfma_f32_16x16x32_bf16 v[64:67], v[188:191], v[220:223], v[64:67]
	s_barrier
; #define PG8_STAGE(bufoff, gbase, voff) do { _Pragma("unroll") for (int _i = 0; _i < 2; ++_i) \
;         __builtin_amdgcn_global_load_lds((const unsigned*)((const char*)(gbase) + (voff)[_i]), (PG8_LAS unsigned*)(lds + (bufoff) + ldsw + _i * 8192), 16, 0, 0); } while (0)
; #define PG8_LDA(dst, b, h) do { _Pragma("unroll") for (int m = 0; m < 4; ++m) _Pragma("unroll") for (int k = 0; k < 2; ++k) dst[m][k] = *(const PG8_LAS bf16x8*)(lds + PG8_SA(b, h) + aoff + m * 2048 + k * 1024); } while (0)
; #define PG8_LDB(dst, b, h) do { _Pragma("unroll") for (int n = 0; n < 2; ++n) _Pragma("unroll") for (int k = 0; k < 2; ++k) dst[n][k] = *(const PG8_LAS bf16x8*)(lds + PG8_SB(b, h) + boff + n * 2048 + k * 1024); } while (0)
; #define PG8_WAIT_V(n) asm volatile("s_waitcnt vmcnt(" #n ")" ::: "memory")
; template <class Epi, class Sched, bool ALIGN_EPI = false, bool SP2 = false>
; __device__ __forceinline__ void gemm_phase(PG8_LAS unsigned char* lds, const Gemm g, const Sched& S, const Epi& E, const int tid_in) {
;     ...
;         for (int t = 0; t < nt; t += 2) {
;             const bool last = (t == nt - 2);
;             const char* a1 = cA + (size_t)(t + 1) * kstep;
;             const char* a2 = last ? nA : cA + (size_t)(t + 2) * kstep; const char* b2 = last ? nB : cB + (size_t)(t + 2) * kstep;
;             const char* a3 = a2 + kstep; const char* b3 = b2 + kstep;
;             if (last && has_next) S.a_ready(nxt);
;             if constexpr (SP2) {
;             PG8_LDB(B0, 0, 0); PG8_LDB(B1, 0, 1); PG8_SCHED; PG8_LDA(At, 0, 0); PG8_STAGE(PG8_SA(1, 1), a1 + hstep, voffA);
;             PG8_WAIT_V(8); PG8_WAIT_L(0); PG8_BAR; PG8_MMA(0, 0, At, B0); PG8_MMA(0, 1, At, B1); PG8_BAR; PG8_SCHED;
;             PG8_LDA(At, 0, 1); PG8_STAGE(PG8_SB(0, 0), b2, voffB); PG8_STAGE(PG8_SB(0, 1), b2 + hstep, voffB); PG8_STAGE(PG8_SA(0, 0), a2, voffA);
;             PG8_WAIT_V(8); PG8_WAIT_L(0); PG8_BAR; PG8_MMA(1, 0, At, B0); PG8_MMA(1, 1, At, B1); PG8_BAR; PG8_SCHED;
;     ...
;             PG8_WAIT_V(8); PG8_WAIT_L(0); PG8_BAR; PG8_MMA(0, 0, At, B0); PG8_MMA(0, 1, At, B1); PG8_BAR; PG8_SCHED;
;             PG8_LDA(At, 1, 1); PG8_STAGE(PG8_SB(1, 0), b3, voffB); PG8_STAGE(PG8_SB(1, 1), b3 + hstep, voffB); PG8_STAGE(PG8_SA(1, 0), a3, voffA);
;             PG8_WAIT_V(8); PG8_WAIT_L(0); PG8_BAR; PG8_MMA(1, 0, At, B0); PG8_MMA(1, 1, At, B1); PG8_BAR; PG8_SCHED;
	s_add_i32 s54, s81, s31
	v_lshl_add_u64 v[144:145], v[144:145], 0, s[26:27]
	s_mov_b32 m0, s54
	ds_read_b128 v[192:195], v156 offset:49152
	ds_read_b128 v[196:199], v156 offset:50176
	ds_read_b128 v[200:203], v156 offset:51200
	ds_read_b128 v[204:207], v156 offset:52224
	ds_read_b128 v[208:211], v156 offset:53248
	ds_read_b128 v[212:215], v156 offset:54272
	ds_read_b128 v[216:219], v156 offset:55296
	ds_read_b128 v[220:223], v156 offset:56320
	global_load_lds_dwordx4 v[144:145], off
	s_add_i32 m0, s54, 0x2000
	s_add_u32 s0, s0, 0x40080
	v_lshl_add_u64 v[144:145], v[224:225], 0, s[26:27]
	s_addc_u32 s1, s1, 0
	s_add_i32 s54, s82, s31
	global_load_lds_dwordx4 v[144:145], off
	v_lshl_add_u64 v[144:145], s[0:1], 0, v[130:131]
	s_mov_b32 m0, s54
	s_nop 0
	global_load_lds_dwordx4 v[144:145], off
	v_lshl_add_u64 v[144:145], s[0:1], 0, v[134:135]
	s_add_i32 m0, s54, 0x2000
	s_nop 0
	global_load_lds_dwordx4 v[144:145], off
	v_lshl_add_u64 v[144:145], v[226:227], 0, s[26:27]
	s_mov_b32 m0, s50
	s_nop 0
	global_load_lds_dwordx4 v[144:145], off
	v_lshl_add_u64 v[144:145], v[228:229], 0, s[26:27]
	s_mov_b32 m0, s51
	s_nop 0
	global_load_lds_dwordx4 v[144:145], off
	s_waitcnt vmcnt(8)
	s_waitcnt lgkmcnt(0)
	s_barrier
	s_waitcnt lgkmcnt(0)
	v_mfma_f32_16x16x32_bf16 v[60:63], v[160:163], v[192:195], v[60:63]
	v_mfma_f32_16x16x32_bf16 v[52:55], v[168:171], v[192:195], v[52:55]
	v_mfma_f32_16x16x32_bf16 v[44:47], v[160:163], v[200:203], v[44:47]
	v_mfma_f32_16x16x32_bf16 v[36:39], v[168:171], v[200:203], v[36:39]
	v_mfma_f32_16x16x32_bf16 v[28:31], v[160:163], v[208:211], v[28:31]
	v_mfma_f32_16x16x32_bf16 v[20:23], v[168:171], v[208:211], v[20:23]
	v_mfma_f32_16x16x32_bf16 v[12:15], v[160:163], v[216:219], v[12:15]
	v_mfma_f32_16x16x32_bf16 v[4:7], v[168:171], v[216:219], v[4:7]
	v_mfma_f32_16x16x32_bf16 v[60:63], v[164:167], v[196:199], v[60:63]
	v_mfma_f32_16x16x32_bf16 v[52:55], v[172:175], v[196:199], v[52:55]
	v_mfma_f32_16x16x32_bf16 v[44:47], v[164:167], v[204:207], v[44:47]
	v_mfma_f32_16x16x32_bf16 v[36:39], v[172:175], v[204:207], v[36:39]
	v_mfma_f32_16x16x32_bf16 v[28:31], v[164:167], v[212:215], v[28:31]
	v_mfma_f32_16x16x32_bf16 v[20:23], v[172:175], v[212:215], v[20:23]
	v_mfma_f32_16x16x32_bf16 v[12:15], v[164:167], v[220:223], v[12:15]
	v_mfma_f32_16x16x32_bf16 v[4:7], v[172:175], v[220:223], v[4:7]
	v_mfma_f32_16x16x32_bf16 v[56:59], v[176:179], v[192:195], v[56:59]
	v_mfma_f32_16x16x32_bf16 v[48:51], v[184:187], v[192:195], v[48:51]
	v_mfma_f32_16x16x32_bf16 v[40:43], v[176:179], v[200:203], v[40:43]
	v_mfma_f32_16x16x32_bf16 v[32:35], v[184:187], v[200:203], v[32:35]
	v_mfma_f32_16x16x32_bf16 v[24:27], v[176:179], v[208:211], v[24:27]
	v_mfma_f32_16x16x32_bf16 v[16:19], v[184:187], v[208:211], v[16:19]
	v_mfma_f32_16x16x32_bf16 v[8:11], v[176:179], v[216:219], v[8:11]
	v_mfma_f32_16x16x32_bf16 v[0:3], v[184:187], v[216:219], v[0:3]
	v_mfma_f32_16x16x32_bf16 v[56:59], v[180:183], v[196:199], v[56:59]
	v_mfma_f32_16x16x32_bf16 v[48:51], v[188:191], v[196:199], v[48:51]
	v_mfma_f32_16x16x32_bf16 v[40:43], v[180:183], v[204:207], v[40:43]
	v_mfma_f32_16x16x32_bf16 v[32:35], v[188:191], v[204:207], v[32:35]
	v_mfma_f32_16x16x32_bf16 v[24:27], v[180:183], v[212:215], v[24:27]
	v_mfma_f32_16x16x32_bf16 v[16:19], v[188:191], v[212:215], v[16:19]
	v_mfma_f32_16x16x32_bf16 v[8:11], v[180:183], v[220:223], v[8:11]
	v_mfma_f32_16x16x32_bf16 v[0:3], v[188:191], v[220:223], v[0:3]
	s_barrier
	s_add_i32 s80, s80, 2
	s_add_u32 s8, s8, 0x100
	s_addc_u32 s9, s9, 0
	s_add_u32 s78, s78, 0x100
	s_addc_u32 s79, s79, 0
	s_cmp_gt_u32 s80, 13
	s_cbranch_scc0 .LBB0_1200
	s_branch .Lmy_kdone_3
.LBB0_1200:
	ds_read_b128 v[160:163], v154
	ds_read_b128 v[164:167], v154 offset:1024
	ds_read_b128 v[168:171], v154 offset:2048
	ds_read_b128 v[172:175], v154 offset:3072
	ds_read_b128 v[176:179], v155
	ds_read_b128 v[180:183], v155 offset:1024
	ds_read_b128 v[184:187], v155 offset:2048
	ds_read_b128 v[188:191], v155 offset:3072
	s_add_u32 s0, s8, 0xfffc0080
	s_addc_u32 s1, s9, -1
	s_cmp_eq_u32 s80, 12
	s_cselect_b32 s55, s45, s1
	s_cselect_b32 s54, s76, s0
	s_cselect_b32 s1, s43, s79
	s_cselect_b32 s0, s77, s78
	v_lshl_add_u64 v[144:145], s[8:9], 0, v[136:137]
	s_add_i32 m0, s38, 0xc000
	ds_read_b128 v[192:195], v156
	ds_read_b128 v[196:199], v156 offset:1024
	ds_read_b128 v[200:203], v156 offset:2048
	ds_read_b128 v[204:207], v156 offset:3072
	ds_read_b128 v[208:211], v156 offset:4096
	ds_read_b128 v[212:215], v156 offset:5120
	ds_read_b128 v[216:219], v156 offset:6144
	ds_read_b128 v[220:223], v156 offset:7168
	global_load_lds_dwordx4 v[144:145], off
	v_lshl_add_u64 v[144:145], s[8:9], 0, v[138:139]
	s_add_i32 m0, s38, 0xe000
	s_nop 0
	global_load_lds_dwordx4 v[144:145], off
	s_waitcnt vmcnt(8)
	s_waitcnt lgkmcnt(0)
	s_barrier
; #define PG8_STAGE(bufoff, gbase, voff) do { _Pragma("unroll") for (int _i = 0; _i < 2; ++_i) \
;         __builtin_amdgcn_global_load_lds((const unsigned*)((const char*)(gbase) + (voff)[_i]), (PG8_LAS unsigned*)(lds + (bufoff) + ldsw + _i * 8192), 16, 0, 0); } while (0)
; #define PG8_LDA(dst, b, h) do { _Pragma("unroll") for (int m = 0; m < 4; ++m) _Pragma("unroll") for (int k = 0; k < 2; ++k) dst[m][k] = *(const PG8_LAS bf16x8*)(lds + PG8_SA(b, h) + aoff + m * 2048 + k * 1024); } while (0)
; #define PG8_LDB(dst, b, h) do { _Pragma("unroll") for (int n = 0; n < 2; ++n) _Pragma("unroll") for (int k = 0; k < 2; ++k) dst[n][k] = *(const PG8_LAS bf16x8*)(lds + PG8_SB(b, h) + boff + n * 2048 + k * 1024); } while (0)
; #define PG8_MMA(ai, bj, At, Bt) do { __builtin_amdgcn_s_setprio(1); _Pragma("unroll") for (int m = 0; m < 4; ++m) _Pragma("unroll") for (int n = 0; n < 2; ++n) _Pragma("unroll") for (int k = 0; k < 2; ++k) \
;         acc[ai][bj][m][n] = __builtin_amdgcn_mfma_f32_16x16x32_bf16(Bt[n][k], At[m][k], acc[ai][bj][m][n], 0, 0, 0); __builtin_amdgcn_s_setprio(0); } while (0)
; #define PG8_WAIT_V(n) asm volatile("s_waitcnt vmcnt(" #n ")" ::: "memory")
; #define PG8_WAIT_L(n) asm volatile("s_waitcnt lgkmcnt(" #n ")" ::: "memory")
; #define PG8_BAR __builtin_amdgcn_s_barrier()
; #define PG8_SCHED __builtin_amdgcn_sched_barrier(0)
; template <class Epi, class Sched, bool ALIGN_EPI = false, bool SP2 = false>
; __device__ __forceinline__ void gemm_phase(PG8_LAS unsigned char* lds, const Gemm g, const Sched& S, const Epi& E, const int tid_in) {
;     ...
;             PG8_LDB(B0, 0, 0); PG8_LDB(B1, 0, 1); PG8_SCHED; PG8_LDA(At, 0, 0); PG8_STAGE(PG8_SA(1, 1), a1 + hstep, voffA);
;             PG8_WAIT_V(8); PG8_WAIT_L(0); PG8_BAR; PG8_MMA(0, 0, At, B0); PG8_MMA(0, 1, At, B1); PG8_BAR; PG8_SCHED;
;             PG8_LDA(At, 0, 1); PG8_STAGE(PG8_SB(0, 0), b2, voffB); PG8_STAGE(PG8_SB(0, 1), b2 + hstep, voffB); PG8_STAGE(PG8_SA(0, 0), a2, voffA);
;             PG8_WAIT_V(8); PG8_WAIT_L(0); PG8_BAR; PG8_MMA(1, 0, At, B0); PG8_MMA(1, 1, At, B1); PG8_BAR; PG8_SCHED;
	s_waitcnt lgkmcnt(0)
	v_mfma_f32_16x16x32_bf16 v[124:127], v[160:163], v[192:195], v[124:127]
	v_mfma_f32_16x16x32_bf16 v[116:119], v[168:171], v[192:195], v[116:119]
	v_mfma_f32_16x16x32_bf16 v[108:111], v[160:163], v[200:203], v[108:111]
	v_mfma_f32_16x16x32_bf16 v[100:103], v[168:171], v[200:203], v[100:103]
	v_mfma_f32_16x16x32_bf16 v[92:95], v[160:163], v[208:211], v[92:95]
	v_mfma_f32_16x16x32_bf16 v[84:87], v[168:171], v[208:211], v[84:87]
	v_mfma_f32_16x16x32_bf16 v[76:79], v[160:163], v[216:219], v[76:79]
	v_mfma_f32_16x16x32_bf16 v[68:71], v[168:171], v[216:219], v[68:71]
	v_mfma_f32_16x16x32_bf16 v[124:127], v[164:167], v[196:199], v[124:127]
	v_mfma_f32_16x16x32_bf16 v[116:119], v[172:175], v[196:199], v[116:119]
	v_mfma_f32_16x16x32_bf16 v[108:111], v[164:167], v[204:207], v[108:111]
	v_mfma_f32_16x16x32_bf16 v[100:103], v[172:175], v[204:207], v[100:103]
	v_mfma_f32_16x16x32_bf16 v[92:95], v[164:167], v[212:215], v[92:95]
	v_mfma_f32_16x16x32_bf16 v[84:87], v[172:175], v[212:215], v[84:87]
	v_mfma_f32_16x16x32_bf16 v[76:79], v[164:167], v[220:223], v[76:79]
	v_mfma_f32_16x16x32_bf16 v[68:71], v[172:175], v[220:223], v[68:71]
	v_mfma_f32_16x16x32_bf16 v[120:123], v[176:179], v[192:195], v[120:123]
	v_mfma_f32_16x16x32_bf16 v[112:115], v[184:187], v[192:195], v[112:115]
	v_mfma_f32_16x16x32_bf16 v[104:107], v[176:179], v[200:203], v[104:107]
	v_mfma_f32_16x16x32_bf16 v[96:99], v[184:187], v[200:203], v[96:99]
	v_mfma_f32_16x16x32_bf16 v[88:91], v[176:179], v[208:211], v[88:91]
	v_mfma_f32_16x16x32_bf16 v[80:83], v[184:187], v[208:211], v[80:83]
	v_mfma_f32_16x16x32_bf16 v[72:75], v[176:179], v[216:219], v[72:75]
	v_mfma_f32_16x16x32_bf16 v[64:67], v[184:187], v[216:219], v[64:67]
	v_mfma_f32_16x16x32_bf16 v[120:123], v[180:183], v[196:199], v[120:123]
	v_mfma_f32_16x16x32_bf16 v[112:115], v[188:191], v[196:199], v[112:115]
	v_mfma_f32_16x16x32_bf16 v[104:107], v[180:183], v[204:207], v[104:107]
	v_mfma_f32_16x16x32_bf16 v[96:99], v[188:191], v[204:207], v[96:99]
	v_mfma_f32_16x16x32_bf16 v[88:91], v[180:183], v[212:215], v[88:91]
	v_mfma_f32_16x16x32_bf16 v[80:83], v[188:191], v[212:215], v[80:83]
	v_mfma_f32_16x16x32_bf16 v[72:75], v[180:183], v[220:223], v[72:75]
	v_mfma_f32_16x16x32_bf16 v[64:67], v[188:191], v[220:223], v[64:67]
	s_barrier
	s_add_i32 s81, s57, s31
	v_lshl_add_u64 v[144:145], s[0:1], 0, v[130:131]
	s_mov_b32 m0, s81
	ds_read_b128 v[192:195], v156 offset:16384
	ds_read_b128 v[196:199], v156 offset:17408
	ds_read_b128 v[200:203], v156 offset:18432
	ds_read_b128 v[204:207], v156 offset:19456
	ds_read_b128 v[208:211], v156 offset:20480
	ds_read_b128 v[212:215], v156 offset:21504
	ds_read_b128 v[216:219], v156 offset:22528
	ds_read_b128 v[220:223], v156 offset:23552
	global_load_lds_dwordx4 v[144:145], off
	s_add_i32 m0, s81, 0x2000
	s_add_u32 s82, s0, 0x40000
	v_lshl_add_u64 v[224:225], s[0:1], 0, v[134:135]
	s_addc_u32 s83, s1, 0
	s_add_i32 s81, s73, s31
	global_load_lds_dwordx4 v[224:225], off
	v_lshl_add_u64 v[226:227], s[82:83], 0, v[130:131]
	s_mov_b32 m0, s81
	v_lshl_add_u64 v[228:229], s[54:55], 0, v[132:133]
	global_load_lds_dwordx4 v[226:227], off
	v_lshl_add_u64 v[226:227], s[82:83], 0, v[134:135]
	s_add_i32 m0, s81, 0x2000
	s_nop 0
	global_load_lds_dwordx4 v[226:227], off
	v_lshl_add_u64 v[226:227], s[54:55], 0, v[128:129]
	s_mov_b32 m0, s38
	s_nop 0
	global_load_lds_dwordx4 v[226:227], off
	s_mov_b32 m0, s39
	s_nop 0
	global_load_lds_dwordx4 v[228:229], off
	s_waitcnt vmcnt(8)
	s_waitcnt lgkmcnt(0)
	s_barrier
	s_waitcnt lgkmcnt(0)
	v_mfma_f32_16x16x32_bf16 v[60:63], v[160:163], v[192:195], v[60:63]
	v_mfma_f32_16x16x32_bf16 v[52:55], v[168:171], v[192:195], v[52:55]
	v_mfma_f32_16x16x32_bf16 v[44:47], v[160:163], v[200:203], v[44:47]
	v_mfma_f32_16x16x32_bf16 v[36:39], v[168:171], v[200:203], v[36:39]
	v_mfma_f32_16x16x32_bf16 v[28:31], v[160:163], v[208:211], v[28:31]
	v_mfma_f32_16x16x32_bf16 v[20:23], v[168:171], v[208:211], v[20:23]
	v_mfma_f32_16x16x32_bf16 v[12:15], v[160:163], v[216:219], v[12:15]
	v_mfma_f32_16x16x32_bf16 v[4:7], v[168:171], v[216:219], v[4:7]
	v_mfma_f32_16x16x32_bf16 v[60:63], v[164:167], v[196:199], v[60:63]
	v_mfma_f32_16x16x32_bf16 v[52:55], v[172:175], v[196:199], v[52:55]
	v_mfma_f32_16x16x32_bf16 v[44:47], v[164:167], v[204:207], v[44:47]
	v_mfma_f32_16x16x32_bf16 v[36:39], v[172:175], v[204:207], v[36:39]
	v_mfma_f32_16x16x32_bf16 v[28:31], v[164:167], v[212:215], v[28:31]
	v_mfma_f32_16x16x32_bf16 v[20:23], v[172:175], v[212:215], v[20:23]
	v_mfma_f32_16x16x32_bf16 v[12:15], v[164:167], v[220:223], v[12:15]
	v_mfma_f32_16x16x32_bf16 v[4:7], v[172:175], v[220:223], v[4:7]
	v_mfma_f32_16x16x32_bf16 v[56:59], v[176:179], v[192:195], v[56:59]
	v_mfma_f32_16x16x32_bf16 v[48:51], v[184:187], v[192:195], v[48:51]
	v_mfma_f32_16x16x32_bf16 v[40:43], v[176:179], v[200:203], v[40:43]
	v_mfma_f32_16x16x32_bf16 v[32:35], v[184:187], v[200:203], v[32:35]
	v_mfma_f32_16x16x32_bf16 v[24:27], v[176:179], v[208:211], v[24:27]
	v_mfma_f32_16x16x32_bf16 v[16:19], v[184:187], v[208:211], v[16:19]
	v_mfma_f32_16x16x32_bf16 v[8:11], v[176:179], v[216:219], v[8:11]
	v_mfma_f32_16x16x32_bf16 v[0:3], v[184:187], v[216:219], v[0:3]
	v_mfma_f32_16x16x32_bf16 v[56:59], v[180:183], v[196:199], v[56:59]
	v_mfma_f32_16x16x32_bf16 v[48:51], v[188:191], v[196:199], v[48:51]
	v_mfma_f32_16x16x32_bf16 v[40:43], v[180:183], v[204:207], v[40:43]
	v_mfma_f32_16x16x32_bf16 v[32:35], v[188:191], v[204:207], v[32:35]
	v_mfma_f32_16x16x32_bf16 v[24:27], v[180:183], v[212:215], v[24:27]
	v_mfma_f32_16x16x32_bf16 v[16:19], v[188:191], v[212:215], v[16:19]
	v_mfma_f32_16x16x32_bf16 v[8:11], v[180:183], v[220:223], v[8:11]
	v_mfma_f32_16x16x32_bf16 v[0:3], v[188:191], v[220:223], v[0:3]
	s_barrier
; #define PG8_STAGE(bufoff, gbase, voff) do { _Pragma("unroll") for (int _i = 0; _i < 2; ++_i) \
;         __builtin_amdgcn_global_load_lds((const unsigned*)((const char*)(gbase) + (voff)[_i]), (PG8_LAS unsigned*)(lds + (bufoff) + ldsw + _i * 8192), 16, 0, 0); } while (0)
; #define PG8_LDA(dst, b, h) do { _Pragma("unroll") for (int m = 0; m < 4; ++m) _Pragma("unroll") for (int k = 0; k < 2; ++k) dst[m][k] = *(const PG8_LAS bf16x8*)(lds + PG8_SA(b, h) + aoff + m * 2048 + k * 1024); } while (0)
; #define PG8_LDB(dst, b, h) do { _Pragma("unroll") for (int n = 0; n < 2; ++n) _Pragma("unroll") for (int k = 0; k < 2; ++k) dst[n][k] = *(const PG8_LAS bf16x8*)(lds + PG8_SB(b, h) + boff + n * 2048 + k * 1024); } while (0)
; #define PG8_MMA(ai, bj, At, Bt) do { __builtin_amdgcn_s_setprio(1); _Pragma("unroll") for (int m = 0; m < 4; ++m) _Pragma("unroll") for (int n = 0; n < 2; ++n) _Pragma("unroll") for (int k = 0; k < 2; ++k) \
;         acc[ai][bj][m][n] = __builtin_amdgcn_mfma_f32_16x16x32_bf16(Bt[n][k], At[m][k], acc[ai][bj][m][n], 0, 0, 0); __builtin_amdgcn_s_setprio(0); } while (0)
; #define PG8_WAIT_V(n) asm volatile("s_waitcnt vmcnt(" #n ")" ::: "memory")
; #define PG8_WAIT_L(n) asm volatile("s_waitcnt lgkmcnt(" #n ")" ::: "memory")
; #define PG8_BAR __builtin_amdgcn_s_barrier()
; #define PG8_SCHED __builtin_amdgcn_sched_barrier(0)
; template <class Epi, class Sched, bool ALIGN_EPI = false, bool SP2 = false>
; __device__ __forceinline__ void gemm_phase(PG8_LAS unsigned char* lds, const Gemm g, const Sched& S, const Epi& E, const int tid_in) {
;     ...
;             PG8_LDB(B0, 1, 0); PG8_LDB(B1, 1, 1); PG8_SCHED; PG8_LDA(At, 1, 0); PG8_STAGE(PG8_SA(0, 1), a2 + hstep, voffA);
;             PG8_WAIT_V(8); PG8_WAIT_L(0); PG8_BAR; PG8_MMA(0, 0, At, B0); PG8_MMA(0, 1, At, B1); PG8_BAR; PG8_SCHED;
;             PG8_LDA(At, 1, 1); PG8_STAGE(PG8_SB(1, 0), b3, voffB); PG8_STAGE(PG8_SB(1, 1), b3 + hstep, voffB); PG8_STAGE(PG8_SA(1, 0), a3, voffA);
;             PG8_WAIT_V(8); PG8_WAIT_L(0); PG8_BAR; PG8_MMA(1, 0, At, B0); PG8_MMA(1, 1, At, B1); PG8_BAR; PG8_SCHED;
	s_add_i32 s81, 0, 0x18000
	v_add_u32_e32 v159, s81, v148
	s_add_i32 s82, 0, 0x1c000
	ds_read_b128 v[160:163], v159
	ds_read_b128 v[164:167], v159 offset:1024
	ds_read_b128 v[168:171], v159 offset:2048
	ds_read_b128 v[172:175], v159 offset:3072
	v_add_u32_e32 v159, s82, v148
	ds_read_b128 v[176:179], v159
	ds_read_b128 v[180:183], v159 offset:1024
	ds_read_b128 v[184:187], v159 offset:2048
	ds_read_b128 v[188:191], v159 offset:3072
	s_add_u32 s54, s54, 0x40000
	s_addc_u32 s55, s55, 0
	s_mov_b32 m0, s40
	v_lshl_add_u64 v[230:231], s[54:55], 0, v[128:129]
	ds_read_b128 v[192:195], v156 offset:32768
	ds_read_b128 v[196:199], v156 offset:33792
	ds_read_b128 v[200:203], v156 offset:34816
	ds_read_b128 v[204:207], v156 offset:35840
	ds_read_b128 v[208:211], v156 offset:36864
	ds_read_b128 v[212:215], v156 offset:37888
	ds_read_b128 v[216:219], v156 offset:38912
	ds_read_b128 v[220:223], v156 offset:39936
	global_load_lds_dwordx4 v[230:231], off
	v_lshl_add_u64 v[230:231], s[54:55], 0, v[132:133]
	s_mov_b32 m0, s41
	s_nop 0
	global_load_lds_dwordx4 v[230:231], off
	s_waitcnt vmcnt(8)
	s_waitcnt lgkmcnt(0)
	s_barrier
	s_waitcnt lgkmcnt(0)
	v_mfma_f32_16x16x32_bf16 v[124:127], v[160:163], v[192:195], v[124:127]
	v_mfma_f32_16x16x32_bf16 v[116:119], v[168:171], v[192:195], v[116:119]
	v_mfma_f32_16x16x32_bf16 v[108:111], v[160:163], v[200:203], v[108:111]
	v_mfma_f32_16x16x32_bf16 v[100:103], v[168:171], v[200:203], v[100:103]
	v_mfma_f32_16x16x32_bf16 v[92:95], v[160:163], v[208:211], v[92:95]
	v_mfma_f32_16x16x32_bf16 v[84:87], v[168:171], v[208:211], v[84:87]
	v_mfma_f32_16x16x32_bf16 v[76:79], v[160:163], v[216:219], v[76:79]
	v_mfma_f32_16x16x32_bf16 v[68:71], v[168:171], v[216:219], v[68:71]
	v_mfma_f32_16x16x32_bf16 v[124:127], v[164:167], v[196:199], v[124:127]
	v_mfma_f32_16x16x32_bf16 v[116:119], v[172:175], v[196:199], v[116:119]
	v_mfma_f32_16x16x32_bf16 v[108:111], v[164:167], v[204:207], v[108:111]
	v_mfma_f32_16x16x32_bf16 v[100:103], v[172:175], v[204:207], v[100:103]
	v_mfma_f32_16x16x32_bf16 v[92:95], v[164:167], v[212:215], v[92:95]
	v_mfma_f32_16x16x32_bf16 v[84:87], v[172:175], v[212:215], v[84:87]
	v_mfma_f32_16x16x32_bf16 v[76:79], v[164:167], v[220:223], v[76:79]
	v_mfma_f32_16x16x32_bf16 v[68:71], v[172:175], v[220:223], v[68:71]
	v_mfma_f32_16x16x32_bf16 v[120:123], v[176:179], v[192:195], v[120:123]
	v_mfma_f32_16x16x32_bf16 v[112:115], v[184:187], v[192:195], v[112:115]
	v_mfma_f32_16x16x32_bf16 v[104:107], v[176:179], v[200:203], v[104:107]
	v_mfma_f32_16x16x32_bf16 v[96:99], v[184:187], v[200:203], v[96:99]
	v_mfma_f32_16x16x32_bf16 v[88:91], v[176:179], v[208:211], v[88:91]
	v_mfma_f32_16x16x32_bf16 v[80:83], v[184:187], v[208:211], v[80:83]
	v_mfma_f32_16x16x32_bf16 v[72:75], v[176:179], v[216:219], v[72:75]
	v_mfma_f32_16x16x32_bf16 v[64:67], v[184:187], v[216:219], v[64:67]
	v_mfma_f32_16x16x32_bf16 v[120:123], v[180:183], v[196:199], v[120:123]
	v_mfma_f32_16x16x32_bf16 v[112:115], v[188:191], v[196:199], v[112:115]
	v_mfma_f32_16x16x32_bf16 v[104:107], v[180:183], v[204:207], v[104:107]
	v_mfma_f32_16x16x32_bf16 v[96:99], v[188:191], v[204:207], v[96:99]
	v_mfma_f32_16x16x32_bf16 v[88:91], v[180:183], v[212:215], v[88:91]
	v_mfma_f32_16x16x32_bf16 v[80:83], v[188:191], v[212:215], v[80:83]
	v_mfma_f32_16x16x32_bf16 v[72:75], v[180:183], v[220:223], v[72:75]
	v_mfma_f32_16x16x32_bf16 v[64:67], v[188:191], v[220:223], v[64:67]
	s_barrier
	s_add_i32 s54, s81, s31
	v_lshl_add_u64 v[144:145], v[144:145], 0, s[26:27]
	s_mov_b32 m0, s54
	ds_read_b128 v[192:195], v156 offset:49152
	ds_read_b128 v[196:199], v156 offset:50176
	ds_read_b128 v[200:203], v156 offset:51200
	ds_read_b128 v[204:207], v156 offset:52224
	ds_read_b128 v[208:211], v156 offset:53248
	ds_read_b128 v[212:215], v156 offset:54272
	ds_read_b128 v[216:219], v156 offset:55296
	ds_read_b128 v[220:223], v156 offset:56320
	global_load_lds_dwordx4 v[144:145], off
	s_add_i32 m0, s54, 0x2000
	s_add_u32 s0, s0, 0x40080
	v_lshl_add_u64 v[144:145], v[224:225], 0, s[26:27]
	s_addc_u32 s1, s1, 0
	s_add_i32 s54, s82, s31
	global_load_lds_dwordx4 v[144:145], off
	v_lshl_add_u64 v[144:145], s[0:1], 0, v[130:131]
	s_mov_b32 m0, s54
	s_nop 0
	global_load_lds_dwordx4 v[144:145], off
	v_lshl_add_u64 v[144:145], s[0:1], 0, v[134:135]
	s_add_i32 m0, s54, 0x2000
	s_nop 0
	global_load_lds_dwordx4 v[144:145], off
	v_lshl_add_u64 v[144:145], v[226:227], 0, s[26:27]
	s_mov_b32 m0, s50
	s_nop 0
	global_load_lds_dwordx4 v[144:145], off
	v_lshl_add_u64 v[144:145], v[228:229], 0, s[26:27]
	s_mov_b32 m0, s51
	s_nop 0
	global_load_lds_dwordx4 v[144:145], off
	s_waitcnt vmcnt(8)
	s_waitcnt lgkmcnt(0)
	s_barrier
	s_waitcnt lgkmcnt(0)
	v_mfma_f32_16x16x32_bf16 v[60:63], v[160:163], v[192:195], v[60:63]
	v_mfma_f32_16x16x32_bf16 v[52:55], v[168:171], v[192:195], v[52:55]
	v_mfma_f32_16x16x32_bf16 v[44:47], v[160:163], v[200:203], v[44:47]
	v_mfma_f32_16x16x32_bf16 v[36:39], v[168:171], v[200:203], v[36:39]
	v_mfma_f32_16x16x32_bf16 v[28:31], v[160:163], v[208:211], v[28:31]
	v_mfma_f32_16x16x32_bf16 v[20:23], v[168:171], v[208:211], v[20:23]
	v_mfma_f32_16x16x32_bf16 v[12:15], v[160:163], v[216:219], v[12:15]
	v_mfma_f32_16x16x32_bf16 v[4:7], v[168:171], v[216:219], v[4:7]
	v_mfma_f32_16x16x32_bf16 v[60:63], v[164:167], v[196:199], v[60:63]
	v_mfma_f32_16x16x32_bf16 v[52:55], v[172:175], v[196:199], v[52:55]
	v_mfma_f32_16x16x32_bf16 v[44:47], v[164:167], v[204:207], v[44:47]
	v_mfma_f32_16x16x32_bf16 v[36:39], v[172:175], v[204:207], v[36:39]
	v_mfma_f32_16x16x32_bf16 v[28:31], v[164:167], v[212:215], v[28:31]
	v_mfma_f32_16x16x32_bf16 v[20:23], v[172:175], v[212:215], v[20:23]
	v_mfma_f32_16x16x32_bf16 v[12:15], v[164:167], v[220:223], v[12:15]
	v_mfma_f32_16x16x32_bf16 v[4:7], v[172:175], v[220:223], v[4:7]
	v_mfma_f32_16x16x32_bf16 v[56:59], v[176:179], v[192:195], v[56:59]
	v_mfma_f32_16x16x32_bf16 v[48:51], v[184:187], v[192:195], v[48:51]
	v_mfma_f32_16x16x32_bf16 v[40:43], v[176:179], v[200:203], v[40:43]
	v_mfma_f32_16x16x32_bf16 v[32:35], v[184:187], v[200:203], v[32:35]
	v_mfma_f32_16x16x32_bf16 v[24:27], v[176:179], v[208:211], v[24:27]
	v_mfma_f32_16x16x32_bf16 v[16:19], v[184:187], v[208:211], v[16:19]
	v_mfma_f32_16x16x32_bf16 v[8:11], v[176:179], v[216:219], v[8:11]
	v_mfma_f32_16x16x32_bf16 v[0:3], v[184:187], v[216:219], v[0:3]
	v_mfma_f32_16x16x32_bf16 v[56:59], v[180:183], v[196:199], v[56:59]
	v_mfma_f32_16x16x32_bf16 v[48:51], v[188:191], v[196:199], v[48:51]
	v_mfma_f32_16x16x32_bf16 v[40:43], v[180:183], v[204:207], v[40:43]
	v_mfma_f32_16x16x32_bf16 v[32:35], v[188:191], v[204:207], v[32:35]
	v_mfma_f32_16x16x32_bf16 v[24:27], v[180:183], v[212:215], v[24:27]
	v_mfma_f32_16x16x32_bf16 v[16:19], v[188:191], v[212:215], v[16:19]
	v_mfma_f32_16x16x32_bf16 v[8:11], v[180:183], v[220:223], v[8:11]
	v_mfma_f32_16x16x32_bf16 v[0:3], v[188:191], v[220:223], v[0:3]
	s_barrier
	s_add_i32 s80, s80, 2
	s_add_u32 s8, s8, 0x100
	s_addc_u32 s9, s9, 0
	s_add_u32 s78, s78, 0x100
	s_addc_u32 s79, s79, 0
	s_cmp_gt_u32 s80, 13
	s_cbranch_scc0 .LBB0_1200

; #define PG8_STAGE(bufoff, gbase, voff) do { _Pragma("unroll") for (int _i = 0; _i < 2; ++_i) \
;         __builtin_amdgcn_global_load_lds((const unsigned*)((const char*)(gbase) + (voff)[_i]), (PG8_LAS unsigned*)(lds + (bufoff) + ldsw + _i * 8192), 16, 0, 0); } while (0)
; #define PG8_LDA(dst, b, h) do { _Pragma("unroll") for (int m = 0; m < 4; ++m) _Pragma("unroll") for (int k = 0; k < 2; ++k) dst[m][k] = *(const PG8_LAS bf16x8*)(lds + PG8_SA(b, h) + aoff + m * 2048 + k * 1024); } while (0)
; #define PG8_LDB(dst, b, h) do { _Pragma("unroll") for (int n = 0; n < 2; ++n) _Pragma("unroll") for (int k = 0; k < 2; ++k) dst[n][k] = *(const PG8_LAS bf16x8*)(lds + PG8_SB(b, h) + boff + n * 2048 + k * 1024); } while (0)
; #define PG8_WAIT_V(n) asm volatile("s_waitcnt vmcnt(" #n ")" ::: "memory")
; #define PG8_WAIT_L(n) asm volatile("s_waitcnt lgkmcnt(" #n ")" ::: "memory")
; #define PG8_BAR __builtin_amdgcn_s_barrier()
; #define PG8_SCHED __builtin_amdgcn_sched_barrier(0)
; template <class Epi, class Sched, bool ALIGN_EPI = false, bool SP2 = false>
; __device__ __forceinline__ void gemm_phase(PG8_LAS unsigned char* lds, const Gemm g, const Sched& S, const Epi& E, const int tid_in) {
;     ...
;         const char* nA = has_next ? (const char*)g.A + (size_t)nxt.pm * tstep : cA; const char* nB = has_next ? (const char*)g.Bt + (size_t)nxt.pn * tstep : cB;
;         for (int t = 0; t < nt; t += 2) {
;             const bool last = (t == nt - 2);
;             const char* a1 = cA + (size_t)(t + 1) * kstep;
;             const char* a2 = last ? nA : cA + (size_t)(t + 2) * kstep; const char* b2 = last ? nB : cB + (size_t)(t + 2) * kstep;
;             const char* a3 = a2 + kstep; const char* b3 = b2 + kstep;
;             if (last && has_next) S.a_ready(nxt);
;             if constexpr (SP2) {
;             PG8_LDB(B0, 0, 0); PG8_LDB(B1, 0, 1); PG8_SCHED; PG8_LDA(At, 0, 0); PG8_STAGE(PG8_SA(1, 1), a1 + hstep, voffA);
;             PG8_WAIT_V(8); PG8_WAIT_L(0); PG8_BAR; PG8_MMA(0, 0, At, B0); PG8_MMA(0, 1, At, B1); PG8_BAR; PG8_SCHED;
;             PG8_LDA(At, 0, 1); PG8_STAGE(PG8_SB(0, 0), b2, voffB); PG8_STAGE(PG8_SB(0, 1), b2 + hstep, voffB); PG8_STAGE(PG8_SA(0, 0), a2, voffA);
;             PG8_WAIT_V(8); PG8_WAIT_L(0); PG8_BAR; PG8_MMA(1, 0, At, B0); PG8_MMA(1, 1, At, B1); PG8_BAR; PG8_SCHED;
.LBB0_1281:
	s_add_u32 s76, s76, 0x100
	v_mov_b32_e32 v0, 0
	s_addc_u32 s77, s77, 0
	s_mov_b32 s81, -2
	ds_read_b128 v[92:95], v207
	ds_read_b128 v[100:103], v207 offset:1024
	ds_read_b128 v[112:115], v207 offset:2048
	ds_read_b128 v[124:127], v207 offset:3072
	ds_read_b128 v[136:139], v208
	ds_read_b128 v[148:151], v208 offset:1024
	ds_read_b128 v[152:155], v208 offset:2048
	ds_read_b128 v[156:159], v208 offset:3072
	s_add_u32 s78, s56, 0x100
	s_addc_u32 s79, s57, 0
	s_cmp_eq_u32 s81, 40
	s_cselect_b32 s75, s9, s79
	s_cselect_b32 s74, s8, s78
	s_cselect_b32 s1, s55, s77
	s_cselect_b32 s0, s54, s76
	v_lshl_add_u64 v[214:215], s[56:57], 0, v[192:193]
	s_add_i32 m0, s31, 0xc000
	ds_read_b128 v[160:163], v209
	ds_read_b128 v[164:167], v209 offset:1024
	ds_read_b128 v[168:171], v209 offset:2048
	ds_read_b128 v[172:175], v209 offset:3072
	ds_read_b128 v[176:179], v209 offset:4096
	ds_read_b128 v[180:183], v209 offset:5120
	ds_read_b128 v[200:203], v209 offset:6144
	ds_read_b128 v[210:213], v209 offset:7168
	global_load_lds_dwordx4 v[214:215], off
	v_lshl_add_u64 v[214:215], s[56:57], 0, v[194:195]
	s_add_i32 m0, s31, 0xe000
	s_nop 0
	global_load_lds_dwordx4 v[214:215], off
	s_waitcnt vmcnt(8)
	s_waitcnt lgkmcnt(0)
	s_barrier
	s_waitcnt lgkmcnt(0)
	v_mfma_f32_16x16x32_bf16 v[144:147], v[92:95], v[160:163], 0
	v_mfma_f32_16x16x32_bf16 v[140:143], v[112:115], v[160:163], 0
	v_mfma_f32_16x16x32_bf16 v[120:123], v[92:95], v[168:171], 0
	v_mfma_f32_16x16x32_bf16 v[116:119], v[112:115], v[168:171], 0
	v_mfma_f32_16x16x32_bf16 v[96:99], v[92:95], v[176:179], 0
	v_mfma_f32_16x16x32_bf16 v[88:91], v[112:115], v[176:179], 0
	v_mfma_f32_16x16x32_bf16 v[76:79], v[92:95], v[200:203], 0
	v_mfma_f32_16x16x32_bf16 v[72:75], v[112:115], v[200:203], 0
	v_mfma_f32_16x16x32_bf16 v[144:147], v[100:103], v[164:167], v[144:147]
	v_mfma_f32_16x16x32_bf16 v[140:143], v[124:127], v[164:167], v[140:143]
	v_mfma_f32_16x16x32_bf16 v[120:123], v[100:103], v[172:175], v[120:123]
	v_mfma_f32_16x16x32_bf16 v[116:119], v[124:127], v[172:175], v[116:119]
	v_mfma_f32_16x16x32_bf16 v[96:99], v[100:103], v[180:183], v[96:99]
	v_mfma_f32_16x16x32_bf16 v[88:91], v[124:127], v[180:183], v[88:91]
	v_mfma_f32_16x16x32_bf16 v[76:79], v[100:103], v[210:213], v[76:79]
	v_mfma_f32_16x16x32_bf16 v[72:75], v[124:127], v[210:213], v[72:75]
	v_mfma_f32_16x16x32_bf16 v[132:135], v[136:139], v[160:163], 0
	v_mfma_f32_16x16x32_bf16 v[128:131], v[152:155], v[160:163], 0
	v_mfma_f32_16x16x32_bf16 v[108:111], v[136:139], v[168:171], 0
	v_mfma_f32_16x16x32_bf16 v[104:107], v[152:155], v[168:171], 0
	v_mfma_f32_16x16x32_bf16 v[84:87], v[136:139], v[176:179], 0
	v_mfma_f32_16x16x32_bf16 v[80:83], v[152:155], v[176:179], 0
	v_mfma_f32_16x16x32_bf16 v[68:71], v[136:139], v[200:203], 0
	v_mfma_f32_16x16x32_bf16 v[64:67], v[152:155], v[200:203], 0
	v_mfma_f32_16x16x32_bf16 v[132:135], v[148:151], v[164:167], v[132:135]
	v_mfma_f32_16x16x32_bf16 v[128:131], v[156:159], v[164:167], v[128:131]
	v_mfma_f32_16x16x32_bf16 v[108:111], v[148:151], v[172:175], v[108:111]
	v_mfma_f32_16x16x32_bf16 v[104:107], v[156:159], v[172:175], v[104:107]
	v_mfma_f32_16x16x32_bf16 v[84:87], v[148:151], v[180:183], v[84:87]
	v_mfma_f32_16x16x32_bf16 v[80:83], v[156:159], v[180:183], v[80:83]
	v_mfma_f32_16x16x32_bf16 v[68:71], v[148:151], v[210:213], v[68:71]
	v_mfma_f32_16x16x32_bf16 v[64:67], v[156:159], v[210:213], v[64:67]
	s_barrier
	s_add_i32 s56, s48, s30
	v_lshl_add_u64 v[214:215], s[0:1], 0, v[186:187]
	s_mov_b32 m0, s56
	ds_read_b128 v[160:163], v209 offset:16384
	ds_read_b128 v[164:167], v209 offset:17408
	ds_read_b128 v[168:171], v209 offset:18432
	ds_read_b128 v[172:175], v209 offset:19456
	ds_read_b128 v[176:179], v209 offset:20480
	ds_read_b128 v[180:183], v209 offset:21504
	ds_read_b128 v[200:203], v209 offset:22528
	ds_read_b128 v[210:213], v209 offset:23552
	global_load_lds_dwordx4 v[214:215], off
	s_add_i32 m0, s56, 0x2000
	s_add_u32 s56, s0, 0xb0000
	v_lshl_add_u64 v[216:217], s[0:1], 0, v[190:191]
	s_addc_u32 s57, s1, 0
	s_add_i32 s82, s49, s30
	global_load_lds_dwordx4 v[216:217], off
	v_lshl_add_u64 v[218:219], s[56:57], 0, v[186:187]
	s_mov_b32 m0, s82
	v_lshl_add_u64 v[220:221], s[74:75], 0, v[188:189]
	global_load_lds_dwordx4 v[218:219], off
	v_lshl_add_u64 v[218:219], s[56:57], 0, v[190:191]
	s_add_i32 m0, s82, 0x2000
	s_nop 0
	global_load_lds_dwordx4 v[218:219], off
	v_lshl_add_u64 v[218:219], s[74:75], 0, v[184:185]
	s_mov_b32 m0, s31
	s_nop 0
	global_load_lds_dwordx4 v[218:219], off
	s_mov_b32 m0, s34
	s_nop 0
	global_load_lds_dwordx4 v[220:221], off
	s_waitcnt vmcnt(8)
	s_waitcnt lgkmcnt(0)
	s_barrier
; #define PG8_STAGE(bufoff, gbase, voff) do { _Pragma("unroll") for (int _i = 0; _i < 2; ++_i) \
;         __builtin_amdgcn_global_load_lds((const unsigned*)((const char*)(gbase) + (voff)[_i]), (PG8_LAS unsigned*)(lds + (bufoff) + ldsw + _i * 8192), 16, 0, 0); } while (0)
; #define PG8_LDA(dst, b, h) do { _Pragma("unroll") for (int m = 0; m < 4; ++m) _Pragma("unroll") for (int k = 0; k < 2; ++k) dst[m][k] = *(const PG8_LAS bf16x8*)(lds + PG8_SA(b, h) + aoff + m * 2048 + k * 1024); } while (0)
; #define PG8_LDB(dst, b, h) do { _Pragma("unroll") for (int n = 0; n < 2; ++n) _Pragma("unroll") for (int k = 0; k < 2; ++k) dst[n][k] = *(const PG8_LAS bf16x8*)(lds + PG8_SB(b, h) + boff + n * 2048 + k * 1024); } while (0)
; #define PG8_MMA(ai, bj, At, Bt) do { __builtin_amdgcn_s_setprio(1); _Pragma("unroll") for (int m = 0; m < 4; ++m) _Pragma("unroll") for (int n = 0; n < 2; ++n) _Pragma("unroll") for (int k = 0; k < 2; ++k) \
;         acc[ai][bj][m][n] = __builtin_amdgcn_mfma_f32_16x16x32_bf16(Bt[n][k], At[m][k], acc[ai][bj][m][n], 0, 0, 0); __builtin_amdgcn_s_setprio(0); } while (0)
; #define PG8_WAIT_V(n) asm volatile("s_waitcnt vmcnt(" #n ")" ::: "memory")
; #define PG8_WAIT_L(n) asm volatile("s_waitcnt lgkmcnt(" #n ")" ::: "memory")
; #define PG8_BAR __builtin_amdgcn_s_barrier()
; #define PG8_SCHED __builtin_amdgcn_sched_barrier(0)
; template <class Epi, class Sched, bool ALIGN_EPI = false, bool SP2 = false>
; __device__ __forceinline__ void gemm_phase(PG8_LAS unsigned char* lds, const Gemm g, const Sched& S, const Epi& E, const int tid_in) {
;     ...
;             PG8_WAIT_V(8); PG8_WAIT_L(0); PG8_BAR; PG8_MMA(0, 0, At, B0); PG8_MMA(0, 1, At, B1); PG8_BAR; PG8_SCHED;
;             PG8_LDA(At, 0, 1); PG8_STAGE(PG8_SB(0, 0), b2, voffB); PG8_STAGE(PG8_SB(0, 1), b2 + hstep, voffB); PG8_STAGE(PG8_SA(0, 0), a2, voffA);
;             PG8_WAIT_V(8); PG8_WAIT_L(0); PG8_BAR; PG8_MMA(1, 0, At, B0); PG8_MMA(1, 1, At, B1); PG8_BAR; PG8_SCHED;
;             PG8_LDB(B0, 1, 0); PG8_LDB(B1, 1, 1); PG8_SCHED; PG8_LDA(At, 1, 0); PG8_STAGE(PG8_SA(0, 1), a2 + hstep, voffA);
;             PG8_WAIT_V(8); PG8_WAIT_L(0); PG8_BAR; PG8_MMA(0, 0, At, B0); PG8_MMA(0, 1, At, B1); PG8_BAR; PG8_SCHED;
	s_waitcnt lgkmcnt(0)
	v_mfma_f32_16x16x32_bf16 v[60:63], v[92:95], v[160:163], 0
	v_mfma_f32_16x16x32_bf16 v[56:59], v[112:115], v[160:163], 0
	v_mfma_f32_16x16x32_bf16 v[44:47], v[92:95], v[168:171], 0
	v_mfma_f32_16x16x32_bf16 v[40:43], v[112:115], v[168:171], 0
	v_mfma_f32_16x16x32_bf16 v[28:31], v[92:95], v[176:179], 0
	v_mfma_f32_16x16x32_bf16 v[24:27], v[112:115], v[176:179], 0
	v_mfma_f32_16x16x32_bf16 v[12:15], v[92:95], v[200:203], 0
	v_mfma_f32_16x16x32_bf16 v[8:11], v[112:115], v[200:203], 0
	v_mfma_f32_16x16x32_bf16 v[60:63], v[100:103], v[164:167], v[60:63]
	v_mfma_f32_16x16x32_bf16 v[56:59], v[124:127], v[164:167], v[56:59]
	v_mfma_f32_16x16x32_bf16 v[44:47], v[100:103], v[172:175], v[44:47]
	v_mfma_f32_16x16x32_bf16 v[40:43], v[124:127], v[172:175], v[40:43]
	v_mfma_f32_16x16x32_bf16 v[28:31], v[100:103], v[180:183], v[28:31]
	v_mfma_f32_16x16x32_bf16 v[24:27], v[124:127], v[180:183], v[24:27]
	v_mfma_f32_16x16x32_bf16 v[12:15], v[100:103], v[210:213], v[12:15]
	v_mfma_f32_16x16x32_bf16 v[8:11], v[124:127], v[210:213], v[8:11]
	v_mfma_f32_16x16x32_bf16 v[52:55], v[136:139], v[160:163], 0
	v_mfma_f32_16x16x32_bf16 v[48:51], v[152:155], v[160:163], 0
	v_mfma_f32_16x16x32_bf16 v[36:39], v[136:139], v[168:171], 0
	v_mfma_f32_16x16x32_bf16 v[32:35], v[152:155], v[168:171], 0
	v_mfma_f32_16x16x32_bf16 v[20:23], v[136:139], v[176:179], 0
	v_mfma_f32_16x16x32_bf16 v[16:19], v[152:155], v[176:179], 0
	v_mfma_f32_16x16x32_bf16 v[4:7], v[136:139], v[200:203], 0
	v_mfma_f32_16x16x32_bf16 v[0:3], v[152:155], v[200:203], 0
	v_mfma_f32_16x16x32_bf16 v[52:55], v[148:151], v[164:167], v[52:55]
	v_mfma_f32_16x16x32_bf16 v[48:51], v[156:159], v[164:167], v[48:51]
	v_mfma_f32_16x16x32_bf16 v[36:39], v[148:151], v[172:175], v[36:39]
	v_mfma_f32_16x16x32_bf16 v[32:35], v[156:159], v[172:175], v[32:35]
	v_mfma_f32_16x16x32_bf16 v[20:23], v[148:151], v[180:183], v[20:23]
	v_mfma_f32_16x16x32_bf16 v[16:19], v[156:159], v[180:183], v[16:19]
	v_mfma_f32_16x16x32_bf16 v[4:7], v[148:151], v[210:213], v[4:7]
	v_mfma_f32_16x16x32_bf16 v[0:3], v[156:159], v[210:213], v[0:3]
	s_barrier
	s_add_i32 s82, 0, 0x18000
	s_add_i32 s83, 0, 0x1c000
	v_add_u32_e32 v124, s82, v205
	v_add_u32_e32 v156, s83, v205
	ds_read_b128 v[92:95], v124
	ds_read_b128 v[100:103], v124 offset:1024
	ds_read_b128 v[112:115], v124 offset:2048
	ds_read_b128 v[124:127], v124 offset:3072
	ds_read_b128 v[136:139], v156
	ds_read_b128 v[148:151], v156 offset:1024
	ds_read_b128 v[152:155], v156 offset:2048
	ds_read_b128 v[156:159], v156 offset:3072
	s_add_u32 s56, s74, 0xb0000
	s_addc_u32 s57, s75, 0
	s_mov_b32 m0, s35
	v_lshl_add_u64 v[222:223], s[56:57], 0, v[184:185]
	ds_read_b128 v[160:163], v209 offset:32768
	ds_read_b128 v[164:167], v209 offset:33792
	ds_read_b128 v[168:171], v209 offset:34816
	ds_read_b128 v[172:175], v209 offset:35840
	ds_read_b128 v[176:179], v209 offset:36864
	ds_read_b128 v[180:183], v209 offset:37888
	ds_read_b128 v[200:203], v209 offset:38912
	ds_read_b128 v[210:213], v209 offset:39936
	global_load_lds_dwordx4 v[222:223], off
	v_lshl_add_u64 v[222:223], s[56:57], 0, v[188:189]
	s_mov_b32 m0, s36
	s_nop 0
	global_load_lds_dwordx4 v[222:223], off
	s_waitcnt vmcnt(8)
	s_waitcnt lgkmcnt(0)
	s_barrier
	s_waitcnt lgkmcnt(0)
	v_mfma_f32_16x16x32_bf16 v[144:147], v[92:95], v[160:163], v[144:147]
	v_mfma_f32_16x16x32_bf16 v[140:143], v[112:115], v[160:163], v[140:143]
	v_mfma_f32_16x16x32_bf16 v[120:123], v[92:95], v[168:171], v[120:123]
	v_mfma_f32_16x16x32_bf16 v[116:119], v[112:115], v[168:171], v[116:119]
	v_mfma_f32_16x16x32_bf16 v[96:99], v[92:95], v[176:179], v[96:99]
	v_mfma_f32_16x16x32_bf16 v[88:91], v[112:115], v[176:179], v[88:91]
	v_mfma_f32_16x16x32_bf16 v[76:79], v[92:95], v[200:203], v[76:79]
	v_mfma_f32_16x16x32_bf16 v[72:75], v[112:115], v[200:203], v[72:75]
	v_mfma_f32_16x16x32_bf16 v[144:147], v[100:103], v[164:167], v[144:147]
	v_mfma_f32_16x16x32_bf16 v[140:143], v[124:127], v[164:167], v[140:143]
	v_mfma_f32_16x16x32_bf16 v[120:123], v[100:103], v[172:175], v[120:123]
	v_mfma_f32_16x16x32_bf16 v[116:119], v[124:127], v[172:175], v[116:119]
	v_mfma_f32_16x16x32_bf16 v[96:99], v[100:103], v[180:183], v[96:99]
	v_mfma_f32_16x16x32_bf16 v[88:91], v[124:127], v[180:183], v[88:91]
	v_mfma_f32_16x16x32_bf16 v[76:79], v[100:103], v[210:213], v[76:79]
	v_mfma_f32_16x16x32_bf16 v[72:75], v[124:127], v[210:213], v[72:75]
	v_mfma_f32_16x16x32_bf16 v[132:135], v[136:139], v[160:163], v[132:135]
	v_mfma_f32_16x16x32_bf16 v[128:131], v[152:155], v[160:163], v[128:131]
	v_mfma_f32_16x16x32_bf16 v[108:111], v[136:139], v[168:171], v[108:111]
	v_mfma_f32_16x16x32_bf16 v[104:107], v[152:155], v[168:171], v[104:107]
	v_mfma_f32_16x16x32_bf16 v[84:87], v[136:139], v[176:179], v[84:87]
	v_mfma_f32_16x16x32_bf16 v[80:83], v[152:155], v[176:179], v[80:83]
	v_mfma_f32_16x16x32_bf16 v[68:71], v[136:139], v[200:203], v[68:71]
	v_mfma_f32_16x16x32_bf16 v[64:67], v[152:155], v[200:203], v[64:67]
	v_mfma_f32_16x16x32_bf16 v[132:135], v[148:151], v[164:167], v[132:135]
	v_mfma_f32_16x16x32_bf16 v[128:131], v[156:159], v[164:167], v[128:131]
	v_mfma_f32_16x16x32_bf16 v[108:111], v[148:151], v[172:175], v[108:111]
	v_mfma_f32_16x16x32_bf16 v[104:107], v[156:159], v[172:175], v[104:107]
	v_mfma_f32_16x16x32_bf16 v[84:87], v[148:151], v[180:183], v[84:87]
	v_mfma_f32_16x16x32_bf16 v[80:83], v[156:159], v[180:183], v[80:83]
	v_mfma_f32_16x16x32_bf16 v[68:71], v[148:151], v[210:213], v[68:71]
	v_mfma_f32_16x16x32_bf16 v[64:67], v[156:159], v[210:213], v[64:67]
	s_barrier
; #define PG8_STAGE(bufoff, gbase, voff) do { _Pragma("unroll") for (int _i = 0; _i < 2; ++_i) \
;         __builtin_amdgcn_global_load_lds((const unsigned*)((const char*)(gbase) + (voff)[_i]), (PG8_LAS unsigned*)(lds + (bufoff) + ldsw + _i * 8192), 16, 0, 0); } while (0)
; #define PG8_LDA(dst, b, h) do { _Pragma("unroll") for (int m = 0; m < 4; ++m) _Pragma("unroll") for (int k = 0; k < 2; ++k) dst[m][k] = *(const PG8_LAS bf16x8*)(lds + PG8_SA(b, h) + aoff + m * 2048 + k * 1024); } while (0)
; #define PG8_LDB(dst, b, h) do { _Pragma("unroll") for (int n = 0; n < 2; ++n) _Pragma("unroll") for (int k = 0; k < 2; ++k) dst[n][k] = *(const PG8_LAS bf16x8*)(lds + PG8_SB(b, h) + boff + n * 2048 + k * 1024); } while (0)
; #define PG8_WAIT_V(n) asm volatile("s_waitcnt vmcnt(" #n ")" ::: "memory")
; template <class Epi, class Sched, bool ALIGN_EPI = false, bool SP2 = false>
; __device__ __forceinline__ void gemm_phase(PG8_LAS unsigned char* lds, const Gemm g, const Sched& S, const Epi& E, const int tid_in) {
;     ...
;         for (int t = 0; t < nt; t += 2) {
;             const bool last = (t == nt - 2);
;             const char* a1 = cA + (size_t)(t + 1) * kstep;
;             const char* a2 = last ? nA : cA + (size_t)(t + 2) * kstep; const char* b2 = last ? nB : cB + (size_t)(t + 2) * kstep;
;             const char* a3 = a2 + kstep; const char* b3 = b2 + kstep;
;             if (last && has_next) S.a_ready(nxt);
;             if constexpr (SP2) {
;             PG8_LDB(B0, 0, 0); PG8_LDB(B1, 0, 1); PG8_SCHED; PG8_LDA(At, 0, 0); PG8_STAGE(PG8_SA(1, 1), a1 + hstep, voffA);
;             PG8_WAIT_V(8); PG8_WAIT_L(0); PG8_BAR; PG8_MMA(0, 0, At, B0); PG8_MMA(0, 1, At, B1); PG8_BAR; PG8_SCHED;
;             PG8_LDA(At, 0, 1); PG8_STAGE(PG8_SB(0, 0), b2, voffB); PG8_STAGE(PG8_SB(0, 1), b2 + hstep, voffB); PG8_STAGE(PG8_SA(0, 0), a2, voffA);
;             PG8_WAIT_V(8); PG8_WAIT_L(0); PG8_BAR; PG8_MMA(1, 0, At, B0); PG8_MMA(1, 1, At, B1); PG8_BAR; PG8_SCHED;
;     ...
;             PG8_WAIT_V(8); PG8_WAIT_L(0); PG8_BAR; PG8_MMA(0, 0, At, B0); PG8_MMA(0, 1, At, B1); PG8_BAR; PG8_SCHED;
;             PG8_LDA(At, 1, 1); PG8_STAGE(PG8_SB(1, 0), b3, voffB); PG8_STAGE(PG8_SB(1, 1), b3 + hstep, voffB); PG8_STAGE(PG8_SA(1, 0), a3, voffA);
;             PG8_WAIT_V(8); PG8_WAIT_L(0); PG8_BAR; PG8_MMA(1, 0, At, B0); PG8_MMA(1, 1, At, B1); PG8_BAR; PG8_SCHED;
	s_add_i32 s56, s82, s30
	v_lshl_add_u64 v[214:215], v[214:215], 0, s[46:47]
	s_mov_b32 m0, s56
	ds_read_b128 v[160:163], v209 offset:49152
	ds_read_b128 v[164:167], v209 offset:50176
	ds_read_b128 v[168:171], v209 offset:51200
	ds_read_b128 v[172:175], v209 offset:52224
	ds_read_b128 v[176:179], v209 offset:53248
	ds_read_b128 v[180:183], v209 offset:54272
	ds_read_b128 v[200:203], v209 offset:55296
	ds_read_b128 v[210:213], v209 offset:56320
	global_load_lds_dwordx4 v[214:215], off
	s_add_i32 m0, s56, 0x2000
	s_add_u32 s0, s0, 0xb0080
	v_lshl_add_u64 v[214:215], v[216:217], 0, s[46:47]
	s_addc_u32 s1, s1, 0
	s_add_i32 s56, s83, s30
	global_load_lds_dwordx4 v[214:215], off
	v_lshl_add_u64 v[214:215], s[0:1], 0, v[186:187]
	s_mov_b32 m0, s56
	s_nop 0
	global_load_lds_dwordx4 v[214:215], off
	v_lshl_add_u64 v[214:215], s[0:1], 0, v[190:191]
	s_add_i32 m0, s56, 0x2000
	s_nop 0
	global_load_lds_dwordx4 v[214:215], off
	v_lshl_add_u64 v[214:215], v[218:219], 0, s[46:47]
	s_mov_b32 m0, s38
	s_nop 0
	global_load_lds_dwordx4 v[214:215], off
	v_lshl_add_u64 v[214:215], v[220:221], 0, s[46:47]
	s_mov_b32 m0, s39
	s_nop 0
	global_load_lds_dwordx4 v[214:215], off
	s_waitcnt vmcnt(8)
	s_waitcnt lgkmcnt(0)
	s_barrier
	s_waitcnt lgkmcnt(0)
	v_mfma_f32_16x16x32_bf16 v[60:63], v[92:95], v[160:163], v[60:63]
	v_mfma_f32_16x16x32_bf16 v[56:59], v[112:115], v[160:163], v[56:59]
	v_mfma_f32_16x16x32_bf16 v[44:47], v[92:95], v[168:171], v[44:47]
	v_mfma_f32_16x16x32_bf16 v[40:43], v[112:115], v[168:171], v[40:43]
	v_mfma_f32_16x16x32_bf16 v[28:31], v[92:95], v[176:179], v[28:31]
	v_mfma_f32_16x16x32_bf16 v[24:27], v[112:115], v[176:179], v[24:27]
	v_mfma_f32_16x16x32_bf16 v[12:15], v[92:95], v[200:203], v[12:15]
	v_mfma_f32_16x16x32_bf16 v[8:11], v[112:115], v[200:203], v[8:11]
	v_mfma_f32_16x16x32_bf16 v[60:63], v[100:103], v[164:167], v[60:63]
	v_mfma_f32_16x16x32_bf16 v[56:59], v[124:127], v[164:167], v[56:59]
	v_mfma_f32_16x16x32_bf16 v[44:47], v[100:103], v[172:175], v[44:47]
	v_mfma_f32_16x16x32_bf16 v[40:43], v[124:127], v[172:175], v[40:43]
	v_mfma_f32_16x16x32_bf16 v[28:31], v[100:103], v[180:183], v[28:31]
	v_mfma_f32_16x16x32_bf16 v[24:27], v[124:127], v[180:183], v[24:27]
	v_mfma_f32_16x16x32_bf16 v[12:15], v[100:103], v[210:213], v[12:15]
	v_mfma_f32_16x16x32_bf16 v[8:11], v[124:127], v[210:213], v[8:11]
	v_mfma_f32_16x16x32_bf16 v[52:55], v[136:139], v[160:163], v[52:55]
	v_mfma_f32_16x16x32_bf16 v[48:51], v[152:155], v[160:163], v[48:51]
	v_mfma_f32_16x16x32_bf16 v[36:39], v[136:139], v[168:171], v[36:39]
	v_mfma_f32_16x16x32_bf16 v[32:35], v[152:155], v[168:171], v[32:35]
	v_mfma_f32_16x16x32_bf16 v[20:23], v[136:139], v[176:179], v[20:23]
	v_mfma_f32_16x16x32_bf16 v[16:19], v[152:155], v[176:179], v[16:19]
	v_mfma_f32_16x16x32_bf16 v[4:7], v[136:139], v[200:203], v[4:7]
	v_mfma_f32_16x16x32_bf16 v[0:3], v[152:155], v[200:203], v[0:3]
	v_mfma_f32_16x16x32_bf16 v[52:55], v[148:151], v[164:167], v[52:55]
	v_mfma_f32_16x16x32_bf16 v[48:51], v[156:159], v[164:167], v[48:51]
	v_mfma_f32_16x16x32_bf16 v[36:39], v[148:151], v[172:175], v[36:39]
	v_mfma_f32_16x16x32_bf16 v[32:35], v[156:159], v[172:175], v[32:35]
	v_mfma_f32_16x16x32_bf16 v[20:23], v[148:151], v[180:183], v[20:23]
	v_mfma_f32_16x16x32_bf16 v[16:19], v[156:159], v[180:183], v[16:19]
	v_mfma_f32_16x16x32_bf16 v[4:7], v[148:151], v[210:213], v[4:7]
	v_mfma_f32_16x16x32_bf16 v[0:3], v[156:159], v[210:213], v[0:3]
	s_barrier
	s_add_i32 s81, s81, 2
	s_add_u32 s76, s76, 0x100
	s_addc_u32 s77, s77, 0
	s_cmp_gt_u32 s81, 41
	s_mov_b64 s[56:57], s[78:79]
	s_cbranch_scc0 .LBB0_1282
	s_branch .Lmy_kdone_4
.LBB0_1282:
	ds_read_b128 v[92:95], v207
	ds_read_b128 v[100:103], v207 offset:1024
	ds_read_b128 v[112:115], v207 offset:2048
	ds_read_b128 v[124:127], v207 offset:3072
	ds_read_b128 v[136:139], v208
	ds_read_b128 v[148:151], v208 offset:1024
	ds_read_b128 v[152:155], v208 offset:2048
	ds_read_b128 v[156:159], v208 offset:3072
	s_add_u32 s78, s56, 0x100
	s_addc_u32 s79, s57, 0
	s_cmp_eq_u32 s81, 40
	s_cselect_b32 s75, s9, s79
	s_cselect_b32 s74, s8, s78
	s_cselect_b32 s1, s55, s77
	s_cselect_b32 s0, s54, s76
	v_lshl_add_u64 v[214:215], s[56:57], 0, v[192:193]
	s_add_i32 m0, s31, 0xc000
	ds_read_b128 v[160:163], v209
	ds_read_b128 v[164:167], v209 offset:1024
	ds_read_b128 v[168:171], v209 offset:2048
	ds_read_b128 v[172:175], v209 offset:3072
	ds_read_b128 v[176:179], v209 offset:4096
	ds_read_b128 v[180:183], v209 offset:5120
	ds_read_b128 v[200:203], v209 offset:6144
	ds_read_b128 v[210:213], v209 offset:7168
	global_load_lds_dwordx4 v[214:215], off
	v_lshl_add_u64 v[214:215], s[56:57], 0, v[194:195]
	s_add_i32 m0, s31, 0xe000
	s_nop 0
	global_load_lds_dwordx4 v[214:215], off
	s_waitcnt vmcnt(8)
	s_waitcnt lgkmcnt(0)
	s_barrier
; #define PG8_STAGE(bufoff, gbase, voff) do { _Pragma("unroll") for (int _i = 0; _i < 2; ++_i) \
;         __builtin_amdgcn_global_load_lds((const unsigned*)((const char*)(gbase) + (voff)[_i]), (PG8_LAS unsigned*)(lds + (bufoff) + ldsw + _i * 8192), 16, 0, 0); } while (0)
; #define PG8_LDA(dst, b, h) do { _Pragma("unroll") for (int m = 0; m < 4; ++m) _Pragma("unroll") for (int k = 0; k < 2; ++k) dst[m][k] = *(const PG8_LAS bf16x8*)(lds + PG8_SA(b, h) + aoff + m * 2048 + k * 1024); } while (0)
; #define PG8_LDB(dst, b, h) do { _Pragma("unroll") for (int n = 0; n < 2; ++n) _Pragma("unroll") for (int k = 0; k < 2; ++k) dst[n][k] = *(const PG8_LAS bf16x8*)(lds + PG8_SB(b, h) + boff + n * 2048 + k * 1024); } while (0)
; #define PG8_MMA(ai, bj, At, Bt) do { __builtin_amdgcn_s_setprio(1); _Pragma("unroll") for (int m = 0; m < 4; ++m) _Pragma("unroll") for (int n = 0; n < 2; ++n) _Pragma("unroll") for (int k = 0; k < 2; ++k) \
;         acc[ai][bj][m][n] = __builtin_amdgcn_mfma_f32_16x16x32_bf16(Bt[n][k], At[m][k], acc[ai][bj][m][n], 0, 0, 0); __builtin_amdgcn_s_setprio(0); } while (0)
; #define PG8_WAIT_V(n) asm volatile("s_waitcnt vmcnt(" #n ")" ::: "memory")
; #define PG8_WAIT_L(n) asm volatile("s_waitcnt lgkmcnt(" #n ")" ::: "memory")
; #define PG8_BAR __builtin_amdgcn_s_barrier()
; #define PG8_SCHED __builtin_amdgcn_sched_barrier(0)
; template <class Epi, class Sched, bool ALIGN_EPI = false, bool SP2 = false>
; __device__ __forceinline__ void gemm_phase(PG8_LAS unsigned char* lds, const Gemm g, const Sched& S, const Epi& E, const int tid_in) {
;     ...
;             PG8_LDB(B0, 0, 0); PG8_LDB(B1, 0, 1); PG8_SCHED; PG8_LDA(At, 0, 0); PG8_STAGE(PG8_SA(1, 1), a1 + hstep, voffA);
;             PG8_WAIT_V(8); PG8_WAIT_L(0); PG8_BAR; PG8_MMA(0, 0, At, B0); PG8_MMA(0, 1, At, B1); PG8_BAR; PG8_SCHED;
;             PG8_LDA(At, 0, 1); PG8_STAGE(PG8_SB(0, 0), b2, voffB); PG8_STAGE(PG8_SB(0, 1), b2 + hstep, voffB); PG8_STAGE(PG8_SA(0, 0), a2, voffA);
;             PG8_WAIT_V(8); PG8_WAIT_L(0); PG8_BAR; PG8_MMA(1, 0, At, B0); PG8_MMA(1, 1, At, B1); PG8_BAR; PG8_SCHED;
	s_waitcnt lgkmcnt(0)
	v_mfma_f32_16x16x32_bf16 v[144:147], v[92:95], v[160:163], v[144:147]
	v_mfma_f32_16x16x32_bf16 v[140:143], v[112:115], v[160:163], v[140:143]
	v_mfma_f32_16x16x32_bf16 v[120:123], v[92:95], v[168:171], v[120:123]
	v_mfma_f32_16x16x32_bf16 v[116:119], v[112:115], v[168:171], v[116:119]
	v_mfma_f32_16x16x32_bf16 v[96:99], v[92:95], v[176:179], v[96:99]
	v_mfma_f32_16x16x32_bf16 v[88:91], v[112:115], v[176:179], v[88:91]
	v_mfma_f32_16x16x32_bf16 v[76:79], v[92:95], v[200:203], v[76:79]
	v_mfma_f32_16x16x32_bf16 v[72:75], v[112:115], v[200:203], v[72:75]
	v_mfma_f32_16x16x32_bf16 v[144:147], v[100:103], v[164:167], v[144:147]
	v_mfma_f32_16x16x32_bf16 v[140:143], v[124:127], v[164:167], v[140:143]
	v_mfma_f32_16x16x32_bf16 v[120:123], v[100:103], v[172:175], v[120:123]
	v_mfma_f32_16x16x32_bf16 v[116:119], v[124:127], v[172:175], v[116:119]
	v_mfma_f32_16x16x32_bf16 v[96:99], v[100:103], v[180:183], v[96:99]
	v_mfma_f32_16x16x32_bf16 v[88:91], v[124:127], v[180:183], v[88:91]
	v_mfma_f32_16x16x32_bf16 v[76:79], v[100:103], v[210:213], v[76:79]
	v_mfma_f32_16x16x32_bf16 v[72:75], v[124:127], v[210:213], v[72:75]
	v_mfma_f32_16x16x32_bf16 v[132:135], v[136:139], v[160:163], v[132:135]
	v_mfma_f32_16x16x32_bf16 v[128:131], v[152:155], v[160:163], v[128:131]
	v_mfma_f32_16x16x32_bf16 v[108:111], v[136:139], v[168:171], v[108:111]
	v_mfma_f32_16x16x32_bf16 v[104:107], v[152:155], v[168:171], v[104:107]
	v_mfma_f32_16x16x32_bf16 v[84:87], v[136:139], v[176:179], v[84:87]
	v_mfma_f32_16x16x32_bf16 v[80:83], v[152:155], v[176:179], v[80:83]
	v_mfma_f32_16x16x32_bf16 v[68:71], v[136:139], v[200:203], v[68:71]
	v_mfma_f32_16x16x32_bf16 v[64:67], v[152:155], v[200:203], v[64:67]
	v_mfma_f32_16x16x32_bf16 v[132:135], v[148:151], v[164:167], v[132:135]
	v_mfma_f32_16x16x32_bf16 v[128:131], v[156:159], v[164:167], v[128:131]
	v_mfma_f32_16x16x32_bf16 v[108:111], v[148:151], v[172:175], v[108:111]
	v_mfma_f32_16x16x32_bf16 v[104:107], v[156:159], v[172:175], v[104:107]
	v_mfma_f32_16x16x32_bf16 v[84:87], v[148:151], v[180:183], v[84:87]
	v_mfma_f32_16x16x32_bf16 v[80:83], v[156:159], v[180:183], v[80:83]
	v_mfma_f32_16x16x32_bf16 v[68:71], v[148:151], v[210:213], v[68:71]
	v_mfma_f32_16x16x32_bf16 v[64:67], v[156:159], v[210:213], v[64:67]
	s_barrier
	s_add_i32 s56, s48, s30
	v_lshl_add_u64 v[214:215], s[0:1], 0, v[186:187]
	s_mov_b32 m0, s56
	ds_read_b128 v[160:163], v209 offset:16384
	ds_read_b128 v[164:167], v209 offset:17408
	ds_read_b128 v[168:171], v209 offset:18432
	ds_read_b128 v[172:175], v209 offset:19456
	ds_read_b128 v[176:179], v209 offset:20480
	ds_read_b128 v[180:183], v209 offset:21504
	ds_read_b128 v[200:203], v209 offset:22528
	ds_read_b128 v[210:213], v209 offset:23552
	global_load_lds_dwordx4 v[214:215], off
	s_add_i32 m0, s56, 0x2000
	s_add_u32 s56, s0, 0xb0000
	v_lshl_add_u64 v[216:217], s[0:1], 0, v[190:191]
	s_addc_u32 s57, s1, 0
	s_add_i32 s82, s49, s30
	global_load_lds_dwordx4 v[216:217], off
	v_lshl_add_u64 v[218:219], s[56:57], 0, v[186:187]
	s_mov_b32 m0, s82
	v_lshl_add_u64 v[220:221], s[74:75], 0, v[188:189]
	global_load_lds_dwordx4 v[218:219], off
	v_lshl_add_u64 v[218:219], s[56:57], 0, v[190:191]
	s_add_i32 m0, s82, 0x2000
	s_nop 0
	global_load_lds_dwordx4 v[218:219], off
	v_lshl_add_u64 v[218:219], s[74:75], 0, v[184:185]
	s_mov_b32 m0, s31
	s_nop 0
	global_load_lds_dwordx4 v[218:219], off
	s_mov_b32 m0, s34
	s_nop 0
	global_load_lds_dwordx4 v[220:221], off
	s_waitcnt vmcnt(8)
	s_waitcnt lgkmcnt(0)
	s_barrier
	s_waitcnt lgkmcnt(0)
	v_mfma_f32_16x16x32_bf16 v[60:63], v[92:95], v[160:163], v[60:63]
	v_mfma_f32_16x16x32_bf16 v[56:59], v[112:115], v[160:163], v[56:59]
	v_mfma_f32_16x16x32_bf16 v[44:47], v[92:95], v[168:171], v[44:47]
	v_mfma_f32_16x16x32_bf16 v[40:43], v[112:115], v[168:171], v[40:43]
	v_mfma_f32_16x16x32_bf16 v[28:31], v[92:95], v[176:179], v[28:31]
	v_mfma_f32_16x16x32_bf16 v[24:27], v[112:115], v[176:179], v[24:27]
	v_mfma_f32_16x16x32_bf16 v[12:15], v[92:95], v[200:203], v[12:15]
	v_mfma_f32_16x16x32_bf16 v[8:11], v[112:115], v[200:203], v[8:11]
	v_mfma_f32_16x16x32_bf16 v[60:63], v[100:103], v[164:167], v[60:63]
	v_mfma_f32_16x16x32_bf16 v[56:59], v[124:127], v[164:167], v[56:59]
	v_mfma_f32_16x16x32_bf16 v[44:47], v[100:103], v[172:175], v[44:47]
	v_mfma_f32_16x16x32_bf16 v[40:43], v[124:127], v[172:175], v[40:43]
	v_mfma_f32_16x16x32_bf16 v[28:31], v[100:103], v[180:183], v[28:31]
	v_mfma_f32_16x16x32_bf16 v[24:27], v[124:127], v[180:183], v[24:27]
	v_mfma_f32_16x16x32_bf16 v[12:15], v[100:103], v[210:213], v[12:15]
	v_mfma_f32_16x16x32_bf16 v[8:11], v[124:127], v[210:213], v[8:11]
	v_mfma_f32_16x16x32_bf16 v[52:55], v[136:139], v[160:163], v[52:55]
	v_mfma_f32_16x16x32_bf16 v[48:51], v[152:155], v[160:163], v[48:51]
	v_mfma_f32_16x16x32_bf16 v[36:39], v[136:139], v[168:171], v[36:39]
	v_mfma_f32_16x16x32_bf16 v[32:35], v[152:155], v[168:171], v[32:35]
	v_mfma_f32_16x16x32_bf16 v[20:23], v[136:139], v[176:179], v[20:23]
	v_mfma_f32_16x16x32_bf16 v[16:19], v[152:155], v[176:179], v[16:19]
	v_mfma_f32_16x16x32_bf16 v[4:7], v[136:139], v[200:203], v[4:7]
	v_mfma_f32_16x16x32_bf16 v[0:3], v[152:155], v[200:203], v[0:3]
	v_mfma_f32_16x16x32_bf16 v[52:55], v[148:151], v[164:167], v[52:55]
	v_mfma_f32_16x16x32_bf16 v[48:51], v[156:159], v[164:167], v[48:51]
	v_mfma_f32_16x16x32_bf16 v[36:39], v[148:151], v[172:175], v[36:39]
	v_mfma_f32_16x16x32_bf16 v[32:35], v[156:159], v[172:175], v[32:35]
	v_mfma_f32_16x16x32_bf16 v[20:23], v[148:151], v[180:183], v[20:23]
	v_mfma_f32_16x16x32_bf16 v[16:19], v[156:159], v[180:183], v[16:19]
	v_mfma_f32_16x16x32_bf16 v[4:7], v[148:151], v[210:213], v[4:7]
	v_mfma_f32_16x16x32_bf16 v[0:3], v[156:159], v[210:213], v[0:3]
	s_barrier
; #define PG8_STAGE(bufoff, gbase, voff) do { _Pragma("unroll") for (int _i = 0; _i < 2; ++_i) \
;         __builtin_amdgcn_global_load_lds((const unsigned*)((const char*)(gbase) + (voff)[_i]), (PG8_LAS unsigned*)(lds + (bufoff) + ldsw + _i * 8192), 16, 0, 0); } while (0)
; #define PG8_LDA(dst, b, h) do { _Pragma("unroll") for (int m = 0; m < 4; ++m) _Pragma("unroll") for (int k = 0; k < 2; ++k) dst[m][k] = *(const PG8_LAS bf16x8*)(lds + PG8_SA(b, h) + aoff + m * 2048 + k * 1024); } while (0)
; #define PG8_LDB(dst, b, h) do { _Pragma("unroll") for (int n = 0; n < 2; ++n) _Pragma("unroll") for (int k = 0; k < 2; ++k) dst[n][k] = *(const PG8_LAS bf16x8*)(lds + PG8_SB(b, h) + boff + n * 2048 + k * 1024); } while (0)
; #define PG8_MMA(ai, bj, At, Bt) do { __builtin_amdgcn_s_setprio(1); _Pragma("unroll") for (int m = 0; m < 4; ++m) _Pragma("unroll") for (int n = 0; n < 2; ++n) _Pragma("unroll") for (int k = 0; k < 2; ++k) \
;         acc[ai][bj][m][n] = __builtin_amdgcn_mfma_f32_16x16x32_bf16(Bt[n][k], At[m][k], acc[ai][bj][m][n], 0, 0, 0); __builtin_amdgcn_s_setprio(0); } while (0)
; #define PG8_WAIT_V(n) asm volatile("s_waitcnt vmcnt(" #n ")" ::: "memory")
; #define PG8_WAIT_L(n) asm volatile("s_waitcnt lgkmcnt(" #n ")" ::: "memory")
; #define PG8_BAR __builtin_amdgcn_s_barrier()
; #define PG8_SCHED __builtin_amdgcn_sched_barrier(0)
; template <class Epi, class Sched, bool ALIGN_EPI = false, bool SP2 = false>
; __device__ __forceinline__ void gemm_phase(PG8_LAS unsigned char* lds, const Gemm g, const Sched& S, const Epi& E, const int tid_in) {
;     ...
;             PG8_LDB(B0, 1, 0); PG8_LDB(B1, 1, 1); PG8_SCHED; PG8_LDA(At, 1, 0); PG8_STAGE(PG8_SA(0, 1), a2 + hstep, voffA);
;             PG8_WAIT_V(8); PG8_WAIT_L(0); PG8_BAR; PG8_MMA(0, 0, At, B0); PG8_MMA(0, 1, At, B1); PG8_BAR; PG8_SCHED;
;             PG8_LDA(At, 1, 1); PG8_STAGE(PG8_SB(1, 0), b3, voffB); PG8_STAGE(PG8_SB(1, 1), b3 + hstep, voffB); PG8_STAGE(PG8_SA(1, 0), a3, voffA);
;             PG8_WAIT_V(8); PG8_WAIT_L(0); PG8_BAR; PG8_MMA(1, 0, At, B0); PG8_MMA(1, 1, At, B1); PG8_BAR; PG8_SCHED;
	s_add_i32 s82, 0, 0x18000
	s_add_i32 s83, 0, 0x1c000
	v_add_u32_e32 v124, s82, v205
	v_add_u32_e32 v156, s83, v205
	ds_read_b128 v[92:95], v124
	ds_read_b128 v[100:103], v124 offset:1024
	ds_read_b128 v[112:115], v124 offset:2048
	ds_read_b128 v[124:127], v124 offset:3072
	ds_read_b128 v[136:139], v156
	ds_read_b128 v[148:151], v156 offset:1024
	ds_read_b128 v[152:155], v156 offset:2048
	ds_read_b128 v[156:159], v156 offset:3072
	s_add_u32 s56, s74, 0xb0000
	s_addc_u32 s57, s75, 0
	s_mov_b32 m0, s35
	v_lshl_add_u64 v[222:223], s[56:57], 0, v[184:185]
	ds_read_b128 v[160:163], v209 offset:32768
	ds_read_b128 v[164:167], v209 offset:33792
	ds_read_b128 v[168:171], v209 offset:34816
	ds_read_b128 v[172:175], v209 offset:35840
	ds_read_b128 v[176:179], v209 offset:36864
	ds_read_b128 v[180:183], v209 offset:37888
	ds_read_b128 v[200:203], v209 offset:38912
	ds_read_b128 v[210:213], v209 offset:39936
	global_load_lds_dwordx4 v[222:223], off
	v_lshl_add_u64 v[222:223], s[56:57], 0, v[188:189]
	s_mov_b32 m0, s36
	s_nop 0
	global_load_lds_dwordx4 v[222:223], off
	s_waitcnt vmcnt(8)
	s_waitcnt lgkmcnt(0)
	s_barrier
	s_waitcnt lgkmcnt(0)
	v_mfma_f32_16x16x32_bf16 v[144:147], v[92:95], v[160:163], v[144:147]
	v_mfma_f32_16x16x32_bf16 v[140:143], v[112:115], v[160:163], v[140:143]
	v_mfma_f32_16x16x32_bf16 v[120:123], v[92:95], v[168:171], v[120:123]
	v_mfma_f32_16x16x32_bf16 v[116:119], v[112:115], v[168:171], v[116:119]
	v_mfma_f32_16x16x32_bf16 v[96:99], v[92:95], v[176:179], v[96:99]
	v_mfma_f32_16x16x32_bf16 v[88:91], v[112:115], v[176:179], v[88:91]
	v_mfma_f32_16x16x32_bf16 v[76:79], v[92:95], v[200:203], v[76:79]
	v_mfma_f32_16x16x32_bf16 v[72:75], v[112:115], v[200:203], v[72:75]
	v_mfma_f32_16x16x32_bf16 v[144:147], v[100:103], v[164:167], v[144:147]
	v_mfma_f32_16x16x32_bf16 v[140:143], v[124:127], v[164:167], v[140:143]
	v_mfma_f32_16x16x32_bf16 v[120:123], v[100:103], v[172:175], v[120:123]
	v_mfma_f32_16x16x32_bf16 v[116:119], v[124:127], v[172:175], v[116:119]
	v_mfma_f32_16x16x32_bf16 v[96:99], v[100:103], v[180:183], v[96:99]
	v_mfma_f32_16x16x32_bf16 v[88:91], v[124:127], v[180:183], v[88:91]
	v_mfma_f32_16x16x32_bf16 v[76:79], v[100:103], v[210:213], v[76:79]
	v_mfma_f32_16x16x32_bf16 v[72:75], v[124:127], v[210:213], v[72:75]
	v_mfma_f32_16x16x32_bf16 v[132:135], v[136:139], v[160:163], v[132:135]
	v_mfma_f32_16x16x32_bf16 v[128:131], v[152:155], v[160:163], v[128:131]
	v_mfma_f32_16x16x32_bf16 v[108:111], v[136:139], v[168:171], v[108:111]
	v_mfma_f32_16x16x32_bf16 v[104:107], v[152:155], v[168:171], v[104:107]
	v_mfma_f32_16x16x32_bf16 v[84:87], v[136:139], v[176:179], v[84:87]
	v_mfma_f32_16x16x32_bf16 v[80:83], v[152:155], v[176:179], v[80:83]
	v_mfma_f32_16x16x32_bf16 v[68:71], v[136:139], v[200:203], v[68:71]
	v_mfma_f32_16x16x32_bf16 v[64:67], v[152:155], v[200:203], v[64:67]
	v_mfma_f32_16x16x32_bf16 v[132:135], v[148:151], v[164:167], v[132:135]
	v_mfma_f32_16x16x32_bf16 v[128:131], v[156:159], v[164:167], v[128:131]
	v_mfma_f32_16x16x32_bf16 v[108:111], v[148:151], v[172:175], v[108:111]
	v_mfma_f32_16x16x32_bf16 v[104:107], v[156:159], v[172:175], v[104:107]
	v_mfma_f32_16x16x32_bf16 v[84:87], v[148:151], v[180:183], v[84:87]
	v_mfma_f32_16x16x32_bf16 v[80:83], v[156:159], v[180:183], v[80:83]
	v_mfma_f32_16x16x32_bf16 v[68:71], v[148:151], v[210:213], v[68:71]
	v_mfma_f32_16x16x32_bf16 v[64:67], v[156:159], v[210:213], v[64:67]
	s_barrier
	s_add_i32 s56, s82, s30
	v_lshl_add_u64 v[214:215], v[214:215], 0, s[46:47]
	s_mov_b32 m0, s56
	ds_read_b128 v[160:163], v209 offset:49152
	ds_read_b128 v[164:167], v209 offset:50176
	ds_read_b128 v[168:171], v209 offset:51200
	ds_read_b128 v[172:175], v209 offset:52224
	ds_read_b128 v[176:179], v209 offset:53248
	ds_read_b128 v[180:183], v209 offset:54272
	ds_read_b128 v[200:203], v209 offset:55296
	ds_read_b128 v[210:213], v209 offset:56320
	global_load_lds_dwordx4 v[214:215], off
	s_add_i32 m0, s56, 0x2000
	s_add_u32 s0, s0, 0xb0080
	v_lshl_add_u64 v[214:215], v[216:217], 0, s[46:47]
	s_addc_u32 s1, s1, 0
	s_add_i32 s56, s83, s30
	global_load_lds_dwordx4 v[214:215], off
	v_lshl_add_u64 v[214:215], s[0:1], 0, v[186:187]
	s_mov_b32 m0, s56
	s_nop 0
	global_load_lds_dwordx4 v[214:215], off
	v_lshl_add_u64 v[214:215], s[0:1], 0, v[190:191]
	s_add_i32 m0, s56, 0x2000
	s_nop 0
	global_load_lds_dwordx4 v[214:215], off
	v_lshl_add_u64 v[214:215], v[218:219], 0, s[46:47]
	s_mov_b32 m0, s38
	s_nop 0
	global_load_lds_dwordx4 v[214:215], off
	v_lshl_add_u64 v[214:215], v[220:221], 0, s[46:47]
	s_mov_b32 m0, s39
	s_nop 0
	global_load_lds_dwordx4 v[214:215], off
	s_waitcnt vmcnt(8)
	s_waitcnt lgkmcnt(0)
	s_barrier
	s_waitcnt lgkmcnt(0)
	v_mfma_f32_16x16x32_bf16 v[60:63], v[92:95], v[160:163], v[60:63]
	v_mfma_f32_16x16x32_bf16 v[56:59], v[112:115], v[160:163], v[56:59]
	v_mfma_f32_16x16x32_bf16 v[44:47], v[92:95], v[168:171], v[44:47]
	v_mfma_f32_16x16x32_bf16 v[40:43], v[112:115], v[168:171], v[40:43]
	v_mfma_f32_16x16x32_bf16 v[28:31], v[92:95], v[176:179], v[28:31]
	v_mfma_f32_16x16x32_bf16 v[24:27], v[112:115], v[176:179], v[24:27]
	v_mfma_f32_16x16x32_bf16 v[12:15], v[92:95], v[200:203], v[12:15]
	v_mfma_f32_16x16x32_bf16 v[8:11], v[112:115], v[200:203], v[8:11]
	v_mfma_f32_16x16x32_bf16 v[60:63], v[100:103], v[164:167], v[60:63]
	v_mfma_f32_16x16x32_bf16 v[56:59], v[124:127], v[164:167], v[56:59]
	v_mfma_f32_16x16x32_bf16 v[44:47], v[100:103], v[172:175], v[44:47]
	v_mfma_f32_16x16x32_bf16 v[40:43], v[124:127], v[172:175], v[40:43]
	v_mfma_f32_16x16x32_bf16 v[28:31], v[100:103], v[180:183], v[28:31]
	v_mfma_f32_16x16x32_bf16 v[24:27], v[124:127], v[180:183], v[24:27]
	v_mfma_f32_16x16x32_bf16 v[12:15], v[100:103], v[210:213], v[12:15]
	v_mfma_f32_16x16x32_bf16 v[8:11], v[124:127], v[210:213], v[8:11]
	v_mfma_f32_16x16x32_bf16 v[52:55], v[136:139], v[160:163], v[52:55]
	v_mfma_f32_16x16x32_bf16 v[48:51], v[152:155], v[160:163], v[48:51]
	v_mfma_f32_16x16x32_bf16 v[36:39], v[136:139], v[168:171], v[36:39]
	v_mfma_f32_16x16x32_bf16 v[32:35], v[152:155], v[168:171], v[32:35]
	v_mfma_f32_16x16x32_bf16 v[20:23], v[136:139], v[176:179], v[20:23]
	v_mfma_f32_16x16x32_bf16 v[16:19], v[152:155], v[176:179], v[16:19]
	v_mfma_f32_16x16x32_bf16 v[4:7], v[136:139], v[200:203], v[4:7]
	v_mfma_f32_16x16x32_bf16 v[0:3], v[152:155], v[200:203], v[0:3]
	v_mfma_f32_16x16x32_bf16 v[52:55], v[148:151], v[164:167], v[52:55]
	v_mfma_f32_16x16x32_bf16 v[48:51], v[156:159], v[164:167], v[48:51]
	v_mfma_f32_16x16x32_bf16 v[36:39], v[148:151], v[172:175], v[36:39]
	v_mfma_f32_16x16x32_bf16 v[32:35], v[156:159], v[172:175], v[32:35]
	v_mfma_f32_16x16x32_bf16 v[20:23], v[148:151], v[180:183], v[20:23]
	v_mfma_f32_16x16x32_bf16 v[16:19], v[156:159], v[180:183], v[16:19]
	v_mfma_f32_16x16x32_bf16 v[4:7], v[148:151], v[210:213], v[4:7]
	v_mfma_f32_16x16x32_bf16 v[0:3], v[156:159], v[210:213], v[0:3]
	s_barrier
	s_add_i32 s81, s81, 2
	s_add_u32 s76, s76, 0x100
	s_addc_u32 s77, s77, 0
	s_cmp_gt_u32 s81, 41
	s_mov_b64 s[56:57], s[78:79]
	s_cbranch_scc0 .LBB0_1282

; #define PG8_STAGE(bufoff, gbase, voff) do { _Pragma("unroll") for (int _i = 0; _i < 2; ++_i) \
;         __builtin_amdgcn_global_load_lds((const unsigned*)((const char*)(gbase) + (voff)[_i]), (PG8_LAS unsigned*)(lds + (bufoff) + ldsw + _i * 8192), 16, 0, 0); } while (0)
; #define PG8_LDA(dst, b, h) do { _Pragma("unroll") for (int m = 0; m < 4; ++m) _Pragma("unroll") for (int k = 0; k < 2; ++k) dst[m][k] = *(const PG8_LAS bf16x8*)(lds + PG8_SA(b, h) + aoff + m * 2048 + k * 1024); } while (0)
; #define PG8_LDB(dst, b, h) do { _Pragma("unroll") for (int n = 0; n < 2; ++n) _Pragma("unroll") for (int k = 0; k < 2; ++k) dst[n][k] = *(const PG8_LAS bf16x8*)(lds + PG8_SB(b, h) + boff + n * 2048 + k * 1024); } while (0)
; #define PG8_WAIT_V(n) asm volatile("s_waitcnt vmcnt(" #n ")" ::: "memory")
; #define PG8_WAIT_L(n) asm volatile("s_waitcnt lgkmcnt(" #n ")" ::: "memory")
; #define PG8_BAR __builtin_amdgcn_s_barrier()
; #define PG8_SCHED __builtin_amdgcn_sched_barrier(0)
; template <class Epi, class Sched, bool ALIGN_EPI = false, bool SP2 = false>
; __device__ __forceinline__ void gemm_phase(PG8_LAS unsigned char* lds, const Gemm g, const Sched& S, const Epi& E, const int tid_in) {
;     ...
;         const char* nA = has_next ? (const char*)g.A + (size_t)nxt.pm * tstep : cA; const char* nB = has_next ? (const char*)g.Bt + (size_t)nxt.pn * tstep : cB;
;         for (int t = 0; t < nt; t += 2) {
;             const bool last = (t == nt - 2);
;             const char* a1 = cA + (size_t)(t + 1) * kstep;
;             const char* a2 = last ? nA : cA + (size_t)(t + 2) * kstep; const char* b2 = last ? nB : cB + (size_t)(t + 2) * kstep;
;             const char* a3 = a2 + kstep; const char* b3 = b2 + kstep;
;             if (last && has_next) S.a_ready(nxt);
;             if constexpr (SP2) {
;             PG8_LDB(B0, 0, 0); PG8_LDB(B1, 0, 1); PG8_SCHED; PG8_LDA(At, 0, 0); PG8_STAGE(PG8_SA(1, 1), a1 + hstep, voffA);
;             PG8_WAIT_V(8); PG8_WAIT_L(0); PG8_BAR; PG8_MMA(0, 0, At, B0); PG8_MMA(0, 1, At, B1); PG8_BAR; PG8_SCHED;
;             PG8_LDA(At, 0, 1); PG8_STAGE(PG8_SB(0, 0), b2, voffB); PG8_STAGE(PG8_SB(0, 1), b2 + hstep, voffB); PG8_STAGE(PG8_SA(0, 0), a2, voffA);
;             PG8_WAIT_V(8); PG8_WAIT_L(0); PG8_BAR; PG8_MMA(1, 0, At, B0); PG8_MMA(1, 1, At, B1); PG8_BAR; PG8_SCHED;
.LBB0_1794:
	s_ashr_i32 s57, s56, 31
	s_lshl_b64 s[10:11], s[56:57], 19
	s_add_u32 s66, s5, s10
	s_addc_u32 s67, s30, s11
	s_and_b64 s[10:11], s[6:7], exec
	s_cselect_b32 s9, s67, s1
	s_cselect_b32 s14, s66, s0
	s_ashr_i32 s55, s54, 31
	s_lshl_b64 s[10:11], s[54:55], 19
	s_add_u32 s68, s3, s10
	s_addc_u32 s69, s4, s11
	s_and_b64 s[10:11], s[6:7], exec
	s_cselect_b32 s15, s69, s13
	s_cselect_b32 s16, s68, s12
	s_add_u32 s10, s0, 0x40080
	s_addc_u32 s11, s1, 0
	s_add_u32 s55, s12, 0x100
	v_mov_b32_e32 v0, 0
	s_addc_u32 s57, s13, 0
	s_mov_b32 s65, -2
	ds_read_b128 v[128:131], v204
	ds_read_b128 v[132:135], v204 offset:1024
	s_waitcnt lgkmcnt(0)
	ds_read_b128 v[156:159], v204 offset:2048
	ds_read_b128 v[160:163], v204 offset:3072
	ds_read_b128 v[164:167], v205
	ds_read_b128 v[168:171], v205 offset:1024
	ds_read_b128 v[172:175], v205 offset:2048
	ds_read_b128 v[176:179], v205 offset:3072
	s_add_u32 s0, s10, 0xfffc0080
	s_addc_u32 s1, s11, -1
	s_cmp_eq_u32 s65, 12
	s_cselect_b32 s13, s9, s1
	s_cselect_b32 s12, s14, s0
	s_cselect_b32 s1, s15, s57
	s_cselect_b32 s0, s16, s55
	v_lshl_add_u64 v[192:193], s[10:11], 0, v[148:149]
	s_add_i32 m0, s31, 0xc000
	ds_read_b128 v[180:183], v206
	ds_read_b128 v[184:187], v206 offset:1024
	ds_read_b128 v[188:191], v206 offset:2048
	ds_read_b128 v[210:213], v206 offset:3072
	ds_read_b128 v[214:217], v206 offset:4096
	ds_read_b128 v[218:221], v206 offset:5120
	ds_read_b128 v[222:225], v206 offset:6144
	ds_read_b128 v[226:229], v206 offset:7168
	global_load_lds_dwordx4 v[192:193], off
	v_lshl_add_u64 v[192:193], s[10:11], 0, v[150:151]
	s_add_i32 m0, s31, 0xe000
	s_nop 0
	global_load_lds_dwordx4 v[192:193], off
	s_waitcnt vmcnt(8)
	s_waitcnt lgkmcnt(0)
	s_barrier
	s_waitcnt lgkmcnt(0)
	v_mfma_f32_16x16x32_bf16 v[124:127], v[128:131], v[180:183], 0
	v_mfma_f32_16x16x32_bf16 v[120:123], v[156:159], v[180:183], 0
	v_mfma_f32_16x16x32_bf16 v[108:111], v[128:131], v[188:191], 0
	v_mfma_f32_16x16x32_bf16 v[104:107], v[156:159], v[188:191], 0
	v_mfma_f32_16x16x32_bf16 v[92:95], v[128:131], v[214:217], 0
	v_mfma_f32_16x16x32_bf16 v[88:91], v[156:159], v[214:217], 0
	v_mfma_f32_16x16x32_bf16 v[76:79], v[128:131], v[222:225], 0
	v_mfma_f32_16x16x32_bf16 v[72:75], v[156:159], v[222:225], 0
	v_mfma_f32_16x16x32_bf16 v[124:127], v[132:135], v[184:187], v[124:127]
	v_mfma_f32_16x16x32_bf16 v[120:123], v[160:163], v[184:187], v[120:123]
	v_mfma_f32_16x16x32_bf16 v[108:111], v[132:135], v[210:213], v[108:111]
	v_mfma_f32_16x16x32_bf16 v[104:107], v[160:163], v[210:213], v[104:107]
	v_mfma_f32_16x16x32_bf16 v[92:95], v[132:135], v[218:221], v[92:95]
	v_mfma_f32_16x16x32_bf16 v[88:91], v[160:163], v[218:221], v[88:91]
	v_mfma_f32_16x16x32_bf16 v[76:79], v[132:135], v[226:229], v[76:79]
	v_mfma_f32_16x16x32_bf16 v[72:75], v[160:163], v[226:229], v[72:75]
	v_mfma_f32_16x16x32_bf16 v[116:119], v[164:167], v[180:183], 0
	v_mfma_f32_16x16x32_bf16 v[112:115], v[172:175], v[180:183], 0
	v_mfma_f32_16x16x32_bf16 v[100:103], v[164:167], v[188:191], 0
	v_mfma_f32_16x16x32_bf16 v[96:99], v[172:175], v[188:191], 0
	v_mfma_f32_16x16x32_bf16 v[84:87], v[164:167], v[214:217], 0
	v_mfma_f32_16x16x32_bf16 v[80:83], v[172:175], v[214:217], 0
	v_mfma_f32_16x16x32_bf16 v[68:71], v[164:167], v[222:225], 0
	v_mfma_f32_16x16x32_bf16 v[64:67], v[172:175], v[222:225], 0
	v_mfma_f32_16x16x32_bf16 v[116:119], v[168:171], v[184:187], v[116:119]
	v_mfma_f32_16x16x32_bf16 v[112:115], v[176:179], v[184:187], v[112:115]
	v_mfma_f32_16x16x32_bf16 v[100:103], v[168:171], v[210:213], v[100:103]
	v_mfma_f32_16x16x32_bf16 v[96:99], v[176:179], v[210:213], v[96:99]
	v_mfma_f32_16x16x32_bf16 v[84:87], v[168:171], v[218:221], v[84:87]
	v_mfma_f32_16x16x32_bf16 v[80:83], v[176:179], v[218:221], v[80:83]
	v_mfma_f32_16x16x32_bf16 v[68:71], v[168:171], v[226:229], v[68:71]
	v_mfma_f32_16x16x32_bf16 v[64:67], v[176:179], v[226:229], v[64:67]
	s_barrier
	s_add_i32 s74, s49, s2
	v_lshl_add_u64 v[192:193], s[0:1], 0, v[136:137]
	s_mov_b32 m0, s74
	ds_read_b128 v[180:183], v206 offset:16384
	ds_read_b128 v[184:187], v206 offset:17408
	ds_read_b128 v[188:191], v206 offset:18432
	ds_read_b128 v[210:213], v206 offset:19456
	ds_read_b128 v[214:217], v206 offset:20480
	ds_read_b128 v[218:221], v206 offset:21504
	ds_read_b128 v[222:225], v206 offset:22528
	ds_read_b128 v[226:229], v206 offset:23552
	global_load_lds_dwordx4 v[192:193], off
	s_add_i32 m0, s74, 0x2000
	s_add_u32 s74, s0, 0x40000
	v_lshl_add_u64 v[230:231], s[0:1], 0, v[138:139]
	s_addc_u32 s75, s1, 0
	s_add_i32 s76, s50, s2
	global_load_lds_dwordx4 v[230:231], off
	v_lshl_add_u64 v[232:233], s[74:75], 0, v[136:137]
	s_mov_b32 m0, s76
	v_lshl_add_u64 v[234:235], s[12:13], 0, v[138:139]
	global_load_lds_dwordx4 v[232:233], off
	v_lshl_add_u64 v[232:233], s[74:75], 0, v[138:139]
	s_add_i32 m0, s76, 0x2000
	s_nop 0
	global_load_lds_dwordx4 v[232:233], off
	v_lshl_add_u64 v[232:233], s[12:13], 0, v[136:137]
	s_mov_b32 m0, s31
	s_nop 0
	global_load_lds_dwordx4 v[232:233], off
	s_mov_b32 m0, s34
	s_nop 0
	global_load_lds_dwordx4 v[234:235], off
	s_waitcnt vmcnt(8)
	s_waitcnt lgkmcnt(0)
	s_barrier
; #define PG8_STAGE(bufoff, gbase, voff) do { _Pragma("unroll") for (int _i = 0; _i < 2; ++_i) \
;         __builtin_amdgcn_global_load_lds((const unsigned*)((const char*)(gbase) + (voff)[_i]), (PG8_LAS unsigned*)(lds + (bufoff) + ldsw + _i * 8192), 16, 0, 0); } while (0)
; #define PG8_LDA(dst, b, h) do { _Pragma("unroll") for (int m = 0; m < 4; ++m) _Pragma("unroll") for (int k = 0; k < 2; ++k) dst[m][k] = *(const PG8_LAS bf16x8*)(lds + PG8_SA(b, h) + aoff + m * 2048 + k * 1024); } while (0)
; #define PG8_LDB(dst, b, h) do { _Pragma("unroll") for (int n = 0; n < 2; ++n) _Pragma("unroll") for (int k = 0; k < 2; ++k) dst[n][k] = *(const PG8_LAS bf16x8*)(lds + PG8_SB(b, h) + boff + n * 2048 + k * 1024); } while (0)
; #define PG8_MMA(ai, bj, At, Bt) do { __builtin_amdgcn_s_setprio(1); _Pragma("unroll") for (int m = 0; m < 4; ++m) _Pragma("unroll") for (int n = 0; n < 2; ++n) _Pragma("unroll") for (int k = 0; k < 2; ++k) \
;         acc[ai][bj][m][n] = __builtin_amdgcn_mfma_f32_16x16x32_bf16(Bt[n][k], At[m][k], acc[ai][bj][m][n], 0, 0, 0); __builtin_amdgcn_s_setprio(0); } while (0)
; #define PG8_WAIT_V(n) asm volatile("s_waitcnt vmcnt(" #n ")" ::: "memory")
; #define PG8_WAIT_L(n) asm volatile("s_waitcnt lgkmcnt(" #n ")" ::: "memory")
; #define PG8_BAR __builtin_amdgcn_s_barrier()
; #define PG8_SCHED __builtin_amdgcn_sched_barrier(0)
; template <class Epi, class Sched, bool ALIGN_EPI = false, bool SP2 = false>
; __device__ __forceinline__ void gemm_phase(PG8_LAS unsigned char* lds, const Gemm g, const Sched& S, const Epi& E, const int tid_in) {
;     ...
;             PG8_WAIT_V(8); PG8_WAIT_L(0); PG8_BAR; PG8_MMA(0, 0, At, B0); PG8_MMA(0, 1, At, B1); PG8_BAR; PG8_SCHED;
;             PG8_LDA(At, 0, 1); PG8_STAGE(PG8_SB(0, 0), b2, voffB); PG8_STAGE(PG8_SB(0, 1), b2 + hstep, voffB); PG8_STAGE(PG8_SA(0, 0), a2, voffA);
;             PG8_WAIT_V(8); PG8_WAIT_L(0); PG8_BAR; PG8_MMA(1, 0, At, B0); PG8_MMA(1, 1, At, B1); PG8_BAR; PG8_SCHED;
;             PG8_LDB(B0, 1, 0); PG8_LDB(B1, 1, 1); PG8_SCHED; PG8_LDA(At, 1, 0); PG8_STAGE(PG8_SA(0, 1), a2 + hstep, voffA);
;             PG8_WAIT_V(8); PG8_WAIT_L(0); PG8_BAR; PG8_MMA(0, 0, At, B0); PG8_MMA(0, 1, At, B1); PG8_BAR; PG8_SCHED;
	s_waitcnt lgkmcnt(0)
	v_mfma_f32_16x16x32_bf16 v[60:63], v[128:131], v[180:183], 0
	v_mfma_f32_16x16x32_bf16 v[56:59], v[156:159], v[180:183], 0
	v_mfma_f32_16x16x32_bf16 v[44:47], v[128:131], v[188:191], 0
	v_mfma_f32_16x16x32_bf16 v[40:43], v[156:159], v[188:191], 0
	v_mfma_f32_16x16x32_bf16 v[28:31], v[128:131], v[214:217], 0
	v_mfma_f32_16x16x32_bf16 v[24:27], v[156:159], v[214:217], 0
	v_mfma_f32_16x16x32_bf16 v[12:15], v[128:131], v[222:225], 0
	v_mfma_f32_16x16x32_bf16 v[8:11], v[156:159], v[222:225], 0
	v_mfma_f32_16x16x32_bf16 v[60:63], v[132:135], v[184:187], v[60:63]
	v_mfma_f32_16x16x32_bf16 v[56:59], v[160:163], v[184:187], v[56:59]
	v_mfma_f32_16x16x32_bf16 v[44:47], v[132:135], v[210:213], v[44:47]
	v_mfma_f32_16x16x32_bf16 v[40:43], v[160:163], v[210:213], v[40:43]
	v_mfma_f32_16x16x32_bf16 v[28:31], v[132:135], v[218:221], v[28:31]
	v_mfma_f32_16x16x32_bf16 v[24:27], v[160:163], v[218:221], v[24:27]
	v_mfma_f32_16x16x32_bf16 v[12:15], v[132:135], v[226:229], v[12:15]
	v_mfma_f32_16x16x32_bf16 v[8:11], v[160:163], v[226:229], v[8:11]
	v_mfma_f32_16x16x32_bf16 v[52:55], v[164:167], v[180:183], 0
	v_mfma_f32_16x16x32_bf16 v[48:51], v[172:175], v[180:183], 0
	v_mfma_f32_16x16x32_bf16 v[36:39], v[164:167], v[188:191], 0
	v_mfma_f32_16x16x32_bf16 v[32:35], v[172:175], v[188:191], 0
	v_mfma_f32_16x16x32_bf16 v[20:23], v[164:167], v[214:217], 0
	v_mfma_f32_16x16x32_bf16 v[16:19], v[172:175], v[214:217], 0
	v_mfma_f32_16x16x32_bf16 v[4:7], v[164:167], v[222:225], 0
	v_mfma_f32_16x16x32_bf16 v[0:3], v[172:175], v[222:225], 0
	v_mfma_f32_16x16x32_bf16 v[52:55], v[168:171], v[184:187], v[52:55]
	v_mfma_f32_16x16x32_bf16 v[48:51], v[176:179], v[184:187], v[48:51]
	v_mfma_f32_16x16x32_bf16 v[36:39], v[168:171], v[210:213], v[36:39]
	v_mfma_f32_16x16x32_bf16 v[32:35], v[176:179], v[210:213], v[32:35]
	v_mfma_f32_16x16x32_bf16 v[20:23], v[168:171], v[218:221], v[20:23]
	v_mfma_f32_16x16x32_bf16 v[16:19], v[176:179], v[218:221], v[16:19]
	v_mfma_f32_16x16x32_bf16 v[4:7], v[168:171], v[226:229], v[4:7]
	v_mfma_f32_16x16x32_bf16 v[0:3], v[176:179], v[226:229], v[0:3]
	s_barrier
	s_add_i32 s74, 0, 0x18000
	v_add_u32_e32 v140, s74, v195
	s_add_i32 s75, 0, 0x1c000
	ds_read_b128 v[128:131], v140
	ds_read_b128 v[132:135], v140 offset:1024
	ds_read_b128 v[156:159], v140 offset:2048
	ds_read_b128 v[160:163], v140 offset:3072
	v_add_u32_e32 v140, s75, v195
	ds_read_b128 v[164:167], v140
	ds_read_b128 v[168:171], v140 offset:1024
	ds_read_b128 v[172:175], v140 offset:2048
	ds_read_b128 v[176:179], v140 offset:3072
	s_add_u32 s12, s12, 0x40000
	s_addc_u32 s13, s13, 0
	s_mov_b32 m0, s35
	v_lshl_add_u64 v[236:237], s[12:13], 0, v[136:137]
	ds_read_b128 v[180:183], v206 offset:32768
	ds_read_b128 v[184:187], v206 offset:33792
	ds_read_b128 v[188:191], v206 offset:34816
	ds_read_b128 v[210:213], v206 offset:35840
	ds_read_b128 v[214:217], v206 offset:36864
	ds_read_b128 v[218:221], v206 offset:37888
	ds_read_b128 v[222:225], v206 offset:38912
	ds_read_b128 v[226:229], v206 offset:39936
	global_load_lds_dwordx4 v[236:237], off
	v_lshl_add_u64 v[236:237], s[12:13], 0, v[138:139]
	s_mov_b32 m0, s36
	s_nop 0
	global_load_lds_dwordx4 v[236:237], off
	s_waitcnt vmcnt(8)
	s_waitcnt lgkmcnt(0)
	s_barrier
	s_waitcnt lgkmcnt(0)
	v_mfma_f32_16x16x32_bf16 v[124:127], v[128:131], v[180:183], v[124:127]
	v_mfma_f32_16x16x32_bf16 v[120:123], v[156:159], v[180:183], v[120:123]
	v_mfma_f32_16x16x32_bf16 v[108:111], v[128:131], v[188:191], v[108:111]
	v_mfma_f32_16x16x32_bf16 v[104:107], v[156:159], v[188:191], v[104:107]
	v_mfma_f32_16x16x32_bf16 v[92:95], v[128:131], v[214:217], v[92:95]
	v_mfma_f32_16x16x32_bf16 v[88:91], v[156:159], v[214:217], v[88:91]
	v_mfma_f32_16x16x32_bf16 v[76:79], v[128:131], v[222:225], v[76:79]
	v_mfma_f32_16x16x32_bf16 v[72:75], v[156:159], v[222:225], v[72:75]
	v_mfma_f32_16x16x32_bf16 v[124:127], v[132:135], v[184:187], v[124:127]
	v_mfma_f32_16x16x32_bf16 v[120:123], v[160:163], v[184:187], v[120:123]
	v_mfma_f32_16x16x32_bf16 v[108:111], v[132:135], v[210:213], v[108:111]
	v_mfma_f32_16x16x32_bf16 v[104:107], v[160:163], v[210:213], v[104:107]
	v_mfma_f32_16x16x32_bf16 v[92:95], v[132:135], v[218:221], v[92:95]
	v_mfma_f32_16x16x32_bf16 v[88:91], v[160:163], v[218:221], v[88:91]
	v_mfma_f32_16x16x32_bf16 v[76:79], v[132:135], v[226:229], v[76:79]
	v_mfma_f32_16x16x32_bf16 v[72:75], v[160:163], v[226:229], v[72:75]
	v_mfma_f32_16x16x32_bf16 v[116:119], v[164:167], v[180:183], v[116:119]
	v_mfma_f32_16x16x32_bf16 v[112:115], v[172:175], v[180:183], v[112:115]
	v_mfma_f32_16x16x32_bf16 v[100:103], v[164:167], v[188:191], v[100:103]
	v_mfma_f32_16x16x32_bf16 v[96:99], v[172:175], v[188:191], v[96:99]
	v_mfma_f32_16x16x32_bf16 v[84:87], v[164:167], v[214:217], v[84:87]
	v_mfma_f32_16x16x32_bf16 v[80:83], v[172:175], v[214:217], v[80:83]
	v_mfma_f32_16x16x32_bf16 v[68:71], v[164:167], v[222:225], v[68:71]
	v_mfma_f32_16x16x32_bf16 v[64:67], v[172:175], v[222:225], v[64:67]
	v_mfma_f32_16x16x32_bf16 v[116:119], v[168:171], v[184:187], v[116:119]
	v_mfma_f32_16x16x32_bf16 v[112:115], v[176:179], v[184:187], v[112:115]
	v_mfma_f32_16x16x32_bf16 v[100:103], v[168:171], v[210:213], v[100:103]
	v_mfma_f32_16x16x32_bf16 v[96:99], v[176:179], v[210:213], v[96:99]
	v_mfma_f32_16x16x32_bf16 v[84:87], v[168:171], v[218:221], v[84:87]
	v_mfma_f32_16x16x32_bf16 v[80:83], v[176:179], v[218:221], v[80:83]
	v_mfma_f32_16x16x32_bf16 v[68:71], v[168:171], v[226:229], v[68:71]
	v_mfma_f32_16x16x32_bf16 v[64:67], v[176:179], v[226:229], v[64:67]
	s_barrier
; #define PG8_STAGE(bufoff, gbase, voff) do { _Pragma("unroll") for (int _i = 0; _i < 2; ++_i) \
;         __builtin_amdgcn_global_load_lds((const unsigned*)((const char*)(gbase) + (voff)[_i]), (PG8_LAS unsigned*)(lds + (bufoff) + ldsw + _i * 8192), 16, 0, 0); } while (0)
; #define PG8_LDA(dst, b, h) do { _Pragma("unroll") for (int m = 0; m < 4; ++m) _Pragma("unroll") for (int k = 0; k < 2; ++k) dst[m][k] = *(const PG8_LAS bf16x8*)(lds + PG8_SA(b, h) + aoff + m * 2048 + k * 1024); } while (0)
; #define PG8_LDB(dst, b, h) do { _Pragma("unroll") for (int n = 0; n < 2; ++n) _Pragma("unroll") for (int k = 0; k < 2; ++k) dst[n][k] = *(const PG8_LAS bf16x8*)(lds + PG8_SB(b, h) + boff + n * 2048 + k * 1024); } while (0)
; #define PG8_WAIT_V(n) asm volatile("s_waitcnt vmcnt(" #n ")" ::: "memory")
; template <class Epi, class Sched, bool ALIGN_EPI = false, bool SP2 = false>
; __device__ __forceinline__ void gemm_phase(PG8_LAS unsigned char* lds, const Gemm g, const Sched& S, const Epi& E, const int tid_in) {
;     ...
;         for (int t = 0; t < nt; t += 2) {
;             const bool last = (t == nt - 2);
;             const char* a1 = cA + (size_t)(t + 1) * kstep;
;             const char* a2 = last ? nA : cA + (size_t)(t + 2) * kstep; const char* b2 = last ? nB : cB + (size_t)(t + 2) * kstep;
;             const char* a3 = a2 + kstep; const char* b3 = b2 + kstep;
;             if (last && has_next) S.a_ready(nxt);
;             if constexpr (SP2) {
;             PG8_LDB(B0, 0, 0); PG8_LDB(B1, 0, 1); PG8_SCHED; PG8_LDA(At, 0, 0); PG8_STAGE(PG8_SA(1, 1), a1 + hstep, voffA);
;             PG8_WAIT_V(8); PG8_WAIT_L(0); PG8_BAR; PG8_MMA(0, 0, At, B0); PG8_MMA(0, 1, At, B1); PG8_BAR; PG8_SCHED;
;             PG8_LDA(At, 0, 1); PG8_STAGE(PG8_SB(0, 0), b2, voffB); PG8_STAGE(PG8_SB(0, 1), b2 + hstep, voffB); PG8_STAGE(PG8_SA(0, 0), a2, voffA);
;             PG8_WAIT_V(8); PG8_WAIT_L(0); PG8_BAR; PG8_MMA(1, 0, At, B0); PG8_MMA(1, 1, At, B1); PG8_BAR; PG8_SCHED;
;     ...
;             PG8_WAIT_V(8); PG8_WAIT_L(0); PG8_BAR; PG8_MMA(0, 0, At, B0); PG8_MMA(0, 1, At, B1); PG8_BAR; PG8_SCHED;
;             PG8_LDA(At, 1, 1); PG8_STAGE(PG8_SB(1, 0), b3, voffB); PG8_STAGE(PG8_SB(1, 1), b3 + hstep, voffB); PG8_STAGE(PG8_SA(1, 0), a3, voffA);
;             PG8_WAIT_V(8); PG8_WAIT_L(0); PG8_BAR; PG8_MMA(1, 0, At, B0); PG8_MMA(1, 1, At, B1); PG8_BAR; PG8_SCHED;
	s_add_i32 s12, s74, s2
	v_lshl_add_u64 v[192:193], v[192:193], 0, s[26:27]
	s_mov_b32 m0, s12
	ds_read_b128 v[180:183], v206 offset:49152
	ds_read_b128 v[184:187], v206 offset:50176
	ds_read_b128 v[188:191], v206 offset:51200
	ds_read_b128 v[210:213], v206 offset:52224
	ds_read_b128 v[214:217], v206 offset:53248
	ds_read_b128 v[218:221], v206 offset:54272
	ds_read_b128 v[222:225], v206 offset:55296
	ds_read_b128 v[226:229], v206 offset:56320
	global_load_lds_dwordx4 v[192:193], off
	s_add_i32 m0, s12, 0x2000
	s_add_u32 s0, s0, 0x40080
	v_lshl_add_u64 v[192:193], v[230:231], 0, s[26:27]
	s_addc_u32 s1, s1, 0
	s_add_i32 s12, s75, s2
	global_load_lds_dwordx4 v[192:193], off
	v_lshl_add_u64 v[192:193], s[0:1], 0, v[136:137]
	s_mov_b32 m0, s12
	s_nop 0
	global_load_lds_dwordx4 v[192:193], off
	v_lshl_add_u64 v[192:193], s[0:1], 0, v[138:139]
	s_add_i32 m0, s12, 0x2000
	s_nop 0
	global_load_lds_dwordx4 v[192:193], off
	v_lshl_add_u64 v[192:193], v[232:233], 0, s[26:27]
	s_mov_b32 m0, s96
	s_nop 0
	global_load_lds_dwordx4 v[192:193], off
	v_lshl_add_u64 v[192:193], v[234:235], 0, s[26:27]
	s_mov_b32 m0, s97
	s_nop 0
	global_load_lds_dwordx4 v[192:193], off
	s_waitcnt vmcnt(8)
	s_waitcnt lgkmcnt(0)
	s_barrier
	s_waitcnt lgkmcnt(0)
	v_mfma_f32_16x16x32_bf16 v[60:63], v[128:131], v[180:183], v[60:63]
	v_mfma_f32_16x16x32_bf16 v[56:59], v[156:159], v[180:183], v[56:59]
	v_mfma_f32_16x16x32_bf16 v[44:47], v[128:131], v[188:191], v[44:47]
	v_mfma_f32_16x16x32_bf16 v[40:43], v[156:159], v[188:191], v[40:43]
	v_mfma_f32_16x16x32_bf16 v[28:31], v[128:131], v[214:217], v[28:31]
	v_mfma_f32_16x16x32_bf16 v[24:27], v[156:159], v[214:217], v[24:27]
	v_mfma_f32_16x16x32_bf16 v[12:15], v[128:131], v[222:225], v[12:15]
	v_mfma_f32_16x16x32_bf16 v[8:11], v[156:159], v[222:225], v[8:11]
	v_mfma_f32_16x16x32_bf16 v[60:63], v[132:135], v[184:187], v[60:63]
	v_mfma_f32_16x16x32_bf16 v[56:59], v[160:163], v[184:187], v[56:59]
	v_mfma_f32_16x16x32_bf16 v[44:47], v[132:135], v[210:213], v[44:47]
	v_mfma_f32_16x16x32_bf16 v[40:43], v[160:163], v[210:213], v[40:43]
	v_mfma_f32_16x16x32_bf16 v[28:31], v[132:135], v[218:221], v[28:31]
	v_mfma_f32_16x16x32_bf16 v[24:27], v[160:163], v[218:221], v[24:27]
	v_mfma_f32_16x16x32_bf16 v[12:15], v[132:135], v[226:229], v[12:15]
	v_mfma_f32_16x16x32_bf16 v[8:11], v[160:163], v[226:229], v[8:11]
	v_mfma_f32_16x16x32_bf16 v[52:55], v[164:167], v[180:183], v[52:55]
	v_mfma_f32_16x16x32_bf16 v[48:51], v[172:175], v[180:183], v[48:51]
	v_mfma_f32_16x16x32_bf16 v[36:39], v[164:167], v[188:191], v[36:39]
	v_mfma_f32_16x16x32_bf16 v[32:35], v[172:175], v[188:191], v[32:35]
	v_mfma_f32_16x16x32_bf16 v[20:23], v[164:167], v[214:217], v[20:23]
	v_mfma_f32_16x16x32_bf16 v[16:19], v[172:175], v[214:217], v[16:19]
	v_mfma_f32_16x16x32_bf16 v[4:7], v[164:167], v[222:225], v[4:7]
	v_mfma_f32_16x16x32_bf16 v[0:3], v[172:175], v[222:225], v[0:3]
	v_mfma_f32_16x16x32_bf16 v[52:55], v[168:171], v[184:187], v[52:55]
	v_mfma_f32_16x16x32_bf16 v[48:51], v[176:179], v[184:187], v[48:51]
	v_mfma_f32_16x16x32_bf16 v[36:39], v[168:171], v[210:213], v[36:39]
	v_mfma_f32_16x16x32_bf16 v[32:35], v[176:179], v[210:213], v[32:35]
	v_mfma_f32_16x16x32_bf16 v[20:23], v[168:171], v[218:221], v[20:23]
	v_mfma_f32_16x16x32_bf16 v[16:19], v[176:179], v[218:221], v[16:19]
	v_mfma_f32_16x16x32_bf16 v[4:7], v[168:171], v[226:229], v[4:7]
	v_mfma_f32_16x16x32_bf16 v[0:3], v[176:179], v[226:229], v[0:3]
	s_barrier
	s_add_i32 s65, s65, 2
	s_add_u32 s10, s10, 0x100
	s_addc_u32 s11, s11, 0
	s_add_u32 s55, s55, 0x100
	s_addc_u32 s57, s57, 0
	s_cmp_gt_u32 s65, 13
	s_cbranch_scc0 .LBB0_1795
	s_branch .Lmy_kdone_5
.LBB0_1795:
	ds_read_b128 v[128:131], v204
	ds_read_b128 v[132:135], v204 offset:1024
	s_waitcnt lgkmcnt(0)
	ds_read_b128 v[156:159], v204 offset:2048
	ds_read_b128 v[160:163], v204 offset:3072
	ds_read_b128 v[164:167], v205
	ds_read_b128 v[168:171], v205 offset:1024
	ds_read_b128 v[172:175], v205 offset:2048
	ds_read_b128 v[176:179], v205 offset:3072
	s_add_u32 s0, s10, 0xfffc0080
	s_addc_u32 s1, s11, -1
	s_cmp_eq_u32 s65, 12
	s_cselect_b32 s13, s9, s1
	s_cselect_b32 s12, s14, s0
	s_cselect_b32 s1, s15, s57
	s_cselect_b32 s0, s16, s55
	v_lshl_add_u64 v[192:193], s[10:11], 0, v[148:149]
	s_add_i32 m0, s31, 0xc000
	ds_read_b128 v[180:183], v206
	ds_read_b128 v[184:187], v206 offset:1024
	ds_read_b128 v[188:191], v206 offset:2048
	ds_read_b128 v[210:213], v206 offset:3072
	ds_read_b128 v[214:217], v206 offset:4096
	ds_read_b128 v[218:221], v206 offset:5120
	ds_read_b128 v[222:225], v206 offset:6144
	ds_read_b128 v[226:229], v206 offset:7168
	global_load_lds_dwordx4 v[192:193], off
	v_lshl_add_u64 v[192:193], s[10:11], 0, v[150:151]
	s_add_i32 m0, s31, 0xe000
	s_nop 0
	global_load_lds_dwordx4 v[192:193], off
	s_waitcnt vmcnt(8)
	s_waitcnt lgkmcnt(0)
	s_barrier
; #define PG8_STAGE(bufoff, gbase, voff) do { _Pragma("unroll") for (int _i = 0; _i < 2; ++_i) \
;         __builtin_amdgcn_global_load_lds((const unsigned*)((const char*)(gbase) + (voff)[_i]), (PG8_LAS unsigned*)(lds + (bufoff) + ldsw + _i * 8192), 16, 0, 0); } while (0)
; #define PG8_LDA(dst, b, h) do { _Pragma("unroll") for (int m = 0; m < 4; ++m) _Pragma("unroll") for (int k = 0; k < 2; ++k) dst[m][k] = *(const PG8_LAS bf16x8*)(lds + PG8_SA(b, h) + aoff + m * 2048 + k * 1024); } while (0)
; #define PG8_LDB(dst, b, h) do { _Pragma("unroll") for (int n = 0; n < 2; ++n) _Pragma("unroll") for (int k = 0; k < 2; ++k) dst[n][k] = *(const PG8_LAS bf16x8*)(lds + PG8_SB(b, h) + boff + n * 2048 + k * 1024); } while (0)
; #define PG8_MMA(ai, bj, At, Bt) do { __builtin_amdgcn_s_setprio(1); _Pragma("unroll") for (int m = 0; m < 4; ++m) _Pragma("unroll") for (int n = 0; n < 2; ++n) _Pragma("unroll") for (int k = 0; k < 2; ++k) \
;         acc[ai][bj][m][n] = __builtin_amdgcn_mfma_f32_16x16x32_bf16(Bt[n][k], At[m][k], acc[ai][bj][m][n], 0, 0, 0); __builtin_amdgcn_s_setprio(0); } while (0)
; #define PG8_WAIT_V(n) asm volatile("s_waitcnt vmcnt(" #n ")" ::: "memory")
; #define PG8_WAIT_L(n) asm volatile("s_waitcnt lgkmcnt(" #n ")" ::: "memory")
; #define PG8_BAR __builtin_amdgcn_s_barrier()
; #define PG8_SCHED __builtin_amdgcn_sched_barrier(0)
; template <class Epi, class Sched, bool ALIGN_EPI = false, bool SP2 = false>
; __device__ __forceinline__ void gemm_phase(PG8_LAS unsigned char* lds, const Gemm g, const Sched& S, const Epi& E, const int tid_in) {
;     ...
;             PG8_LDB(B0, 0, 0); PG8_LDB(B1, 0, 1); PG8_SCHED; PG8_LDA(At, 0, 0); PG8_STAGE(PG8_SA(1, 1), a1 + hstep, voffA);
;             PG8_WAIT_V(8); PG8_WAIT_L(0); PG8_BAR; PG8_MMA(0, 0, At, B0); PG8_MMA(0, 1, At, B1); PG8_BAR; PG8_SCHED;
;             PG8_LDA(At, 0, 1); PG8_STAGE(PG8_SB(0, 0), b2, voffB); PG8_STAGE(PG8_SB(0, 1), b2 + hstep, voffB); PG8_STAGE(PG8_SA(0, 0), a2, voffA);
;             PG8_WAIT_V(8); PG8_WAIT_L(0); PG8_BAR; PG8_MMA(1, 0, At, B0); PG8_MMA(1, 1, At, B1); PG8_BAR; PG8_SCHED;
	s_waitcnt lgkmcnt(0)
	v_mfma_f32_16x16x32_bf16 v[124:127], v[128:131], v[180:183], v[124:127]
	v_mfma_f32_16x16x32_bf16 v[120:123], v[156:159], v[180:183], v[120:123]
	v_mfma_f32_16x16x32_bf16 v[108:111], v[128:131], v[188:191], v[108:111]
	v_mfma_f32_16x16x32_bf16 v[104:107], v[156:159], v[188:191], v[104:107]
	v_mfma_f32_16x16x32_bf16 v[92:95], v[128:131], v[214:217], v[92:95]
	v_mfma_f32_16x16x32_bf16 v[88:91], v[156:159], v[214:217], v[88:91]
	v_mfma_f32_16x16x32_bf16 v[76:79], v[128:131], v[222:225], v[76:79]
	v_mfma_f32_16x16x32_bf16 v[72:75], v[156:159], v[222:225], v[72:75]
	v_mfma_f32_16x16x32_bf16 v[124:127], v[132:135], v[184:187], v[124:127]
	v_mfma_f32_16x16x32_bf16 v[120:123], v[160:163], v[184:187], v[120:123]
	v_mfma_f32_16x16x32_bf16 v[108:111], v[132:135], v[210:213], v[108:111]
	v_mfma_f32_16x16x32_bf16 v[104:107], v[160:163], v[210:213], v[104:107]
	v_mfma_f32_16x16x32_bf16 v[92:95], v[132:135], v[218:221], v[92:95]
	v_mfma_f32_16x16x32_bf16 v[88:91], v[160:163], v[218:221], v[88:91]
	v_mfma_f32_16x16x32_bf16 v[76:79], v[132:135], v[226:229], v[76:79]
	v_mfma_f32_16x16x32_bf16 v[72:75], v[160:163], v[226:229], v[72:75]
	v_mfma_f32_16x16x32_bf16 v[116:119], v[164:167], v[180:183], v[116:119]
	v_mfma_f32_16x16x32_bf16 v[112:115], v[172:175], v[180:183], v[112:115]
	v_mfma_f32_16x16x32_bf16 v[100:103], v[164:167], v[188:191], v[100:103]
	v_mfma_f32_16x16x32_bf16 v[96:99], v[172:175], v[188:191], v[96:99]
	v_mfma_f32_16x16x32_bf16 v[84:87], v[164:167], v[214:217], v[84:87]
	v_mfma_f32_16x16x32_bf16 v[80:83], v[172:175], v[214:217], v[80:83]
	v_mfma_f32_16x16x32_bf16 v[68:71], v[164:167], v[222:225], v[68:71]
	v_mfma_f32_16x16x32_bf16 v[64:67], v[172:175], v[222:225], v[64:67]
	v_mfma_f32_16x16x32_bf16 v[116:119], v[168:171], v[184:187], v[116:119]
	v_mfma_f32_16x16x32_bf16 v[112:115], v[176:179], v[184:187], v[112:115]
	v_mfma_f32_16x16x32_bf16 v[100:103], v[168:171], v[210:213], v[100:103]
	v_mfma_f32_16x16x32_bf16 v[96:99], v[176:179], v[210:213], v[96:99]
	v_mfma_f32_16x16x32_bf16 v[84:87], v[168:171], v[218:221], v[84:87]
	v_mfma_f32_16x16x32_bf16 v[80:83], v[176:179], v[218:221], v[80:83]
	v_mfma_f32_16x16x32_bf16 v[68:71], v[168:171], v[226:229], v[68:71]
	v_mfma_f32_16x16x32_bf16 v[64:67], v[176:179], v[226:229], v[64:67]
	s_barrier
	s_add_i32 s74, s49, s2
	v_lshl_add_u64 v[192:193], s[0:1], 0, v[136:137]
	s_mov_b32 m0, s74
	ds_read_b128 v[180:183], v206 offset:16384
	ds_read_b128 v[184:187], v206 offset:17408
	ds_read_b128 v[188:191], v206 offset:18432
	ds_read_b128 v[210:213], v206 offset:19456
	ds_read_b128 v[214:217], v206 offset:20480
	ds_read_b128 v[218:221], v206 offset:21504
	ds_read_b128 v[222:225], v206 offset:22528
	ds_read_b128 v[226:229], v206 offset:23552
	global_load_lds_dwordx4 v[192:193], off
	s_add_i32 m0, s74, 0x2000
	s_add_u32 s74, s0, 0x40000
	v_lshl_add_u64 v[230:231], s[0:1], 0, v[138:139]
	s_addc_u32 s75, s1, 0
	s_add_i32 s76, s50, s2
	global_load_lds_dwordx4 v[230:231], off
	v_lshl_add_u64 v[232:233], s[74:75], 0, v[136:137]
	s_mov_b32 m0, s76
	v_lshl_add_u64 v[234:235], s[12:13], 0, v[138:139]
	global_load_lds_dwordx4 v[232:233], off
	v_lshl_add_u64 v[232:233], s[74:75], 0, v[138:139]
	s_add_i32 m0, s76, 0x2000
	s_nop 0
	global_load_lds_dwordx4 v[232:233], off
	v_lshl_add_u64 v[232:233], s[12:13], 0, v[136:137]
	s_mov_b32 m0, s31
	s_nop 0
	global_load_lds_dwordx4 v[232:233], off
	s_mov_b32 m0, s34
	s_nop 0
	global_load_lds_dwordx4 v[234:235], off
	s_waitcnt vmcnt(8)
	s_waitcnt lgkmcnt(0)
	s_barrier
	s_waitcnt lgkmcnt(0)
	v_mfma_f32_16x16x32_bf16 v[60:63], v[128:131], v[180:183], v[60:63]
	v_mfma_f32_16x16x32_bf16 v[56:59], v[156:159], v[180:183], v[56:59]
	v_mfma_f32_16x16x32_bf16 v[44:47], v[128:131], v[188:191], v[44:47]
	v_mfma_f32_16x16x32_bf16 v[40:43], v[156:159], v[188:191], v[40:43]
	v_mfma_f32_16x16x32_bf16 v[28:31], v[128:131], v[214:217], v[28:31]
	v_mfma_f32_16x16x32_bf16 v[24:27], v[156:159], v[214:217], v[24:27]
	v_mfma_f32_16x16x32_bf16 v[12:15], v[128:131], v[222:225], v[12:15]
	v_mfma_f32_16x16x32_bf16 v[8:11], v[156:159], v[222:225], v[8:11]
	v_mfma_f32_16x16x32_bf16 v[60:63], v[132:135], v[184:187], v[60:63]
	v_mfma_f32_16x16x32_bf16 v[56:59], v[160:163], v[184:187], v[56:59]
	v_mfma_f32_16x16x32_bf16 v[44:47], v[132:135], v[210:213], v[44:47]
	v_mfma_f32_16x16x32_bf16 v[40:43], v[160:163], v[210:213], v[40:43]
	v_mfma_f32_16x16x32_bf16 v[28:31], v[132:135], v[218:221], v[28:31]
	v_mfma_f32_16x16x32_bf16 v[24:27], v[160:163], v[218:221], v[24:27]
	v_mfma_f32_16x16x32_bf16 v[12:15], v[132:135], v[226:229], v[12:15]
	v_mfma_f32_16x16x32_bf16 v[8:11], v[160:163], v[226:229], v[8:11]
	v_mfma_f32_16x16x32_bf16 v[52:55], v[164:167], v[180:183], v[52:55]
	v_mfma_f32_16x16x32_bf16 v[48:51], v[172:175], v[180:183], v[48:51]
	v_mfma_f32_16x16x32_bf16 v[36:39], v[164:167], v[188:191], v[36:39]
	v_mfma_f32_16x16x32_bf16 v[32:35], v[172:175], v[188:191], v[32:35]
	v_mfma_f32_16x16x32_bf16 v[20:23], v[164:167], v[214:217], v[20:23]
	v_mfma_f32_16x16x32_bf16 v[16:19], v[172:175], v[214:217], v[16:19]
	v_mfma_f32_16x16x32_bf16 v[4:7], v[164:167], v[222:225], v[4:7]
	v_mfma_f32_16x16x32_bf16 v[0:3], v[172:175], v[222:225], v[0:3]
	v_mfma_f32_16x16x32_bf16 v[52:55], v[168:171], v[184:187], v[52:55]
	v_mfma_f32_16x16x32_bf16 v[48:51], v[176:179], v[184:187], v[48:51]
	v_mfma_f32_16x16x32_bf16 v[36:39], v[168:171], v[210:213], v[36:39]
	v_mfma_f32_16x16x32_bf16 v[32:35], v[176:179], v[210:213], v[32:35]
	v_mfma_f32_16x16x32_bf16 v[20:23], v[168:171], v[218:221], v[20:23]
	v_mfma_f32_16x16x32_bf16 v[16:19], v[176:179], v[218:221], v[16:19]
	v_mfma_f32_16x16x32_bf16 v[4:7], v[168:171], v[226:229], v[4:7]
	v_mfma_f32_16x16x32_bf16 v[0:3], v[176:179], v[226:229], v[0:3]
	s_barrier
; #define PG8_STAGE(bufoff, gbase, voff) do { _Pragma("unroll") for (int _i = 0; _i < 2; ++_i) \
;         __builtin_amdgcn_global_load_lds((const unsigned*)((const char*)(gbase) + (voff)[_i]), (PG8_LAS unsigned*)(lds + (bufoff) + ldsw + _i * 8192), 16, 0, 0); } while (0)
; #define PG8_LDA(dst, b, h) do { _Pragma("unroll") for (int m = 0; m < 4; ++m) _Pragma("unroll") for (int k = 0; k < 2; ++k) dst[m][k] = *(const PG8_LAS bf16x8*)(lds + PG8_SA(b, h) + aoff + m * 2048 + k * 1024); } while (0)
; #define PG8_LDB(dst, b, h) do { _Pragma("unroll") for (int n = 0; n < 2; ++n) _Pragma("unroll") for (int k = 0; k < 2; ++k) dst[n][k] = *(const PG8_LAS bf16x8*)(lds + PG8_SB(b, h) + boff + n * 2048 + k * 1024); } while (0)
; #define PG8_MMA(ai, bj, At, Bt) do { __builtin_amdgcn_s_setprio(1); _Pragma("unroll") for (int m = 0; m < 4; ++m) _Pragma("unroll") for (int n = 0; n < 2; ++n) _Pragma("unroll") for (int k = 0; k < 2; ++k) \
;         acc[ai][bj][m][n] = __builtin_amdgcn_mfma_f32_16x16x32_bf16(Bt[n][k], At[m][k], acc[ai][bj][m][n], 0, 0, 0); __builtin_amdgcn_s_setprio(0); } while (0)
; #define PG8_WAIT_V(n) asm volatile("s_waitcnt vmcnt(" #n ")" ::: "memory")
; #define PG8_WAIT_L(n) asm volatile("s_waitcnt lgkmcnt(" #n ")" ::: "memory")
; #define PG8_BAR __builtin_amdgcn_s_barrier()
; #define PG8_SCHED __builtin_amdgcn_sched_barrier(0)
; template <class Epi, class Sched, bool ALIGN_EPI = false, bool SP2 = false>
; __device__ __forceinline__ void gemm_phase(PG8_LAS unsigned char* lds, const Gemm g, const Sched& S, const Epi& E, const int tid_in) {
;     ...
;             PG8_LDB(B0, 1, 0); PG8_LDB(B1, 1, 1); PG8_SCHED; PG8_LDA(At, 1, 0); PG8_STAGE(PG8_SA(0, 1), a2 + hstep, voffA);
;             PG8_WAIT_V(8); PG8_WAIT_L(0); PG8_BAR; PG8_MMA(0, 0, At, B0); PG8_MMA(0, 1, At, B1); PG8_BAR; PG8_SCHED;
;             PG8_LDA(At, 1, 1); PG8_STAGE(PG8_SB(1, 0), b3, voffB); PG8_STAGE(PG8_SB(1, 1), b3 + hstep, voffB); PG8_STAGE(PG8_SA(1, 0), a3, voffA);
;             PG8_WAIT_V(8); PG8_WAIT_L(0); PG8_BAR; PG8_MMA(1, 0, At, B0); PG8_MMA(1, 1, At, B1); PG8_BAR; PG8_SCHED;
	s_add_i32 s74, 0, 0x18000
	v_add_u32_e32 v140, s74, v195
	s_add_i32 s75, 0, 0x1c000
	ds_read_b128 v[128:131], v140
	ds_read_b128 v[132:135], v140 offset:1024
	ds_read_b128 v[156:159], v140 offset:2048
	ds_read_b128 v[160:163], v140 offset:3072
	v_add_u32_e32 v140, s75, v195
	ds_read_b128 v[164:167], v140
	ds_read_b128 v[168:171], v140 offset:1024
	ds_read_b128 v[172:175], v140 offset:2048
	ds_read_b128 v[176:179], v140 offset:3072
	s_add_u32 s12, s12, 0x40000
	s_addc_u32 s13, s13, 0
	s_mov_b32 m0, s35
	v_lshl_add_u64 v[236:237], s[12:13], 0, v[136:137]
	ds_read_b128 v[180:183], v206 offset:32768
	ds_read_b128 v[184:187], v206 offset:33792
	ds_read_b128 v[188:191], v206 offset:34816
	ds_read_b128 v[210:213], v206 offset:35840
	ds_read_b128 v[214:217], v206 offset:36864
	ds_read_b128 v[218:221], v206 offset:37888
	ds_read_b128 v[222:225], v206 offset:38912
	ds_read_b128 v[226:229], v206 offset:39936
	global_load_lds_dwordx4 v[236:237], off
	v_lshl_add_u64 v[236:237], s[12:13], 0, v[138:139]
	s_mov_b32 m0, s36
	s_nop 0
	global_load_lds_dwordx4 v[236:237], off
	s_waitcnt vmcnt(8)
	s_waitcnt lgkmcnt(0)
	s_barrier
	s_waitcnt lgkmcnt(0)
	v_mfma_f32_16x16x32_bf16 v[124:127], v[128:131], v[180:183], v[124:127]
	v_mfma_f32_16x16x32_bf16 v[120:123], v[156:159], v[180:183], v[120:123]
	v_mfma_f32_16x16x32_bf16 v[108:111], v[128:131], v[188:191], v[108:111]
	v_mfma_f32_16x16x32_bf16 v[104:107], v[156:159], v[188:191], v[104:107]
	v_mfma_f32_16x16x32_bf16 v[92:95], v[128:131], v[214:217], v[92:95]
	v_mfma_f32_16x16x32_bf16 v[88:91], v[156:159], v[214:217], v[88:91]
	v_mfma_f32_16x16x32_bf16 v[76:79], v[128:131], v[222:225], v[76:79]
	v_mfma_f32_16x16x32_bf16 v[72:75], v[156:159], v[222:225], v[72:75]
	v_mfma_f32_16x16x32_bf16 v[124:127], v[132:135], v[184:187], v[124:127]
	v_mfma_f32_16x16x32_bf16 v[120:123], v[160:163], v[184:187], v[120:123]
	v_mfma_f32_16x16x32_bf16 v[108:111], v[132:135], v[210:213], v[108:111]
	v_mfma_f32_16x16x32_bf16 v[104:107], v[160:163], v[210:213], v[104:107]
	v_mfma_f32_16x16x32_bf16 v[92:95], v[132:135], v[218:221], v[92:95]
	v_mfma_f32_16x16x32_bf16 v[88:91], v[160:163], v[218:221], v[88:91]
	v_mfma_f32_16x16x32_bf16 v[76:79], v[132:135], v[226:229], v[76:79]
	v_mfma_f32_16x16x32_bf16 v[72:75], v[160:163], v[226:229], v[72:75]
	v_mfma_f32_16x16x32_bf16 v[116:119], v[164:167], v[180:183], v[116:119]
	v_mfma_f32_16x16x32_bf16 v[112:115], v[172:175], v[180:183], v[112:115]
	v_mfma_f32_16x16x32_bf16 v[100:103], v[164:167], v[188:191], v[100:103]
	v_mfma_f32_16x16x32_bf16 v[96:99], v[172:175], v[188:191], v[96:99]
	v_mfma_f32_16x16x32_bf16 v[84:87], v[164:167], v[214:217], v[84:87]
	v_mfma_f32_16x16x32_bf16 v[80:83], v[172:175], v[214:217], v[80:83]
	v_mfma_f32_16x16x32_bf16 v[68:71], v[164:167], v[222:225], v[68:71]
	v_mfma_f32_16x16x32_bf16 v[64:67], v[172:175], v[222:225], v[64:67]
	v_mfma_f32_16x16x32_bf16 v[116:119], v[168:171], v[184:187], v[116:119]
	v_mfma_f32_16x16x32_bf16 v[112:115], v[176:179], v[184:187], v[112:115]
	v_mfma_f32_16x16x32_bf16 v[100:103], v[168:171], v[210:213], v[100:103]
	v_mfma_f32_16x16x32_bf16 v[96:99], v[176:179], v[210:213], v[96:99]
	v_mfma_f32_16x16x32_bf16 v[84:87], v[168:171], v[218:221], v[84:87]
	v_mfma_f32_16x16x32_bf16 v[80:83], v[176:179], v[218:221], v[80:83]
	v_mfma_f32_16x16x32_bf16 v[68:71], v[168:171], v[226:229], v[68:71]
	v_mfma_f32_16x16x32_bf16 v[64:67], v[176:179], v[226:229], v[64:67]
	s_barrier
	s_add_i32 s12, s74, s2
	v_lshl_add_u64 v[192:193], v[192:193], 0, s[26:27]
	s_mov_b32 m0, s12
	ds_read_b128 v[180:183], v206 offset:49152
	ds_read_b128 v[184:187], v206 offset:50176
	ds_read_b128 v[188:191], v206 offset:51200
	ds_read_b128 v[210:213], v206 offset:52224
	ds_read_b128 v[214:217], v206 offset:53248
	ds_read_b128 v[218:221], v206 offset:54272
	ds_read_b128 v[222:225], v206 offset:55296
	ds_read_b128 v[226:229], v206 offset:56320
	global_load_lds_dwordx4 v[192:193], off
	s_add_i32 m0, s12, 0x2000
	s_add_u32 s0, s0, 0x40080
	v_lshl_add_u64 v[192:193], v[230:231], 0, s[26:27]
	s_addc_u32 s1, s1, 0
	s_add_i32 s12, s75, s2
	global_load_lds_dwordx4 v[192:193], off
	v_lshl_add_u64 v[192:193], s[0:1], 0, v[136:137]
	s_mov_b32 m0, s12
	s_nop 0
	global_load_lds_dwordx4 v[192:193], off
	v_lshl_add_u64 v[192:193], s[0:1], 0, v[138:139]
	s_add_i32 m0, s12, 0x2000
	s_nop 0
	global_load_lds_dwordx4 v[192:193], off
	v_lshl_add_u64 v[192:193], v[232:233], 0, s[26:27]
	s_mov_b32 m0, s96
	s_nop 0
	global_load_lds_dwordx4 v[192:193], off
	v_lshl_add_u64 v[192:193], v[234:235], 0, s[26:27]
	s_mov_b32 m0, s97
	s_nop 0
	global_load_lds_dwordx4 v[192:193], off
	s_waitcnt vmcnt(8)
	s_waitcnt lgkmcnt(0)
	s_barrier
	s_waitcnt lgkmcnt(0)
	v_mfma_f32_16x16x32_bf16 v[60:63], v[128:131], v[180:183], v[60:63]
	v_mfma_f32_16x16x32_bf16 v[56:59], v[156:159], v[180:183], v[56:59]
	v_mfma_f32_16x16x32_bf16 v[44:47], v[128:131], v[188:191], v[44:47]
	v_mfma_f32_16x16x32_bf16 v[40:43], v[156:159], v[188:191], v[40:43]
	v_mfma_f32_16x16x32_bf16 v[28:31], v[128:131], v[214:217], v[28:31]
	v_mfma_f32_16x16x32_bf16 v[24:27], v[156:159], v[214:217], v[24:27]
	v_mfma_f32_16x16x32_bf16 v[12:15], v[128:131], v[222:225], v[12:15]
	v_mfma_f32_16x16x32_bf16 v[8:11], v[156:159], v[222:225], v[8:11]
	v_mfma_f32_16x16x32_bf16 v[60:63], v[132:135], v[184:187], v[60:63]
	v_mfma_f32_16x16x32_bf16 v[56:59], v[160:163], v[184:187], v[56:59]
	v_mfma_f32_16x16x32_bf16 v[44:47], v[132:135], v[210:213], v[44:47]
	v_mfma_f32_16x16x32_bf16 v[40:43], v[160:163], v[210:213], v[40:43]
	v_mfma_f32_16x16x32_bf16 v[28:31], v[132:135], v[218:221], v[28:31]
	v_mfma_f32_16x16x32_bf16 v[24:27], v[160:163], v[218:221], v[24:27]
	v_mfma_f32_16x16x32_bf16 v[12:15], v[132:135], v[226:229], v[12:15]
	v_mfma_f32_16x16x32_bf16 v[8:11], v[160:163], v[226:229], v[8:11]
	v_mfma_f32_16x16x32_bf16 v[52:55], v[164:167], v[180:183], v[52:55]
	v_mfma_f32_16x16x32_bf16 v[48:51], v[172:175], v[180:183], v[48:51]
	v_mfma_f32_16x16x32_bf16 v[36:39], v[164:167], v[188:191], v[36:39]
	v_mfma_f32_16x16x32_bf16 v[32:35], v[172:175], v[188:191], v[32:35]
	v_mfma_f32_16x16x32_bf16 v[20:23], v[164:167], v[214:217], v[20:23]
	v_mfma_f32_16x16x32_bf16 v[16:19], v[172:175], v[214:217], v[16:19]
	v_mfma_f32_16x16x32_bf16 v[4:7], v[164:167], v[222:225], v[4:7]
	v_mfma_f32_16x16x32_bf16 v[0:3], v[172:175], v[222:225], v[0:3]
	v_mfma_f32_16x16x32_bf16 v[52:55], v[168:171], v[184:187], v[52:55]
	v_mfma_f32_16x16x32_bf16 v[48:51], v[176:179], v[184:187], v[48:51]
	v_mfma_f32_16x16x32_bf16 v[36:39], v[168:171], v[210:213], v[36:39]
	v_mfma_f32_16x16x32_bf16 v[32:35], v[176:179], v[210:213], v[32:35]
	v_mfma_f32_16x16x32_bf16 v[20:23], v[168:171], v[218:221], v[20:23]
	v_mfma_f32_16x16x32_bf16 v[16:19], v[176:179], v[218:221], v[16:19]
	v_mfma_f32_16x16x32_bf16 v[4:7], v[168:171], v[226:229], v[4:7]
	v_mfma_f32_16x16x32_bf16 v[0:3], v[176:179], v[226:229], v[0:3]
	s_barrier
	s_add_i32 s65, s65, 2
	s_add_u32 s10, s10, 0x100
	s_addc_u32 s11, s11, 0
	s_add_u32 s55, s55, 0x100
	s_addc_u32 s57, s57, 0
	s_cmp_gt_u32 s65, 13
	s_cbranch_scc0 .LBB0_1795

; #define PG8_STAGE(bufoff, gbase, voff) do { _Pragma("unroll") for (int _i = 0; _i < 2; ++_i) \
;         __builtin_amdgcn_global_load_lds((const unsigned*)((const char*)(gbase) + (voff)[_i]), (PG8_LAS unsigned*)(lds + (bufoff) + ldsw + _i * 8192), 16, 0, 0); } while (0)
; #define PG8_LDA(dst, b, h) do { _Pragma("unroll") for (int m = 0; m < 4; ++m) _Pragma("unroll") for (int k = 0; k < 2; ++k) dst[m][k] = *(const PG8_LAS bf16x8*)(lds + PG8_SA(b, h) + aoff + m * 2048 + k * 1024); } while (0)
; #define PG8_LDB(dst, b, h) do { _Pragma("unroll") for (int n = 0; n < 2; ++n) _Pragma("unroll") for (int k = 0; k < 2; ++k) dst[n][k] = *(const PG8_LAS bf16x8*)(lds + PG8_SB(b, h) + boff + n * 2048 + k * 1024); } while (0)
; #define PG8_WAIT_V(n) asm volatile("s_waitcnt vmcnt(" #n ")" ::: "memory")
; #define PG8_WAIT_L(n) asm volatile("s_waitcnt lgkmcnt(" #n ")" ::: "memory")
; #define PG8_BAR __builtin_amdgcn_s_barrier()
; #define PG8_SCHED __builtin_amdgcn_sched_barrier(0)
; template <class Epi, class Sched, bool ALIGN_EPI = false, bool SP2 = false>
; __device__ __forceinline__ void gemm_phase(PG8_LAS unsigned char* lds, const Gemm g, const Sched& S, const Epi& E, const int tid_in) {
;     ...
;         const char* nA = has_next ? (const char*)g.A + (size_t)nxt.pm * tstep : cA; const char* nB = has_next ? (const char*)g.Bt + (size_t)nxt.pn * tstep : cB;
;         for (int t = 0; t < nt; t += 2) {
;             const bool last = (t == nt - 2);
;             const char* a1 = cA + (size_t)(t + 1) * kstep;
;             const char* a2 = last ? nA : cA + (size_t)(t + 2) * kstep; const char* b2 = last ? nB : cB + (size_t)(t + 2) * kstep;
;             const char* a3 = a2 + kstep; const char* b3 = b2 + kstep;
;             if (last && has_next) S.a_ready(nxt);
;             if constexpr (SP2) {
;             PG8_LDB(B0, 0, 0); PG8_LDB(B1, 0, 1); PG8_SCHED; PG8_LDA(At, 0, 0); PG8_STAGE(PG8_SA(1, 1), a1 + hstep, voffA);
;             PG8_WAIT_V(8); PG8_WAIT_L(0); PG8_BAR; PG8_MMA(0, 0, At, B0); PG8_MMA(0, 1, At, B1); PG8_BAR; PG8_SCHED;
;             PG8_LDA(At, 0, 1); PG8_STAGE(PG8_SB(0, 0), b2, voffB); PG8_STAGE(PG8_SB(0, 1), b2 + hstep, voffB); PG8_STAGE(PG8_SA(0, 0), a2, voffA);
;             PG8_WAIT_V(8); PG8_WAIT_L(0); PG8_BAR; PG8_MMA(1, 0, At, B0); PG8_MMA(1, 1, At, B1); PG8_BAR; PG8_SCHED;
.LBB0_2953:
	s_ashr_i32 s55, s54, 31
	s_lshl_b64 s[56:57], s[54:55], 19
	s_add_u32 s56, s16, s56
	s_addc_u32 s57, s17, s57
	s_and_b64 s[58:59], s[8:9], exec
	s_cselect_b32 s55, s57, s63
	s_cselect_b32 s61, s56, s62
	s_ashr_i32 s53, s52, 31
	s_lshl_b64 s[58:59], s[52:53], 19
	s_add_u32 s58, s10, s58
	s_addc_u32 s59, s11, s59
	s_and_b64 s[64:65], s[8:9], exec
	s_cselect_b32 s53, s59, s1
	s_cselect_b32 s74, s58, s0
	s_add_u32 s62, s62, 0x40080
	s_addc_u32 s63, s63, 0
	s_add_u32 s75, s0, 0x100
	v_mov_b32_e32 v0, 0
	s_addc_u32 s76, s1, 0
	s_mov_b32 s77, -2
	ds_read_b128 v[92:95], v207
	ds_read_b128 v[100:103], v207 offset:1024
	ds_read_b128 v[112:115], v207 offset:2048
	ds_read_b128 v[124:127], v207 offset:3072
	ds_read_b128 v[136:139], v208
	ds_read_b128 v[148:151], v208 offset:1024
	ds_read_b128 v[152:155], v208 offset:2048
	ds_read_b128 v[156:159], v208 offset:3072
	s_add_u32 s0, s62, 0xfffc0080
	s_addc_u32 s1, s63, -1
	s_cmp_eq_u32 s77, 12
	s_cselect_b32 s65, s55, s1
	s_cselect_b32 s64, s61, s0
	s_cselect_b32 s1, s53, s76
	s_cselect_b32 s0, s74, s75
	v_lshl_add_u64 v[214:215], s[62:63], 0, v[192:193]
	s_add_i32 m0, s4, 0xc000
	ds_read_b128 v[160:163], v209
	ds_read_b128 v[164:167], v209 offset:1024
	ds_read_b128 v[168:171], v209 offset:2048
	ds_read_b128 v[172:175], v209 offset:3072
	ds_read_b128 v[176:179], v209 offset:4096
	ds_read_b128 v[180:183], v209 offset:5120
	ds_read_b128 v[200:203], v209 offset:6144
	ds_read_b128 v[210:213], v209 offset:7168
	global_load_lds_dwordx4 v[214:215], off
	v_lshl_add_u64 v[214:215], s[62:63], 0, v[194:195]
	s_add_i32 m0, s4, 0xe000
	s_nop 0
	global_load_lds_dwordx4 v[214:215], off
	s_waitcnt vmcnt(8)
	s_waitcnt lgkmcnt(0)
	s_barrier
	s_waitcnt lgkmcnt(0)
	v_mfma_f32_16x16x32_bf16 v[144:147], v[92:95], v[160:163], 0
	v_mfma_f32_16x16x32_bf16 v[140:143], v[112:115], v[160:163], 0
	v_mfma_f32_16x16x32_bf16 v[120:123], v[92:95], v[168:171], 0
	v_mfma_f32_16x16x32_bf16 v[116:119], v[112:115], v[168:171], 0
	v_mfma_f32_16x16x32_bf16 v[96:99], v[92:95], v[176:179], 0
	v_mfma_f32_16x16x32_bf16 v[88:91], v[112:115], v[176:179], 0
	v_mfma_f32_16x16x32_bf16 v[76:79], v[92:95], v[200:203], 0
	v_mfma_f32_16x16x32_bf16 v[72:75], v[112:115], v[200:203], 0
	v_mfma_f32_16x16x32_bf16 v[144:147], v[100:103], v[164:167], v[144:147]
	v_mfma_f32_16x16x32_bf16 v[140:143], v[124:127], v[164:167], v[140:143]
	v_mfma_f32_16x16x32_bf16 v[120:123], v[100:103], v[172:175], v[120:123]
	v_mfma_f32_16x16x32_bf16 v[116:119], v[124:127], v[172:175], v[116:119]
	v_mfma_f32_16x16x32_bf16 v[96:99], v[100:103], v[180:183], v[96:99]
	v_mfma_f32_16x16x32_bf16 v[88:91], v[124:127], v[180:183], v[88:91]
	v_mfma_f32_16x16x32_bf16 v[76:79], v[100:103], v[210:213], v[76:79]
	v_mfma_f32_16x16x32_bf16 v[72:75], v[124:127], v[210:213], v[72:75]
	v_mfma_f32_16x16x32_bf16 v[132:135], v[136:139], v[160:163], 0
	v_mfma_f32_16x16x32_bf16 v[128:131], v[152:155], v[160:163], 0
	v_mfma_f32_16x16x32_bf16 v[108:111], v[136:139], v[168:171], 0
	v_mfma_f32_16x16x32_bf16 v[104:107], v[152:155], v[168:171], 0
	v_mfma_f32_16x16x32_bf16 v[84:87], v[136:139], v[176:179], 0
	v_mfma_f32_16x16x32_bf16 v[80:83], v[152:155], v[176:179], 0
	v_mfma_f32_16x16x32_bf16 v[68:71], v[136:139], v[200:203], 0
	v_mfma_f32_16x16x32_bf16 v[64:67], v[152:155], v[200:203], 0
	v_mfma_f32_16x16x32_bf16 v[132:135], v[148:151], v[164:167], v[132:135]
	v_mfma_f32_16x16x32_bf16 v[128:131], v[156:159], v[164:167], v[128:131]
	v_mfma_f32_16x16x32_bf16 v[108:111], v[148:151], v[172:175], v[108:111]
	v_mfma_f32_16x16x32_bf16 v[104:107], v[156:159], v[172:175], v[104:107]
	v_mfma_f32_16x16x32_bf16 v[84:87], v[148:151], v[180:183], v[84:87]
	v_mfma_f32_16x16x32_bf16 v[80:83], v[156:159], v[180:183], v[80:83]
	v_mfma_f32_16x16x32_bf16 v[68:71], v[148:151], v[210:213], v[68:71]
	v_mfma_f32_16x16x32_bf16 v[64:67], v[156:159], v[210:213], v[64:67]
	s_barrier
	s_add_i32 s78, s3, s2
	v_lshl_add_u64 v[214:215], s[0:1], 0, v[186:187]
	s_mov_b32 m0, s78
	ds_read_b128 v[160:163], v209 offset:16384
	ds_read_b128 v[164:167], v209 offset:17408
	ds_read_b128 v[168:171], v209 offset:18432
	ds_read_b128 v[172:175], v209 offset:19456
	ds_read_b128 v[176:179], v209 offset:20480
	ds_read_b128 v[180:183], v209 offset:21504
	ds_read_b128 v[200:203], v209 offset:22528
	ds_read_b128 v[210:213], v209 offset:23552
	global_load_lds_dwordx4 v[214:215], off
	s_add_i32 m0, s78, 0x2000
	s_add_u32 s78, s0, 0x40000
	v_lshl_add_u64 v[216:217], s[0:1], 0, v[190:191]
	s_addc_u32 s79, s1, 0
	s_add_i32 s80, s41, s2
	global_load_lds_dwordx4 v[216:217], off
	v_lshl_add_u64 v[218:219], s[78:79], 0, v[186:187]
	s_mov_b32 m0, s80
	v_lshl_add_u64 v[220:221], s[64:65], 0, v[188:189]
	global_load_lds_dwordx4 v[218:219], off
	v_lshl_add_u64 v[218:219], s[78:79], 0, v[190:191]
	s_add_i32 m0, s80, 0x2000
	s_nop 0
	global_load_lds_dwordx4 v[218:219], off
	v_lshl_add_u64 v[218:219], s[64:65], 0, v[184:185]
	s_mov_b32 m0, s4
	s_nop 0
	global_load_lds_dwordx4 v[218:219], off
	s_mov_b32 m0, s5
	s_nop 0
	global_load_lds_dwordx4 v[220:221], off
	s_waitcnt vmcnt(8)
	s_waitcnt lgkmcnt(0)
	s_barrier
; #define PG8_STAGE(bufoff, gbase, voff) do { _Pragma("unroll") for (int _i = 0; _i < 2; ++_i) \
;         __builtin_amdgcn_global_load_lds((const unsigned*)((const char*)(gbase) + (voff)[_i]), (PG8_LAS unsigned*)(lds + (bufoff) + ldsw + _i * 8192), 16, 0, 0); } while (0)
; #define PG8_LDA(dst, b, h) do { _Pragma("unroll") for (int m = 0; m < 4; ++m) _Pragma("unroll") for (int k = 0; k < 2; ++k) dst[m][k] = *(const PG8_LAS bf16x8*)(lds + PG8_SA(b, h) + aoff + m * 2048 + k * 1024); } while (0)
; #define PG8_LDB(dst, b, h) do { _Pragma("unroll") for (int n = 0; n < 2; ++n) _Pragma("unroll") for (int k = 0; k < 2; ++k) dst[n][k] = *(const PG8_LAS bf16x8*)(lds + PG8_SB(b, h) + boff + n * 2048 + k * 1024); } while (0)
; #define PG8_MMA(ai, bj, At, Bt) do { __builtin_amdgcn_s_setprio(1); _Pragma("unroll") for (int m = 0; m < 4; ++m) _Pragma("unroll") for (int n = 0; n < 2; ++n) _Pragma("unroll") for (int k = 0; k < 2; ++k) \
;         acc[ai][bj][m][n] = __builtin_amdgcn_mfma_f32_16x16x32_bf16(Bt[n][k], At[m][k], acc[ai][bj][m][n], 0, 0, 0); __builtin_amdgcn_s_setprio(0); } while (0)
; #define PG8_WAIT_V(n) asm volatile("s_waitcnt vmcnt(" #n ")" ::: "memory")
; #define PG8_WAIT_L(n) asm volatile("s_waitcnt lgkmcnt(" #n ")" ::: "memory")
; #define PG8_BAR __builtin_amdgcn_s_barrier()
; #define PG8_SCHED __builtin_amdgcn_sched_barrier(0)
; template <class Epi, class Sched, bool ALIGN_EPI = false, bool SP2 = false>
; __device__ __forceinline__ void gemm_phase(PG8_LAS unsigned char* lds, const Gemm g, const Sched& S, const Epi& E, const int tid_in) {
;     ...
;             PG8_WAIT_V(8); PG8_WAIT_L(0); PG8_BAR; PG8_MMA(0, 0, At, B0); PG8_MMA(0, 1, At, B1); PG8_BAR; PG8_SCHED;
;             PG8_LDA(At, 0, 1); PG8_STAGE(PG8_SB(0, 0), b2, voffB); PG8_STAGE(PG8_SB(0, 1), b2 + hstep, voffB); PG8_STAGE(PG8_SA(0, 0), a2, voffA);
;             PG8_WAIT_V(8); PG8_WAIT_L(0); PG8_BAR; PG8_MMA(1, 0, At, B0); PG8_MMA(1, 1, At, B1); PG8_BAR; PG8_SCHED;
;             PG8_LDB(B0, 1, 0); PG8_LDB(B1, 1, 1); PG8_SCHED; PG8_LDA(At, 1, 0); PG8_STAGE(PG8_SA(0, 1), a2 + hstep, voffA);
;             PG8_WAIT_V(8); PG8_WAIT_L(0); PG8_BAR; PG8_MMA(0, 0, At, B0); PG8_MMA(0, 1, At, B1); PG8_BAR; PG8_SCHED;
	s_waitcnt lgkmcnt(0)
	v_mfma_f32_16x16x32_bf16 v[60:63], v[92:95], v[160:163], 0
	v_mfma_f32_16x16x32_bf16 v[56:59], v[112:115], v[160:163], 0
	v_mfma_f32_16x16x32_bf16 v[44:47], v[92:95], v[168:171], 0
	v_mfma_f32_16x16x32_bf16 v[40:43], v[112:115], v[168:171], 0
	v_mfma_f32_16x16x32_bf16 v[28:31], v[92:95], v[176:179], 0
	v_mfma_f32_16x16x32_bf16 v[24:27], v[112:115], v[176:179], 0
	v_mfma_f32_16x16x32_bf16 v[12:15], v[92:95], v[200:203], 0
	v_mfma_f32_16x16x32_bf16 v[8:11], v[112:115], v[200:203], 0
	v_mfma_f32_16x16x32_bf16 v[60:63], v[100:103], v[164:167], v[60:63]
	v_mfma_f32_16x16x32_bf16 v[56:59], v[124:127], v[164:167], v[56:59]
	v_mfma_f32_16x16x32_bf16 v[44:47], v[100:103], v[172:175], v[44:47]
	v_mfma_f32_16x16x32_bf16 v[40:43], v[124:127], v[172:175], v[40:43]
	v_mfma_f32_16x16x32_bf16 v[28:31], v[100:103], v[180:183], v[28:31]
	v_mfma_f32_16x16x32_bf16 v[24:27], v[124:127], v[180:183], v[24:27]
	v_mfma_f32_16x16x32_bf16 v[12:15], v[100:103], v[210:213], v[12:15]
	v_mfma_f32_16x16x32_bf16 v[8:11], v[124:127], v[210:213], v[8:11]
	v_mfma_f32_16x16x32_bf16 v[52:55], v[136:139], v[160:163], 0
	v_mfma_f32_16x16x32_bf16 v[48:51], v[152:155], v[160:163], 0
	v_mfma_f32_16x16x32_bf16 v[36:39], v[136:139], v[168:171], 0
	v_mfma_f32_16x16x32_bf16 v[32:35], v[152:155], v[168:171], 0
	v_mfma_f32_16x16x32_bf16 v[20:23], v[136:139], v[176:179], 0
	v_mfma_f32_16x16x32_bf16 v[16:19], v[152:155], v[176:179], 0
	v_mfma_f32_16x16x32_bf16 v[4:7], v[136:139], v[200:203], 0
	v_mfma_f32_16x16x32_bf16 v[0:3], v[152:155], v[200:203], 0
	v_mfma_f32_16x16x32_bf16 v[52:55], v[148:151], v[164:167], v[52:55]
	v_mfma_f32_16x16x32_bf16 v[48:51], v[156:159], v[164:167], v[48:51]
	v_mfma_f32_16x16x32_bf16 v[36:39], v[148:151], v[172:175], v[36:39]
	v_mfma_f32_16x16x32_bf16 v[32:35], v[156:159], v[172:175], v[32:35]
	v_mfma_f32_16x16x32_bf16 v[20:23], v[148:151], v[180:183], v[20:23]
	v_mfma_f32_16x16x32_bf16 v[16:19], v[156:159], v[180:183], v[16:19]
	v_mfma_f32_16x16x32_bf16 v[4:7], v[148:151], v[210:213], v[4:7]
	v_mfma_f32_16x16x32_bf16 v[0:3], v[156:159], v[210:213], v[0:3]
	s_barrier
	s_add_i32 s78, 0, 0x18000
	s_add_i32 s79, 0, 0x1c000
	v_add_u32_e32 v124, s78, v205
	v_add_u32_e32 v156, s79, v205
	ds_read_b128 v[92:95], v124
	ds_read_b128 v[100:103], v124 offset:1024
	ds_read_b128 v[112:115], v124 offset:2048
	ds_read_b128 v[124:127], v124 offset:3072
	ds_read_b128 v[136:139], v156
	ds_read_b128 v[148:151], v156 offset:1024
	ds_read_b128 v[152:155], v156 offset:2048
	ds_read_b128 v[156:159], v156 offset:3072
	s_add_u32 s64, s64, 0x40000
	s_addc_u32 s65, s65, 0
	s_mov_b32 m0, s30
	v_lshl_add_u64 v[222:223], s[64:65], 0, v[184:185]
	ds_read_b128 v[160:163], v209 offset:32768
	ds_read_b128 v[164:167], v209 offset:33792
	ds_read_b128 v[168:171], v209 offset:34816
	ds_read_b128 v[172:175], v209 offset:35840
	ds_read_b128 v[176:179], v209 offset:36864
	ds_read_b128 v[180:183], v209 offset:37888
	ds_read_b128 v[200:203], v209 offset:38912
	ds_read_b128 v[210:213], v209 offset:39936
	global_load_lds_dwordx4 v[222:223], off
	v_lshl_add_u64 v[222:223], s[64:65], 0, v[188:189]
	s_mov_b32 m0, s31
	s_nop 0
	global_load_lds_dwordx4 v[222:223], off
	s_waitcnt vmcnt(8)
	s_waitcnt lgkmcnt(0)
	s_barrier
	s_waitcnt lgkmcnt(0)
	v_mfma_f32_16x16x32_bf16 v[144:147], v[92:95], v[160:163], v[144:147]
	v_mfma_f32_16x16x32_bf16 v[140:143], v[112:115], v[160:163], v[140:143]
	v_mfma_f32_16x16x32_bf16 v[120:123], v[92:95], v[168:171], v[120:123]
	v_mfma_f32_16x16x32_bf16 v[116:119], v[112:115], v[168:171], v[116:119]
	v_mfma_f32_16x16x32_bf16 v[96:99], v[92:95], v[176:179], v[96:99]
	v_mfma_f32_16x16x32_bf16 v[88:91], v[112:115], v[176:179], v[88:91]
	v_mfma_f32_16x16x32_bf16 v[76:79], v[92:95], v[200:203], v[76:79]
	v_mfma_f32_16x16x32_bf16 v[72:75], v[112:115], v[200:203], v[72:75]
	v_mfma_f32_16x16x32_bf16 v[144:147], v[100:103], v[164:167], v[144:147]
	v_mfma_f32_16x16x32_bf16 v[140:143], v[124:127], v[164:167], v[140:143]
	v_mfma_f32_16x16x32_bf16 v[120:123], v[100:103], v[172:175], v[120:123]
	v_mfma_f32_16x16x32_bf16 v[116:119], v[124:127], v[172:175], v[116:119]
	v_mfma_f32_16x16x32_bf16 v[96:99], v[100:103], v[180:183], v[96:99]
	v_mfma_f32_16x16x32_bf16 v[88:91], v[124:127], v[180:183], v[88:91]
	v_mfma_f32_16x16x32_bf16 v[76:79], v[100:103], v[210:213], v[76:79]
	v_mfma_f32_16x16x32_bf16 v[72:75], v[124:127], v[210:213], v[72:75]
	v_mfma_f32_16x16x32_bf16 v[132:135], v[136:139], v[160:163], v[132:135]
	v_mfma_f32_16x16x32_bf16 v[128:131], v[152:155], v[160:163], v[128:131]
	v_mfma_f32_16x16x32_bf16 v[108:111], v[136:139], v[168:171], v[108:111]
	v_mfma_f32_16x16x32_bf16 v[104:107], v[152:155], v[168:171], v[104:107]
	v_mfma_f32_16x16x32_bf16 v[84:87], v[136:139], v[176:179], v[84:87]
	v_mfma_f32_16x16x32_bf16 v[80:83], v[152:155], v[176:179], v[80:83]
	v_mfma_f32_16x16x32_bf16 v[68:71], v[136:139], v[200:203], v[68:71]
	v_mfma_f32_16x16x32_bf16 v[64:67], v[152:155], v[200:203], v[64:67]
	v_mfma_f32_16x16x32_bf16 v[132:135], v[148:151], v[164:167], v[132:135]
	v_mfma_f32_16x16x32_bf16 v[128:131], v[156:159], v[164:167], v[128:131]
	v_mfma_f32_16x16x32_bf16 v[108:111], v[148:151], v[172:175], v[108:111]
	v_mfma_f32_16x16x32_bf16 v[104:107], v[156:159], v[172:175], v[104:107]
	v_mfma_f32_16x16x32_bf16 v[84:87], v[148:151], v[180:183], v[84:87]
	v_mfma_f32_16x16x32_bf16 v[80:83], v[156:159], v[180:183], v[80:83]
	v_mfma_f32_16x16x32_bf16 v[68:71], v[148:151], v[210:213], v[68:71]
	v_mfma_f32_16x16x32_bf16 v[64:67], v[156:159], v[210:213], v[64:67]
	s_barrier
; #define PG8_STAGE(bufoff, gbase, voff) do { _Pragma("unroll") for (int _i = 0; _i < 2; ++_i) \
;         __builtin_amdgcn_global_load_lds((const unsigned*)((const char*)(gbase) + (voff)[_i]), (PG8_LAS unsigned*)(lds + (bufoff) + ldsw + _i * 8192), 16, 0, 0); } while (0)
; #define PG8_LDA(dst, b, h) do { _Pragma("unroll") for (int m = 0; m < 4; ++m) _Pragma("unroll") for (int k = 0; k < 2; ++k) dst[m][k] = *(const PG8_LAS bf16x8*)(lds + PG8_SA(b, h) + aoff + m * 2048 + k * 1024); } while (0)
; #define PG8_LDB(dst, b, h) do { _Pragma("unroll") for (int n = 0; n < 2; ++n) _Pragma("unroll") for (int k = 0; k < 2; ++k) dst[n][k] = *(const PG8_LAS bf16x8*)(lds + PG8_SB(b, h) + boff + n * 2048 + k * 1024); } while (0)
; #define PG8_WAIT_V(n) asm volatile("s_waitcnt vmcnt(" #n ")" ::: "memory")
; template <class Epi, class Sched, bool ALIGN_EPI = false, bool SP2 = false>
; __device__ __forceinline__ void gemm_phase(PG8_LAS unsigned char* lds, const Gemm g, const Sched& S, const Epi& E, const int tid_in) {
;     ...
;         for (int t = 0; t < nt; t += 2) {
;             const bool last = (t == nt - 2);
;             const char* a1 = cA + (size_t)(t + 1) * kstep;
;             const char* a2 = last ? nA : cA + (size_t)(t + 2) * kstep; const char* b2 = last ? nB : cB + (size_t)(t + 2) * kstep;
;             const char* a3 = a2 + kstep; const char* b3 = b2 + kstep;
;             if (last && has_next) S.a_ready(nxt);
;             if constexpr (SP2) {
;             PG8_LDB(B0, 0, 0); PG8_LDB(B1, 0, 1); PG8_SCHED; PG8_LDA(At, 0, 0); PG8_STAGE(PG8_SA(1, 1), a1 + hstep, voffA);
;             PG8_WAIT_V(8); PG8_WAIT_L(0); PG8_BAR; PG8_MMA(0, 0, At, B0); PG8_MMA(0, 1, At, B1); PG8_BAR; PG8_SCHED;
;             PG8_LDA(At, 0, 1); PG8_STAGE(PG8_SB(0, 0), b2, voffB); PG8_STAGE(PG8_SB(0, 1), b2 + hstep, voffB); PG8_STAGE(PG8_SA(0, 0), a2, voffA);
;             PG8_WAIT_V(8); PG8_WAIT_L(0); PG8_BAR; PG8_MMA(1, 0, At, B0); PG8_MMA(1, 1, At, B1); PG8_BAR; PG8_SCHED;
;     ...
;             PG8_WAIT_V(8); PG8_WAIT_L(0); PG8_BAR; PG8_MMA(0, 0, At, B0); PG8_MMA(0, 1, At, B1); PG8_BAR; PG8_SCHED;
;             PG8_LDA(At, 1, 1); PG8_STAGE(PG8_SB(1, 0), b3, voffB); PG8_STAGE(PG8_SB(1, 1), b3 + hstep, voffB); PG8_STAGE(PG8_SA(1, 0), a3, voffA);
;             PG8_WAIT_V(8); PG8_WAIT_L(0); PG8_BAR; PG8_MMA(1, 0, At, B0); PG8_MMA(1, 1, At, B1); PG8_BAR; PG8_SCHED;
	s_add_i32 s64, s78, s2
	v_lshl_add_u64 v[214:215], v[214:215], 0, s[22:23]
	s_mov_b32 m0, s64
	ds_read_b128 v[160:163], v209 offset:49152
	ds_read_b128 v[164:167], v209 offset:50176
	ds_read_b128 v[168:171], v209 offset:51200
	ds_read_b128 v[172:175], v209 offset:52224
	ds_read_b128 v[176:179], v209 offset:53248
	ds_read_b128 v[180:183], v209 offset:54272
	ds_read_b128 v[200:203], v209 offset:55296
	ds_read_b128 v[210:213], v209 offset:56320
	global_load_lds_dwordx4 v[214:215], off
	s_add_i32 m0, s64, 0x2000
	s_add_u32 s0, s0, 0x40080
	v_lshl_add_u64 v[214:215], v[216:217], 0, s[22:23]
	s_addc_u32 s1, s1, 0
	s_add_i32 s64, s79, s2
	global_load_lds_dwordx4 v[214:215], off
	v_lshl_add_u64 v[214:215], s[0:1], 0, v[186:187]
	s_mov_b32 m0, s64
	s_nop 0
	global_load_lds_dwordx4 v[214:215], off
	v_lshl_add_u64 v[214:215], s[0:1], 0, v[190:191]
	s_add_i32 m0, s64, 0x2000
	s_nop 0
	global_load_lds_dwordx4 v[214:215], off
	v_lshl_add_u64 v[214:215], v[218:219], 0, s[22:23]
	s_mov_b32 m0, s35
	s_nop 0
	global_load_lds_dwordx4 v[214:215], off
	v_lshl_add_u64 v[214:215], v[220:221], 0, s[22:23]
	s_mov_b32 m0, s36
	s_nop 0
	global_load_lds_dwordx4 v[214:215], off
	s_waitcnt vmcnt(8)
	s_waitcnt lgkmcnt(0)
	s_barrier
	s_waitcnt lgkmcnt(0)
	v_mfma_f32_16x16x32_bf16 v[60:63], v[92:95], v[160:163], v[60:63]
	v_mfma_f32_16x16x32_bf16 v[56:59], v[112:115], v[160:163], v[56:59]
	v_mfma_f32_16x16x32_bf16 v[44:47], v[92:95], v[168:171], v[44:47]
	v_mfma_f32_16x16x32_bf16 v[40:43], v[112:115], v[168:171], v[40:43]
	v_mfma_f32_16x16x32_bf16 v[28:31], v[92:95], v[176:179], v[28:31]
	v_mfma_f32_16x16x32_bf16 v[24:27], v[112:115], v[176:179], v[24:27]
	v_mfma_f32_16x16x32_bf16 v[12:15], v[92:95], v[200:203], v[12:15]
	v_mfma_f32_16x16x32_bf16 v[8:11], v[112:115], v[200:203], v[8:11]
	v_mfma_f32_16x16x32_bf16 v[60:63], v[100:103], v[164:167], v[60:63]
	v_mfma_f32_16x16x32_bf16 v[56:59], v[124:127], v[164:167], v[56:59]
	v_mfma_f32_16x16x32_bf16 v[44:47], v[100:103], v[172:175], v[44:47]
	v_mfma_f32_16x16x32_bf16 v[40:43], v[124:127], v[172:175], v[40:43]
	v_mfma_f32_16x16x32_bf16 v[28:31], v[100:103], v[180:183], v[28:31]
	v_mfma_f32_16x16x32_bf16 v[24:27], v[124:127], v[180:183], v[24:27]
	v_mfma_f32_16x16x32_bf16 v[12:15], v[100:103], v[210:213], v[12:15]
	v_mfma_f32_16x16x32_bf16 v[8:11], v[124:127], v[210:213], v[8:11]
	v_mfma_f32_16x16x32_bf16 v[52:55], v[136:139], v[160:163], v[52:55]
	v_mfma_f32_16x16x32_bf16 v[48:51], v[152:155], v[160:163], v[48:51]
	v_mfma_f32_16x16x32_bf16 v[36:39], v[136:139], v[168:171], v[36:39]
	v_mfma_f32_16x16x32_bf16 v[32:35], v[152:155], v[168:171], v[32:35]
	v_mfma_f32_16x16x32_bf16 v[20:23], v[136:139], v[176:179], v[20:23]
	v_mfma_f32_16x16x32_bf16 v[16:19], v[152:155], v[176:179], v[16:19]
	v_mfma_f32_16x16x32_bf16 v[4:7], v[136:139], v[200:203], v[4:7]
	v_mfma_f32_16x16x32_bf16 v[0:3], v[152:155], v[200:203], v[0:3]
	v_mfma_f32_16x16x32_bf16 v[52:55], v[148:151], v[164:167], v[52:55]
	v_mfma_f32_16x16x32_bf16 v[48:51], v[156:159], v[164:167], v[48:51]
	v_mfma_f32_16x16x32_bf16 v[36:39], v[148:151], v[172:175], v[36:39]
	v_mfma_f32_16x16x32_bf16 v[32:35], v[156:159], v[172:175], v[32:35]
	v_mfma_f32_16x16x32_bf16 v[20:23], v[148:151], v[180:183], v[20:23]
	v_mfma_f32_16x16x32_bf16 v[16:19], v[156:159], v[180:183], v[16:19]
	v_mfma_f32_16x16x32_bf16 v[4:7], v[148:151], v[210:213], v[4:7]
	v_mfma_f32_16x16x32_bf16 v[0:3], v[156:159], v[210:213], v[0:3]
	s_barrier
	s_add_i32 s77, s77, 2
	s_add_u32 s62, s62, 0x100
	s_addc_u32 s63, s63, 0
	s_add_u32 s75, s75, 0x100
	s_addc_u32 s76, s76, 0
	s_cmp_gt_u32 s77, 13
	s_cbranch_scc0 .LBB0_2954
	s_branch .Lmy_kdone_6
.LBB0_2954:
	ds_read_b128 v[92:95], v207
	ds_read_b128 v[100:103], v207 offset:1024
	ds_read_b128 v[112:115], v207 offset:2048
	ds_read_b128 v[124:127], v207 offset:3072
	ds_read_b128 v[136:139], v208
	ds_read_b128 v[148:151], v208 offset:1024
	ds_read_b128 v[152:155], v208 offset:2048
	ds_read_b128 v[156:159], v208 offset:3072
	s_add_u32 s0, s62, 0xfffc0080
	s_addc_u32 s1, s63, -1
	s_cmp_eq_u32 s77, 12
	s_cselect_b32 s65, s55, s1
	s_cselect_b32 s64, s61, s0
	s_cselect_b32 s1, s53, s76
	s_cselect_b32 s0, s74, s75
	v_lshl_add_u64 v[214:215], s[62:63], 0, v[192:193]
	s_add_i32 m0, s4, 0xc000
	ds_read_b128 v[160:163], v209
	ds_read_b128 v[164:167], v209 offset:1024
	ds_read_b128 v[168:171], v209 offset:2048
	ds_read_b128 v[172:175], v209 offset:3072
	ds_read_b128 v[176:179], v209 offset:4096
	ds_read_b128 v[180:183], v209 offset:5120
	ds_read_b128 v[200:203], v209 offset:6144
	ds_read_b128 v[210:213], v209 offset:7168
	global_load_lds_dwordx4 v[214:215], off
	v_lshl_add_u64 v[214:215], s[62:63], 0, v[194:195]
	s_add_i32 m0, s4, 0xe000
	s_nop 0
	global_load_lds_dwordx4 v[214:215], off
	s_waitcnt vmcnt(8)
	s_waitcnt lgkmcnt(0)
	s_barrier
; #define PG8_STAGE(bufoff, gbase, voff) do { _Pragma("unroll") for (int _i = 0; _i < 2; ++_i) \
;         __builtin_amdgcn_global_load_lds((const unsigned*)((const char*)(gbase) + (voff)[_i]), (PG8_LAS unsigned*)(lds + (bufoff) + ldsw + _i * 8192), 16, 0, 0); } while (0)
; #define PG8_LDA(dst, b, h) do { _Pragma("unroll") for (int m = 0; m < 4; ++m) _Pragma("unroll") for (int k = 0; k < 2; ++k) dst[m][k] = *(const PG8_LAS bf16x8*)(lds + PG8_SA(b, h) + aoff + m * 2048 + k * 1024); } while (0)
; #define PG8_LDB(dst, b, h) do { _Pragma("unroll") for (int n = 0; n < 2; ++n) _Pragma("unroll") for (int k = 0; k < 2; ++k) dst[n][k] = *(const PG8_LAS bf16x8*)(lds + PG8_SB(b, h) + boff + n * 2048 + k * 1024); } while (0)
; #define PG8_MMA(ai, bj, At, Bt) do { __builtin_amdgcn_s_setprio(1); _Pragma("unroll") for (int m = 0; m < 4; ++m) _Pragma("unroll") for (int n = 0; n < 2; ++n) _Pragma("unroll") for (int k = 0; k < 2; ++k) \
;         acc[ai][bj][m][n] = __builtin_amdgcn_mfma_f32_16x16x32_bf16(Bt[n][k], At[m][k], acc[ai][bj][m][n], 0, 0, 0); __builtin_amdgcn_s_setprio(0); } while (0)
; #define PG8_WAIT_V(n) asm volatile("s_waitcnt vmcnt(" #n ")" ::: "memory")
; #define PG8_WAIT_L(n) asm volatile("s_waitcnt lgkmcnt(" #n ")" ::: "memory")
; #define PG8_BAR __builtin_amdgcn_s_barrier()
; #define PG8_SCHED __builtin_amdgcn_sched_barrier(0)
; template <class Epi, class Sched, bool ALIGN_EPI = false, bool SP2 = false>
; __device__ __forceinline__ void gemm_phase(PG8_LAS unsigned char* lds, const Gemm g, const Sched& S, const Epi& E, const int tid_in) {
;     ...
;             PG8_LDB(B0, 0, 0); PG8_LDB(B1, 0, 1); PG8_SCHED; PG8_LDA(At, 0, 0); PG8_STAGE(PG8_SA(1, 1), a1 + hstep, voffA);
;             PG8_WAIT_V(8); PG8_WAIT_L(0); PG8_BAR; PG8_MMA(0, 0, At, B0); PG8_MMA(0, 1, At, B1); PG8_BAR; PG8_SCHED;
;             PG8_LDA(At, 0, 1); PG8_STAGE(PG8_SB(0, 0), b2, voffB); PG8_STAGE(PG8_SB(0, 1), b2 + hstep, voffB); PG8_STAGE(PG8_SA(0, 0), a2, voffA);
;             PG8_WAIT_V(8); PG8_WAIT_L(0); PG8_BAR; PG8_MMA(1, 0, At, B0); PG8_MMA(1, 1, At, B1); PG8_BAR; PG8_SCHED;
	s_waitcnt lgkmcnt(0)
	v_mfma_f32_16x16x32_bf16 v[144:147], v[92:95], v[160:163], v[144:147]
	v_mfma_f32_16x16x32_bf16 v[140:143], v[112:115], v[160:163], v[140:143]
	v_mfma_f32_16x16x32_bf16 v[120:123], v[92:95], v[168:171], v[120:123]
	v_mfma_f32_16x16x32_bf16 v[116:119], v[112:115], v[168:171], v[116:119]
	v_mfma_f32_16x16x32_bf16 v[96:99], v[92:95], v[176:179], v[96:99]
	v_mfma_f32_16x16x32_bf16 v[88:91], v[112:115], v[176:179], v[88:91]
	v_mfma_f32_16x16x32_bf16 v[76:79], v[92:95], v[200:203], v[76:79]
	v_mfma_f32_16x16x32_bf16 v[72:75], v[112:115], v[200:203], v[72:75]
	v_mfma_f32_16x16x32_bf16 v[144:147], v[100:103], v[164:167], v[144:147]
	v_mfma_f32_16x16x32_bf16 v[140:143], v[124:127], v[164:167], v[140:143]
	v_mfma_f32_16x16x32_bf16 v[120:123], v[100:103], v[172:175], v[120:123]
	v_mfma_f32_16x16x32_bf16 v[116:119], v[124:127], v[172:175], v[116:119]
	v_mfma_f32_16x16x32_bf16 v[96:99], v[100:103], v[180:183], v[96:99]
	v_mfma_f32_16x16x32_bf16 v[88:91], v[124:127], v[180:183], v[88:91]
	v_mfma_f32_16x16x32_bf16 v[76:79], v[100:103], v[210:213], v[76:79]
	v_mfma_f32_16x16x32_bf16 v[72:75], v[124:127], v[210:213], v[72:75]
	v_mfma_f32_16x16x32_bf16 v[132:135], v[136:139], v[160:163], v[132:135]
	v_mfma_f32_16x16x32_bf16 v[128:131], v[152:155], v[160:163], v[128:131]
	v_mfma_f32_16x16x32_bf16 v[108:111], v[136:139], v[168:171], v[108:111]
	v_mfma_f32_16x16x32_bf16 v[104:107], v[152:155], v[168:171], v[104:107]
	v_mfma_f32_16x16x32_bf16 v[84:87], v[136:139], v[176:179], v[84:87]
	v_mfma_f32_16x16x32_bf16 v[80:83], v[152:155], v[176:179], v[80:83]
	v_mfma_f32_16x16x32_bf16 v[68:71], v[136:139], v[200:203], v[68:71]
	v_mfma_f32_16x16x32_bf16 v[64:67], v[152:155], v[200:203], v[64:67]
	v_mfma_f32_16x16x32_bf16 v[132:135], v[148:151], v[164:167], v[132:135]
	v_mfma_f32_16x16x32_bf16 v[128:131], v[156:159], v[164:167], v[128:131]
	v_mfma_f32_16x16x32_bf16 v[108:111], v[148:151], v[172:175], v[108:111]
	v_mfma_f32_16x16x32_bf16 v[104:107], v[156:159], v[172:175], v[104:107]
	v_mfma_f32_16x16x32_bf16 v[84:87], v[148:151], v[180:183], v[84:87]
	v_mfma_f32_16x16x32_bf16 v[80:83], v[156:159], v[180:183], v[80:83]
	v_mfma_f32_16x16x32_bf16 v[68:71], v[148:151], v[210:213], v[68:71]
	v_mfma_f32_16x16x32_bf16 v[64:67], v[156:159], v[210:213], v[64:67]
	s_barrier
	s_add_i32 s78, s3, s2
	v_lshl_add_u64 v[214:215], s[0:1], 0, v[186:187]
	s_mov_b32 m0, s78
	ds_read_b128 v[160:163], v209 offset:16384
	ds_read_b128 v[164:167], v209 offset:17408
	ds_read_b128 v[168:171], v209 offset:18432
	ds_read_b128 v[172:175], v209 offset:19456
	ds_read_b128 v[176:179], v209 offset:20480
	ds_read_b128 v[180:183], v209 offset:21504
	ds_read_b128 v[200:203], v209 offset:22528
	ds_read_b128 v[210:213], v209 offset:23552
	global_load_lds_dwordx4 v[214:215], off
	s_add_i32 m0, s78, 0x2000
	s_add_u32 s78, s0, 0x40000
	v_lshl_add_u64 v[216:217], s[0:1], 0, v[190:191]
	s_addc_u32 s79, s1, 0
	s_add_i32 s80, s41, s2
	global_load_lds_dwordx4 v[216:217], off
	v_lshl_add_u64 v[218:219], s[78:79], 0, v[186:187]
	s_mov_b32 m0, s80
	v_lshl_add_u64 v[220:221], s[64:65], 0, v[188:189]
	global_load_lds_dwordx4 v[218:219], off
	v_lshl_add_u64 v[218:219], s[78:79], 0, v[190:191]
	s_add_i32 m0, s80, 0x2000
	s_nop 0
	global_load_lds_dwordx4 v[218:219], off
	v_lshl_add_u64 v[218:219], s[64:65], 0, v[184:185]
	s_mov_b32 m0, s4
	s_nop 0
	global_load_lds_dwordx4 v[218:219], off
	s_mov_b32 m0, s5
	s_nop 0
	global_load_lds_dwordx4 v[220:221], off
	s_waitcnt vmcnt(8)
	s_waitcnt lgkmcnt(0)
	s_barrier
	s_waitcnt lgkmcnt(0)
	v_mfma_f32_16x16x32_bf16 v[60:63], v[92:95], v[160:163], v[60:63]
	v_mfma_f32_16x16x32_bf16 v[56:59], v[112:115], v[160:163], v[56:59]
	v_mfma_f32_16x16x32_bf16 v[44:47], v[92:95], v[168:171], v[44:47]
	v_mfma_f32_16x16x32_bf16 v[40:43], v[112:115], v[168:171], v[40:43]
	v_mfma_f32_16x16x32_bf16 v[28:31], v[92:95], v[176:179], v[28:31]
	v_mfma_f32_16x16x32_bf16 v[24:27], v[112:115], v[176:179], v[24:27]
	v_mfma_f32_16x16x32_bf16 v[12:15], v[92:95], v[200:203], v[12:15]
	v_mfma_f32_16x16x32_bf16 v[8:11], v[112:115], v[200:203], v[8:11]
	v_mfma_f32_16x16x32_bf16 v[60:63], v[100:103], v[164:167], v[60:63]
	v_mfma_f32_16x16x32_bf16 v[56:59], v[124:127], v[164:167], v[56:59]
	v_mfma_f32_16x16x32_bf16 v[44:47], v[100:103], v[172:175], v[44:47]
	v_mfma_f32_16x16x32_bf16 v[40:43], v[124:127], v[172:175], v[40:43]
	v_mfma_f32_16x16x32_bf16 v[28:31], v[100:103], v[180:183], v[28:31]
	v_mfma_f32_16x16x32_bf16 v[24:27], v[124:127], v[180:183], v[24:27]
	v_mfma_f32_16x16x32_bf16 v[12:15], v[100:103], v[210:213], v[12:15]
	v_mfma_f32_16x16x32_bf16 v[8:11], v[124:127], v[210:213], v[8:11]
	v_mfma_f32_16x16x32_bf16 v[52:55], v[136:139], v[160:163], v[52:55]
	v_mfma_f32_16x16x32_bf16 v[48:51], v[152:155], v[160:163], v[48:51]
	v_mfma_f32_16x16x32_bf16 v[36:39], v[136:139], v[168:171], v[36:39]
	v_mfma_f32_16x16x32_bf16 v[32:35], v[152:155], v[168:171], v[32:35]
	v_mfma_f32_16x16x32_bf16 v[20:23], v[136:139], v[176:179], v[20:23]
	v_mfma_f32_16x16x32_bf16 v[16:19], v[152:155], v[176:179], v[16:19]
	v_mfma_f32_16x16x32_bf16 v[4:7], v[136:139], v[200:203], v[4:7]
	v_mfma_f32_16x16x32_bf16 v[0:3], v[152:155], v[200:203], v[0:3]
	v_mfma_f32_16x16x32_bf16 v[52:55], v[148:151], v[164:167], v[52:55]
	v_mfma_f32_16x16x32_bf16 v[48:51], v[156:159], v[164:167], v[48:51]
	v_mfma_f32_16x16x32_bf16 v[36:39], v[148:151], v[172:175], v[36:39]
	v_mfma_f32_16x16x32_bf16 v[32:35], v[156:159], v[172:175], v[32:35]
	v_mfma_f32_16x16x32_bf16 v[20:23], v[148:151], v[180:183], v[20:23]
	v_mfma_f32_16x16x32_bf16 v[16:19], v[156:159], v[180:183], v[16:19]
	v_mfma_f32_16x16x32_bf16 v[4:7], v[148:151], v[210:213], v[4:7]
	v_mfma_f32_16x16x32_bf16 v[0:3], v[156:159], v[210:213], v[0:3]
	s_barrier
; #define PG8_STAGE(bufoff, gbase, voff) do { _Pragma("unroll") for (int _i = 0; _i < 2; ++_i) \
;         __builtin_amdgcn_global_load_lds((const unsigned*)((const char*)(gbase) + (voff)[_i]), (PG8_LAS unsigned*)(lds + (bufoff) + ldsw + _i * 8192), 16, 0, 0); } while (0)
; #define PG8_LDA(dst, b, h) do { _Pragma("unroll") for (int m = 0; m < 4; ++m) _Pragma("unroll") for (int k = 0; k < 2; ++k) dst[m][k] = *(const PG8_LAS bf16x8*)(lds + PG8_SA(b, h) + aoff + m * 2048 + k * 1024); } while (0)
; #define PG8_LDB(dst, b, h) do { _Pragma("unroll") for (int n = 0; n < 2; ++n) _Pragma("unroll") for (int k = 0; k < 2; ++k) dst[n][k] = *(const PG8_LAS bf16x8*)(lds + PG8_SB(b, h) + boff + n * 2048 + k * 1024); } while (0)
; #define PG8_MMA(ai, bj, At, Bt) do { __builtin_amdgcn_s_setprio(1); _Pragma("unroll") for (int m = 0; m < 4; ++m) _Pragma("unroll") for (int n = 0; n < 2; ++n) _Pragma("unroll") for (int k = 0; k < 2; ++k) \
;         acc[ai][bj][m][n] = __builtin_amdgcn_mfma_f32_16x16x32_bf16(Bt[n][k], At[m][k], acc[ai][bj][m][n], 0, 0, 0); __builtin_amdgcn_s_setprio(0); } while (0)
; #define PG8_WAIT_V(n) asm volatile("s_waitcnt vmcnt(" #n ")" ::: "memory")
; #define PG8_WAIT_L(n) asm volatile("s_waitcnt lgkmcnt(" #n ")" ::: "memory")
; #define PG8_BAR __builtin_amdgcn_s_barrier()
; #define PG8_SCHED __builtin_amdgcn_sched_barrier(0)
; template <class Epi, class Sched, bool ALIGN_EPI = false, bool SP2 = false>
; __device__ __forceinline__ void gemm_phase(PG8_LAS unsigned char* lds, const Gemm g, const Sched& S, const Epi& E, const int tid_in) {
;     ...
;             PG8_LDB(B0, 1, 0); PG8_LDB(B1, 1, 1); PG8_SCHED; PG8_LDA(At, 1, 0); PG8_STAGE(PG8_SA(0, 1), a2 + hstep, voffA);
;             PG8_WAIT_V(8); PG8_WAIT_L(0); PG8_BAR; PG8_MMA(0, 0, At, B0); PG8_MMA(0, 1, At, B1); PG8_BAR; PG8_SCHED;
;             PG8_LDA(At, 1, 1); PG8_STAGE(PG8_SB(1, 0), b3, voffB); PG8_STAGE(PG8_SB(1, 1), b3 + hstep, voffB); PG8_STAGE(PG8_SA(1, 0), a3, voffA);
;             PG8_WAIT_V(8); PG8_WAIT_L(0); PG8_BAR; PG8_MMA(1, 0, At, B0); PG8_MMA(1, 1, At, B1); PG8_BAR; PG8_SCHED;
	s_add_i32 s78, 0, 0x18000
	s_add_i32 s79, 0, 0x1c000
	v_add_u32_e32 v124, s78, v205
	v_add_u32_e32 v156, s79, v205
	ds_read_b128 v[92:95], v124
	ds_read_b128 v[100:103], v124 offset:1024
	ds_read_b128 v[112:115], v124 offset:2048
	ds_read_b128 v[124:127], v124 offset:3072
	ds_read_b128 v[136:139], v156
	ds_read_b128 v[148:151], v156 offset:1024
	ds_read_b128 v[152:155], v156 offset:2048
	ds_read_b128 v[156:159], v156 offset:3072
	s_add_u32 s64, s64, 0x40000
	s_addc_u32 s65, s65, 0
	s_mov_b32 m0, s30
	v_lshl_add_u64 v[222:223], s[64:65], 0, v[184:185]
	ds_read_b128 v[160:163], v209 offset:32768
	ds_read_b128 v[164:167], v209 offset:33792
	ds_read_b128 v[168:171], v209 offset:34816
	ds_read_b128 v[172:175], v209 offset:35840
	ds_read_b128 v[176:179], v209 offset:36864
	ds_read_b128 v[180:183], v209 offset:37888
	ds_read_b128 v[200:203], v209 offset:38912
	ds_read_b128 v[210:213], v209 offset:39936
	global_load_lds_dwordx4 v[222:223], off
	v_lshl_add_u64 v[222:223], s[64:65], 0, v[188:189]
	s_mov_b32 m0, s31
	s_nop 0
	global_load_lds_dwordx4 v[222:223], off
	s_waitcnt vmcnt(8)
	s_waitcnt lgkmcnt(0)
	s_barrier
	s_waitcnt lgkmcnt(0)
	v_mfma_f32_16x16x32_bf16 v[144:147], v[92:95], v[160:163], v[144:147]
	v_mfma_f32_16x16x32_bf16 v[140:143], v[112:115], v[160:163], v[140:143]
	v_mfma_f32_16x16x32_bf16 v[120:123], v[92:95], v[168:171], v[120:123]
	v_mfma_f32_16x16x32_bf16 v[116:119], v[112:115], v[168:171], v[116:119]
	v_mfma_f32_16x16x32_bf16 v[96:99], v[92:95], v[176:179], v[96:99]
	v_mfma_f32_16x16x32_bf16 v[88:91], v[112:115], v[176:179], v[88:91]
	v_mfma_f32_16x16x32_bf16 v[76:79], v[92:95], v[200:203], v[76:79]
	v_mfma_f32_16x16x32_bf16 v[72:75], v[112:115], v[200:203], v[72:75]
	v_mfma_f32_16x16x32_bf16 v[144:147], v[100:103], v[164:167], v[144:147]
	v_mfma_f32_16x16x32_bf16 v[140:143], v[124:127], v[164:167], v[140:143]
	v_mfma_f32_16x16x32_bf16 v[120:123], v[100:103], v[172:175], v[120:123]
	v_mfma_f32_16x16x32_bf16 v[116:119], v[124:127], v[172:175], v[116:119]
	v_mfma_f32_16x16x32_bf16 v[96:99], v[100:103], v[180:183], v[96:99]
	v_mfma_f32_16x16x32_bf16 v[88:91], v[124:127], v[180:183], v[88:91]
	v_mfma_f32_16x16x32_bf16 v[76:79], v[100:103], v[210:213], v[76:79]
	v_mfma_f32_16x16x32_bf16 v[72:75], v[124:127], v[210:213], v[72:75]
	v_mfma_f32_16x16x32_bf16 v[132:135], v[136:139], v[160:163], v[132:135]
	v_mfma_f32_16x16x32_bf16 v[128:131], v[152:155], v[160:163], v[128:131]
	v_mfma_f32_16x16x32_bf16 v[108:111], v[136:139], v[168:171], v[108:111]
	v_mfma_f32_16x16x32_bf16 v[104:107], v[152:155], v[168:171], v[104:107]
	v_mfma_f32_16x16x32_bf16 v[84:87], v[136:139], v[176:179], v[84:87]
	v_mfma_f32_16x16x32_bf16 v[80:83], v[152:155], v[176:179], v[80:83]
	v_mfma_f32_16x16x32_bf16 v[68:71], v[136:139], v[200:203], v[68:71]
	v_mfma_f32_16x16x32_bf16 v[64:67], v[152:155], v[200:203], v[64:67]
	v_mfma_f32_16x16x32_bf16 v[132:135], v[148:151], v[164:167], v[132:135]
	v_mfma_f32_16x16x32_bf16 v[128:131], v[156:159], v[164:167], v[128:131]
	v_mfma_f32_16x16x32_bf16 v[108:111], v[148:151], v[172:175], v[108:111]
	v_mfma_f32_16x16x32_bf16 v[104:107], v[156:159], v[172:175], v[104:107]
	v_mfma_f32_16x16x32_bf16 v[84:87], v[148:151], v[180:183], v[84:87]
	v_mfma_f32_16x16x32_bf16 v[80:83], v[156:159], v[180:183], v[80:83]
	v_mfma_f32_16x16x32_bf16 v[68:71], v[148:151], v[210:213], v[68:71]
	v_mfma_f32_16x16x32_bf16 v[64:67], v[156:159], v[210:213], v[64:67]
	s_barrier
	s_add_i32 s64, s78, s2
	v_lshl_add_u64 v[214:215], v[214:215], 0, s[22:23]
	s_mov_b32 m0, s64
	ds_read_b128 v[160:163], v209 offset:49152
	ds_read_b128 v[164:167], v209 offset:50176
	ds_read_b128 v[168:171], v209 offset:51200
	ds_read_b128 v[172:175], v209 offset:52224
	ds_read_b128 v[176:179], v209 offset:53248
	ds_read_b128 v[180:183], v209 offset:54272
	ds_read_b128 v[200:203], v209 offset:55296
	ds_read_b128 v[210:213], v209 offset:56320
	global_load_lds_dwordx4 v[214:215], off
	s_add_i32 m0, s64, 0x2000
	s_add_u32 s0, s0, 0x40080
	v_lshl_add_u64 v[214:215], v[216:217], 0, s[22:23]
	s_addc_u32 s1, s1, 0
	s_add_i32 s64, s79, s2
	global_load_lds_dwordx4 v[214:215], off
	v_lshl_add_u64 v[214:215], s[0:1], 0, v[186:187]
	s_mov_b32 m0, s64
	s_nop 0
	global_load_lds_dwordx4 v[214:215], off
	v_lshl_add_u64 v[214:215], s[0:1], 0, v[190:191]
	s_add_i32 m0, s64, 0x2000
	s_nop 0
	global_load_lds_dwordx4 v[214:215], off
	v_lshl_add_u64 v[214:215], v[218:219], 0, s[22:23]
	s_mov_b32 m0, s35
	s_nop 0
	global_load_lds_dwordx4 v[214:215], off
	v_lshl_add_u64 v[214:215], v[220:221], 0, s[22:23]
	s_mov_b32 m0, s36
	s_nop 0
	global_load_lds_dwordx4 v[214:215], off
	s_waitcnt vmcnt(8)
	s_waitcnt lgkmcnt(0)
	s_barrier
	s_waitcnt lgkmcnt(0)
	v_mfma_f32_16x16x32_bf16 v[60:63], v[92:95], v[160:163], v[60:63]
	v_mfma_f32_16x16x32_bf16 v[56:59], v[112:115], v[160:163], v[56:59]
	v_mfma_f32_16x16x32_bf16 v[44:47], v[92:95], v[168:171], v[44:47]
	v_mfma_f32_16x16x32_bf16 v[40:43], v[112:115], v[168:171], v[40:43]
	v_mfma_f32_16x16x32_bf16 v[28:31], v[92:95], v[176:179], v[28:31]
	v_mfma_f32_16x16x32_bf16 v[24:27], v[112:115], v[176:179], v[24:27]
	v_mfma_f32_16x16x32_bf16 v[12:15], v[92:95], v[200:203], v[12:15]
	v_mfma_f32_16x16x32_bf16 v[8:11], v[112:115], v[200:203], v[8:11]
	v_mfma_f32_16x16x32_bf16 v[60:63], v[100:103], v[164:167], v[60:63]
	v_mfma_f32_16x16x32_bf16 v[56:59], v[124:127], v[164:167], v[56:59]
	v_mfma_f32_16x16x32_bf16 v[44:47], v[100:103], v[172:175], v[44:47]
	v_mfma_f32_16x16x32_bf16 v[40:43], v[124:127], v[172:175], v[40:43]
	v_mfma_f32_16x16x32_bf16 v[28:31], v[100:103], v[180:183], v[28:31]
	v_mfma_f32_16x16x32_bf16 v[24:27], v[124:127], v[180:183], v[24:27]
	v_mfma_f32_16x16x32_bf16 v[12:15], v[100:103], v[210:213], v[12:15]
	v_mfma_f32_16x16x32_bf16 v[8:11], v[124:127], v[210:213], v[8:11]
	v_mfma_f32_16x16x32_bf16 v[52:55], v[136:139], v[160:163], v[52:55]
	v_mfma_f32_16x16x32_bf16 v[48:51], v[152:155], v[160:163], v[48:51]
	v_mfma_f32_16x16x32_bf16 v[36:39], v[136:139], v[168:171], v[36:39]
	v_mfma_f32_16x16x32_bf16 v[32:35], v[152:155], v[168:171], v[32:35]
	v_mfma_f32_16x16x32_bf16 v[20:23], v[136:139], v[176:179], v[20:23]
	v_mfma_f32_16x16x32_bf16 v[16:19], v[152:155], v[176:179], v[16:19]
	v_mfma_f32_16x16x32_bf16 v[4:7], v[136:139], v[200:203], v[4:7]
	v_mfma_f32_16x16x32_bf16 v[0:3], v[152:155], v[200:203], v[0:3]
	v_mfma_f32_16x16x32_bf16 v[52:55], v[148:151], v[164:167], v[52:55]
	v_mfma_f32_16x16x32_bf16 v[48:51], v[156:159], v[164:167], v[48:51]
	v_mfma_f32_16x16x32_bf16 v[36:39], v[148:151], v[172:175], v[36:39]
	v_mfma_f32_16x16x32_bf16 v[32:35], v[156:159], v[172:175], v[32:35]
	v_mfma_f32_16x16x32_bf16 v[20:23], v[148:151], v[180:183], v[20:23]
	v_mfma_f32_16x16x32_bf16 v[16:19], v[156:159], v[180:183], v[16:19]
	v_mfma_f32_16x16x32_bf16 v[4:7], v[148:151], v[210:213], v[4:7]
	v_mfma_f32_16x16x32_bf16 v[0:3], v[156:159], v[210:213], v[0:3]
	s_barrier
	s_add_i32 s77, s77, 2
	s_add_u32 s62, s62, 0x100
	s_addc_u32 s63, s63, 0
	s_add_u32 s75, s75, 0x100
	s_addc_u32 s76, s76, 0
	s_cmp_gt_u32 s77, 13
	s_cbranch_scc0 .LBB0_2954

; #define PG8_STAGE(bufoff, gbase, voff) do { _Pragma("unroll") for (int _i = 0; _i < 2; ++_i) \
;         __builtin_amdgcn_global_load_lds((const unsigned*)((const char*)(gbase) + (voff)[_i]), (PG8_LAS unsigned*)(lds + (bufoff) + ldsw + _i * 8192), 16, 0, 0); } while (0)
; #define PG8_LDA(dst, b, h) do { _Pragma("unroll") for (int m = 0; m < 4; ++m) _Pragma("unroll") for (int k = 0; k < 2; ++k) dst[m][k] = *(const PG8_LAS bf16x8*)(lds + PG8_SA(b, h) + aoff + m * 2048 + k * 1024); } while (0)
; #define PG8_LDB(dst, b, h) do { _Pragma("unroll") for (int n = 0; n < 2; ++n) _Pragma("unroll") for (int k = 0; k < 2; ++k) dst[n][k] = *(const PG8_LAS bf16x8*)(lds + PG8_SB(b, h) + boff + n * 2048 + k * 1024); } while (0)
; #define PG8_WAIT_V(n) asm volatile("s_waitcnt vmcnt(" #n ")" ::: "memory")
; #define PG8_WAIT_L(n) asm volatile("s_waitcnt lgkmcnt(" #n ")" ::: "memory")
; #define PG8_BAR __builtin_amdgcn_s_barrier()
; #define PG8_SCHED __builtin_amdgcn_sched_barrier(0)
; template <class Epi, class Sched, bool ALIGN_EPI = false, bool SP2 = false>
; __device__ __forceinline__ void gemm_phase(PG8_LAS unsigned char* lds, const Gemm g, const Sched& S, const Epi& E, const int tid_in) {
;     ...
;         const char* nA = has_next ? (const char*)g.A + (size_t)nxt.pm * tstep : cA; const char* nB = has_next ? (const char*)g.Bt + (size_t)nxt.pn * tstep : cB;
;         for (int t = 0; t < nt; t += 2) {
;             const bool last = (t == nt - 2);
;             const char* a1 = cA + (size_t)(t + 1) * kstep;
;             const char* a2 = last ? nA : cA + (size_t)(t + 2) * kstep; const char* b2 = last ? nB : cB + (size_t)(t + 2) * kstep;
;             const char* a3 = a2 + kstep; const char* b3 = b2 + kstep;
;             if (last && has_next) S.a_ready(nxt);
;             if constexpr (SP2) {
;             PG8_LDB(B0, 0, 0); PG8_LDB(B1, 0, 1); PG8_SCHED; PG8_LDA(At, 0, 0); PG8_STAGE(PG8_SA(1, 1), a1 + hstep, voffA);
;             PG8_WAIT_V(8); PG8_WAIT_L(0); PG8_BAR; PG8_MMA(0, 0, At, B0); PG8_MMA(0, 1, At, B1); PG8_BAR; PG8_SCHED;
;             PG8_LDA(At, 0, 1); PG8_STAGE(PG8_SB(0, 0), b2, voffB); PG8_STAGE(PG8_SB(0, 1), b2 + hstep, voffB); PG8_STAGE(PG8_SA(0, 0), a2, voffA);
;             PG8_WAIT_V(8); PG8_WAIT_L(0); PG8_BAR; PG8_MMA(1, 0, At, B0); PG8_MMA(1, 1, At, B1); PG8_BAR; PG8_SCHED;
.LBB0_3052:
	s_ashr_i32 s25, s24, 31
	s_lshl_b64 s[26:27], s[24:25], 19
	s_add_u32 s26, s30, s26
	s_addc_u32 s27, s31, s27
	s_and_b64 s[28:29], s[6:7], exec
	s_cselect_b32 s25, s27, s11
	s_cselect_b32 s49, s26, s10
	s_ashr_i32 s23, s22, 31
	s_lshl_b64 s[28:29], s[22:23], 19
	s_add_u32 s28, s4, s28
	s_addc_u32 s29, s5, s29
	s_and_b64 s[38:39], s[6:7], exec
	s_cselect_b32 s23, s29, s1
	s_cselect_b32 s50, s28, s0
	s_add_u32 s10, s10, 0x40080
	s_addc_u32 s11, s11, 0
	s_add_u32 s51, s0, 0x100
	v_mov_b32_e32 v0, 0
	s_addc_u32 s52, s1, 0
	s_mov_b32 s53, -2
	ds_read_b128 v[160:163], v154
	ds_read_b128 v[164:167], v154 offset:1024
	ds_read_b128 v[168:171], v154 offset:2048
	ds_read_b128 v[172:175], v154 offset:3072
	ds_read_b128 v[176:179], v155
	ds_read_b128 v[180:183], v155 offset:1024
	ds_read_b128 v[184:187], v155 offset:2048
	ds_read_b128 v[188:191], v155 offset:3072
	s_add_u32 s0, s10, 0xfffc0080
	s_addc_u32 s1, s11, -1
	s_cmp_eq_u32 s53, 12
	s_cselect_b32 s39, s25, s1
	s_cselect_b32 s38, s49, s0
	s_cselect_b32 s1, s23, s52
	s_cselect_b32 s0, s50, s51
	v_lshl_add_u64 v[144:145], s[10:11], 0, v[136:137]
	s_add_i32 m0, s35, 0xc000
	ds_read_b128 v[192:195], v156
	ds_read_b128 v[196:199], v156 offset:1024
	ds_read_b128 v[200:203], v156 offset:2048
	ds_read_b128 v[204:207], v156 offset:3072
	ds_read_b128 v[208:211], v156 offset:4096
	ds_read_b128 v[212:215], v156 offset:5120
	ds_read_b128 v[216:219], v156 offset:6144
	ds_read_b128 v[220:223], v156 offset:7168
	global_load_lds_dwordx4 v[144:145], off
	v_lshl_add_u64 v[144:145], s[10:11], 0, v[138:139]
	s_add_i32 m0, s35, 0xe000
	s_nop 0
	global_load_lds_dwordx4 v[144:145], off
	s_waitcnt vmcnt(8)
	s_waitcnt lgkmcnt(0)
	s_barrier
	s_waitcnt lgkmcnt(0)
	v_mfma_f32_16x16x32_bf16 v[124:127], v[160:163], v[192:195], 0
	v_mfma_f32_16x16x32_bf16 v[116:119], v[168:171], v[192:195], 0
	v_mfma_f32_16x16x32_bf16 v[108:111], v[160:163], v[200:203], 0
	v_mfma_f32_16x16x32_bf16 v[100:103], v[168:171], v[200:203], 0
	v_mfma_f32_16x16x32_bf16 v[92:95], v[160:163], v[208:211], 0
	v_mfma_f32_16x16x32_bf16 v[84:87], v[168:171], v[208:211], 0
	v_mfma_f32_16x16x32_bf16 v[76:79], v[160:163], v[216:219], 0
	v_mfma_f32_16x16x32_bf16 v[68:71], v[168:171], v[216:219], 0
	v_mfma_f32_16x16x32_bf16 v[124:127], v[164:167], v[196:199], v[124:127]
	v_mfma_f32_16x16x32_bf16 v[116:119], v[172:175], v[196:199], v[116:119]
	v_mfma_f32_16x16x32_bf16 v[108:111], v[164:167], v[204:207], v[108:111]
	v_mfma_f32_16x16x32_bf16 v[100:103], v[172:175], v[204:207], v[100:103]
	v_mfma_f32_16x16x32_bf16 v[92:95], v[164:167], v[212:215], v[92:95]
	v_mfma_f32_16x16x32_bf16 v[84:87], v[172:175], v[212:215], v[84:87]
	v_mfma_f32_16x16x32_bf16 v[76:79], v[164:167], v[220:223], v[76:79]
	v_mfma_f32_16x16x32_bf16 v[68:71], v[172:175], v[220:223], v[68:71]
	v_mfma_f32_16x16x32_bf16 v[120:123], v[176:179], v[192:195], 0
	v_mfma_f32_16x16x32_bf16 v[112:115], v[184:187], v[192:195], 0
	v_mfma_f32_16x16x32_bf16 v[104:107], v[176:179], v[200:203], 0
	v_mfma_f32_16x16x32_bf16 v[96:99], v[184:187], v[200:203], 0
	v_mfma_f32_16x16x32_bf16 v[88:91], v[176:179], v[208:211], 0
	v_mfma_f32_16x16x32_bf16 v[80:83], v[184:187], v[208:211], 0
	v_mfma_f32_16x16x32_bf16 v[72:75], v[176:179], v[216:219], 0
	v_mfma_f32_16x16x32_bf16 v[64:67], v[184:187], v[216:219], 0
	v_mfma_f32_16x16x32_bf16 v[120:123], v[180:183], v[196:199], v[120:123]
	v_mfma_f32_16x16x32_bf16 v[112:115], v[188:191], v[196:199], v[112:115]
	v_mfma_f32_16x16x32_bf16 v[104:107], v[180:183], v[204:207], v[104:107]
	v_mfma_f32_16x16x32_bf16 v[96:99], v[188:191], v[204:207], v[96:99]
	v_mfma_f32_16x16x32_bf16 v[88:91], v[180:183], v[212:215], v[88:91]
	v_mfma_f32_16x16x32_bf16 v[80:83], v[188:191], v[212:215], v[80:83]
	v_mfma_f32_16x16x32_bf16 v[72:75], v[180:183], v[220:223], v[72:75]
	v_mfma_f32_16x16x32_bf16 v[64:67], v[188:191], v[220:223], v[64:67]
	s_barrier
	s_add_i32 s54, s3, s34
	v_lshl_add_u64 v[144:145], s[0:1], 0, v[130:131]
	s_mov_b32 m0, s54
	ds_read_b128 v[192:195], v156 offset:16384
	ds_read_b128 v[196:199], v156 offset:17408
	ds_read_b128 v[200:203], v156 offset:18432
	ds_read_b128 v[204:207], v156 offset:19456
	ds_read_b128 v[208:211], v156 offset:20480
	ds_read_b128 v[212:215], v156 offset:21504
	ds_read_b128 v[216:219], v156 offset:22528
	ds_read_b128 v[220:223], v156 offset:23552
	global_load_lds_dwordx4 v[144:145], off
	s_add_i32 m0, s54, 0x2000
	s_add_u32 s54, s0, 0x40000
	v_lshl_add_u64 v[224:225], s[0:1], 0, v[134:135]
	s_addc_u32 s55, s1, 0
	s_add_i32 s56, s46, s34
	global_load_lds_dwordx4 v[224:225], off
	v_lshl_add_u64 v[226:227], s[54:55], 0, v[130:131]
	s_mov_b32 m0, s56
	v_lshl_add_u64 v[228:229], s[38:39], 0, v[132:133]
	global_load_lds_dwordx4 v[226:227], off
	v_lshl_add_u64 v[226:227], s[54:55], 0, v[134:135]
	s_add_i32 m0, s56, 0x2000
	s_nop 0
	global_load_lds_dwordx4 v[226:227], off
	v_lshl_add_u64 v[226:227], s[38:39], 0, v[128:129]
	s_mov_b32 m0, s35
	s_nop 0
	global_load_lds_dwordx4 v[226:227], off
	s_mov_b32 m0, s36
	s_nop 0
	global_load_lds_dwordx4 v[228:229], off
	s_waitcnt vmcnt(8)
	s_waitcnt lgkmcnt(0)
	s_barrier
; #define PG8_STAGE(bufoff, gbase, voff) do { _Pragma("unroll") for (int _i = 0; _i < 2; ++_i) \
;         __builtin_amdgcn_global_load_lds((const unsigned*)((const char*)(gbase) + (voff)[_i]), (PG8_LAS unsigned*)(lds + (bufoff) + ldsw + _i * 8192), 16, 0, 0); } while (0)
; #define PG8_LDA(dst, b, h) do { _Pragma("unroll") for (int m = 0; m < 4; ++m) _Pragma("unroll") for (int k = 0; k < 2; ++k) dst[m][k] = *(const PG8_LAS bf16x8*)(lds + PG8_SA(b, h) + aoff + m * 2048 + k * 1024); } while (0)
; #define PG8_LDB(dst, b, h) do { _Pragma("unroll") for (int n = 0; n < 2; ++n) _Pragma("unroll") for (int k = 0; k < 2; ++k) dst[n][k] = *(const PG8_LAS bf16x8*)(lds + PG8_SB(b, h) + boff + n * 2048 + k * 1024); } while (0)
; #define PG8_MMA(ai, bj, At, Bt) do { __builtin_amdgcn_s_setprio(1); _Pragma("unroll") for (int m = 0; m < 4; ++m) _Pragma("unroll") for (int n = 0; n < 2; ++n) _Pragma("unroll") for (int k = 0; k < 2; ++k) \
;         acc[ai][bj][m][n] = __builtin_amdgcn_mfma_f32_16x16x32_bf16(Bt[n][k], At[m][k], acc[ai][bj][m][n], 0, 0, 0); __builtin_amdgcn_s_setprio(0); } while (0)
; #define PG8_BAR __builtin_amdgcn_s_barrier()
; template <class Epi, class Sched, bool ALIGN_EPI = false, bool SP2 = false>
; __device__ __forceinline__ void gemm_phase(PG8_LAS unsigned char* lds, const Gemm g, const Sched& S, const Epi& E, const int tid_in) {
;     ...
;             PG8_LDB(B0, 0, 0); PG8_LDB(B1, 0, 1); PG8_SCHED; PG8_LDA(At, 0, 0); PG8_STAGE(PG8_SA(1, 1), a1 + hstep, voffA);
;             PG8_WAIT_V(8); PG8_WAIT_L(0); PG8_BAR; PG8_MMA(0, 0, At, B0); PG8_MMA(0, 1, At, B1); PG8_BAR; PG8_SCHED;
;             PG8_LDA(At, 0, 1); PG8_STAGE(PG8_SB(0, 0), b2, voffB); PG8_STAGE(PG8_SB(0, 1), b2 + hstep, voffB); PG8_STAGE(PG8_SA(0, 0), a2, voffA);
;             PG8_WAIT_V(8); PG8_WAIT_L(0); PG8_BAR; PG8_MMA(1, 0, At, B0); PG8_MMA(1, 1, At, B1); PG8_BAR; PG8_SCHED;
;             PG8_LDB(B0, 1, 0); PG8_LDB(B1, 1, 1); PG8_SCHED; PG8_LDA(At, 1, 0); PG8_STAGE(PG8_SA(0, 1), a2 + hstep, voffA);
;             PG8_WAIT_V(8); PG8_WAIT_L(0); PG8_BAR; PG8_MMA(0, 0, At, B0); PG8_MMA(0, 1, At, B1); PG8_BAR; PG8_SCHED;
;             PG8_LDA(At, 1, 1); PG8_STAGE(PG8_SB(1, 0), b3, voffB); PG8_STAGE(PG8_SB(1, 1), b3 + hstep, voffB); PG8_STAGE(PG8_SA(1, 0), a3, voffA);
;             PG8_WAIT_V(8); PG8_WAIT_L(0); PG8_BAR; PG8_MMA(1, 0, At, B0); PG8_MMA(1, 1, At, B1); PG8_BAR; PG8_SCHED;
	s_waitcnt lgkmcnt(0)
	v_mfma_f32_16x16x32_bf16 v[60:63], v[160:163], v[192:195], 0
	v_mfma_f32_16x16x32_bf16 v[52:55], v[168:171], v[192:195], 0
	v_mfma_f32_16x16x32_bf16 v[44:47], v[160:163], v[200:203], 0
	v_mfma_f32_16x16x32_bf16 v[36:39], v[168:171], v[200:203], 0
	v_mfma_f32_16x16x32_bf16 v[28:31], v[160:163], v[208:211], 0
	v_mfma_f32_16x16x32_bf16 v[20:23], v[168:171], v[208:211], 0
	v_mfma_f32_16x16x32_bf16 v[12:15], v[160:163], v[216:219], 0
	v_mfma_f32_16x16x32_bf16 v[4:7], v[168:171], v[216:219], 0
	v_mfma_f32_16x16x32_bf16 v[60:63], v[164:167], v[196:199], v[60:63]
	v_mfma_f32_16x16x32_bf16 v[52:55], v[172:175], v[196:199], v[52:55]
	v_mfma_f32_16x16x32_bf16 v[44:47], v[164:167], v[204:207], v[44:47]
	v_mfma_f32_16x16x32_bf16 v[36:39], v[172:175], v[204:207], v[36:39]
	v_mfma_f32_16x16x32_bf16 v[28:31], v[164:167], v[212:215], v[28:31]
	v_mfma_f32_16x16x32_bf16 v[20:23], v[172:175], v[212:215], v[20:23]
	v_mfma_f32_16x16x32_bf16 v[12:15], v[164:167], v[220:223], v[12:15]
	v_mfma_f32_16x16x32_bf16 v[4:7], v[172:175], v[220:223], v[4:7]
	v_mfma_f32_16x16x32_bf16 v[56:59], v[176:179], v[192:195], 0
	v_mfma_f32_16x16x32_bf16 v[48:51], v[184:187], v[192:195], 0
	v_mfma_f32_16x16x32_bf16 v[40:43], v[176:179], v[200:203], 0
	v_mfma_f32_16x16x32_bf16 v[32:35], v[184:187], v[200:203], 0
	v_mfma_f32_16x16x32_bf16 v[24:27], v[176:179], v[208:211], 0
	v_mfma_f32_16x16x32_bf16 v[16:19], v[184:187], v[208:211], 0
	v_mfma_f32_16x16x32_bf16 v[8:11], v[176:179], v[216:219], 0
	v_mfma_f32_16x16x32_bf16 v[0:3], v[184:187], v[216:219], 0
	v_mfma_f32_16x16x32_bf16 v[56:59], v[180:183], v[196:199], v[56:59]
	v_mfma_f32_16x16x32_bf16 v[48:51], v[188:191], v[196:199], v[48:51]
	v_mfma_f32_16x16x32_bf16 v[40:43], v[180:183], v[204:207], v[40:43]
	v_mfma_f32_16x16x32_bf16 v[32:35], v[188:191], v[204:207], v[32:35]
	v_mfma_f32_16x16x32_bf16 v[24:27], v[180:183], v[212:215], v[24:27]
	v_mfma_f32_16x16x32_bf16 v[16:19], v[188:191], v[212:215], v[16:19]
	v_mfma_f32_16x16x32_bf16 v[8:11], v[180:183], v[220:223], v[8:11]
	v_mfma_f32_16x16x32_bf16 v[0:3], v[188:191], v[220:223], v[0:3]
	s_barrier
	s_add_i32 s54, 0, 0x18000
	v_add_u32_e32 v159, s54, v148
	s_add_i32 s55, 0, 0x1c000
	ds_read_b128 v[160:163], v159
	ds_read_b128 v[164:167], v159 offset:1024
	ds_read_b128 v[168:171], v159 offset:2048
	ds_read_b128 v[172:175], v159 offset:3072
	v_add_u32_e32 v159, s55, v148
	ds_read_b128 v[176:179], v159
	ds_read_b128 v[180:183], v159 offset:1024
	ds_read_b128 v[184:187], v159 offset:2048
	ds_read_b128 v[188:191], v159 offset:3072
	s_add_u32 s38, s38, 0x40000
	s_addc_u32 s39, s39, 0
	s_mov_b32 m0, s37
	v_lshl_add_u64 v[230:231], s[38:39], 0, v[128:129]
	ds_read_b128 v[192:195], v156 offset:32768
	ds_read_b128 v[196:199], v156 offset:33792
	ds_read_b128 v[200:203], v156 offset:34816
	ds_read_b128 v[204:207], v156 offset:35840
	ds_read_b128 v[208:211], v156 offset:36864
	ds_read_b128 v[212:215], v156 offset:37888
	ds_read_b128 v[216:219], v156 offset:38912
	ds_read_b128 v[220:223], v156 offset:39936
	global_load_lds_dwordx4 v[230:231], off
	v_lshl_add_u64 v[230:231], s[38:39], 0, v[132:133]
	s_mov_b32 m0, s40
	s_nop 0
	global_load_lds_dwordx4 v[230:231], off
	s_waitcnt vmcnt(8)
	s_waitcnt lgkmcnt(0)
	s_barrier
	s_waitcnt lgkmcnt(0)
	v_mfma_f32_16x16x32_bf16 v[124:127], v[160:163], v[192:195], v[124:127]
	v_mfma_f32_16x16x32_bf16 v[116:119], v[168:171], v[192:195], v[116:119]
	v_mfma_f32_16x16x32_bf16 v[108:111], v[160:163], v[200:203], v[108:111]
	v_mfma_f32_16x16x32_bf16 v[100:103], v[168:171], v[200:203], v[100:103]
	v_mfma_f32_16x16x32_bf16 v[92:95], v[160:163], v[208:211], v[92:95]
	v_mfma_f32_16x16x32_bf16 v[84:87], v[168:171], v[208:211], v[84:87]
	v_mfma_f32_16x16x32_bf16 v[76:79], v[160:163], v[216:219], v[76:79]
	v_mfma_f32_16x16x32_bf16 v[68:71], v[168:171], v[216:219], v[68:71]
	v_mfma_f32_16x16x32_bf16 v[124:127], v[164:167], v[196:199], v[124:127]
	v_mfma_f32_16x16x32_bf16 v[116:119], v[172:175], v[196:199], v[116:119]
	v_mfma_f32_16x16x32_bf16 v[108:111], v[164:167], v[204:207], v[108:111]
	v_mfma_f32_16x16x32_bf16 v[100:103], v[172:175], v[204:207], v[100:103]
	v_mfma_f32_16x16x32_bf16 v[92:95], v[164:167], v[212:215], v[92:95]
	v_mfma_f32_16x16x32_bf16 v[84:87], v[172:175], v[212:215], v[84:87]
	v_mfma_f32_16x16x32_bf16 v[76:79], v[164:167], v[220:223], v[76:79]
	v_mfma_f32_16x16x32_bf16 v[68:71], v[172:175], v[220:223], v[68:71]
	v_mfma_f32_16x16x32_bf16 v[120:123], v[176:179], v[192:195], v[120:123]
	v_mfma_f32_16x16x32_bf16 v[112:115], v[184:187], v[192:195], v[112:115]
	v_mfma_f32_16x16x32_bf16 v[104:107], v[176:179], v[200:203], v[104:107]
	v_mfma_f32_16x16x32_bf16 v[96:99], v[184:187], v[200:203], v[96:99]
	v_mfma_f32_16x16x32_bf16 v[88:91], v[176:179], v[208:211], v[88:91]
	v_mfma_f32_16x16x32_bf16 v[80:83], v[184:187], v[208:211], v[80:83]
	v_mfma_f32_16x16x32_bf16 v[72:75], v[176:179], v[216:219], v[72:75]
	v_mfma_f32_16x16x32_bf16 v[64:67], v[184:187], v[216:219], v[64:67]
	v_mfma_f32_16x16x32_bf16 v[120:123], v[180:183], v[196:199], v[120:123]
	v_mfma_f32_16x16x32_bf16 v[112:115], v[188:191], v[196:199], v[112:115]
	v_mfma_f32_16x16x32_bf16 v[104:107], v[180:183], v[204:207], v[104:107]
	v_mfma_f32_16x16x32_bf16 v[96:99], v[188:191], v[204:207], v[96:99]
	v_mfma_f32_16x16x32_bf16 v[88:91], v[180:183], v[212:215], v[88:91]
	v_mfma_f32_16x16x32_bf16 v[80:83], v[188:191], v[212:215], v[80:83]
	v_mfma_f32_16x16x32_bf16 v[72:75], v[180:183], v[220:223], v[72:75]
	v_mfma_f32_16x16x32_bf16 v[64:67], v[188:191], v[220:223], v[64:67]
	s_barrier
; #define PG8_STAGE(bufoff, gbase, voff) do { _Pragma("unroll") for (int _i = 0; _i < 2; ++_i) \
;         __builtin_amdgcn_global_load_lds((const unsigned*)((const char*)(gbase) + (voff)[_i]), (PG8_LAS unsigned*)(lds + (bufoff) + ldsw + _i * 8192), 16, 0, 0); } while (0)
; #define PG8_LDA(dst, b, h) do { _Pragma("unroll") for (int m = 0; m < 4; ++m) _Pragma("unroll") for (int k = 0; k < 2; ++k) dst[m][k] = *(const PG8_LAS bf16x8*)(lds + PG8_SA(b, h) + aoff + m * 2048 + k * 1024); } while (0)
; #define PG8_LDB(dst, b, h) do { _Pragma("unroll") for (int n = 0; n < 2; ++n) _Pragma("unroll") for (int k = 0; k < 2; ++k) dst[n][k] = *(const PG8_LAS bf16x8*)(lds + PG8_SB(b, h) + boff + n * 2048 + k * 1024); } while (0)
; #define PG8_MMA(ai, bj, At, Bt) do { __builtin_amdgcn_s_setprio(1); _Pragma("unroll") for (int m = 0; m < 4; ++m) _Pragma("unroll") for (int n = 0; n < 2; ++n) _Pragma("unroll") for (int k = 0; k < 2; ++k) \
;         acc[ai][bj][m][n] = __builtin_amdgcn_mfma_f32_16x16x32_bf16(Bt[n][k], At[m][k], acc[ai][bj][m][n], 0, 0, 0); __builtin_amdgcn_s_setprio(0); } while (0)
; #define PG8_WAIT_V(n) asm volatile("s_waitcnt vmcnt(" #n ")" ::: "memory")
; #define PG8_WAIT_L(n) asm volatile("s_waitcnt lgkmcnt(" #n ")" ::: "memory")
; #define PG8_BAR __builtin_amdgcn_s_barrier()
; #define PG8_SCHED __builtin_amdgcn_sched_barrier(0)
; template <class Epi, class Sched, bool ALIGN_EPI = false, bool SP2 = false>
; __device__ __forceinline__ void gemm_phase(PG8_LAS unsigned char* lds, const Gemm g, const Sched& S, const Epi& E, const int tid_in) {
;     ...
;             PG8_LDB(B0, 0, 0); PG8_LDB(B1, 0, 1); PG8_SCHED; PG8_LDA(At, 0, 0); PG8_STAGE(PG8_SA(1, 1), a1 + hstep, voffA);
;             PG8_WAIT_V(8); PG8_WAIT_L(0); PG8_BAR; PG8_MMA(0, 0, At, B0); PG8_MMA(0, 1, At, B1); PG8_BAR; PG8_SCHED;
;     ...
;             PG8_LDA(At, 1, 1); PG8_STAGE(PG8_SB(1, 0), b3, voffB); PG8_STAGE(PG8_SB(1, 1), b3 + hstep, voffB); PG8_STAGE(PG8_SA(1, 0), a3, voffA);
;             PG8_WAIT_V(8); PG8_WAIT_L(0); PG8_BAR; PG8_MMA(1, 0, At, B0); PG8_MMA(1, 1, At, B1); PG8_BAR; PG8_SCHED;
	s_add_i32 s38, s54, s34
	v_lshl_add_u64 v[144:145], v[144:145], 0, s[18:19]
	s_mov_b32 m0, s38
	ds_read_b128 v[192:195], v156 offset:49152
	ds_read_b128 v[196:199], v156 offset:50176
	ds_read_b128 v[200:203], v156 offset:51200
	ds_read_b128 v[204:207], v156 offset:52224
	ds_read_b128 v[208:211], v156 offset:53248
	ds_read_b128 v[212:215], v156 offset:54272
	ds_read_b128 v[216:219], v156 offset:55296
	ds_read_b128 v[220:223], v156 offset:56320
	global_load_lds_dwordx4 v[144:145], off
	s_add_i32 m0, s38, 0x2000
	s_add_u32 s0, s0, 0x40080
	v_lshl_add_u64 v[144:145], v[224:225], 0, s[18:19]
	s_addc_u32 s1, s1, 0
	s_add_i32 s38, s55, s34
	global_load_lds_dwordx4 v[144:145], off
	v_lshl_add_u64 v[144:145], s[0:1], 0, v[130:131]
	s_mov_b32 m0, s38
	s_nop 0
	global_load_lds_dwordx4 v[144:145], off
	v_lshl_add_u64 v[144:145], s[0:1], 0, v[134:135]
	s_add_i32 m0, s38, 0x2000
	s_nop 0
	global_load_lds_dwordx4 v[144:145], off
	v_lshl_add_u64 v[144:145], v[226:227], 0, s[18:19]
	s_mov_b32 m0, s43
	s_nop 0
	global_load_lds_dwordx4 v[144:145], off
	v_lshl_add_u64 v[144:145], v[228:229], 0, s[18:19]
	s_mov_b32 m0, s44
	s_nop 0
	global_load_lds_dwordx4 v[144:145], off
	s_waitcnt vmcnt(8)
	s_waitcnt lgkmcnt(0)
	s_barrier
	s_waitcnt lgkmcnt(0)
	v_mfma_f32_16x16x32_bf16 v[60:63], v[160:163], v[192:195], v[60:63]
	v_mfma_f32_16x16x32_bf16 v[52:55], v[168:171], v[192:195], v[52:55]
	v_mfma_f32_16x16x32_bf16 v[44:47], v[160:163], v[200:203], v[44:47]
	v_mfma_f32_16x16x32_bf16 v[36:39], v[168:171], v[200:203], v[36:39]
	v_mfma_f32_16x16x32_bf16 v[28:31], v[160:163], v[208:211], v[28:31]
	v_mfma_f32_16x16x32_bf16 v[20:23], v[168:171], v[208:211], v[20:23]
	v_mfma_f32_16x16x32_bf16 v[12:15], v[160:163], v[216:219], v[12:15]
	v_mfma_f32_16x16x32_bf16 v[4:7], v[168:171], v[216:219], v[4:7]
	v_mfma_f32_16x16x32_bf16 v[60:63], v[164:167], v[196:199], v[60:63]
	v_mfma_f32_16x16x32_bf16 v[52:55], v[172:175], v[196:199], v[52:55]
	v_mfma_f32_16x16x32_bf16 v[44:47], v[164:167], v[204:207], v[44:47]
	v_mfma_f32_16x16x32_bf16 v[36:39], v[172:175], v[204:207], v[36:39]
	v_mfma_f32_16x16x32_bf16 v[28:31], v[164:167], v[212:215], v[28:31]
	v_mfma_f32_16x16x32_bf16 v[20:23], v[172:175], v[212:215], v[20:23]
	v_mfma_f32_16x16x32_bf16 v[12:15], v[164:167], v[220:223], v[12:15]
	v_mfma_f32_16x16x32_bf16 v[4:7], v[172:175], v[220:223], v[4:7]
	v_mfma_f32_16x16x32_bf16 v[56:59], v[176:179], v[192:195], v[56:59]
	v_mfma_f32_16x16x32_bf16 v[48:51], v[184:187], v[192:195], v[48:51]
	v_mfma_f32_16x16x32_bf16 v[40:43], v[176:179], v[200:203], v[40:43]
	v_mfma_f32_16x16x32_bf16 v[32:35], v[184:187], v[200:203], v[32:35]
	v_mfma_f32_16x16x32_bf16 v[24:27], v[176:179], v[208:211], v[24:27]
	v_mfma_f32_16x16x32_bf16 v[16:19], v[184:187], v[208:211], v[16:19]
	v_mfma_f32_16x16x32_bf16 v[8:11], v[176:179], v[216:219], v[8:11]
	v_mfma_f32_16x16x32_bf16 v[0:3], v[184:187], v[216:219], v[0:3]
	v_mfma_f32_16x16x32_bf16 v[56:59], v[180:183], v[196:199], v[56:59]
	v_mfma_f32_16x16x32_bf16 v[48:51], v[188:191], v[196:199], v[48:51]
	v_mfma_f32_16x16x32_bf16 v[40:43], v[180:183], v[204:207], v[40:43]
	v_mfma_f32_16x16x32_bf16 v[32:35], v[188:191], v[204:207], v[32:35]
	v_mfma_f32_16x16x32_bf16 v[24:27], v[180:183], v[212:215], v[24:27]
	v_mfma_f32_16x16x32_bf16 v[16:19], v[188:191], v[212:215], v[16:19]
	v_mfma_f32_16x16x32_bf16 v[8:11], v[180:183], v[220:223], v[8:11]
	v_mfma_f32_16x16x32_bf16 v[0:3], v[188:191], v[220:223], v[0:3]
	s_barrier
	s_add_i32 s53, s53, 2
	s_add_u32 s10, s10, 0x100
	s_addc_u32 s11, s11, 0
	s_add_u32 s51, s51, 0x100
	s_addc_u32 s52, s52, 0
	s_cmp_gt_u32 s53, 13
	s_cbranch_scc0 .LBB0_3053
	s_branch .Lmy_kdone_7
.LBB0_3053:
	ds_read_b128 v[160:163], v154
	ds_read_b128 v[164:167], v154 offset:1024
	ds_read_b128 v[168:171], v154 offset:2048
	ds_read_b128 v[172:175], v154 offset:3072
	ds_read_b128 v[176:179], v155
	ds_read_b128 v[180:183], v155 offset:1024
	ds_read_b128 v[184:187], v155 offset:2048
	ds_read_b128 v[188:191], v155 offset:3072
	s_add_u32 s0, s10, 0xfffc0080
	s_addc_u32 s1, s11, -1
	s_cmp_eq_u32 s53, 12
	s_cselect_b32 s39, s25, s1
	s_cselect_b32 s38, s49, s0
	s_cselect_b32 s1, s23, s52
	s_cselect_b32 s0, s50, s51
	v_lshl_add_u64 v[144:145], s[10:11], 0, v[136:137]
	s_add_i32 m0, s35, 0xc000
	ds_read_b128 v[192:195], v156
	ds_read_b128 v[196:199], v156 offset:1024
	ds_read_b128 v[200:203], v156 offset:2048
	ds_read_b128 v[204:207], v156 offset:3072
	ds_read_b128 v[208:211], v156 offset:4096
	ds_read_b128 v[212:215], v156 offset:5120
	ds_read_b128 v[216:219], v156 offset:6144
	ds_read_b128 v[220:223], v156 offset:7168
	global_load_lds_dwordx4 v[144:145], off
	v_lshl_add_u64 v[144:145], s[10:11], 0, v[138:139]
	s_add_i32 m0, s35, 0xe000
	s_nop 0
	global_load_lds_dwordx4 v[144:145], off
	s_waitcnt vmcnt(8)
	s_waitcnt lgkmcnt(0)
	s_barrier
; #define PG8_STAGE(bufoff, gbase, voff) do { _Pragma("unroll") for (int _i = 0; _i < 2; ++_i) \
;         __builtin_amdgcn_global_load_lds((const unsigned*)((const char*)(gbase) + (voff)[_i]), (PG8_LAS unsigned*)(lds + (bufoff) + ldsw + _i * 8192), 16, 0, 0); } while (0)
; #define PG8_LDA(dst, b, h) do { _Pragma("unroll") for (int m = 0; m < 4; ++m) _Pragma("unroll") for (int k = 0; k < 2; ++k) dst[m][k] = *(const PG8_LAS bf16x8*)(lds + PG8_SA(b, h) + aoff + m * 2048 + k * 1024); } while (0)
; #define PG8_LDB(dst, b, h) do { _Pragma("unroll") for (int n = 0; n < 2; ++n) _Pragma("unroll") for (int k = 0; k < 2; ++k) dst[n][k] = *(const PG8_LAS bf16x8*)(lds + PG8_SB(b, h) + boff + n * 2048 + k * 1024); } while (0)
; #define PG8_MMA(ai, bj, At, Bt) do { __builtin_amdgcn_s_setprio(1); _Pragma("unroll") for (int m = 0; m < 4; ++m) _Pragma("unroll") for (int n = 0; n < 2; ++n) _Pragma("unroll") for (int k = 0; k < 2; ++k) \
;         acc[ai][bj][m][n] = __builtin_amdgcn_mfma_f32_16x16x32_bf16(Bt[n][k], At[m][k], acc[ai][bj][m][n], 0, 0, 0); __builtin_amdgcn_s_setprio(0); } while (0)
; #define PG8_WAIT_V(n) asm volatile("s_waitcnt vmcnt(" #n ")" ::: "memory")
; #define PG8_WAIT_L(n) asm volatile("s_waitcnt lgkmcnt(" #n ")" ::: "memory")
; #define PG8_BAR __builtin_amdgcn_s_barrier()
; #define PG8_SCHED __builtin_amdgcn_sched_barrier(0)
; template <class Epi, class Sched, bool ALIGN_EPI = false, bool SP2 = false>
; __device__ __forceinline__ void gemm_phase(PG8_LAS unsigned char* lds, const Gemm g, const Sched& S, const Epi& E, const int tid_in) {
;     ...
;             PG8_LDB(B0, 0, 0); PG8_LDB(B1, 0, 1); PG8_SCHED; PG8_LDA(At, 0, 0); PG8_STAGE(PG8_SA(1, 1), a1 + hstep, voffA);
;             PG8_WAIT_V(8); PG8_WAIT_L(0); PG8_BAR; PG8_MMA(0, 0, At, B0); PG8_MMA(0, 1, At, B1); PG8_BAR; PG8_SCHED;
;             PG8_LDA(At, 0, 1); PG8_STAGE(PG8_SB(0, 0), b2, voffB); PG8_STAGE(PG8_SB(0, 1), b2 + hstep, voffB); PG8_STAGE(PG8_SA(0, 0), a2, voffA);
;             PG8_WAIT_V(8); PG8_WAIT_L(0); PG8_BAR; PG8_MMA(1, 0, At, B0); PG8_MMA(1, 1, At, B1); PG8_BAR; PG8_SCHED;
;             PG8_LDB(B0, 1, 0); PG8_LDB(B1, 1, 1); PG8_SCHED; PG8_LDA(At, 1, 0); PG8_STAGE(PG8_SA(0, 1), a2 + hstep, voffA);
;             PG8_WAIT_V(8); PG8_WAIT_L(0); PG8_BAR; PG8_MMA(0, 0, At, B0); PG8_MMA(0, 1, At, B1); PG8_BAR; PG8_SCHED;
	s_waitcnt lgkmcnt(0)
	v_mfma_f32_16x16x32_bf16 v[124:127], v[160:163], v[192:195], v[124:127]
	v_mfma_f32_16x16x32_bf16 v[116:119], v[168:171], v[192:195], v[116:119]
	v_mfma_f32_16x16x32_bf16 v[108:111], v[160:163], v[200:203], v[108:111]
	v_mfma_f32_16x16x32_bf16 v[100:103], v[168:171], v[200:203], v[100:103]
	v_mfma_f32_16x16x32_bf16 v[92:95], v[160:163], v[208:211], v[92:95]
	v_mfma_f32_16x16x32_bf16 v[84:87], v[168:171], v[208:211], v[84:87]
	v_mfma_f32_16x16x32_bf16 v[76:79], v[160:163], v[216:219], v[76:79]
	v_mfma_f32_16x16x32_bf16 v[68:71], v[168:171], v[216:219], v[68:71]
	v_mfma_f32_16x16x32_bf16 v[124:127], v[164:167], v[196:199], v[124:127]
	v_mfma_f32_16x16x32_bf16 v[116:119], v[172:175], v[196:199], v[116:119]
	v_mfma_f32_16x16x32_bf16 v[108:111], v[164:167], v[204:207], v[108:111]
	v_mfma_f32_16x16x32_bf16 v[100:103], v[172:175], v[204:207], v[100:103]
	v_mfma_f32_16x16x32_bf16 v[92:95], v[164:167], v[212:215], v[92:95]
	v_mfma_f32_16x16x32_bf16 v[84:87], v[172:175], v[212:215], v[84:87]
	v_mfma_f32_16x16x32_bf16 v[76:79], v[164:167], v[220:223], v[76:79]
	v_mfma_f32_16x16x32_bf16 v[68:71], v[172:175], v[220:223], v[68:71]
	v_mfma_f32_16x16x32_bf16 v[120:123], v[176:179], v[192:195], v[120:123]
	v_mfma_f32_16x16x32_bf16 v[112:115], v[184:187], v[192:195], v[112:115]
	v_mfma_f32_16x16x32_bf16 v[104:107], v[176:179], v[200:203], v[104:107]
	v_mfma_f32_16x16x32_bf16 v[96:99], v[184:187], v[200:203], v[96:99]
	v_mfma_f32_16x16x32_bf16 v[88:91], v[176:179], v[208:211], v[88:91]
	v_mfma_f32_16x16x32_bf16 v[80:83], v[184:187], v[208:211], v[80:83]
	v_mfma_f32_16x16x32_bf16 v[72:75], v[176:179], v[216:219], v[72:75]
	v_mfma_f32_16x16x32_bf16 v[64:67], v[184:187], v[216:219], v[64:67]
	v_mfma_f32_16x16x32_bf16 v[120:123], v[180:183], v[196:199], v[120:123]
	v_mfma_f32_16x16x32_bf16 v[112:115], v[188:191], v[196:199], v[112:115]
	v_mfma_f32_16x16x32_bf16 v[104:107], v[180:183], v[204:207], v[104:107]
	v_mfma_f32_16x16x32_bf16 v[96:99], v[188:191], v[204:207], v[96:99]
	v_mfma_f32_16x16x32_bf16 v[88:91], v[180:183], v[212:215], v[88:91]
	v_mfma_f32_16x16x32_bf16 v[80:83], v[188:191], v[212:215], v[80:83]
	v_mfma_f32_16x16x32_bf16 v[72:75], v[180:183], v[220:223], v[72:75]
	v_mfma_f32_16x16x32_bf16 v[64:67], v[188:191], v[220:223], v[64:67]
	s_barrier
	s_add_i32 s54, s3, s34
	v_lshl_add_u64 v[144:145], s[0:1], 0, v[130:131]
	s_mov_b32 m0, s54
	ds_read_b128 v[192:195], v156 offset:16384
	ds_read_b128 v[196:199], v156 offset:17408
	ds_read_b128 v[200:203], v156 offset:18432
	ds_read_b128 v[204:207], v156 offset:19456
	ds_read_b128 v[208:211], v156 offset:20480
	ds_read_b128 v[212:215], v156 offset:21504
	ds_read_b128 v[216:219], v156 offset:22528
	ds_read_b128 v[220:223], v156 offset:23552
	global_load_lds_dwordx4 v[144:145], off
	s_add_i32 m0, s54, 0x2000
	s_add_u32 s54, s0, 0x40000
	v_lshl_add_u64 v[224:225], s[0:1], 0, v[134:135]
	s_addc_u32 s55, s1, 0
	s_add_i32 s56, s46, s34
	global_load_lds_dwordx4 v[224:225], off
	v_lshl_add_u64 v[226:227], s[54:55], 0, v[130:131]
	s_mov_b32 m0, s56
	v_lshl_add_u64 v[228:229], s[38:39], 0, v[132:133]
	global_load_lds_dwordx4 v[226:227], off
	v_lshl_add_u64 v[226:227], s[54:55], 0, v[134:135]
	s_add_i32 m0, s56, 0x2000
	s_nop 0
	global_load_lds_dwordx4 v[226:227], off
	v_lshl_add_u64 v[226:227], s[38:39], 0, v[128:129]
	s_mov_b32 m0, s35
	s_nop 0
	global_load_lds_dwordx4 v[226:227], off
	s_mov_b32 m0, s36
	s_nop 0
	global_load_lds_dwordx4 v[228:229], off
	s_waitcnt vmcnt(8)
	s_waitcnt lgkmcnt(0)
	s_barrier
	s_waitcnt lgkmcnt(0)
	v_mfma_f32_16x16x32_bf16 v[60:63], v[160:163], v[192:195], v[60:63]
	v_mfma_f32_16x16x32_bf16 v[52:55], v[168:171], v[192:195], v[52:55]
	v_mfma_f32_16x16x32_bf16 v[44:47], v[160:163], v[200:203], v[44:47]
	v_mfma_f32_16x16x32_bf16 v[36:39], v[168:171], v[200:203], v[36:39]
	v_mfma_f32_16x16x32_bf16 v[28:31], v[160:163], v[208:211], v[28:31]
	v_mfma_f32_16x16x32_bf16 v[20:23], v[168:171], v[208:211], v[20:23]
	v_mfma_f32_16x16x32_bf16 v[12:15], v[160:163], v[216:219], v[12:15]
	v_mfma_f32_16x16x32_bf16 v[4:7], v[168:171], v[216:219], v[4:7]
	v_mfma_f32_16x16x32_bf16 v[60:63], v[164:167], v[196:199], v[60:63]
	v_mfma_f32_16x16x32_bf16 v[52:55], v[172:175], v[196:199], v[52:55]
	v_mfma_f32_16x16x32_bf16 v[44:47], v[164:167], v[204:207], v[44:47]
	v_mfma_f32_16x16x32_bf16 v[36:39], v[172:175], v[204:207], v[36:39]
	v_mfma_f32_16x16x32_bf16 v[28:31], v[164:167], v[212:215], v[28:31]
	v_mfma_f32_16x16x32_bf16 v[20:23], v[172:175], v[212:215], v[20:23]
	v_mfma_f32_16x16x32_bf16 v[12:15], v[164:167], v[220:223], v[12:15]
	v_mfma_f32_16x16x32_bf16 v[4:7], v[172:175], v[220:223], v[4:7]
	v_mfma_f32_16x16x32_bf16 v[56:59], v[176:179], v[192:195], v[56:59]
	v_mfma_f32_16x16x32_bf16 v[48:51], v[184:187], v[192:195], v[48:51]
	v_mfma_f32_16x16x32_bf16 v[40:43], v[176:179], v[200:203], v[40:43]
	v_mfma_f32_16x16x32_bf16 v[32:35], v[184:187], v[200:203], v[32:35]
	v_mfma_f32_16x16x32_bf16 v[24:27], v[176:179], v[208:211], v[24:27]
	v_mfma_f32_16x16x32_bf16 v[16:19], v[184:187], v[208:211], v[16:19]
	v_mfma_f32_16x16x32_bf16 v[8:11], v[176:179], v[216:219], v[8:11]
	v_mfma_f32_16x16x32_bf16 v[0:3], v[184:187], v[216:219], v[0:3]
	v_mfma_f32_16x16x32_bf16 v[56:59], v[180:183], v[196:199], v[56:59]
	v_mfma_f32_16x16x32_bf16 v[48:51], v[188:191], v[196:199], v[48:51]
	v_mfma_f32_16x16x32_bf16 v[40:43], v[180:183], v[204:207], v[40:43]
	v_mfma_f32_16x16x32_bf16 v[32:35], v[188:191], v[204:207], v[32:35]
	v_mfma_f32_16x16x32_bf16 v[24:27], v[180:183], v[212:215], v[24:27]
	v_mfma_f32_16x16x32_bf16 v[16:19], v[188:191], v[212:215], v[16:19]
	v_mfma_f32_16x16x32_bf16 v[8:11], v[180:183], v[220:223], v[8:11]
	v_mfma_f32_16x16x32_bf16 v[0:3], v[188:191], v[220:223], v[0:3]
	s_barrier
; #define PG8_STAGE(bufoff, gbase, voff) do { _Pragma("unroll") for (int _i = 0; _i < 2; ++_i) \
;         __builtin_amdgcn_global_load_lds((const unsigned*)((const char*)(gbase) + (voff)[_i]), (PG8_LAS unsigned*)(lds + (bufoff) + ldsw + _i * 8192), 16, 0, 0); } while (0)
; #define PG8_LDA(dst, b, h) do { _Pragma("unroll") for (int m = 0; m < 4; ++m) _Pragma("unroll") for (int k = 0; k < 2; ++k) dst[m][k] = *(const PG8_LAS bf16x8*)(lds + PG8_SA(b, h) + aoff + m * 2048 + k * 1024); } while (0)
; #define PG8_LDB(dst, b, h) do { _Pragma("unroll") for (int n = 0; n < 2; ++n) _Pragma("unroll") for (int k = 0; k < 2; ++k) dst[n][k] = *(const PG8_LAS bf16x8*)(lds + PG8_SB(b, h) + boff + n * 2048 + k * 1024); } while (0)
; #define PG8_MMA(ai, bj, At, Bt) do { __builtin_amdgcn_s_setprio(1); _Pragma("unroll") for (int m = 0; m < 4; ++m) _Pragma("unroll") for (int n = 0; n < 2; ++n) _Pragma("unroll") for (int k = 0; k < 2; ++k) \
;         acc[ai][bj][m][n] = __builtin_amdgcn_mfma_f32_16x16x32_bf16(Bt[n][k], At[m][k], acc[ai][bj][m][n], 0, 0, 0); __builtin_amdgcn_s_setprio(0); } while (0)
; #define PG8_WAIT_V(n) asm volatile("s_waitcnt vmcnt(" #n ")" ::: "memory")
; #define PG8_WAIT_L(n) asm volatile("s_waitcnt lgkmcnt(" #n ")" ::: "memory")
; #define PG8_BAR __builtin_amdgcn_s_barrier()
; #define PG8_SCHED __builtin_amdgcn_sched_barrier(0)
; template <class Epi, class Sched, bool ALIGN_EPI = false, bool SP2 = false>
; __device__ __forceinline__ void gemm_phase(PG8_LAS unsigned char* lds, const Gemm g, const Sched& S, const Epi& E, const int tid_in) {
;     ...
;             PG8_LDB(B0, 1, 0); PG8_LDB(B1, 1, 1); PG8_SCHED; PG8_LDA(At, 1, 0); PG8_STAGE(PG8_SA(0, 1), a2 + hstep, voffA);
;             PG8_WAIT_V(8); PG8_WAIT_L(0); PG8_BAR; PG8_MMA(0, 0, At, B0); PG8_MMA(0, 1, At, B1); PG8_BAR; PG8_SCHED;
;             PG8_LDA(At, 1, 1); PG8_STAGE(PG8_SB(1, 0), b3, voffB); PG8_STAGE(PG8_SB(1, 1), b3 + hstep, voffB); PG8_STAGE(PG8_SA(1, 0), a3, voffA);
;             PG8_WAIT_V(8); PG8_WAIT_L(0); PG8_BAR; PG8_MMA(1, 0, At, B0); PG8_MMA(1, 1, At, B1); PG8_BAR; PG8_SCHED;
	s_add_i32 s54, 0, 0x18000
	v_add_u32_e32 v159, s54, v148
	s_add_i32 s55, 0, 0x1c000
	ds_read_b128 v[160:163], v159
	ds_read_b128 v[164:167], v159 offset:1024
	ds_read_b128 v[168:171], v159 offset:2048
	ds_read_b128 v[172:175], v159 offset:3072
	v_add_u32_e32 v159, s55, v148
	ds_read_b128 v[176:179], v159
	ds_read_b128 v[180:183], v159 offset:1024
	ds_read_b128 v[184:187], v159 offset:2048
	ds_read_b128 v[188:191], v159 offset:3072
	s_add_u32 s38, s38, 0x40000
	s_addc_u32 s39, s39, 0
	s_mov_b32 m0, s37
	v_lshl_add_u64 v[230:231], s[38:39], 0, v[128:129]
	ds_read_b128 v[192:195], v156 offset:32768
	ds_read_b128 v[196:199], v156 offset:33792
	ds_read_b128 v[200:203], v156 offset:34816
	ds_read_b128 v[204:207], v156 offset:35840
	ds_read_b128 v[208:211], v156 offset:36864
	ds_read_b128 v[212:215], v156 offset:37888
	ds_read_b128 v[216:219], v156 offset:38912
	ds_read_b128 v[220:223], v156 offset:39936
	global_load_lds_dwordx4 v[230:231], off
	v_lshl_add_u64 v[230:231], s[38:39], 0, v[132:133]
	s_mov_b32 m0, s40
	s_nop 0
	global_load_lds_dwordx4 v[230:231], off
	s_waitcnt vmcnt(8)
	s_waitcnt lgkmcnt(0)
	s_barrier
	s_waitcnt lgkmcnt(0)
	v_mfma_f32_16x16x32_bf16 v[124:127], v[160:163], v[192:195], v[124:127]
	v_mfma_f32_16x16x32_bf16 v[116:119], v[168:171], v[192:195], v[116:119]
	v_mfma_f32_16x16x32_bf16 v[108:111], v[160:163], v[200:203], v[108:111]
	v_mfma_f32_16x16x32_bf16 v[100:103], v[168:171], v[200:203], v[100:103]
	v_mfma_f32_16x16x32_bf16 v[92:95], v[160:163], v[208:211], v[92:95]
	v_mfma_f32_16x16x32_bf16 v[84:87], v[168:171], v[208:211], v[84:87]
	v_mfma_f32_16x16x32_bf16 v[76:79], v[160:163], v[216:219], v[76:79]
	v_mfma_f32_16x16x32_bf16 v[68:71], v[168:171], v[216:219], v[68:71]
	v_mfma_f32_16x16x32_bf16 v[124:127], v[164:167], v[196:199], v[124:127]
	v_mfma_f32_16x16x32_bf16 v[116:119], v[172:175], v[196:199], v[116:119]
	v_mfma_f32_16x16x32_bf16 v[108:111], v[164:167], v[204:207], v[108:111]
	v_mfma_f32_16x16x32_bf16 v[100:103], v[172:175], v[204:207], v[100:103]
	v_mfma_f32_16x16x32_bf16 v[92:95], v[164:167], v[212:215], v[92:95]
	v_mfma_f32_16x16x32_bf16 v[84:87], v[172:175], v[212:215], v[84:87]
	v_mfma_f32_16x16x32_bf16 v[76:79], v[164:167], v[220:223], v[76:79]
	v_mfma_f32_16x16x32_bf16 v[68:71], v[172:175], v[220:223], v[68:71]
	v_mfma_f32_16x16x32_bf16 v[120:123], v[176:179], v[192:195], v[120:123]
	v_mfma_f32_16x16x32_bf16 v[112:115], v[184:187], v[192:195], v[112:115]
	v_mfma_f32_16x16x32_bf16 v[104:107], v[176:179], v[200:203], v[104:107]
	v_mfma_f32_16x16x32_bf16 v[96:99], v[184:187], v[200:203], v[96:99]
	v_mfma_f32_16x16x32_bf16 v[88:91], v[176:179], v[208:211], v[88:91]
	v_mfma_f32_16x16x32_bf16 v[80:83], v[184:187], v[208:211], v[80:83]
	v_mfma_f32_16x16x32_bf16 v[72:75], v[176:179], v[216:219], v[72:75]
	v_mfma_f32_16x16x32_bf16 v[64:67], v[184:187], v[216:219], v[64:67]
	v_mfma_f32_16x16x32_bf16 v[120:123], v[180:183], v[196:199], v[120:123]
	v_mfma_f32_16x16x32_bf16 v[112:115], v[188:191], v[196:199], v[112:115]
	v_mfma_f32_16x16x32_bf16 v[104:107], v[180:183], v[204:207], v[104:107]
	v_mfma_f32_16x16x32_bf16 v[96:99], v[188:191], v[204:207], v[96:99]
	v_mfma_f32_16x16x32_bf16 v[88:91], v[180:183], v[212:215], v[88:91]
	v_mfma_f32_16x16x32_bf16 v[80:83], v[188:191], v[212:215], v[80:83]
	v_mfma_f32_16x16x32_bf16 v[72:75], v[180:183], v[220:223], v[72:75]
	v_mfma_f32_16x16x32_bf16 v[64:67], v[188:191], v[220:223], v[64:67]
	s_barrier
	s_add_i32 s38, s54, s34
	v_lshl_add_u64 v[144:145], v[144:145], 0, s[18:19]
	s_mov_b32 m0, s38
	ds_read_b128 v[192:195], v156 offset:49152
	ds_read_b128 v[196:199], v156 offset:50176
	ds_read_b128 v[200:203], v156 offset:51200
	ds_read_b128 v[204:207], v156 offset:52224
	ds_read_b128 v[208:211], v156 offset:53248
	ds_read_b128 v[212:215], v156 offset:54272
	ds_read_b128 v[216:219], v156 offset:55296
	ds_read_b128 v[220:223], v156 offset:56320
	global_load_lds_dwordx4 v[144:145], off
	s_add_i32 m0, s38, 0x2000
	s_add_u32 s0, s0, 0x40080
	v_lshl_add_u64 v[144:145], v[224:225], 0, s[18:19]
	s_addc_u32 s1, s1, 0
	s_add_i32 s38, s55, s34
	global_load_lds_dwordx4 v[144:145], off
	v_lshl_add_u64 v[144:145], s[0:1], 0, v[130:131]
	s_mov_b32 m0, s38
	s_nop 0
	global_load_lds_dwordx4 v[144:145], off
	v_lshl_add_u64 v[144:145], s[0:1], 0, v[134:135]
	s_add_i32 m0, s38, 0x2000
	s_nop 0
	global_load_lds_dwordx4 v[144:145], off
	v_lshl_add_u64 v[144:145], v[226:227], 0, s[18:19]
	s_mov_b32 m0, s43
	s_nop 0
	global_load_lds_dwordx4 v[144:145], off
	v_lshl_add_u64 v[144:145], v[228:229], 0, s[18:19]
	s_mov_b32 m0, s44
	s_nop 0
	global_load_lds_dwordx4 v[144:145], off
	s_waitcnt vmcnt(8)
	s_waitcnt lgkmcnt(0)
	s_barrier
	s_waitcnt lgkmcnt(0)
	v_mfma_f32_16x16x32_bf16 v[60:63], v[160:163], v[192:195], v[60:63]
	v_mfma_f32_16x16x32_bf16 v[52:55], v[168:171], v[192:195], v[52:55]
	v_mfma_f32_16x16x32_bf16 v[44:47], v[160:163], v[200:203], v[44:47]
	v_mfma_f32_16x16x32_bf16 v[36:39], v[168:171], v[200:203], v[36:39]
	v_mfma_f32_16x16x32_bf16 v[28:31], v[160:163], v[208:211], v[28:31]
	v_mfma_f32_16x16x32_bf16 v[20:23], v[168:171], v[208:211], v[20:23]
	v_mfma_f32_16x16x32_bf16 v[12:15], v[160:163], v[216:219], v[12:15]
	v_mfma_f32_16x16x32_bf16 v[4:7], v[168:171], v[216:219], v[4:7]
	v_mfma_f32_16x16x32_bf16 v[60:63], v[164:167], v[196:199], v[60:63]
	v_mfma_f32_16x16x32_bf16 v[52:55], v[172:175], v[196:199], v[52:55]
	v_mfma_f32_16x16x32_bf16 v[44:47], v[164:167], v[204:207], v[44:47]
	v_mfma_f32_16x16x32_bf16 v[36:39], v[172:175], v[204:207], v[36:39]
	v_mfma_f32_16x16x32_bf16 v[28:31], v[164:167], v[212:215], v[28:31]
	v_mfma_f32_16x16x32_bf16 v[20:23], v[172:175], v[212:215], v[20:23]
	v_mfma_f32_16x16x32_bf16 v[12:15], v[164:167], v[220:223], v[12:15]
	v_mfma_f32_16x16x32_bf16 v[4:7], v[172:175], v[220:223], v[4:7]
	v_mfma_f32_16x16x32_bf16 v[56:59], v[176:179], v[192:195], v[56:59]
	v_mfma_f32_16x16x32_bf16 v[48:51], v[184:187], v[192:195], v[48:51]
	v_mfma_f32_16x16x32_bf16 v[40:43], v[176:179], v[200:203], v[40:43]
	v_mfma_f32_16x16x32_bf16 v[32:35], v[184:187], v[200:203], v[32:35]
	v_mfma_f32_16x16x32_bf16 v[24:27], v[176:179], v[208:211], v[24:27]
	v_mfma_f32_16x16x32_bf16 v[16:19], v[184:187], v[208:211], v[16:19]
	v_mfma_f32_16x16x32_bf16 v[8:11], v[176:179], v[216:219], v[8:11]
	v_mfma_f32_16x16x32_bf16 v[0:3], v[184:187], v[216:219], v[0:3]
	v_mfma_f32_16x16x32_bf16 v[56:59], v[180:183], v[196:199], v[56:59]
	v_mfma_f32_16x16x32_bf16 v[48:51], v[188:191], v[196:199], v[48:51]
	v_mfma_f32_16x16x32_bf16 v[40:43], v[180:183], v[204:207], v[40:43]
	v_mfma_f32_16x16x32_bf16 v[32:35], v[188:191], v[204:207], v[32:35]
	v_mfma_f32_16x16x32_bf16 v[24:27], v[180:183], v[212:215], v[24:27]
	v_mfma_f32_16x16x32_bf16 v[16:19], v[188:191], v[212:215], v[16:19]
	v_mfma_f32_16x16x32_bf16 v[8:11], v[180:183], v[220:223], v[8:11]
	v_mfma_f32_16x16x32_bf16 v[0:3], v[188:191], v[220:223], v[0:3]
	s_barrier
	s_add_i32 s53, s53, 2
	s_add_u32 s10, s10, 0x100
	s_addc_u32 s11, s11, 0
	s_add_u32 s51, s51, 0x100
	s_addc_u32 s52, s52, 0
	s_cmp_gt_u32 s53, 13
	s_cbranch_scc0 .LBB0_3053

; #define PG8_STAGE(bufoff, gbase, voff) do { _Pragma("unroll") for (int _i = 0; _i < 2; ++_i) \
;         __builtin_amdgcn_global_load_lds((const unsigned*)((const char*)(gbase) + (voff)[_i]), (PG8_LAS unsigned*)(lds + (bufoff) + ldsw + _i * 8192), 16, 0, 0); } while (0)
; #define PG8_LDA(dst, b, h) do { _Pragma("unroll") for (int m = 0; m < 4; ++m) _Pragma("unroll") for (int k = 0; k < 2; ++k) dst[m][k] = *(const PG8_LAS bf16x8*)(lds + PG8_SA(b, h) + aoff + m * 2048 + k * 1024); } while (0)
; #define PG8_LDB(dst, b, h) do { _Pragma("unroll") for (int n = 0; n < 2; ++n) _Pragma("unroll") for (int k = 0; k < 2; ++k) dst[n][k] = *(const PG8_LAS bf16x8*)(lds + PG8_SB(b, h) + boff + n * 2048 + k * 1024); } while (0)
; #define PG8_MMA(ai, bj, At, Bt) do { __builtin_amdgcn_s_setprio(1); _Pragma("unroll") for (int m = 0; m < 4; ++m) _Pragma("unroll") for (int n = 0; n < 2; ++n) _Pragma("unroll") for (int k = 0; k < 2; ++k) \
;         acc[ai][bj][m][n] = __builtin_amdgcn_mfma_f32_16x16x32_bf16(Bt[n][k], At[m][k], acc[ai][bj][m][n], 0, 0, 0); __builtin_amdgcn_s_setprio(0); } while (0)
; #define PG8_BAR __builtin_amdgcn_s_barrier()
; template <class Epi, class Sched, bool ALIGN_EPI = false, bool SP2 = false>
; __device__ __forceinline__ void gemm_phase(PG8_LAS unsigned char* lds, const Gemm g, const Sched& S, const Epi& E, const int tid_in) {
;     ...
;             PG8_LDB(B0, 0, 0); PG8_LDB(B1, 0, 1); PG8_SCHED; PG8_LDA(At, 0, 0); PG8_STAGE(PG8_SA(1, 1), a1 + hstep, voffA);
;             PG8_WAIT_V(8); PG8_WAIT_L(0); PG8_BAR; PG8_MMA(0, 0, At, B0); PG8_MMA(0, 1, At, B1); PG8_BAR; PG8_SCHED;
;             PG8_LDA(At, 0, 1); PG8_STAGE(PG8_SB(0, 0), b2, voffB); PG8_STAGE(PG8_SB(0, 1), b2 + hstep, voffB); PG8_STAGE(PG8_SA(0, 0), a2, voffA);
;             PG8_WAIT_V(8); PG8_WAIT_L(0); PG8_BAR; PG8_MMA(1, 0, At, B0); PG8_MMA(1, 1, At, B1); PG8_BAR; PG8_SCHED;
;             PG8_LDB(B0, 1, 0); PG8_LDB(B1, 1, 1); PG8_SCHED; PG8_LDA(At, 1, 0); PG8_STAGE(PG8_SA(0, 1), a2 + hstep, voffA);
;             PG8_WAIT_V(8); PG8_WAIT_L(0); PG8_BAR; PG8_MMA(0, 0, At, B0); PG8_MMA(0, 1, At, B1); PG8_BAR; PG8_SCHED;
;             PG8_LDA(At, 1, 1); PG8_STAGE(PG8_SB(1, 0), b3, voffB); PG8_STAGE(PG8_SB(1, 1), b3 + hstep, voffB); PG8_STAGE(PG8_SA(1, 0), a3, voffA);
;             PG8_WAIT_V(8); PG8_WAIT_L(0); PG8_BAR; PG8_MMA(1, 0, At, B0); PG8_MMA(1, 1, At, B1); PG8_BAR; PG8_SCHED;
.LBB0_3134:
	s_add_u32 s81, s0, 0x100
	v_mov_b32_e32 v0, 0
	s_addc_u32 s82, s1, 0
	s_mov_b32 s83, -2
	ds_read_b128 v[92:95], v207
	ds_read_b128 v[100:103], v207 offset:1024
	ds_read_b128 v[112:115], v207 offset:2048
	ds_read_b128 v[124:127], v207 offset:3072
	ds_read_b128 v[136:139], v208
	ds_read_b128 v[148:151], v208 offset:1024
	ds_read_b128 v[152:155], v208 offset:2048
	ds_read_b128 v[156:159], v208 offset:3072
	s_add_u32 s62, s60, 0x100
	s_addc_u32 s63, s61, 0
	s_cmp_eq_u32 s83, 40
	s_cselect_b32 s65, s9, s63
	s_cselect_b32 s64, s8, s62
	s_cselect_b32 s1, s59, s82
	s_cselect_b32 s0, s58, s81
	v_lshl_add_u64 v[214:215], s[60:61], 0, v[192:193]
	s_add_i32 m0, s4, 0xc000
	ds_read_b128 v[160:163], v209
	ds_read_b128 v[164:167], v209 offset:1024
	ds_read_b128 v[168:171], v209 offset:2048
	ds_read_b128 v[172:175], v209 offset:3072
	ds_read_b128 v[176:179], v209 offset:4096
	ds_read_b128 v[180:183], v209 offset:5120
	ds_read_b128 v[200:203], v209 offset:6144
	ds_read_b128 v[210:213], v209 offset:7168
	global_load_lds_dwordx4 v[214:215], off
	v_lshl_add_u64 v[214:215], s[60:61], 0, v[194:195]
	s_add_i32 m0, s4, 0xe000
	s_nop 0
	global_load_lds_dwordx4 v[214:215], off
	s_waitcnt vmcnt(8)
	s_waitcnt lgkmcnt(0)
	s_barrier
	s_waitcnt lgkmcnt(0)
	v_mfma_f32_16x16x32_bf16 v[144:147], v[92:95], v[160:163], 0
	v_mfma_f32_16x16x32_bf16 v[140:143], v[112:115], v[160:163], 0
	v_mfma_f32_16x16x32_bf16 v[120:123], v[92:95], v[168:171], 0
	v_mfma_f32_16x16x32_bf16 v[116:119], v[112:115], v[168:171], 0
	v_mfma_f32_16x16x32_bf16 v[96:99], v[92:95], v[176:179], 0
	v_mfma_f32_16x16x32_bf16 v[88:91], v[112:115], v[176:179], 0
	v_mfma_f32_16x16x32_bf16 v[76:79], v[92:95], v[200:203], 0
	v_mfma_f32_16x16x32_bf16 v[72:75], v[112:115], v[200:203], 0
	v_mfma_f32_16x16x32_bf16 v[144:147], v[100:103], v[164:167], v[144:147]
	v_mfma_f32_16x16x32_bf16 v[140:143], v[124:127], v[164:167], v[140:143]
	v_mfma_f32_16x16x32_bf16 v[120:123], v[100:103], v[172:175], v[120:123]
	v_mfma_f32_16x16x32_bf16 v[116:119], v[124:127], v[172:175], v[116:119]
	v_mfma_f32_16x16x32_bf16 v[96:99], v[100:103], v[180:183], v[96:99]
	v_mfma_f32_16x16x32_bf16 v[88:91], v[124:127], v[180:183], v[88:91]
	v_mfma_f32_16x16x32_bf16 v[76:79], v[100:103], v[210:213], v[76:79]
	v_mfma_f32_16x16x32_bf16 v[72:75], v[124:127], v[210:213], v[72:75]
	v_mfma_f32_16x16x32_bf16 v[132:135], v[136:139], v[160:163], 0
	v_mfma_f32_16x16x32_bf16 v[128:131], v[152:155], v[160:163], 0
	v_mfma_f32_16x16x32_bf16 v[108:111], v[136:139], v[168:171], 0
	v_mfma_f32_16x16x32_bf16 v[104:107], v[152:155], v[168:171], 0
	v_mfma_f32_16x16x32_bf16 v[84:87], v[136:139], v[176:179], 0
	v_mfma_f32_16x16x32_bf16 v[80:83], v[152:155], v[176:179], 0
	v_mfma_f32_16x16x32_bf16 v[68:71], v[136:139], v[200:203], 0
	v_mfma_f32_16x16x32_bf16 v[64:67], v[152:155], v[200:203], 0
	v_mfma_f32_16x16x32_bf16 v[132:135], v[148:151], v[164:167], v[132:135]
	v_mfma_f32_16x16x32_bf16 v[128:131], v[156:159], v[164:167], v[128:131]
	v_mfma_f32_16x16x32_bf16 v[108:111], v[148:151], v[172:175], v[108:111]
	v_mfma_f32_16x16x32_bf16 v[104:107], v[156:159], v[172:175], v[104:107]
	v_mfma_f32_16x16x32_bf16 v[84:87], v[148:151], v[180:183], v[84:87]
	v_mfma_f32_16x16x32_bf16 v[80:83], v[156:159], v[180:183], v[80:83]
	v_mfma_f32_16x16x32_bf16 v[68:71], v[148:151], v[210:213], v[68:71]
	v_mfma_f32_16x16x32_bf16 v[64:67], v[156:159], v[210:213], v[64:67]
	s_barrier
	s_add_i32 s60, s3, s2
	v_lshl_add_u64 v[214:215], s[0:1], 0, v[186:187]
	s_mov_b32 m0, s60
	ds_read_b128 v[160:163], v209 offset:16384
	ds_read_b128 v[164:167], v209 offset:17408
	ds_read_b128 v[168:171], v209 offset:18432
	ds_read_b128 v[172:175], v209 offset:19456
	ds_read_b128 v[176:179], v209 offset:20480
	ds_read_b128 v[180:183], v209 offset:21504
	ds_read_b128 v[200:203], v209 offset:22528
	ds_read_b128 v[210:213], v209 offset:23552
	global_load_lds_dwordx4 v[214:215], off
	s_add_i32 m0, s60, 0x2000
	s_add_u32 s60, s0, 0xb0000
	v_lshl_add_u64 v[216:217], s[0:1], 0, v[190:191]
	s_addc_u32 s61, s1, 0
	s_add_i32 s84, s69, s2
	global_load_lds_dwordx4 v[216:217], off
	v_lshl_add_u64 v[218:219], s[60:61], 0, v[186:187]
	s_mov_b32 m0, s84
	v_lshl_add_u64 v[220:221], s[64:65], 0, v[188:189]
	global_load_lds_dwordx4 v[218:219], off
	v_lshl_add_u64 v[218:219], s[60:61], 0, v[190:191]
	s_add_i32 m0, s84, 0x2000
	s_nop 0
	global_load_lds_dwordx4 v[218:219], off
	v_lshl_add_u64 v[218:219], s[64:65], 0, v[184:185]
	s_mov_b32 m0, s4
	s_nop 0
	global_load_lds_dwordx4 v[218:219], off
	s_mov_b32 m0, s5
	s_nop 0
	global_load_lds_dwordx4 v[220:221], off
	s_waitcnt vmcnt(8)
	s_waitcnt lgkmcnt(0)
	s_barrier
; #define PG8_STAGE(bufoff, gbase, voff) do { _Pragma("unroll") for (int _i = 0; _i < 2; ++_i) \
;         __builtin_amdgcn_global_load_lds((const unsigned*)((const char*)(gbase) + (voff)[_i]), (PG8_LAS unsigned*)(lds + (bufoff) + ldsw + _i * 8192), 16, 0, 0); } while (0)
; #define PG8_LDA(dst, b, h) do { _Pragma("unroll") for (int m = 0; m < 4; ++m) _Pragma("unroll") for (int k = 0; k < 2; ++k) dst[m][k] = *(const PG8_LAS bf16x8*)(lds + PG8_SA(b, h) + aoff + m * 2048 + k * 1024); } while (0)
; #define PG8_LDB(dst, b, h) do { _Pragma("unroll") for (int n = 0; n < 2; ++n) _Pragma("unroll") for (int k = 0; k < 2; ++k) dst[n][k] = *(const PG8_LAS bf16x8*)(lds + PG8_SB(b, h) + boff + n * 2048 + k * 1024); } while (0)
; #define PG8_MMA(ai, bj, At, Bt) do { __builtin_amdgcn_s_setprio(1); _Pragma("unroll") for (int m = 0; m < 4; ++m) _Pragma("unroll") for (int n = 0; n < 2; ++n) _Pragma("unroll") for (int k = 0; k < 2; ++k) \
;         acc[ai][bj][m][n] = __builtin_amdgcn_mfma_f32_16x16x32_bf16(Bt[n][k], At[m][k], acc[ai][bj][m][n], 0, 0, 0); __builtin_amdgcn_s_setprio(0); } while (0)
; #define PG8_WAIT_V(n) asm volatile("s_waitcnt vmcnt(" #n ")" ::: "memory")
; #define PG8_WAIT_L(n) asm volatile("s_waitcnt lgkmcnt(" #n ")" ::: "memory")
; #define PG8_BAR __builtin_amdgcn_s_barrier()
; #define PG8_SCHED __builtin_amdgcn_sched_barrier(0)
; template <class Epi, class Sched, bool ALIGN_EPI = false, bool SP2 = false>
; __device__ __forceinline__ void gemm_phase(PG8_LAS unsigned char* lds, const Gemm g, const Sched& S, const Epi& E, const int tid_in) {
;     ...
;             PG8_LDB(B0, 0, 0); PG8_LDB(B1, 0, 1); PG8_SCHED; PG8_LDA(At, 0, 0); PG8_STAGE(PG8_SA(1, 1), a1 + hstep, voffA);
;             PG8_WAIT_V(8); PG8_WAIT_L(0); PG8_BAR; PG8_MMA(0, 0, At, B0); PG8_MMA(0, 1, At, B1); PG8_BAR; PG8_SCHED;
;             PG8_LDA(At, 0, 1); PG8_STAGE(PG8_SB(0, 0), b2, voffB); PG8_STAGE(PG8_SB(0, 1), b2 + hstep, voffB); PG8_STAGE(PG8_SA(0, 0), a2, voffA);
;             PG8_WAIT_V(8); PG8_WAIT_L(0); PG8_BAR; PG8_MMA(1, 0, At, B0); PG8_MMA(1, 1, At, B1); PG8_BAR; PG8_SCHED;
;             PG8_LDB(B0, 1, 0); PG8_LDB(B1, 1, 1); PG8_SCHED; PG8_LDA(At, 1, 0); PG8_STAGE(PG8_SA(0, 1), a2 + hstep, voffA);
;             PG8_WAIT_V(8); PG8_WAIT_L(0); PG8_BAR; PG8_MMA(0, 0, At, B0); PG8_MMA(0, 1, At, B1); PG8_BAR; PG8_SCHED;
	s_waitcnt lgkmcnt(0)
	v_mfma_f32_16x16x32_bf16 v[60:63], v[92:95], v[160:163], 0
	v_mfma_f32_16x16x32_bf16 v[56:59], v[112:115], v[160:163], 0
	v_mfma_f32_16x16x32_bf16 v[44:47], v[92:95], v[168:171], 0
	v_mfma_f32_16x16x32_bf16 v[40:43], v[112:115], v[168:171], 0
	v_mfma_f32_16x16x32_bf16 v[28:31], v[92:95], v[176:179], 0
	v_mfma_f32_16x16x32_bf16 v[24:27], v[112:115], v[176:179], 0
	v_mfma_f32_16x16x32_bf16 v[12:15], v[92:95], v[200:203], 0
	v_mfma_f32_16x16x32_bf16 v[8:11], v[112:115], v[200:203], 0
	v_mfma_f32_16x16x32_bf16 v[60:63], v[100:103], v[164:167], v[60:63]
	v_mfma_f32_16x16x32_bf16 v[56:59], v[124:127], v[164:167], v[56:59]
	v_mfma_f32_16x16x32_bf16 v[44:47], v[100:103], v[172:175], v[44:47]
	v_mfma_f32_16x16x32_bf16 v[40:43], v[124:127], v[172:175], v[40:43]
	v_mfma_f32_16x16x32_bf16 v[28:31], v[100:103], v[180:183], v[28:31]
	v_mfma_f32_16x16x32_bf16 v[24:27], v[124:127], v[180:183], v[24:27]
	v_mfma_f32_16x16x32_bf16 v[12:15], v[100:103], v[210:213], v[12:15]
	v_mfma_f32_16x16x32_bf16 v[8:11], v[124:127], v[210:213], v[8:11]
	v_mfma_f32_16x16x32_bf16 v[52:55], v[136:139], v[160:163], 0
	v_mfma_f32_16x16x32_bf16 v[48:51], v[152:155], v[160:163], 0
	v_mfma_f32_16x16x32_bf16 v[36:39], v[136:139], v[168:171], 0
	v_mfma_f32_16x16x32_bf16 v[32:35], v[152:155], v[168:171], 0
	v_mfma_f32_16x16x32_bf16 v[20:23], v[136:139], v[176:179], 0
	v_mfma_f32_16x16x32_bf16 v[16:19], v[152:155], v[176:179], 0
	v_mfma_f32_16x16x32_bf16 v[4:7], v[136:139], v[200:203], 0
	v_mfma_f32_16x16x32_bf16 v[0:3], v[152:155], v[200:203], 0
	v_mfma_f32_16x16x32_bf16 v[52:55], v[148:151], v[164:167], v[52:55]
	v_mfma_f32_16x16x32_bf16 v[48:51], v[156:159], v[164:167], v[48:51]
	v_mfma_f32_16x16x32_bf16 v[36:39], v[148:151], v[172:175], v[36:39]
	v_mfma_f32_16x16x32_bf16 v[32:35], v[156:159], v[172:175], v[32:35]
	v_mfma_f32_16x16x32_bf16 v[20:23], v[148:151], v[180:183], v[20:23]
	v_mfma_f32_16x16x32_bf16 v[16:19], v[156:159], v[180:183], v[16:19]
	v_mfma_f32_16x16x32_bf16 v[4:7], v[148:151], v[210:213], v[4:7]
	v_mfma_f32_16x16x32_bf16 v[0:3], v[156:159], v[210:213], v[0:3]
	s_barrier
	s_add_i32 s84, 0, 0x18000
	s_add_i32 s85, 0, 0x1c000
	v_add_u32_e32 v124, s84, v205
	v_add_u32_e32 v156, s85, v205
	ds_read_b128 v[92:95], v124
	ds_read_b128 v[100:103], v124 offset:1024
	ds_read_b128 v[112:115], v124 offset:2048
	ds_read_b128 v[124:127], v124 offset:3072
	ds_read_b128 v[136:139], v156
	ds_read_b128 v[148:151], v156 offset:1024
	ds_read_b128 v[152:155], v156 offset:2048
	ds_read_b128 v[156:159], v156 offset:3072
	s_add_u32 s60, s64, 0xb0000
	s_addc_u32 s61, s65, 0
	s_mov_b32 m0, s34
	v_lshl_add_u64 v[222:223], s[60:61], 0, v[184:185]
	ds_read_b128 v[160:163], v209 offset:32768
	ds_read_b128 v[164:167], v209 offset:33792
	ds_read_b128 v[168:171], v209 offset:34816
	ds_read_b128 v[172:175], v209 offset:35840
	ds_read_b128 v[176:179], v209 offset:36864
	ds_read_b128 v[180:183], v209 offset:37888
	ds_read_b128 v[200:203], v209 offset:38912
	ds_read_b128 v[210:213], v209 offset:39936
	global_load_lds_dwordx4 v[222:223], off
	v_lshl_add_u64 v[222:223], s[60:61], 0, v[188:189]
	s_mov_b32 m0, s35
	s_nop 0
	global_load_lds_dwordx4 v[222:223], off
	s_waitcnt vmcnt(8)
	s_waitcnt lgkmcnt(0)
	s_barrier
	s_waitcnt lgkmcnt(0)
	v_mfma_f32_16x16x32_bf16 v[144:147], v[92:95], v[160:163], v[144:147]
	v_mfma_f32_16x16x32_bf16 v[140:143], v[112:115], v[160:163], v[140:143]
	v_mfma_f32_16x16x32_bf16 v[120:123], v[92:95], v[168:171], v[120:123]
	v_mfma_f32_16x16x32_bf16 v[116:119], v[112:115], v[168:171], v[116:119]
	v_mfma_f32_16x16x32_bf16 v[96:99], v[92:95], v[176:179], v[96:99]
	v_mfma_f32_16x16x32_bf16 v[88:91], v[112:115], v[176:179], v[88:91]
	v_mfma_f32_16x16x32_bf16 v[76:79], v[92:95], v[200:203], v[76:79]
	v_mfma_f32_16x16x32_bf16 v[72:75], v[112:115], v[200:203], v[72:75]
	v_mfma_f32_16x16x32_bf16 v[144:147], v[100:103], v[164:167], v[144:147]
	v_mfma_f32_16x16x32_bf16 v[140:143], v[124:127], v[164:167], v[140:143]
	v_mfma_f32_16x16x32_bf16 v[120:123], v[100:103], v[172:175], v[120:123]
	v_mfma_f32_16x16x32_bf16 v[116:119], v[124:127], v[172:175], v[116:119]
	v_mfma_f32_16x16x32_bf16 v[96:99], v[100:103], v[180:183], v[96:99]
	v_mfma_f32_16x16x32_bf16 v[88:91], v[124:127], v[180:183], v[88:91]
	v_mfma_f32_16x16x32_bf16 v[76:79], v[100:103], v[210:213], v[76:79]
	v_mfma_f32_16x16x32_bf16 v[72:75], v[124:127], v[210:213], v[72:75]
	v_mfma_f32_16x16x32_bf16 v[132:135], v[136:139], v[160:163], v[132:135]
	v_mfma_f32_16x16x32_bf16 v[128:131], v[152:155], v[160:163], v[128:131]
	v_mfma_f32_16x16x32_bf16 v[108:111], v[136:139], v[168:171], v[108:111]
	v_mfma_f32_16x16x32_bf16 v[104:107], v[152:155], v[168:171], v[104:107]
	v_mfma_f32_16x16x32_bf16 v[84:87], v[136:139], v[176:179], v[84:87]
	v_mfma_f32_16x16x32_bf16 v[80:83], v[152:155], v[176:179], v[80:83]
	v_mfma_f32_16x16x32_bf16 v[68:71], v[136:139], v[200:203], v[68:71]
	v_mfma_f32_16x16x32_bf16 v[64:67], v[152:155], v[200:203], v[64:67]
	v_mfma_f32_16x16x32_bf16 v[132:135], v[148:151], v[164:167], v[132:135]
	v_mfma_f32_16x16x32_bf16 v[128:131], v[156:159], v[164:167], v[128:131]
	v_mfma_f32_16x16x32_bf16 v[108:111], v[148:151], v[172:175], v[108:111]
	v_mfma_f32_16x16x32_bf16 v[104:107], v[156:159], v[172:175], v[104:107]
	v_mfma_f32_16x16x32_bf16 v[84:87], v[148:151], v[180:183], v[84:87]
	v_mfma_f32_16x16x32_bf16 v[80:83], v[156:159], v[180:183], v[80:83]
	v_mfma_f32_16x16x32_bf16 v[68:71], v[148:151], v[210:213], v[68:71]
	v_mfma_f32_16x16x32_bf16 v[64:67], v[156:159], v[210:213], v[64:67]
	s_barrier
; #define PG8_STAGE(bufoff, gbase, voff) do { _Pragma("unroll") for (int _i = 0; _i < 2; ++_i) \
;         __builtin_amdgcn_global_load_lds((const unsigned*)((const char*)(gbase) + (voff)[_i]), (PG8_LAS unsigned*)(lds + (bufoff) + ldsw + _i * 8192), 16, 0, 0); } while (0)
; #define PG8_LDA(dst, b, h) do { _Pragma("unroll") for (int m = 0; m < 4; ++m) _Pragma("unroll") for (int k = 0; k < 2; ++k) dst[m][k] = *(const PG8_LAS bf16x8*)(lds + PG8_SA(b, h) + aoff + m * 2048 + k * 1024); } while (0)
; #define PG8_LDB(dst, b, h) do { _Pragma("unroll") for (int n = 0; n < 2; ++n) _Pragma("unroll") for (int k = 0; k < 2; ++k) dst[n][k] = *(const PG8_LAS bf16x8*)(lds + PG8_SB(b, h) + boff + n * 2048 + k * 1024); } while (0)
; #define PG8_MMA(ai, bj, At, Bt) do { __builtin_amdgcn_s_setprio(1); _Pragma("unroll") for (int m = 0; m < 4; ++m) _Pragma("unroll") for (int n = 0; n < 2; ++n) _Pragma("unroll") for (int k = 0; k < 2; ++k) \
;         acc[ai][bj][m][n] = __builtin_amdgcn_mfma_f32_16x16x32_bf16(Bt[n][k], At[m][k], acc[ai][bj][m][n], 0, 0, 0); __builtin_amdgcn_s_setprio(0); } while (0)
; #define PG8_WAIT_V(n) asm volatile("s_waitcnt vmcnt(" #n ")" ::: "memory")
; #define PG8_WAIT_L(n) asm volatile("s_waitcnt lgkmcnt(" #n ")" ::: "memory")
; #define PG8_BAR __builtin_amdgcn_s_barrier()
; #define PG8_SCHED __builtin_amdgcn_sched_barrier(0)
; template <class Epi, class Sched, bool ALIGN_EPI = false, bool SP2 = false>
; __device__ __forceinline__ void gemm_phase(PG8_LAS unsigned char* lds, const Gemm g, const Sched& S, const Epi& E, const int tid_in) {
;     ...
;             PG8_LDB(B0, 0, 0); PG8_LDB(B1, 0, 1); PG8_SCHED; PG8_LDA(At, 0, 0); PG8_STAGE(PG8_SA(1, 1), a1 + hstep, voffA);
;             PG8_WAIT_V(8); PG8_WAIT_L(0); PG8_BAR; PG8_MMA(0, 0, At, B0); PG8_MMA(0, 1, At, B1); PG8_BAR; PG8_SCHED;
;     ...
;             PG8_LDA(At, 1, 1); PG8_STAGE(PG8_SB(1, 0), b3, voffB); PG8_STAGE(PG8_SB(1, 1), b3 + hstep, voffB); PG8_STAGE(PG8_SA(1, 0), a3, voffA);
;             PG8_WAIT_V(8); PG8_WAIT_L(0); PG8_BAR; PG8_MMA(1, 0, At, B0); PG8_MMA(1, 1, At, B1); PG8_BAR; PG8_SCHED;
	s_add_i32 s60, s84, s2
	v_lshl_add_u64 v[214:215], v[214:215], 0, s[26:27]
	s_mov_b32 m0, s60
	ds_read_b128 v[160:163], v209 offset:49152
	ds_read_b128 v[164:167], v209 offset:50176
	ds_read_b128 v[168:171], v209 offset:51200
	ds_read_b128 v[172:175], v209 offset:52224
	ds_read_b128 v[176:179], v209 offset:53248
	ds_read_b128 v[180:183], v209 offset:54272
	ds_read_b128 v[200:203], v209 offset:55296
	ds_read_b128 v[210:213], v209 offset:56320
	global_load_lds_dwordx4 v[214:215], off
	s_add_i32 m0, s60, 0x2000
	s_add_u32 s0, s0, 0xb0080
	v_lshl_add_u64 v[214:215], v[216:217], 0, s[26:27]
	s_addc_u32 s1, s1, 0
	s_add_i32 s60, s85, s2
	global_load_lds_dwordx4 v[214:215], off
	v_lshl_add_u64 v[214:215], s[0:1], 0, v[186:187]
	s_mov_b32 m0, s60
	s_nop 0
	global_load_lds_dwordx4 v[214:215], off
	v_lshl_add_u64 v[214:215], s[0:1], 0, v[190:191]
	s_add_i32 m0, s60, 0x2000
	s_nop 0
	global_load_lds_dwordx4 v[214:215], off
	v_lshl_add_u64 v[214:215], v[218:219], 0, s[26:27]
	s_mov_b32 m0, s37
	s_nop 0
	global_load_lds_dwordx4 v[214:215], off
	v_lshl_add_u64 v[214:215], v[220:221], 0, s[26:27]
	s_mov_b32 m0, s66
	s_nop 0
	global_load_lds_dwordx4 v[214:215], off
	s_waitcnt vmcnt(8)
	s_waitcnt lgkmcnt(0)
	s_barrier
	s_waitcnt lgkmcnt(0)
	v_mfma_f32_16x16x32_bf16 v[60:63], v[92:95], v[160:163], v[60:63]
	v_mfma_f32_16x16x32_bf16 v[56:59], v[112:115], v[160:163], v[56:59]
	v_mfma_f32_16x16x32_bf16 v[44:47], v[92:95], v[168:171], v[44:47]
	v_mfma_f32_16x16x32_bf16 v[40:43], v[112:115], v[168:171], v[40:43]
	v_mfma_f32_16x16x32_bf16 v[28:31], v[92:95], v[176:179], v[28:31]
	v_mfma_f32_16x16x32_bf16 v[24:27], v[112:115], v[176:179], v[24:27]
	v_mfma_f32_16x16x32_bf16 v[12:15], v[92:95], v[200:203], v[12:15]
	v_mfma_f32_16x16x32_bf16 v[8:11], v[112:115], v[200:203], v[8:11]
	v_mfma_f32_16x16x32_bf16 v[60:63], v[100:103], v[164:167], v[60:63]
	v_mfma_f32_16x16x32_bf16 v[56:59], v[124:127], v[164:167], v[56:59]
	v_mfma_f32_16x16x32_bf16 v[44:47], v[100:103], v[172:175], v[44:47]
	v_mfma_f32_16x16x32_bf16 v[40:43], v[124:127], v[172:175], v[40:43]
	v_mfma_f32_16x16x32_bf16 v[28:31], v[100:103], v[180:183], v[28:31]
	v_mfma_f32_16x16x32_bf16 v[24:27], v[124:127], v[180:183], v[24:27]
	v_mfma_f32_16x16x32_bf16 v[12:15], v[100:103], v[210:213], v[12:15]
	v_mfma_f32_16x16x32_bf16 v[8:11], v[124:127], v[210:213], v[8:11]
	v_mfma_f32_16x16x32_bf16 v[52:55], v[136:139], v[160:163], v[52:55]
	v_mfma_f32_16x16x32_bf16 v[48:51], v[152:155], v[160:163], v[48:51]
	v_mfma_f32_16x16x32_bf16 v[36:39], v[136:139], v[168:171], v[36:39]
	v_mfma_f32_16x16x32_bf16 v[32:35], v[152:155], v[168:171], v[32:35]
	v_mfma_f32_16x16x32_bf16 v[20:23], v[136:139], v[176:179], v[20:23]
	v_mfma_f32_16x16x32_bf16 v[16:19], v[152:155], v[176:179], v[16:19]
	v_mfma_f32_16x16x32_bf16 v[4:7], v[136:139], v[200:203], v[4:7]
	v_mfma_f32_16x16x32_bf16 v[0:3], v[152:155], v[200:203], v[0:3]
	v_mfma_f32_16x16x32_bf16 v[52:55], v[148:151], v[164:167], v[52:55]
	v_mfma_f32_16x16x32_bf16 v[48:51], v[156:159], v[164:167], v[48:51]
	v_mfma_f32_16x16x32_bf16 v[36:39], v[148:151], v[172:175], v[36:39]
	v_mfma_f32_16x16x32_bf16 v[32:35], v[156:159], v[172:175], v[32:35]
	v_mfma_f32_16x16x32_bf16 v[20:23], v[148:151], v[180:183], v[20:23]
	v_mfma_f32_16x16x32_bf16 v[16:19], v[156:159], v[180:183], v[16:19]
	v_mfma_f32_16x16x32_bf16 v[4:7], v[148:151], v[210:213], v[4:7]
	v_mfma_f32_16x16x32_bf16 v[0:3], v[156:159], v[210:213], v[0:3]
	s_barrier
	s_add_i32 s83, s83, 2
	s_add_u32 s81, s81, 0x100
	s_addc_u32 s82, s82, 0
	s_cmp_gt_u32 s83, 41
	s_mov_b64 s[60:61], s[62:63]
	s_cbranch_scc0 .LBB0_3135
	s_branch .Lmy_kdone_8
.LBB0_3135:
	ds_read_b128 v[92:95], v207
	ds_read_b128 v[100:103], v207 offset:1024
	ds_read_b128 v[112:115], v207 offset:2048
	ds_read_b128 v[124:127], v207 offset:3072
	ds_read_b128 v[136:139], v208
	ds_read_b128 v[148:151], v208 offset:1024
	ds_read_b128 v[152:155], v208 offset:2048
	ds_read_b128 v[156:159], v208 offset:3072
	s_add_u32 s62, s60, 0x100
	s_addc_u32 s63, s61, 0
	s_cmp_eq_u32 s83, 40
	s_cselect_b32 s65, s9, s63
	s_cselect_b32 s64, s8, s62
	s_cselect_b32 s1, s59, s82
	s_cselect_b32 s0, s58, s81
	v_lshl_add_u64 v[214:215], s[60:61], 0, v[192:193]
	s_add_i32 m0, s4, 0xc000
	ds_read_b128 v[160:163], v209
	ds_read_b128 v[164:167], v209 offset:1024
	ds_read_b128 v[168:171], v209 offset:2048
	ds_read_b128 v[172:175], v209 offset:3072
	ds_read_b128 v[176:179], v209 offset:4096
	ds_read_b128 v[180:183], v209 offset:5120
	ds_read_b128 v[200:203], v209 offset:6144
	ds_read_b128 v[210:213], v209 offset:7168
	global_load_lds_dwordx4 v[214:215], off
	v_lshl_add_u64 v[214:215], s[60:61], 0, v[194:195]
	s_add_i32 m0, s4, 0xe000
	s_nop 0
	global_load_lds_dwordx4 v[214:215], off
	s_waitcnt vmcnt(8)
	s_waitcnt lgkmcnt(0)
	s_barrier
; #define PG8_STAGE(bufoff, gbase, voff) do { _Pragma("unroll") for (int _i = 0; _i < 2; ++_i) \
;         __builtin_amdgcn_global_load_lds((const unsigned*)((const char*)(gbase) + (voff)[_i]), (PG8_LAS unsigned*)(lds + (bufoff) + ldsw + _i * 8192), 16, 0, 0); } while (0)
; #define PG8_LDA(dst, b, h) do { _Pragma("unroll") for (int m = 0; m < 4; ++m) _Pragma("unroll") for (int k = 0; k < 2; ++k) dst[m][k] = *(const PG8_LAS bf16x8*)(lds + PG8_SA(b, h) + aoff + m * 2048 + k * 1024); } while (0)
; #define PG8_LDB(dst, b, h) do { _Pragma("unroll") for (int n = 0; n < 2; ++n) _Pragma("unroll") for (int k = 0; k < 2; ++k) dst[n][k] = *(const PG8_LAS bf16x8*)(lds + PG8_SB(b, h) + boff + n * 2048 + k * 1024); } while (0)
; #define PG8_MMA(ai, bj, At, Bt) do { __builtin_amdgcn_s_setprio(1); _Pragma("unroll") for (int m = 0; m < 4; ++m) _Pragma("unroll") for (int n = 0; n < 2; ++n) _Pragma("unroll") for (int k = 0; k < 2; ++k) \
;         acc[ai][bj][m][n] = __builtin_amdgcn_mfma_f32_16x16x32_bf16(Bt[n][k], At[m][k], acc[ai][bj][m][n], 0, 0, 0); __builtin_amdgcn_s_setprio(0); } while (0)
; #define PG8_WAIT_V(n) asm volatile("s_waitcnt vmcnt(" #n ")" ::: "memory")
; #define PG8_WAIT_L(n) asm volatile("s_waitcnt lgkmcnt(" #n ")" ::: "memory")
; #define PG8_BAR __builtin_amdgcn_s_barrier()
; #define PG8_SCHED __builtin_amdgcn_sched_barrier(0)
; template <class Epi, class Sched, bool ALIGN_EPI = false, bool SP2 = false>
; __device__ __forceinline__ void gemm_phase(PG8_LAS unsigned char* lds, const Gemm g, const Sched& S, const Epi& E, const int tid_in) {
;     ...
;             PG8_LDB(B0, 0, 0); PG8_LDB(B1, 0, 1); PG8_SCHED; PG8_LDA(At, 0, 0); PG8_STAGE(PG8_SA(1, 1), a1 + hstep, voffA);
;             PG8_WAIT_V(8); PG8_WAIT_L(0); PG8_BAR; PG8_MMA(0, 0, At, B0); PG8_MMA(0, 1, At, B1); PG8_BAR; PG8_SCHED;
;             PG8_LDA(At, 0, 1); PG8_STAGE(PG8_SB(0, 0), b2, voffB); PG8_STAGE(PG8_SB(0, 1), b2 + hstep, voffB); PG8_STAGE(PG8_SA(0, 0), a2, voffA);
;             PG8_WAIT_V(8); PG8_WAIT_L(0); PG8_BAR; PG8_MMA(1, 0, At, B0); PG8_MMA(1, 1, At, B1); PG8_BAR; PG8_SCHED;
;             PG8_LDB(B0, 1, 0); PG8_LDB(B1, 1, 1); PG8_SCHED; PG8_LDA(At, 1, 0); PG8_STAGE(PG8_SA(0, 1), a2 + hstep, voffA);
;             PG8_WAIT_V(8); PG8_WAIT_L(0); PG8_BAR; PG8_MMA(0, 0, At, B0); PG8_MMA(0, 1, At, B1); PG8_BAR; PG8_SCHED;
	s_waitcnt lgkmcnt(0)
	v_mfma_f32_16x16x32_bf16 v[144:147], v[92:95], v[160:163], v[144:147]
	v_mfma_f32_16x16x32_bf16 v[140:143], v[112:115], v[160:163], v[140:143]
	v_mfma_f32_16x16x32_bf16 v[120:123], v[92:95], v[168:171], v[120:123]
	v_mfma_f32_16x16x32_bf16 v[116:119], v[112:115], v[168:171], v[116:119]
	v_mfma_f32_16x16x32_bf16 v[96:99], v[92:95], v[176:179], v[96:99]
	v_mfma_f32_16x16x32_bf16 v[88:91], v[112:115], v[176:179], v[88:91]
	v_mfma_f32_16x16x32_bf16 v[76:79], v[92:95], v[200:203], v[76:79]
	v_mfma_f32_16x16x32_bf16 v[72:75], v[112:115], v[200:203], v[72:75]
	v_mfma_f32_16x16x32_bf16 v[144:147], v[100:103], v[164:167], v[144:147]
	v_mfma_f32_16x16x32_bf16 v[140:143], v[124:127], v[164:167], v[140:143]
	v_mfma_f32_16x16x32_bf16 v[120:123], v[100:103], v[172:175], v[120:123]
	v_mfma_f32_16x16x32_bf16 v[116:119], v[124:127], v[172:175], v[116:119]
	v_mfma_f32_16x16x32_bf16 v[96:99], v[100:103], v[180:183], v[96:99]
	v_mfma_f32_16x16x32_bf16 v[88:91], v[124:127], v[180:183], v[88:91]
	v_mfma_f32_16x16x32_bf16 v[76:79], v[100:103], v[210:213], v[76:79]
	v_mfma_f32_16x16x32_bf16 v[72:75], v[124:127], v[210:213], v[72:75]
	v_mfma_f32_16x16x32_bf16 v[132:135], v[136:139], v[160:163], v[132:135]
	v_mfma_f32_16x16x32_bf16 v[128:131], v[152:155], v[160:163], v[128:131]
	v_mfma_f32_16x16x32_bf16 v[108:111], v[136:139], v[168:171], v[108:111]
	v_mfma_f32_16x16x32_bf16 v[104:107], v[152:155], v[168:171], v[104:107]
	v_mfma_f32_16x16x32_bf16 v[84:87], v[136:139], v[176:179], v[84:87]
	v_mfma_f32_16x16x32_bf16 v[80:83], v[152:155], v[176:179], v[80:83]
	v_mfma_f32_16x16x32_bf16 v[68:71], v[136:139], v[200:203], v[68:71]
	v_mfma_f32_16x16x32_bf16 v[64:67], v[152:155], v[200:203], v[64:67]
	v_mfma_f32_16x16x32_bf16 v[132:135], v[148:151], v[164:167], v[132:135]
	v_mfma_f32_16x16x32_bf16 v[128:131], v[156:159], v[164:167], v[128:131]
	v_mfma_f32_16x16x32_bf16 v[108:111], v[148:151], v[172:175], v[108:111]
	v_mfma_f32_16x16x32_bf16 v[104:107], v[156:159], v[172:175], v[104:107]
	v_mfma_f32_16x16x32_bf16 v[84:87], v[148:151], v[180:183], v[84:87]
	v_mfma_f32_16x16x32_bf16 v[80:83], v[156:159], v[180:183], v[80:83]
	v_mfma_f32_16x16x32_bf16 v[68:71], v[148:151], v[210:213], v[68:71]
	v_mfma_f32_16x16x32_bf16 v[64:67], v[156:159], v[210:213], v[64:67]
	s_barrier
	s_add_i32 s60, s3, s2
	v_lshl_add_u64 v[214:215], s[0:1], 0, v[186:187]
	s_mov_b32 m0, s60
	ds_read_b128 v[160:163], v209 offset:16384
	ds_read_b128 v[164:167], v209 offset:17408
	ds_read_b128 v[168:171], v209 offset:18432
	ds_read_b128 v[172:175], v209 offset:19456
	ds_read_b128 v[176:179], v209 offset:20480
	ds_read_b128 v[180:183], v209 offset:21504
	ds_read_b128 v[200:203], v209 offset:22528
	ds_read_b128 v[210:213], v209 offset:23552
	global_load_lds_dwordx4 v[214:215], off
	s_add_i32 m0, s60, 0x2000
	s_add_u32 s60, s0, 0xb0000
	v_lshl_add_u64 v[216:217], s[0:1], 0, v[190:191]
	s_addc_u32 s61, s1, 0
	s_add_i32 s84, s69, s2
	global_load_lds_dwordx4 v[216:217], off
	v_lshl_add_u64 v[218:219], s[60:61], 0, v[186:187]
	s_mov_b32 m0, s84
	v_lshl_add_u64 v[220:221], s[64:65], 0, v[188:189]
	global_load_lds_dwordx4 v[218:219], off
	v_lshl_add_u64 v[218:219], s[60:61], 0, v[190:191]
	s_add_i32 m0, s84, 0x2000
	s_nop 0
	global_load_lds_dwordx4 v[218:219], off
	v_lshl_add_u64 v[218:219], s[64:65], 0, v[184:185]
	s_mov_b32 m0, s4
	s_nop 0
	global_load_lds_dwordx4 v[218:219], off
	s_mov_b32 m0, s5
	s_nop 0
	global_load_lds_dwordx4 v[220:221], off
	s_waitcnt vmcnt(8)
	s_waitcnt lgkmcnt(0)
	s_barrier
	s_waitcnt lgkmcnt(0)
	v_mfma_f32_16x16x32_bf16 v[60:63], v[92:95], v[160:163], v[60:63]
	v_mfma_f32_16x16x32_bf16 v[56:59], v[112:115], v[160:163], v[56:59]
	v_mfma_f32_16x16x32_bf16 v[44:47], v[92:95], v[168:171], v[44:47]
	v_mfma_f32_16x16x32_bf16 v[40:43], v[112:115], v[168:171], v[40:43]
	v_mfma_f32_16x16x32_bf16 v[28:31], v[92:95], v[176:179], v[28:31]
	v_mfma_f32_16x16x32_bf16 v[24:27], v[112:115], v[176:179], v[24:27]
	v_mfma_f32_16x16x32_bf16 v[12:15], v[92:95], v[200:203], v[12:15]
	v_mfma_f32_16x16x32_bf16 v[8:11], v[112:115], v[200:203], v[8:11]
	v_mfma_f32_16x16x32_bf16 v[60:63], v[100:103], v[164:167], v[60:63]
	v_mfma_f32_16x16x32_bf16 v[56:59], v[124:127], v[164:167], v[56:59]
	v_mfma_f32_16x16x32_bf16 v[44:47], v[100:103], v[172:175], v[44:47]
	v_mfma_f32_16x16x32_bf16 v[40:43], v[124:127], v[172:175], v[40:43]
	v_mfma_f32_16x16x32_bf16 v[28:31], v[100:103], v[180:183], v[28:31]
	v_mfma_f32_16x16x32_bf16 v[24:27], v[124:127], v[180:183], v[24:27]
	v_mfma_f32_16x16x32_bf16 v[12:15], v[100:103], v[210:213], v[12:15]
	v_mfma_f32_16x16x32_bf16 v[8:11], v[124:127], v[210:213], v[8:11]
	v_mfma_f32_16x16x32_bf16 v[52:55], v[136:139], v[160:163], v[52:55]
	v_mfma_f32_16x16x32_bf16 v[48:51], v[152:155], v[160:163], v[48:51]
	v_mfma_f32_16x16x32_bf16 v[36:39], v[136:139], v[168:171], v[36:39]
	v_mfma_f32_16x16x32_bf16 v[32:35], v[152:155], v[168:171], v[32:35]
	v_mfma_f32_16x16x32_bf16 v[20:23], v[136:139], v[176:179], v[20:23]
	v_mfma_f32_16x16x32_bf16 v[16:19], v[152:155], v[176:179], v[16:19]
	v_mfma_f32_16x16x32_bf16 v[4:7], v[136:139], v[200:203], v[4:7]
	v_mfma_f32_16x16x32_bf16 v[0:3], v[152:155], v[200:203], v[0:3]
	v_mfma_f32_16x16x32_bf16 v[52:55], v[148:151], v[164:167], v[52:55]
	v_mfma_f32_16x16x32_bf16 v[48:51], v[156:159], v[164:167], v[48:51]
	v_mfma_f32_16x16x32_bf16 v[36:39], v[148:151], v[172:175], v[36:39]
	v_mfma_f32_16x16x32_bf16 v[32:35], v[156:159], v[172:175], v[32:35]
	v_mfma_f32_16x16x32_bf16 v[20:23], v[148:151], v[180:183], v[20:23]
	v_mfma_f32_16x16x32_bf16 v[16:19], v[156:159], v[180:183], v[16:19]
	v_mfma_f32_16x16x32_bf16 v[4:7], v[148:151], v[210:213], v[4:7]
	v_mfma_f32_16x16x32_bf16 v[0:3], v[156:159], v[210:213], v[0:3]
	s_barrier
; #define PG8_STAGE(bufoff, gbase, voff) do { _Pragma("unroll") for (int _i = 0; _i < 2; ++_i) \
;         __builtin_amdgcn_global_load_lds((const unsigned*)((const char*)(gbase) + (voff)[_i]), (PG8_LAS unsigned*)(lds + (bufoff) + ldsw + _i * 8192), 16, 0, 0); } while (0)
; #define PG8_LDA(dst, b, h) do { _Pragma("unroll") for (int m = 0; m < 4; ++m) _Pragma("unroll") for (int k = 0; k < 2; ++k) dst[m][k] = *(const PG8_LAS bf16x8*)(lds + PG8_SA(b, h) + aoff + m * 2048 + k * 1024); } while (0)
; #define PG8_LDB(dst, b, h) do { _Pragma("unroll") for (int n = 0; n < 2; ++n) _Pragma("unroll") for (int k = 0; k < 2; ++k) dst[n][k] = *(const PG8_LAS bf16x8*)(lds + PG8_SB(b, h) + boff + n * 2048 + k * 1024); } while (0)
; #define PG8_MMA(ai, bj, At, Bt) do { __builtin_amdgcn_s_setprio(1); _Pragma("unroll") for (int m = 0; m < 4; ++m) _Pragma("unroll") for (int n = 0; n < 2; ++n) _Pragma("unroll") for (int k = 0; k < 2; ++k) \
;         acc[ai][bj][m][n] = __builtin_amdgcn_mfma_f32_16x16x32_bf16(Bt[n][k], At[m][k], acc[ai][bj][m][n], 0, 0, 0); __builtin_amdgcn_s_setprio(0); } while (0)
; #define PG8_WAIT_V(n) asm volatile("s_waitcnt vmcnt(" #n ")" ::: "memory")
; #define PG8_WAIT_L(n) asm volatile("s_waitcnt lgkmcnt(" #n ")" ::: "memory")
; #define PG8_BAR __builtin_amdgcn_s_barrier()
; #define PG8_SCHED __builtin_amdgcn_sched_barrier(0)
; template <class Epi, class Sched, bool ALIGN_EPI = false, bool SP2 = false>
; __device__ __forceinline__ void gemm_phase(PG8_LAS unsigned char* lds, const Gemm g, const Sched& S, const Epi& E, const int tid_in) {
;     ...
;             PG8_LDB(B0, 1, 0); PG8_LDB(B1, 1, 1); PG8_SCHED; PG8_LDA(At, 1, 0); PG8_STAGE(PG8_SA(0, 1), a2 + hstep, voffA);
;             PG8_WAIT_V(8); PG8_WAIT_L(0); PG8_BAR; PG8_MMA(0, 0, At, B0); PG8_MMA(0, 1, At, B1); PG8_BAR; PG8_SCHED;
;             PG8_LDA(At, 1, 1); PG8_STAGE(PG8_SB(1, 0), b3, voffB); PG8_STAGE(PG8_SB(1, 1), b3 + hstep, voffB); PG8_STAGE(PG8_SA(1, 0), a3, voffA);
;             PG8_WAIT_V(8); PG8_WAIT_L(0); PG8_BAR; PG8_MMA(1, 0, At, B0); PG8_MMA(1, 1, At, B1); PG8_BAR; PG8_SCHED;
	s_add_i32 s84, 0, 0x18000
	s_add_i32 s85, 0, 0x1c000
	v_add_u32_e32 v124, s84, v205
	v_add_u32_e32 v156, s85, v205
	ds_read_b128 v[92:95], v124
	ds_read_b128 v[100:103], v124 offset:1024
	ds_read_b128 v[112:115], v124 offset:2048
	ds_read_b128 v[124:127], v124 offset:3072
	ds_read_b128 v[136:139], v156
	ds_read_b128 v[148:151], v156 offset:1024
	ds_read_b128 v[152:155], v156 offset:2048
	ds_read_b128 v[156:159], v156 offset:3072
	s_add_u32 s60, s64, 0xb0000
	s_addc_u32 s61, s65, 0
	s_mov_b32 m0, s34
	v_lshl_add_u64 v[222:223], s[60:61], 0, v[184:185]
	ds_read_b128 v[160:163], v209 offset:32768
	ds_read_b128 v[164:167], v209 offset:33792
	ds_read_b128 v[168:171], v209 offset:34816
	ds_read_b128 v[172:175], v209 offset:35840
	ds_read_b128 v[176:179], v209 offset:36864
	ds_read_b128 v[180:183], v209 offset:37888
	ds_read_b128 v[200:203], v209 offset:38912
	ds_read_b128 v[210:213], v209 offset:39936
	global_load_lds_dwordx4 v[222:223], off
	v_lshl_add_u64 v[222:223], s[60:61], 0, v[188:189]
	s_mov_b32 m0, s35
	s_nop 0
	global_load_lds_dwordx4 v[222:223], off
	s_waitcnt vmcnt(8)
	s_waitcnt lgkmcnt(0)
	s_barrier
	s_waitcnt lgkmcnt(0)
	v_mfma_f32_16x16x32_bf16 v[144:147], v[92:95], v[160:163], v[144:147]
	v_mfma_f32_16x16x32_bf16 v[140:143], v[112:115], v[160:163], v[140:143]
	v_mfma_f32_16x16x32_bf16 v[120:123], v[92:95], v[168:171], v[120:123]
	v_mfma_f32_16x16x32_bf16 v[116:119], v[112:115], v[168:171], v[116:119]
	v_mfma_f32_16x16x32_bf16 v[96:99], v[92:95], v[176:179], v[96:99]
	v_mfma_f32_16x16x32_bf16 v[88:91], v[112:115], v[176:179], v[88:91]
	v_mfma_f32_16x16x32_bf16 v[76:79], v[92:95], v[200:203], v[76:79]
	v_mfma_f32_16x16x32_bf16 v[72:75], v[112:115], v[200:203], v[72:75]
	v_mfma_f32_16x16x32_bf16 v[144:147], v[100:103], v[164:167], v[144:147]
	v_mfma_f32_16x16x32_bf16 v[140:143], v[124:127], v[164:167], v[140:143]
	v_mfma_f32_16x16x32_bf16 v[120:123], v[100:103], v[172:175], v[120:123]
	v_mfma_f32_16x16x32_bf16 v[116:119], v[124:127], v[172:175], v[116:119]
	v_mfma_f32_16x16x32_bf16 v[96:99], v[100:103], v[180:183], v[96:99]
	v_mfma_f32_16x16x32_bf16 v[88:91], v[124:127], v[180:183], v[88:91]
	v_mfma_f32_16x16x32_bf16 v[76:79], v[100:103], v[210:213], v[76:79]
	v_mfma_f32_16x16x32_bf16 v[72:75], v[124:127], v[210:213], v[72:75]
	v_mfma_f32_16x16x32_bf16 v[132:135], v[136:139], v[160:163], v[132:135]
	v_mfma_f32_16x16x32_bf16 v[128:131], v[152:155], v[160:163], v[128:131]
	v_mfma_f32_16x16x32_bf16 v[108:111], v[136:139], v[168:171], v[108:111]
	v_mfma_f32_16x16x32_bf16 v[104:107], v[152:155], v[168:171], v[104:107]
	v_mfma_f32_16x16x32_bf16 v[84:87], v[136:139], v[176:179], v[84:87]
	v_mfma_f32_16x16x32_bf16 v[80:83], v[152:155], v[176:179], v[80:83]
	v_mfma_f32_16x16x32_bf16 v[68:71], v[136:139], v[200:203], v[68:71]
	v_mfma_f32_16x16x32_bf16 v[64:67], v[152:155], v[200:203], v[64:67]
	v_mfma_f32_16x16x32_bf16 v[132:135], v[148:151], v[164:167], v[132:135]
	v_mfma_f32_16x16x32_bf16 v[128:131], v[156:159], v[164:167], v[128:131]
	v_mfma_f32_16x16x32_bf16 v[108:111], v[148:151], v[172:175], v[108:111]
	v_mfma_f32_16x16x32_bf16 v[104:107], v[156:159], v[172:175], v[104:107]
	v_mfma_f32_16x16x32_bf16 v[84:87], v[148:151], v[180:183], v[84:87]
	v_mfma_f32_16x16x32_bf16 v[80:83], v[156:159], v[180:183], v[80:83]
	v_mfma_f32_16x16x32_bf16 v[68:71], v[148:151], v[210:213], v[68:71]
	v_mfma_f32_16x16x32_bf16 v[64:67], v[156:159], v[210:213], v[64:67]
	s_barrier
	s_add_i32 s60, s84, s2
	v_lshl_add_u64 v[214:215], v[214:215], 0, s[26:27]
	s_mov_b32 m0, s60
	ds_read_b128 v[160:163], v209 offset:49152
	ds_read_b128 v[164:167], v209 offset:50176
	ds_read_b128 v[168:171], v209 offset:51200
	ds_read_b128 v[172:175], v209 offset:52224
	ds_read_b128 v[176:179], v209 offset:53248
	ds_read_b128 v[180:183], v209 offset:54272
	ds_read_b128 v[200:203], v209 offset:55296
	ds_read_b128 v[210:213], v209 offset:56320
	global_load_lds_dwordx4 v[214:215], off
	s_add_i32 m0, s60, 0x2000
	s_add_u32 s0, s0, 0xb0080
	v_lshl_add_u64 v[214:215], v[216:217], 0, s[26:27]
	s_addc_u32 s1, s1, 0
	s_add_i32 s60, s85, s2
	global_load_lds_dwordx4 v[214:215], off
	v_lshl_add_u64 v[214:215], s[0:1], 0, v[186:187]
	s_mov_b32 m0, s60
	s_nop 0
	global_load_lds_dwordx4 v[214:215], off
	v_lshl_add_u64 v[214:215], s[0:1], 0, v[190:191]
	s_add_i32 m0, s60, 0x2000
	s_nop 0
	global_load_lds_dwordx4 v[214:215], off
	v_lshl_add_u64 v[214:215], v[218:219], 0, s[26:27]
	s_mov_b32 m0, s37
	s_nop 0
	global_load_lds_dwordx4 v[214:215], off
	v_lshl_add_u64 v[214:215], v[220:221], 0, s[26:27]
	s_mov_b32 m0, s66
	s_nop 0
	global_load_lds_dwordx4 v[214:215], off
	s_waitcnt vmcnt(8)
	s_waitcnt lgkmcnt(0)
	s_barrier
	s_waitcnt lgkmcnt(0)
	v_mfma_f32_16x16x32_bf16 v[60:63], v[92:95], v[160:163], v[60:63]
	v_mfma_f32_16x16x32_bf16 v[56:59], v[112:115], v[160:163], v[56:59]
	v_mfma_f32_16x16x32_bf16 v[44:47], v[92:95], v[168:171], v[44:47]
	v_mfma_f32_16x16x32_bf16 v[40:43], v[112:115], v[168:171], v[40:43]
	v_mfma_f32_16x16x32_bf16 v[28:31], v[92:95], v[176:179], v[28:31]
	v_mfma_f32_16x16x32_bf16 v[24:27], v[112:115], v[176:179], v[24:27]
	v_mfma_f32_16x16x32_bf16 v[12:15], v[92:95], v[200:203], v[12:15]
	v_mfma_f32_16x16x32_bf16 v[8:11], v[112:115], v[200:203], v[8:11]
	v_mfma_f32_16x16x32_bf16 v[60:63], v[100:103], v[164:167], v[60:63]
	v_mfma_f32_16x16x32_bf16 v[56:59], v[124:127], v[164:167], v[56:59]
	v_mfma_f32_16x16x32_bf16 v[44:47], v[100:103], v[172:175], v[44:47]
	v_mfma_f32_16x16x32_bf16 v[40:43], v[124:127], v[172:175], v[40:43]
	v_mfma_f32_16x16x32_bf16 v[28:31], v[100:103], v[180:183], v[28:31]
	v_mfma_f32_16x16x32_bf16 v[24:27], v[124:127], v[180:183], v[24:27]
	v_mfma_f32_16x16x32_bf16 v[12:15], v[100:103], v[210:213], v[12:15]
	v_mfma_f32_16x16x32_bf16 v[8:11], v[124:127], v[210:213], v[8:11]
	v_mfma_f32_16x16x32_bf16 v[52:55], v[136:139], v[160:163], v[52:55]
	v_mfma_f32_16x16x32_bf16 v[48:51], v[152:155], v[160:163], v[48:51]
	v_mfma_f32_16x16x32_bf16 v[36:39], v[136:139], v[168:171], v[36:39]
	v_mfma_f32_16x16x32_bf16 v[32:35], v[152:155], v[168:171], v[32:35]
	v_mfma_f32_16x16x32_bf16 v[20:23], v[136:139], v[176:179], v[20:23]
	v_mfma_f32_16x16x32_bf16 v[16:19], v[152:155], v[176:179], v[16:19]
	v_mfma_f32_16x16x32_bf16 v[4:7], v[136:139], v[200:203], v[4:7]
	v_mfma_f32_16x16x32_bf16 v[0:3], v[152:155], v[200:203], v[0:3]
	v_mfma_f32_16x16x32_bf16 v[52:55], v[148:151], v[164:167], v[52:55]
	v_mfma_f32_16x16x32_bf16 v[48:51], v[156:159], v[164:167], v[48:51]
	v_mfma_f32_16x16x32_bf16 v[36:39], v[148:151], v[172:175], v[36:39]
	v_mfma_f32_16x16x32_bf16 v[32:35], v[156:159], v[172:175], v[32:35]
	v_mfma_f32_16x16x32_bf16 v[20:23], v[148:151], v[180:183], v[20:23]
	v_mfma_f32_16x16x32_bf16 v[16:19], v[156:159], v[180:183], v[16:19]
	v_mfma_f32_16x16x32_bf16 v[4:7], v[148:151], v[210:213], v[4:7]
	v_mfma_f32_16x16x32_bf16 v[0:3], v[156:159], v[210:213], v[0:3]
	s_barrier
	s_add_i32 s83, s83, 2
	s_add_u32 s81, s81, 0x100
	s_addc_u32 s82, s82, 0
	s_cmp_gt_u32 s83, 41
	s_mov_b64 s[60:61], s[62:63]
	s_cbranch_scc0 .LBB0_3135
